# GEMM K loops: first iteration peeled with constant-zero accumulator inputs, accumulator zero-init removed (8 loops), on top of v37
# speedup vs baseline: 1.0232x; 1.0003x over previous
; #define LDA8(dst, b, h) _Pragma("unroll") for (int m = 0; m < 4; ++m) _Pragma("unroll") for (int k = 0; k < 2; ++k) \
;     dst[m][k] = *(const bf16x8*)((const char*)SA8(b, h) + lds_byte8(wr * 64 + m * 16 + fr, k * 32 + fq * 8))
; #define LDB8(dst, b, h) _Pragma("unroll") for (int n = 0; n < 2; ++n) _Pragma("unroll") for (int k = 0; k < 2; ++k) \
;     dst[n][k] = *(const bf16x8*)((const char*)SB8(b, h) + lds_byte8(wc * 32 + n * 16 + fr, k * 32 + fq * 8))
; #define WAIT_V8(n) asm volatile("s_waitcnt vmcnt(" #n ")" ::: "memory")
; #define WAIT_L8(n) asm volatile("s_waitcnt lgkmcnt(" #n ")" ::: "memory")
; #define BAR8 __builtin_amdgcn_s_barrier()
; #define SCHED8 __builtin_amdgcn_sched_barrier(0)
;     ...
;   f32x4 acc[2][2][4][2];
;   {
;     float zinit = 0.f;
;     asm volatile("" : "+v"(zinit));
; #pragma unroll
;     for (int a = 0; a < 2; ++a)
; #pragma unroll
;       for (int b = 0; b < 2; ++b)
; #pragma unroll
;         for (int m = 0; m < 4; ++m)
; #pragma unroll
;           for (int n = 0; n < 2; ++n)
; #pragma unroll
;             for (int j = 0; j < 4; ++j) acc[a][b][m][n][j] = zinit;
;   }
;   bf16x8 At[4][2], B0[2][2], B1[2][2];
;   const int nt = K / 64;
;   if (!pre) {
;     STAGE8(SB8(0, 0), Bt, K, bcol, 0); STAGE8(SA8(0, 0), A, lda, brow, 0);
;     STAGE8(SB8(0, 1), Bt, K, bcol + 128, 0); STAGE8(SA8(0, 1), A, lda, brow + 128, 0);
;   }
;   if (wr == 1) BAR8;
;   WAIT_V8(4); BAR8;
;   STAGE8(SB8(1, 0), Bt, K, bcol, 1); STAGE8(SA8(1, 0), A, lda, brow, 1); STAGE8(SB8(1, 1), Bt, K, bcol + 128, 1);
;   WAIT_V8(6); BAR8;
;   for (int tt = 0; tt < nt - 2; tt += 2) {
;     LDB8(B0, 0, 0); SCHED8; LDA8(At, 0, 0); STAGE8(SA8(1, 1), A, lda, brow + 128, tt + 1);
;     WAIT_L8(8); BAR8; WAIT_L8(0); MMA8(0, 0, At, B0); BAR8; SCHED8;
;     LDB8(B1, 0, 1); STAGE8(SB8(0, 0), Bt, K, bcol, tt + 2);
;     BAR8; WAIT_L8(0); MMA8(0, 1, At, B1); BAR8;
;     LDA8(At, 0, 1); STAGE8(SA8(0, 0), A, lda, brow, tt + 2);
;     BAR8; WAIT_L8(0); MMA8(1, 0, At, B0); BAR8; SCHED8;
;     STAGE8(SB8(0, 1), Bt, K, bcol + 128, tt + 2);
;     WAIT_V8(6); BAR8; MMA8(1, 1, At, B1); BAR8;
.LBB0_191:
	s_or_b64 exec, exec, s[14:15]
	v_add_u32_e32 v164, 0x18000, v150
	s_mov_b64 s[60:61], 0x80
	v_readfirstlane_b32 s14, v164
	v_add_u32_e32 v165, 0x1a000, v150
	v_lshl_add_u64 v[10:11], v[10:11], 0, s[60:61]
	s_mov_b32 m0, s14
	v_readfirstlane_b32 s14, v165
	v_add_u32_e32 v166, 0x8000, v150
	s_waitcnt vmcnt(4)
	s_barrier
	global_load_lds_dwordx4 v[10:11], off
	v_lshl_add_u64 v[10:11], v[12:13], 0, s[60:61]
	s_mov_b32 m0, s14
	v_readfirstlane_b32 s14, v166
	v_add_u32_e32 v167, 0xa000, v150
	global_load_lds_dwordx4 v[10:11], off
	v_lshl_add_u64 v[10:11], v[14:15], 0, s[60:61]
	s_mov_b32 m0, s14
	v_readfirstlane_b32 s14, v167
	v_add_u32_e32 v168, 0x1c000, v150
	global_load_lds_dwordx4 v[10:11], off
	v_lshl_add_u64 v[10:11], v[16:17], 0, s[60:61]
	s_mov_b32 m0, s14
	v_readfirstlane_b32 s14, v168
	v_add_u32_e32 v170, 0x1e000, v150
	global_load_lds_dwordx4 v[10:11], off
	v_lshl_add_u64 v[10:11], v[18:19], 0, s[60:61]
	s_mov_b32 m0, s14
	v_readfirstlane_b32 s14, v170
	global_load_lds_dwordx4 v[10:11], off
	v_lshl_add_u64 v[10:11], v[20:21], 0, s[60:61]
	s_mov_b32 m0, s14
	v_and_b32_e32 v147, 15, v3
	global_load_lds_dwordx4 v[10:11], off
	v_bfe_u32 v148, v3, 4, 2
	v_lshlrev_b32_e32 v10, 4, v148
	v_lshlrev_b32_e32 v11, 6, v147
	v_lshlrev_b32_e32 v14, 2, v3
	v_or_b32_e32 v13, v10, v11
	v_and_b32_e32 v14, 32, v14
	s_mov_b32 s14, 0x10000
	v_bitop3_b32 v16, v13, s14, v14 bitop3:0xde
	s_mov_b32 s14, 0x14000
	v_bitop3_b32 v15, v10, v14, v11 bitop3:0x36
	v_bitop3_b32 v17, v13, s14, v14 bitop3:0xde
	s_mov_b32 s14, 0x18000
	v_lshlrev_b32_e32 v11, 6, v3
	v_bitop3_b32 v18, v13, s14, v14 bitop3:0xde
	s_mov_b32 s14, 0x1c000
	v_and_b32_e32 v11, 0x3c0, v11
	v_bitop3_b32 v13, v13, s14, v14 bitop3:0xde
	v_bitop3_b32 v14, v11, v14, v10 bitop3:0x36
	v_lshl_add_u64 v[10:11], s[30:31], 0, v[136:137]
	v_lshl_add_u64 v[10:11], v[10:11], 0, v[8:9]
	v_lshl_add_u64 v[138:139], s[12:13], 0, v[10:11]
	v_lshl_add_u64 v[10:11], s[30:31], 0, v[132:133]
	v_lshl_add_u64 v[10:11], v[10:11], 0, v[6:7]
	v_lshl_add_u64 v[140:141], s[12:13], 0, v[10:11]
	v_lshl_add_u64 v[10:11], s[56:57], 0, v[132:133]
	v_lshl_add_u64 v[6:7], v[10:11], 0, v[6:7]
	v_bfe_u32 v146, v3, 6, 2
	s_waitcnt vmcnt(6)
	v_lshlrev_b32_e32 v149, 6, v5
	v_lshlrev_b32_e32 v5, 13, v5
	v_lshl_add_u64 v[142:143], s[46:47], 0, v[6:7]
	v_lshl_add_u64 v[6:7], s[56:57], 0, v[136:137]
	v_lshlrev_b32_e32 v12, 12, v146
	v_or_b32_e32 v19, 0x800, v5
	v_or_b32_e32 v20, 0x1000, v5
	v_or_b32_e32 v21, 0x1800, v5
	v_lshl_add_u64 v[6:7], v[6:7], 0, v[8:9]
	v_lshl_add_u64 v[144:145], s[46:47], 0, v[6:7]
	s_mov_b32 s14, -2
	s_mov_b64 s[12:13], 0
	v_add_u32_e32 v173, v16, v12
	v_add_u32_e32 v156, v15, v5
	v_add_u32_e32 v154, v14, v19
	v_add_u32_e32 v153, v14, v20
	v_add_u32_e32 v152, v14, v21
	v_add_u32_e32 v172, 0xc000, v150
	v_add_u32_e32 v171, 0xe000, v150
	v_add_u32_e32 v169, v17, v12
	v_add_u32_e32 v159, v18, v12
	v_add_u32_e32 v158, v13, v12
	s_mov_b64 s[60:61], 0xc000100
	s_mov_b64 s[62:63], 0xc040100
	s_mov_b64 s[64:65], 0xc000180
	s_mov_b64 s[66:67], 0xc040180
	s_barrier
	ds_read_b128 v[174:177], v173
	ds_read_b128 v[178:181], v173 offset:1024
	ds_read_b128 v[182:185], v173 offset:2048
	ds_read_b128 v[186:189], v173 offset:3072
	v_lshl_add_u64 v[222:223], v[140:141], 0, s[12:13]
	v_readfirstlane_b32 s15, v172
	v_lshl_add_u64 v[226:227], v[222:223], 0, s[34:35]
	s_mov_b32 m0, s15
	ds_read_b128 v[190:193], v156
	ds_read_b128 v[194:197], v156 offset:1024
	ds_read_b128 v[198:201], v154
	ds_read_b128 v[202:205], v154 offset:1024
	ds_read_b128 v[206:209], v153
	ds_read_b128 v[210:213], v153 offset:1024
	ds_read_b128 v[214:217], v152
	ds_read_b128 v[218:221], v152 offset:1024
	global_load_lds_dwordx4 v[226:227], off
	v_lshl_add_u64 v[226:227], v[138:139], 0, s[12:13]
	v_readfirstlane_b32 s15, v171
	v_lshl_add_u64 v[228:229], v[226:227], 0, s[34:35]
	s_mov_b32 m0, s15
	s_nop 0
	global_load_lds_dwordx4 v[228:229], off
	s_waitcnt lgkmcnt(8)
	s_barrier
	s_waitcnt lgkmcnt(0)
	s_setprio 1
	s_waitcnt lgkmcnt(0)
	v_mfma_f32_16x16x32_f16 v[128:131], v[190:193], v[174:177], 0
	v_mfma_f32_16x16x32_f16 v[124:127], v[190:193], v[182:185], 0
	v_mfma_f32_16x16x32_f16 v[120:123], v[198:201], v[174:177], 0
	v_mfma_f32_16x16x32_f16 v[116:119], v[198:201], v[182:185], 0
	v_mfma_f32_16x16x32_f16 v[112:115], v[206:209], v[174:177], 0
	v_mfma_f32_16x16x32_f16 v[108:111], v[206:209], v[182:185], 0
	v_mfma_f32_16x16x32_f16 v[104:107], v[214:217], v[174:177], 0
	v_mfma_f32_16x16x32_f16 v[100:103], v[214:217], v[182:185], 0
	v_mfma_f32_16x16x32_f16 v[128:131], v[194:197], v[178:181], v[128:131]
	v_mfma_f32_16x16x32_f16 v[124:127], v[194:197], v[186:189], v[124:127]
	v_mfma_f32_16x16x32_f16 v[120:123], v[202:205], v[178:181], v[120:123]
	v_mfma_f32_16x16x32_f16 v[116:119], v[202:205], v[186:189], v[116:119]
	v_mfma_f32_16x16x32_f16 v[112:115], v[210:213], v[178:181], v[112:115]
	v_mfma_f32_16x16x32_f16 v[108:111], v[210:213], v[186:189], v[108:111]
	v_mfma_f32_16x16x32_f16 v[104:107], v[218:221], v[178:181], v[104:107]
	v_mfma_f32_16x16x32_f16 v[100:103], v[218:221], v[186:189], v[100:103]
	s_setprio 0
	s_barrier
	v_lshl_add_u64 v[228:229], v[142:143], 0, s[12:13]
	v_readfirstlane_b32 s15, v151
	v_lshl_add_u64 v[236:237], v[228:229], 0, s[60:61]
	s_mov_b32 m0, s15
	ds_read_b128 v[238:241], v169
	ds_read_b128 v[242:245], v169 offset:1024
	ds_read_b128 v[246:249], v169 offset:2048
	ds_read_b128 v[230:233], v169 offset:3072
	global_load_lds_dwordx4 v[236:237], off
	v_lshl_add_u64 v[236:237], v[144:145], 0, s[12:13]
	v_readfirstlane_b32 s15, v157
	v_lshl_add_u64 v[250:251], v[236:237], 0, s[60:61]
	s_mov_b32 m0, s15
	s_nop 0
	global_load_lds_dwordx4 v[250:251], off
	s_barrier
; #define LDA8(dst, b, h) _Pragma("unroll") for (int m = 0; m < 4; ++m) _Pragma("unroll") for (int k = 0; k < 2; ++k) \
;     dst[m][k] = *(const bf16x8*)((const char*)SA8(b, h) + lds_byte8(wr * 64 + m * 16 + fr, k * 32 + fq * 8))
; #define LDB8(dst, b, h) _Pragma("unroll") for (int n = 0; n < 2; ++n) _Pragma("unroll") for (int k = 0; k < 2; ++k) \
;     dst[n][k] = *(const bf16x8*)((const char*)SB8(b, h) + lds_byte8(wc * 32 + n * 16 + fr, k * 32 + fq * 8))
; #define WAIT_V8(n) asm volatile("s_waitcnt vmcnt(" #n ")" ::: "memory")
; #define WAIT_L8(n) asm volatile("s_waitcnt lgkmcnt(" #n ")" ::: "memory")
; #define BAR8 __builtin_amdgcn_s_barrier()
; #define SCHED8 __builtin_amdgcn_sched_barrier(0)
;     ...
;     LDB8(B1, 0, 1); STAGE8(SB8(0, 0), Bt, K, bcol, tt + 2);
;     BAR8; WAIT_L8(0); MMA8(0, 1, At, B1); BAR8;
;     LDA8(At, 0, 1); STAGE8(SA8(0, 0), A, lda, brow, tt + 2);
;     BAR8; WAIT_L8(0); MMA8(1, 0, At, B0); BAR8; SCHED8;
;     STAGE8(SB8(0, 1), Bt, K, bcol + 128, tt + 2);
;     WAIT_V8(6); BAR8; MMA8(1, 1, At, B1); BAR8;
;     LDB8(B0, 1, 0); SCHED8; LDA8(At, 1, 0); STAGE8(SA8(0, 1), A, lda, brow + 128, tt + 2);
;     WAIT_L8(8); BAR8; WAIT_L8(0); MMA8(0, 0, At, B0); BAR8; SCHED8;
	s_waitcnt lgkmcnt(0)
	s_setprio 1
	s_waitcnt lgkmcnt(0)
	v_mfma_f32_16x16x32_f16 v[96:99], v[190:193], v[238:241], 0
	v_mfma_f32_16x16x32_f16 v[92:95], v[190:193], v[246:249], 0
	v_mfma_f32_16x16x32_f16 v[88:91], v[198:201], v[238:241], 0
	v_mfma_f32_16x16x32_f16 v[84:87], v[198:201], v[246:249], 0
	v_mfma_f32_16x16x32_f16 v[80:83], v[206:209], v[238:241], 0
	v_mfma_f32_16x16x32_f16 v[76:79], v[206:209], v[246:249], 0
	v_mfma_f32_16x16x32_f16 v[72:75], v[214:217], v[238:241], 0
	v_mfma_f32_16x16x32_f16 v[68:71], v[214:217], v[246:249], 0
	v_mfma_f32_16x16x32_f16 v[96:99], v[194:197], v[242:245], v[96:99]
	v_mfma_f32_16x16x32_f16 v[92:95], v[194:197], v[230:233], v[92:95]
	v_mfma_f32_16x16x32_f16 v[88:91], v[202:205], v[242:245], v[88:91]
	v_mfma_f32_16x16x32_f16 v[84:87], v[202:205], v[230:233], v[84:87]
	v_mfma_f32_16x16x32_f16 v[80:83], v[210:213], v[242:245], v[80:83]
	v_mfma_f32_16x16x32_f16 v[76:79], v[210:213], v[230:233], v[76:79]
	v_mfma_f32_16x16x32_f16 v[72:75], v[218:221], v[242:245], v[72:75]
	v_mfma_f32_16x16x32_f16 v[68:71], v[218:221], v[230:233], v[68:71]
	s_setprio 0
	v_readfirstlane_b32 s15, v150
	v_lshl_add_u64 v[250:251], v[222:223], 0, s[10:11]
	s_mov_b32 m0, s15
	v_readfirstlane_b32 s15, v155
	s_barrier
	ds_read_b128 v[190:193], v156 offset:16384
	ds_read_b128 v[194:197], v156 offset:17408
	ds_read_b128 v[198:201], v154 offset:16384
	ds_read_b128 v[202:205], v154 offset:17408
	ds_read_b128 v[206:209], v153 offset:16384
	ds_read_b128 v[210:213], v153 offset:17408
	ds_read_b128 v[214:217], v152 offset:16384
	ds_read_b128 v[218:221], v152 offset:17408
	global_load_lds_dwordx4 v[250:251], off
	v_lshl_add_u64 v[250:251], v[226:227], 0, s[10:11]
	s_mov_b32 m0, s15
	s_nop 0
	global_load_lds_dwordx4 v[250:251], off
	s_barrier
	s_waitcnt lgkmcnt(0)
	s_setprio 1
	s_waitcnt lgkmcnt(0)
	v_mfma_f32_16x16x32_f16 v[64:67], v[190:193], v[174:177], 0
	v_mfma_f32_16x16x32_f16 v[60:63], v[190:193], v[182:185], 0
	v_mfma_f32_16x16x32_f16 v[56:59], v[198:201], v[174:177], 0
	v_mfma_f32_16x16x32_f16 v[52:55], v[198:201], v[182:185], 0
	v_mfma_f32_16x16x32_f16 v[48:51], v[206:209], v[174:177], 0
	v_mfma_f32_16x16x32_f16 v[44:47], v[206:209], v[182:185], 0
	v_mfma_f32_16x16x32_f16 v[40:43], v[214:217], v[174:177], 0
	v_mfma_f32_16x16x32_f16 v[36:39], v[214:217], v[182:185], 0
	v_mfma_f32_16x16x32_f16 v[64:67], v[194:197], v[178:181], v[64:67]
	v_mfma_f32_16x16x32_f16 v[60:63], v[194:197], v[186:189], v[60:63]
	v_mfma_f32_16x16x32_f16 v[56:59], v[202:205], v[178:181], v[56:59]
	v_mfma_f32_16x16x32_f16 v[52:55], v[202:205], v[186:189], v[52:55]
	v_mfma_f32_16x16x32_f16 v[48:51], v[210:213], v[178:181], v[48:51]
	v_mfma_f32_16x16x32_f16 v[44:47], v[210:213], v[186:189], v[44:47]
	v_mfma_f32_16x16x32_f16 v[40:43], v[218:221], v[178:181], v[40:43]
	v_mfma_f32_16x16x32_f16 v[36:39], v[218:221], v[186:189], v[36:39]
	s_setprio 0
	s_barrier
	v_readfirstlane_b32 s15, v160
	v_lshl_add_u64 v[174:175], v[228:229], 0, s[62:63]
	s_mov_b32 m0, s15
	v_readfirstlane_b32 s15, v161
	global_load_lds_dwordx4 v[174:175], off
	v_lshl_add_u64 v[174:175], v[236:237], 0, s[62:63]
	s_mov_b32 m0, s15
	s_nop 0
	global_load_lds_dwordx4 v[174:175], off
	s_waitcnt vmcnt(6)
	s_barrier
	s_setprio 1
	v_mfma_f32_16x16x32_f16 v[32:35], v[190:193], v[238:241], 0
	v_mfma_f32_16x16x32_f16 v[28:31], v[190:193], v[246:249], 0
	v_mfma_f32_16x16x32_f16 v[24:27], v[198:201], v[238:241], 0
	v_mfma_f32_16x16x32_f16 v[20:23], v[198:201], v[246:249], 0
	v_mfma_f32_16x16x32_f16 v[16:19], v[206:209], v[238:241], 0
	v_mfma_f32_16x16x32_f16 v[12:15], v[206:209], v[246:249], 0
	v_mfma_f32_16x16x32_f16 v[8:11], v[214:217], v[238:241], 0
	v_mfma_f32_16x16x32_f16 v[4:7], v[214:217], v[246:249], 0
	v_mfma_f32_16x16x32_f16 v[32:35], v[194:197], v[242:245], v[32:35]
	v_mfma_f32_16x16x32_f16 v[28:31], v[194:197], v[230:233], v[28:31]
	v_mfma_f32_16x16x32_f16 v[24:27], v[202:205], v[242:245], v[24:27]
	v_mfma_f32_16x16x32_f16 v[20:23], v[202:205], v[230:233], v[20:23]
	v_mfma_f32_16x16x32_f16 v[16:19], v[210:213], v[242:245], v[16:19]
	v_mfma_f32_16x16x32_f16 v[12:15], v[210:213], v[230:233], v[12:15]
	v_mfma_f32_16x16x32_f16 v[8:11], v[218:221], v[242:245], v[8:11]
	v_mfma_f32_16x16x32_f16 v[4:7], v[218:221], v[230:233], v[4:7]
	s_setprio 0
	s_barrier
	ds_read_b128 v[174:177], v159
	ds_read_b128 v[178:181], v159 offset:1024
	ds_read_b128 v[182:185], v159 offset:2048
	ds_read_b128 v[186:189], v159 offset:3072
	v_readfirstlane_b32 s15, v162
	v_lshl_add_u64 v[230:231], v[222:223], 0, s[18:19]
	s_mov_b32 m0, s15
	v_readfirstlane_b32 s15, v163
	ds_read_b128 v[190:193], v156 offset:32768
	ds_read_b128 v[194:197], v156 offset:33792
	ds_read_b128 v[198:201], v154 offset:32768
	ds_read_b128 v[202:205], v154 offset:33792
	ds_read_b128 v[206:209], v153 offset:32768
	ds_read_b128 v[210:213], v153 offset:33792
	ds_read_b128 v[214:217], v152 offset:32768
	ds_read_b128 v[218:221], v152 offset:33792
	global_load_lds_dwordx4 v[230:231], off
	v_lshl_add_u64 v[230:231], v[226:227], 0, s[18:19]
	s_mov_b32 m0, s15
	s_nop 0
	global_load_lds_dwordx4 v[230:231], off
	s_waitcnt lgkmcnt(8)
	s_barrier
; #define LDA8(dst, b, h) _Pragma("unroll") for (int m = 0; m < 4; ++m) _Pragma("unroll") for (int k = 0; k < 2; ++k) \
;     dst[m][k] = *(const bf16x8*)((const char*)SA8(b, h) + lds_byte8(wr * 64 + m * 16 + fr, k * 32 + fq * 8))
; #define LDB8(dst, b, h) _Pragma("unroll") for (int n = 0; n < 2; ++n) _Pragma("unroll") for (int k = 0; k < 2; ++k) \
;     dst[n][k] = *(const bf16x8*)((const char*)SB8(b, h) + lds_byte8(wc * 32 + n * 16 + fr, k * 32 + fq * 8))
; #define WAIT_V8(n) asm volatile("s_waitcnt vmcnt(" #n ")" ::: "memory")
; #define WAIT_L8(n) asm volatile("s_waitcnt lgkmcnt(" #n ")" ::: "memory")
; #define BAR8 __builtin_amdgcn_s_barrier()
; #define SCHED8 __builtin_amdgcn_sched_barrier(0)
;     ...
;     WAIT_L8(8); BAR8; WAIT_L8(0); MMA8(0, 0, At, B0); BAR8; SCHED8;
;     LDB8(B1, 1, 1); STAGE8(SB8(1, 0), Bt, K, bcol, tt + 3);
;     BAR8; WAIT_L8(0); MMA8(0, 1, At, B1); BAR8;
;     LDA8(At, 1, 1); STAGE8(SA8(1, 0), A, lda, brow, tt + 3);
;     BAR8; WAIT_L8(0); MMA8(1, 0, At, B0); BAR8; SCHED8;
;     STAGE8(SB8(1, 1), Bt, K, bcol + 128, tt + 3);
;     WAIT_V8(6); BAR8; MMA8(1, 1, At, B1); BAR8;
;   }
	s_waitcnt lgkmcnt(0)
	s_setprio 1
	s_waitcnt lgkmcnt(0)
	v_mfma_f32_16x16x32_f16 v[128:131], v[190:193], v[174:177], v[128:131]
	v_mfma_f32_16x16x32_f16 v[124:127], v[190:193], v[182:185], v[124:127]
	v_mfma_f32_16x16x32_f16 v[120:123], v[198:201], v[174:177], v[120:123]
	v_mfma_f32_16x16x32_f16 v[116:119], v[198:201], v[182:185], v[116:119]
	v_mfma_f32_16x16x32_f16 v[112:115], v[206:209], v[174:177], v[112:115]
	v_mfma_f32_16x16x32_f16 v[108:111], v[206:209], v[182:185], v[108:111]
	v_mfma_f32_16x16x32_f16 v[104:107], v[214:217], v[174:177], v[104:107]
	v_mfma_f32_16x16x32_f16 v[100:103], v[214:217], v[182:185], v[100:103]
	v_mfma_f32_16x16x32_f16 v[128:131], v[194:197], v[178:181], v[128:131]
	v_mfma_f32_16x16x32_f16 v[124:127], v[194:197], v[186:189], v[124:127]
	v_mfma_f32_16x16x32_f16 v[120:123], v[202:205], v[178:181], v[120:123]
	v_mfma_f32_16x16x32_f16 v[116:119], v[202:205], v[186:189], v[116:119]
	v_mfma_f32_16x16x32_f16 v[112:115], v[210:213], v[178:181], v[112:115]
	v_mfma_f32_16x16x32_f16 v[108:111], v[210:213], v[186:189], v[108:111]
	v_mfma_f32_16x16x32_f16 v[104:107], v[218:221], v[178:181], v[104:107]
	v_mfma_f32_16x16x32_f16 v[100:103], v[218:221], v[186:189], v[100:103]
	s_setprio 0
	s_barrier
	v_readfirstlane_b32 s15, v164
	v_lshl_add_u64 v[250:251], v[228:229], 0, s[64:65]
	s_mov_b32 m0, s15
	v_readfirstlane_b32 s15, v165
	ds_read_b128 v[230:233], v158
	ds_read_b128 v[238:241], v158 offset:1024
	ds_read_b128 v[242:245], v158 offset:2048
	ds_read_b128 v[246:249], v158 offset:3072
	global_load_lds_dwordx4 v[250:251], off
	v_lshl_add_u64 v[250:251], v[236:237], 0, s[64:65]
	s_mov_b32 m0, s15
	s_nop 0
	global_load_lds_dwordx4 v[250:251], off
	s_barrier
	s_waitcnt lgkmcnt(0)
	s_setprio 1
	s_waitcnt lgkmcnt(0)
	v_mfma_f32_16x16x32_f16 v[96:99], v[190:193], v[230:233], v[96:99]
	v_mfma_f32_16x16x32_f16 v[92:95], v[190:193], v[242:245], v[92:95]
	v_mfma_f32_16x16x32_f16 v[88:91], v[198:201], v[230:233], v[88:91]
	v_mfma_f32_16x16x32_f16 v[84:87], v[198:201], v[242:245], v[84:87]
	v_mfma_f32_16x16x32_f16 v[80:83], v[206:209], v[230:233], v[80:83]
	v_mfma_f32_16x16x32_f16 v[76:79], v[206:209], v[242:245], v[76:79]
	v_mfma_f32_16x16x32_f16 v[72:75], v[214:217], v[230:233], v[72:75]
	v_mfma_f32_16x16x32_f16 v[68:71], v[214:217], v[242:245], v[68:71]
	v_mfma_f32_16x16x32_f16 v[96:99], v[194:197], v[238:241], v[96:99]
	v_mfma_f32_16x16x32_f16 v[92:95], v[194:197], v[246:249], v[92:95]
	v_mfma_f32_16x16x32_f16 v[88:91], v[202:205], v[238:241], v[88:91]
	v_mfma_f32_16x16x32_f16 v[84:87], v[202:205], v[246:249], v[84:87]
	v_mfma_f32_16x16x32_f16 v[80:83], v[210:213], v[238:241], v[80:83]
	v_mfma_f32_16x16x32_f16 v[76:79], v[210:213], v[246:249], v[76:79]
	v_mfma_f32_16x16x32_f16 v[72:75], v[218:221], v[238:241], v[72:75]
	v_mfma_f32_16x16x32_f16 v[68:71], v[218:221], v[246:249], v[68:71]
	s_setprio 0
	v_readfirstlane_b32 s15, v166
	v_lshl_add_u64 v[222:223], v[222:223], 0, s[22:23]
	s_mov_b32 m0, s15
	v_readfirstlane_b32 s15, v167
	s_barrier
	ds_read_b128 v[190:193], v156 offset:49152
	ds_read_b128 v[194:197], v156 offset:50176
	ds_read_b128 v[198:201], v154 offset:49152
	ds_read_b128 v[202:205], v154 offset:50176
	ds_read_b128 v[206:209], v153 offset:49152
	ds_read_b128 v[210:213], v153 offset:50176
	ds_read_b128 v[214:217], v152 offset:49152
	ds_read_b128 v[218:221], v152 offset:50176
	global_load_lds_dwordx4 v[222:223], off
	v_lshl_add_u64 v[222:223], v[226:227], 0, s[22:23]
	s_mov_b32 m0, s15
	s_nop 0
	global_load_lds_dwordx4 v[222:223], off
	s_barrier
	s_waitcnt lgkmcnt(0)
	s_setprio 1
	s_waitcnt lgkmcnt(0)
	v_mfma_f32_16x16x32_f16 v[64:67], v[190:193], v[174:177], v[64:67]
	v_mfma_f32_16x16x32_f16 v[60:63], v[190:193], v[182:185], v[60:63]
	v_mfma_f32_16x16x32_f16 v[56:59], v[198:201], v[174:177], v[56:59]
	v_mfma_f32_16x16x32_f16 v[52:55], v[198:201], v[182:185], v[52:55]
	v_mfma_f32_16x16x32_f16 v[48:51], v[206:209], v[174:177], v[48:51]
	v_mfma_f32_16x16x32_f16 v[44:47], v[206:209], v[182:185], v[44:47]
	v_mfma_f32_16x16x32_f16 v[40:43], v[214:217], v[174:177], v[40:43]
	v_mfma_f32_16x16x32_f16 v[36:39], v[214:217], v[182:185], v[36:39]
	v_mfma_f32_16x16x32_f16 v[64:67], v[194:197], v[178:181], v[64:67]
	v_mfma_f32_16x16x32_f16 v[60:63], v[194:197], v[186:189], v[60:63]
	v_mfma_f32_16x16x32_f16 v[56:59], v[202:205], v[178:181], v[56:59]
	v_mfma_f32_16x16x32_f16 v[52:55], v[202:205], v[186:189], v[52:55]
	v_mfma_f32_16x16x32_f16 v[48:51], v[210:213], v[178:181], v[48:51]
	v_mfma_f32_16x16x32_f16 v[44:47], v[210:213], v[186:189], v[44:47]
	v_mfma_f32_16x16x32_f16 v[40:43], v[218:221], v[178:181], v[40:43]
	v_mfma_f32_16x16x32_f16 v[36:39], v[218:221], v[186:189], v[36:39]
	s_setprio 0
	s_barrier
	v_readfirstlane_b32 s15, v168
	v_lshl_add_u64 v[174:175], v[228:229], 0, s[66:67]
	s_mov_b32 m0, s15
	v_readfirstlane_b32 s15, v170
	global_load_lds_dwordx4 v[174:175], off
	v_lshl_add_u64 v[174:175], v[236:237], 0, s[66:67]
	s_mov_b32 m0, s15
	s_nop 0
	global_load_lds_dwordx4 v[174:175], off
	s_waitcnt vmcnt(6)
	s_barrier
	s_setprio 1
	v_mfma_f32_16x16x32_f16 v[32:35], v[190:193], v[230:233], v[32:35]
	v_mfma_f32_16x16x32_f16 v[28:31], v[190:193], v[242:245], v[28:31]
	v_mfma_f32_16x16x32_f16 v[24:27], v[198:201], v[230:233], v[24:27]
	v_mfma_f32_16x16x32_f16 v[20:23], v[198:201], v[242:245], v[20:23]
	v_mfma_f32_16x16x32_f16 v[16:19], v[206:209], v[230:233], v[16:19]
	v_mfma_f32_16x16x32_f16 v[12:15], v[206:209], v[242:245], v[12:15]
	v_mfma_f32_16x16x32_f16 v[8:11], v[214:217], v[230:233], v[8:11]
	v_mfma_f32_16x16x32_f16 v[4:7], v[214:217], v[242:245], v[4:7]
	v_mfma_f32_16x16x32_f16 v[32:35], v[194:197], v[238:241], v[32:35]
	v_mfma_f32_16x16x32_f16 v[28:31], v[194:197], v[246:249], v[28:31]
	v_mfma_f32_16x16x32_f16 v[24:27], v[202:205], v[238:241], v[24:27]
	v_mfma_f32_16x16x32_f16 v[20:23], v[202:205], v[246:249], v[20:23]
	v_mfma_f32_16x16x32_f16 v[16:19], v[210:213], v[238:241], v[16:19]
	v_mfma_f32_16x16x32_f16 v[12:15], v[210:213], v[246:249], v[12:15]
	v_mfma_f32_16x16x32_f16 v[8:11], v[218:221], v[238:241], v[8:11]
	v_mfma_f32_16x16x32_f16 v[4:7], v[218:221], v[246:249], v[4:7]
	s_setprio 0
	s_add_i32 s14, s14, 2
	s_add_u32 s12, s12, 0x100
	s_addc_u32 s13, s13, 0
	s_cmp_lt_u32 s14, 12
	s_barrier
	s_cbranch_scc0 .Lpk_exit_0

; #define LDA8(dst, b, h) _Pragma("unroll") for (int m = 0; m < 4; ++m) _Pragma("unroll") for (int k = 0; k < 2; ++k) \
;     dst[m][k] = *(const bf16x8*)((const char*)SA8(b, h) + lds_byte8(wr * 64 + m * 16 + fr, k * 32 + fq * 8))
; #define LDB8(dst, b, h) _Pragma("unroll") for (int n = 0; n < 2; ++n) _Pragma("unroll") for (int k = 0; k < 2; ++k) \
;     dst[n][k] = *(const bf16x8*)((const char*)SB8(b, h) + lds_byte8(wc * 32 + n * 16 + fr, k * 32 + fq * 8))
; #define WAIT_V8(n) asm volatile("s_waitcnt vmcnt(" #n ")" ::: "memory")
; #define WAIT_L8(n) asm volatile("s_waitcnt lgkmcnt(" #n ")" ::: "memory")
; #define BAR8 __builtin_amdgcn_s_barrier()
;     ...
;   { LDB8(B0, 0, 0); LDA8(At, 0, 0); STAGE8(SA8(1, 1), A, lda, brow + 128, nt - 1);
;     BAR8; WAIT_L8(0); MMA8(0, 0, At, B0); BAR8;
;     LDB8(B1, 0, 1); BAR8; WAIT_L8(0); MMA8(0, 1, At, B1); BAR8;
;     LDA8(At, 0, 1); WAIT_V8(4); BAR8; WAIT_L8(0); MMA8(1, 0, At, B0); MMA8(1, 1, At, B1); BAR8; }
;   { LDB8(B0, 1, 0); LDA8(At, 1, 0); WAIT_V8(2); BAR8; WAIT_L8(0); MMA8(0, 0, At, B0); BAR8;
;     LDB8(B1, 1, 1); WAIT_V8(0); BAR8; WAIT_L8(0); MMA8(0, 1, At, B1); BAR8;
.Lpk_exit_0:
	s_add_u32 s4, s4, 0x40780
	s_addc_u32 s5, s5, 0
	v_lshl_add_u64 v[132:133], s[4:5], 0, v[132:133]
	v_readfirstlane_b32 s12, v172
	v_lshl_add_u64 v[0:1], v[0:1], 1, v[132:133]
	s_mov_b32 m0, s12
	ds_read_b128 v[138:141], v173
	ds_read_b128 v[142:145], v173 offset:1024
	ds_read_b128 v[160:163], v173 offset:2048
	ds_read_b128 v[164:167], v173 offset:3072
	ds_read_b128 v[174:177], v156
	ds_read_b128 v[178:181], v156 offset:1024
	ds_read_b128 v[182:185], v154
	ds_read_b128 v[186:189], v154 offset:1024
	ds_read_b128 v[190:193], v153
	ds_read_b128 v[194:197], v153 offset:1024
	ds_read_b128 v[198:201], v152
	ds_read_b128 v[202:205], v152 offset:1024
	global_load_lds_dwordx4 v[0:1], off
	v_lshl_add_u64 v[0:1], s[4:5], 0, v[136:137]
	v_readfirstlane_b32 s4, v171
	v_lshl_add_u64 v[0:1], v[134:135], 1, v[0:1]
	s_mov_b32 m0, s4
	s_nop 0
	global_load_lds_dwordx4 v[0:1], off
	s_barrier
	s_waitcnt lgkmcnt(0)
	s_setprio 1
	s_waitcnt lgkmcnt(0)
	v_mfma_f32_16x16x32_f16 v[128:131], v[174:177], v[138:141], v[128:131]
	v_mfma_f32_16x16x32_f16 v[124:127], v[174:177], v[160:163], v[124:127]
	v_mfma_f32_16x16x32_f16 v[120:123], v[182:185], v[138:141], v[120:123]
	v_mfma_f32_16x16x32_f16 v[112:115], v[190:193], v[138:141], v[112:115]
	v_mfma_f32_16x16x32_f16 v[128:131], v[178:181], v[142:145], v[128:131]
	v_mfma_f32_16x16x32_f16 v[124:127], v[178:181], v[164:167], v[124:127]
	v_mfma_f32_16x16x32_f16 v[120:123], v[186:189], v[142:145], v[120:123]
	v_mfma_f32_16x16x32_f16 v[116:119], v[182:185], v[160:163], v[116:119]
	v_mfma_f32_16x16x32_f16 v[112:115], v[194:197], v[142:145], v[112:115]
	v_mfma_f32_16x16x32_f16 v[108:111], v[190:193], v[160:163], v[108:111]
	v_mfma_f32_16x16x32_f16 v[104:107], v[198:201], v[138:141], v[104:107]
	v_mfma_f32_16x16x32_f16 v[100:103], v[198:201], v[160:163], v[100:103]
	v_mfma_f32_16x16x32_f16 v[132:135], v[186:189], v[164:167], v[116:119]
	v_mfma_f32_16x16x32_f16 v[170:173], v[194:197], v[164:167], v[108:111]
	v_mfma_f32_16x16x32_f16 v[206:209], v[202:205], v[142:145], v[104:107]
	v_mfma_f32_16x16x32_f16 v[210:213], v[202:205], v[164:167], v[100:103]
	s_setprio 0
	s_barrier
	s_nop 1
	ds_read_b128 v[100:103], v169
	ds_read_b128 v[104:107], v169 offset:1024
	ds_read_b128 v[108:111], v169 offset:2048
	ds_read_b128 v[116:119], v169 offset:3072
	s_barrier
	s_waitcnt lgkmcnt(0)
	s_setprio 1
	s_waitcnt lgkmcnt(0)
	v_mfma_f32_16x16x32_f16 v[80:83], v[190:193], v[100:103], v[80:83]
	v_mfma_f32_16x16x32_f16 v[76:79], v[190:193], v[108:111], v[76:79]
	v_mfma_f32_16x16x32_f16 v[72:75], v[198:201], v[100:103], v[72:75]
	v_mfma_f32_16x16x32_f16 v[68:71], v[198:201], v[108:111], v[68:71]
	v_mfma_f32_16x16x32_f16 v[96:99], v[174:177], v[100:103], v[96:99]
	v_mfma_f32_16x16x32_f16 v[92:95], v[174:177], v[108:111], v[92:95]
	v_mfma_f32_16x16x32_f16 v[88:91], v[182:185], v[100:103], v[88:91]
	v_mfma_f32_16x16x32_f16 v[84:87], v[182:185], v[108:111], v[84:87]
	v_mfma_f32_16x16x32_f16 v[80:83], v[194:197], v[104:107], v[80:83]
	v_mfma_f32_16x16x32_f16 v[76:79], v[194:197], v[116:119], v[76:79]
	v_mfma_f32_16x16x32_f16 v[72:75], v[202:205], v[104:107], v[72:75]
	v_mfma_f32_16x16x32_f16 v[68:71], v[202:205], v[116:119], v[68:71]
	v_mfma_f32_16x16x32_f16 v[214:217], v[178:181], v[104:107], v[96:99]
	v_mfma_f32_16x16x32_f16 v[174:177], v[178:181], v[116:119], v[92:95]
	v_mfma_f32_16x16x32_f16 v[178:181], v[186:189], v[104:107], v[88:91]
	v_mfma_f32_16x16x32_f16 v[182:185], v[186:189], v[116:119], v[84:87]
	s_setprio 0
	s_barrier
	s_nop 0
	ds_read_b128 v[84:87], v156 offset:16384
	ds_read_b128 v[88:91], v156 offset:17408
	ds_read_b128 v[92:95], v154 offset:16384
	ds_read_b128 v[96:99], v154 offset:17408
	ds_read_b128 v[186:189], v153 offset:16384
	ds_read_b128 v[190:193], v153 offset:17408
	ds_read_b128 v[194:197], v152 offset:16384
	ds_read_b128 v[198:201], v152 offset:17408
	s_waitcnt vmcnt(4)
	s_barrier
	s_waitcnt lgkmcnt(0)
	s_setprio 1
	s_waitcnt lgkmcnt(0)
	v_mfma_f32_16x16x32_f16 v[64:67], v[84:87], v[138:141], v[64:67]
	v_mfma_f32_16x16x32_f16 v[60:63], v[84:87], v[160:163], v[60:63]
	v_mfma_f32_16x16x32_f16 v[56:59], v[92:95], v[138:141], v[56:59]
	v_mfma_f32_16x16x32_f16 v[52:55], v[92:95], v[160:163], v[52:55]
	v_mfma_f32_16x16x32_f16 v[48:51], v[186:189], v[138:141], v[48:51]
	v_mfma_f32_16x16x32_f16 v[44:47], v[186:189], v[160:163], v[44:47]
	v_mfma_f32_16x16x32_f16 v[64:67], v[88:91], v[142:145], v[64:67]
	v_mfma_f32_16x16x32_f16 v[60:63], v[88:91], v[164:167], v[60:63]
	v_mfma_f32_16x16x32_f16 v[56:59], v[96:99], v[142:145], v[56:59]
	v_mfma_f32_16x16x32_f16 v[52:55], v[96:99], v[164:167], v[52:55]
	v_mfma_f32_16x16x32_f16 v[48:51], v[190:193], v[142:145], v[48:51]
	v_mfma_f32_16x16x32_f16 v[44:47], v[190:193], v[164:167], v[44:47]
	v_mfma_f32_16x16x32_f16 v[40:43], v[194:197], v[138:141], v[40:43]
	v_mfma_f32_16x16x32_f16 v[36:39], v[194:197], v[160:163], v[36:39]
	v_mfma_f32_16x16x32_f16 v[136:139], v[198:201], v[142:145], v[40:43]
	v_mfma_f32_16x16x32_f16 v[140:143], v[198:201], v[164:167], v[36:39]
	s_setprio 0
	s_setprio 1
	v_mfma_f32_16x16x32_f16 v[32:35], v[84:87], v[100:103], v[32:35]
	v_mfma_f32_16x16x32_f16 v[28:31], v[84:87], v[108:111], v[28:31]
	v_mfma_f32_16x16x32_f16 v[24:27], v[92:95], v[100:103], v[24:27]
	v_mfma_f32_16x16x32_f16 v[20:23], v[92:95], v[108:111], v[20:23]
	v_mfma_f32_16x16x32_f16 v[16:19], v[186:189], v[100:103], v[16:19]
	v_mfma_f32_16x16x32_f16 v[12:15], v[186:189], v[108:111], v[12:15]
	v_mfma_f32_16x16x32_f16 v[8:11], v[194:197], v[100:103], v[8:11]
	v_mfma_f32_16x16x32_f16 v[4:7], v[194:197], v[108:111], v[4:7]
	v_mfma_f32_16x16x32_f16 v[160:163], v[88:91], v[104:107], v[32:35]
	v_mfma_f32_16x16x32_f16 v[164:167], v[88:91], v[116:119], v[28:31]
	v_mfma_f32_16x16x32_f16 v[202:205], v[96:99], v[104:107], v[24:27]
	v_mfma_f32_16x16x32_f16 v[218:221], v[96:99], v[116:119], v[20:23]
	v_mfma_f32_16x16x32_f16 v[230:233], v[190:193], v[104:107], v[16:19]
	v_mfma_f32_16x16x32_f16 v[186:189], v[190:193], v[116:119], v[12:15]
	v_mfma_f32_16x16x32_f16 v[190:193], v[198:201], v[104:107], v[8:11]
	v_mfma_f32_16x16x32_f16 v[194:197], v[198:201], v[116:119], v[4:7]
	s_setprio 0
	s_barrier
; #define LDA8(dst, b, h) _Pragma("unroll") for (int m = 0; m < 4; ++m) _Pragma("unroll") for (int k = 0; k < 2; ++k) \
;     dst[m][k] = *(const bf16x8*)((const char*)SA8(b, h) + lds_byte8(wr * 64 + m * 16 + fr, k * 32 + fq * 8))
; #define LDB8(dst, b, h) _Pragma("unroll") for (int n = 0; n < 2; ++n) _Pragma("unroll") for (int k = 0; k < 2; ++k) \
;     dst[n][k] = *(const bf16x8*)((const char*)SB8(b, h) + lds_byte8(wc * 32 + n * 16 + fr, k * 32 + fq * 8))
; #define WAIT_V8(n) asm volatile("s_waitcnt vmcnt(" #n ")" ::: "memory")
; #define WAIT_L8(n) asm volatile("s_waitcnt lgkmcnt(" #n ")" ::: "memory")
; #define BAR8 __builtin_amdgcn_s_barrier()
;     ...
;   { LDB8(B0, 1, 0); LDA8(At, 1, 0); WAIT_V8(2); BAR8; WAIT_L8(0); MMA8(0, 0, At, B0); BAR8;
;     LDB8(B1, 1, 1); WAIT_V8(0); BAR8; WAIT_L8(0); MMA8(0, 1, At, B1); BAR8;
;     LDA8(At, 1, 1); BAR8; WAIT_L8(0); MMA8(1, 0, At, B0); MMA8(1, 1, At, B1); BAR8; }
;   if (wr == 0) BAR8;
;   __syncthreads();
;     ...
;   if (t < 256) {
	s_nop 0
	ds_read_b128 v[4:7], v159
	ds_read_b128 v[8:11], v159 offset:1024
	ds_read_b128 v[198:201], v159 offset:2048
	ds_read_b128 v[238:241], v159 offset:3072
	ds_read_b128 v[16:19], v156 offset:32768
	ds_read_b128 v[20:23], v156 offset:33792
	ds_read_b128 v[24:27], v154 offset:32768
	ds_read_b128 v[32:35], v154 offset:33792
	ds_read_b128 v[36:39], v153 offset:32768
	ds_read_b128 v[40:43], v153 offset:33792
	ds_read_b128 v[242:245], v152 offset:32768
	ds_read_b128 v[246:249], v152 offset:33792
	s_waitcnt vmcnt(2)
	s_barrier
	s_waitcnt lgkmcnt(0)
	s_setprio 1
	s_waitcnt lgkmcnt(0)
	v_mfma_f32_16x16x32_f16 v[12:15], v[16:19], v[4:7], v[128:131]
	v_mfma_f32_16x16x32_f16 v[104:107], v[20:23], v[8:11], v[12:15]
	v_mfma_f32_16x16x32_f16 v[12:15], v[16:19], v[198:201], v[124:127]
	v_mfma_f32_16x16x32_f16 v[116:119], v[20:23], v[238:241], v[12:15]
	v_mfma_f32_16x16x32_f16 v[12:15], v[24:27], v[4:7], v[120:123]
	v_mfma_f32_16x16x32_f16 v[100:103], v[32:35], v[8:11], v[12:15]
	v_mfma_f32_16x16x32_f16 v[12:15], v[24:27], v[198:201], v[132:135]
	v_mfma_f32_16x16x32_f16 v[108:111], v[32:35], v[238:241], v[12:15]
	v_mfma_f32_16x16x32_f16 v[12:15], v[36:39], v[4:7], v[112:115]
	v_mfma_f32_16x16x32_f16 v[92:95], v[40:43], v[8:11], v[12:15]
	v_mfma_f32_16x16x32_f16 v[12:15], v[36:39], v[198:201], v[170:173]
	v_mfma_f32_16x16x32_f16 v[96:99], v[40:43], v[238:241], v[12:15]
	v_mfma_f32_16x16x32_f16 v[12:15], v[242:245], v[4:7], v[206:209]
	v_mfma_f32_16x16x32_f16 v[84:87], v[246:249], v[8:11], v[12:15]
	v_mfma_f32_16x16x32_f16 v[12:15], v[242:245], v[198:201], v[210:213]
	v_mfma_f32_16x16x32_f16 v[88:91], v[246:249], v[238:241], v[12:15]
	s_setprio 0
	s_barrier
	ds_read_b128 v[132:135], v158
	ds_read_b128 v[168:171], v158 offset:1024
	ds_read_b128 v[206:209], v158 offset:2048
	ds_read_b128 v[210:213], v158 offset:3072
	s_waitcnt vmcnt(0)
	s_barrier
	s_waitcnt lgkmcnt(0)
	s_setprio 1
	s_waitcnt lgkmcnt(0)
	v_mfma_f32_16x16x32_f16 v[12:15], v[16:19], v[132:135], v[214:217]
	v_mfma_f32_16x16x32_f16 v[16:19], v[16:19], v[206:209], v[174:177]
	v_mfma_f32_16x16x32_f16 v[12:15], v[20:23], v[168:171], v[12:15]
	v_mfma_f32_16x16x32_f16 v[28:31], v[20:23], v[210:213], v[16:19]
	v_mfma_f32_16x16x32_f16 v[16:19], v[24:27], v[132:135], v[178:181]
	v_mfma_f32_16x16x32_f16 v[20:23], v[24:27], v[206:209], v[182:185]
	v_mfma_f32_16x16x32_f16 v[16:19], v[32:35], v[168:171], v[16:19]
	v_mfma_f32_16x16x32_f16 v[32:35], v[32:35], v[210:213], v[20:23]
	v_mfma_f32_16x16x32_f16 v[20:23], v[36:39], v[132:135], v[80:83]
	v_mfma_f32_16x16x32_f16 v[24:27], v[36:39], v[206:209], v[76:79]
	v_mfma_f32_16x16x32_f16 v[20:23], v[40:43], v[168:171], v[20:23]
	v_mfma_f32_16x16x32_f16 v[36:39], v[40:43], v[210:213], v[24:27]
	v_mfma_f32_16x16x32_f16 v[24:27], v[242:245], v[132:135], v[72:75]
	v_mfma_f32_16x16x32_f16 v[40:43], v[242:245], v[206:209], v[68:71]
	v_mfma_f32_16x16x32_f16 v[24:27], v[246:249], v[168:171], v[24:27]
	v_mfma_f32_16x16x32_f16 v[40:43], v[246:249], v[210:213], v[40:43]
	s_setprio 0
	s_barrier
	ds_read_b128 v[68:71], v156 offset:49152
	ds_read_b128 v[72:75], v156 offset:50176
	ds_read_b128 v[156:159], v154 offset:49152
	ds_read_b128 v[172:175], v154 offset:50176
	ds_read_b128 v[176:179], v153 offset:49152
	ds_read_b128 v[180:183], v153 offset:50176
	ds_read_b128 v[214:217], v152 offset:49152
	ds_read_b128 v[150:153], v152 offset:50176
	s_barrier
	s_waitcnt lgkmcnt(0)
	s_setprio 1
	s_waitcnt lgkmcnt(0)
	v_mfma_f32_16x16x32_f16 v[64:67], v[68:71], v[4:7], v[64:67]
	v_mfma_f32_16x16x32_f16 v[56:59], v[156:159], v[4:7], v[56:59]
	v_mfma_f32_16x16x32_f16 v[48:51], v[176:179], v[4:7], v[48:51]
	v_mfma_f32_16x16x32_f16 v[4:7], v[214:217], v[4:7], v[136:139]
	v_mfma_f32_16x16x32_f16 v[128:131], v[72:75], v[8:11], v[64:67]
	v_mfma_f32_16x16x32_f16 v[60:63], v[68:71], v[198:201], v[60:63]
	v_mfma_f32_16x16x32_f16 v[120:123], v[172:175], v[8:11], v[56:59]
	v_mfma_f32_16x16x32_f16 v[52:55], v[156:159], v[198:201], v[52:55]
	v_mfma_f32_16x16x32_f16 v[80:83], v[180:183], v[8:11], v[48:51]
	v_mfma_f32_16x16x32_f16 v[44:47], v[176:179], v[198:201], v[44:47]
	v_mfma_f32_16x16x32_f16 v[8:11], v[150:153], v[8:11], v[4:7]
	v_mfma_f32_16x16x32_f16 v[4:7], v[214:217], v[198:201], v[140:143]
	v_mfma_f32_16x16x32_f16 v[124:127], v[72:75], v[238:241], v[60:63]
	v_mfma_f32_16x16x32_f16 v[112:115], v[172:175], v[238:241], v[52:55]
	v_mfma_f32_16x16x32_f16 v[76:79], v[180:183], v[238:241], v[44:47]
	v_mfma_f32_16x16x32_f16 v[4:7], v[150:153], v[238:241], v[4:7]
	s_setprio 0
	s_setprio 1
	v_mfma_f32_16x16x32_f16 v[44:47], v[68:71], v[132:135], v[160:163]
	v_mfma_f32_16x16x32_f16 v[48:51], v[68:71], v[206:209], v[164:167]
	v_mfma_f32_16x16x32_f16 v[52:55], v[156:159], v[206:209], v[218:221]
	v_mfma_f32_16x16x32_f16 v[56:59], v[176:179], v[206:209], v[186:189]
	v_mfma_f32_16x16x32_f16 v[44:47], v[72:75], v[168:171], v[44:47]
	v_mfma_f32_16x16x32_f16 v[60:63], v[72:75], v[210:213], v[48:51]
	v_mfma_f32_16x16x32_f16 v[48:51], v[156:159], v[132:135], v[202:205]
	v_mfma_f32_16x16x32_f16 v[64:67], v[172:175], v[210:213], v[52:55]
	v_mfma_f32_16x16x32_f16 v[52:55], v[176:179], v[132:135], v[230:233]
	v_mfma_f32_16x16x32_f16 v[68:71], v[180:183], v[210:213], v[56:59]
	v_mfma_f32_16x16x32_f16 v[56:59], v[214:217], v[132:135], v[190:193]
	v_mfma_f32_16x16x32_f16 v[72:75], v[214:217], v[206:209], v[194:197]
	v_mfma_f32_16x16x32_f16 v[48:51], v[172:175], v[168:171], v[48:51]
	v_mfma_f32_16x16x32_f16 v[52:55], v[180:183], v[168:171], v[52:55]
	v_mfma_f32_16x16x32_f16 v[56:59], v[150:153], v[168:171], v[56:59]
	v_mfma_f32_16x16x32_f16 v[72:75], v[150:153], v[210:213], v[72:75]
	s_setprio 0
	s_movk_i32 s4, 0x100
	v_cmp_gt_u32_e32 vcc, s4, v3
	s_barrier
	s_and_saveexec_b64 s[4:5], vcc
	s_cbranch_execz .LBB0_195
	s_barrier

; #define LDA8(dst, b, h) _Pragma("unroll") for (int m = 0; m < 4; ++m) _Pragma("unroll") for (int k = 0; k < 2; ++k) \
;     dst[m][k] = *(const bf16x8*)((const char*)SA8(b, h) + lds_byte8(wr * 64 + m * 16 + fr, k * 32 + fq * 8))
; #define LDB8(dst, b, h) _Pragma("unroll") for (int n = 0; n < 2; ++n) _Pragma("unroll") for (int k = 0; k < 2; ++k) \
;     dst[n][k] = *(const bf16x8*)((const char*)SB8(b, h) + lds_byte8(wc * 32 + n * 16 + fr, k * 32 + fq * 8))
; #define WAIT_V8(n) asm volatile("s_waitcnt vmcnt(" #n ")" ::: "memory")
; #define WAIT_L8(n) asm volatile("s_waitcnt lgkmcnt(" #n ")" ::: "memory")
; #define BAR8 __builtin_amdgcn_s_barrier()
; #define SCHED8 __builtin_amdgcn_sched_barrier(0)
;     ...
;   f32x4 acc[2][2][4][2];
;   {
;     float zinit = 0.f;
;     asm volatile("" : "+v"(zinit));
; #pragma unroll
;     for (int a = 0; a < 2; ++a)
; #pragma unroll
;       for (int b = 0; b < 2; ++b)
; #pragma unroll
;         for (int m = 0; m < 4; ++m)
; #pragma unroll
;           for (int n = 0; n < 2; ++n)
; #pragma unroll
;             for (int j = 0; j < 4; ++j) acc[a][b][m][n][j] = zinit;
;   }
;   bf16x8 At[4][2], B0[2][2], B1[2][2];
;   const int nt = K / 64;
;   if (!pre) {
;     STAGE8(SB8(0, 0), Bt, K, bcol, 0); STAGE8(SA8(0, 0), A, lda, brow, 0);
;     STAGE8(SB8(0, 1), Bt, K, bcol + 128, 0); STAGE8(SA8(0, 1), A, lda, brow + 128, 0);
;   }
;   if (wr == 1) BAR8;
;   WAIT_V8(4); BAR8;
;   STAGE8(SB8(1, 0), Bt, K, bcol, 1); STAGE8(SA8(1, 0), A, lda, brow, 1); STAGE8(SB8(1, 1), Bt, K, bcol + 128, 1);
;   WAIT_V8(6); BAR8;
;   for (int tt = 0; tt < nt - 2; tt += 2) {
;     LDB8(B0, 0, 0); SCHED8; LDA8(At, 0, 0); STAGE8(SA8(1, 1), A, lda, brow + 128, tt + 1);
;     WAIT_L8(8); BAR8; WAIT_L8(0); MMA8(0, 0, At, B0); BAR8; SCHED8;
;     LDB8(B1, 0, 1); STAGE8(SB8(0, 0), Bt, K, bcol, tt + 2);
;     BAR8; WAIT_L8(0); MMA8(0, 1, At, B1); BAR8;
;     LDA8(At, 0, 1); STAGE8(SA8(0, 0), A, lda, brow, tt + 2);
;     BAR8; WAIT_L8(0); MMA8(1, 0, At, B0); BAR8; SCHED8;
;     STAGE8(SB8(0, 1), Bt, K, bcol + 128, tt + 2);
;     WAIT_V8(6); BAR8; MMA8(1, 1, At, B1); BAR8;
.LBB0_241:
	s_or_b64 exec, exec, s[20:21]
	v_add_u32_e32 v164, 0x18000, v150
	s_mov_b64 s[20:21], 0x80
	v_readfirstlane_b32 s1, v164
	v_add_u32_e32 v165, 0x1a000, v150
	v_lshl_add_u64 v[10:11], v[10:11], 0, s[20:21]
	s_mov_b32 m0, s1
	v_readfirstlane_b32 s1, v165
	v_add_u32_e32 v166, 0x8000, v150
	s_waitcnt vmcnt(4)
	s_barrier
	global_load_lds_dwordx4 v[10:11], off
	v_lshl_add_u64 v[10:11], v[12:13], 0, s[20:21]
	s_mov_b32 m0, s1
	v_readfirstlane_b32 s1, v166
	v_add_u32_e32 v167, 0xa000, v150
	global_load_lds_dwordx4 v[10:11], off
	v_lshl_add_u64 v[10:11], v[14:15], 0, s[20:21]
	s_mov_b32 m0, s1
	v_readfirstlane_b32 s1, v167
	v_add_u32_e32 v169, 0x1c000, v150
	global_load_lds_dwordx4 v[10:11], off
	v_lshl_add_u64 v[10:11], v[16:17], 0, s[20:21]
	s_mov_b32 m0, s1
	v_readfirstlane_b32 s1, v169
	v_add_u32_e32 v170, 0x1e000, v150
	global_load_lds_dwordx4 v[10:11], off
	v_lshl_add_u64 v[10:11], v[18:19], 0, s[20:21]
	s_mov_b32 m0, s1
	v_readfirstlane_b32 s1, v170
	global_load_lds_dwordx4 v[10:11], off
	v_lshl_add_u64 v[10:11], v[20:21], 0, s[20:21]
	s_mov_b32 m0, s1
	v_and_b32_e32 v147, 15, v3
	global_load_lds_dwordx4 v[10:11], off
	v_bfe_u32 v148, v3, 4, 2
	v_lshlrev_b32_e32 v10, 4, v148
	v_lshlrev_b32_e32 v11, 6, v147
	v_lshlrev_b32_e32 v14, 2, v3
	v_or_b32_e32 v13, v10, v11
	v_and_b32_e32 v14, 32, v14
	s_mov_b32 s1, 0x10000
	v_bitop3_b32 v16, v13, s1, v14 bitop3:0xde
	s_mov_b32 s1, 0x14000
	v_bitop3_b32 v15, v10, v14, v11 bitop3:0x36
	v_bitop3_b32 v17, v13, s1, v14 bitop3:0xde
	s_mov_b32 s1, 0x18000
	v_lshlrev_b32_e32 v11, 6, v3
	v_bitop3_b32 v18, v13, s1, v14 bitop3:0xde
	s_mov_b32 s1, 0x1c000
	v_and_b32_e32 v11, 0x3c0, v11
	v_bitop3_b32 v13, v13, s1, v14 bitop3:0xde
	v_bitop3_b32 v14, v11, v14, v10 bitop3:0x36
	v_lshl_add_u64 v[10:11], s[30:31], 0, v[136:137]
	v_lshl_add_u64 v[10:11], v[10:11], 0, v[8:9]
	v_lshl_add_u64 v[138:139], s[14:15], 0, v[10:11]
	v_lshl_add_u64 v[10:11], s[30:31], 0, v[132:133]
	v_lshl_add_u64 v[10:11], v[10:11], 0, v[6:7]
	v_lshl_add_u64 v[140:141], s[14:15], 0, v[10:11]
	v_lshl_add_u64 v[10:11], s[56:57], 0, v[132:133]
	v_lshl_add_u64 v[6:7], v[10:11], 0, v[6:7]
	v_bfe_u32 v146, v3, 6, 2
	s_waitcnt vmcnt(6)
	v_lshlrev_b32_e32 v149, 6, v5
	v_lshlrev_b32_e32 v5, 13, v5
	v_lshl_add_u64 v[142:143], s[46:47], 0, v[6:7]
	v_lshl_add_u64 v[6:7], s[56:57], 0, v[136:137]
	v_lshlrev_b32_e32 v12, 12, v146
	v_or_b32_e32 v19, 0x800, v5
	v_or_b32_e32 v20, 0x1000, v5
	v_or_b32_e32 v21, 0x1800, v5
	v_lshl_add_u64 v[6:7], v[6:7], 0, v[8:9]
	v_lshl_add_u64 v[144:145], s[46:47], 0, v[6:7]
	s_mov_b32 s1, -2
	s_mov_b64 s[14:15], 0
	v_add_u32_e32 v171, v16, v12
	v_add_u32_e32 v156, v15, v5
	v_add_u32_e32 v154, v14, v19
	v_add_u32_e32 v153, v14, v20
	v_add_u32_e32 v152, v14, v21
	v_add_u32_e32 v168, v17, v12
	v_add_u32_e32 v159, v18, v12
	v_add_u32_e32 v157, v13, v12
	s_mov_b64 s[30:31], 0xc000100
	s_mov_b64 s[56:57], 0xc040100
	s_mov_b64 s[58:59], 0xc000180
	s_mov_b64 s[60:61], 0xc040180
	s_barrier
	ds_read_b128 v[174:177], v171
	ds_read_b128 v[178:181], v171 offset:1024
	ds_read_b128 v[182:185], v171 offset:2048
	ds_read_b128 v[186:189], v171 offset:3072
	v_add_u32_e32 v172, 0xc000, v150
	v_lshl_add_u64 v[222:223], v[140:141], 0, s[14:15]
	v_readfirstlane_b32 s20, v172
	v_lshl_add_u64 v[226:227], v[222:223], 0, s[34:35]
	s_mov_b32 m0, s20
	v_add_u32_e32 v173, 0xe000, v150
	ds_read_b128 v[190:193], v156
	ds_read_b128 v[194:197], v156 offset:1024
	ds_read_b128 v[198:201], v154
	ds_read_b128 v[202:205], v154 offset:1024
	ds_read_b128 v[206:209], v153
	ds_read_b128 v[210:213], v153 offset:1024
	ds_read_b128 v[214:217], v152
	ds_read_b128 v[218:221], v152 offset:1024
	global_load_lds_dwordx4 v[226:227], off
	v_lshl_add_u64 v[226:227], v[138:139], 0, s[14:15]
	v_readfirstlane_b32 s20, v173
	v_lshl_add_u64 v[228:229], v[226:227], 0, s[34:35]
	s_mov_b32 m0, s20
	s_nop 0
	global_load_lds_dwordx4 v[228:229], off
	s_waitcnt lgkmcnt(8)
	s_barrier
	s_waitcnt lgkmcnt(0)
	s_setprio 1
	s_waitcnt lgkmcnt(0)
	v_mfma_f32_16x16x32_f16 v[128:131], v[190:193], v[174:177], 0
	v_mfma_f32_16x16x32_f16 v[124:127], v[190:193], v[182:185], 0
	v_mfma_f32_16x16x32_f16 v[120:123], v[198:201], v[174:177], 0
	v_mfma_f32_16x16x32_f16 v[116:119], v[198:201], v[182:185], 0
	v_mfma_f32_16x16x32_f16 v[112:115], v[206:209], v[174:177], 0
	v_mfma_f32_16x16x32_f16 v[108:111], v[206:209], v[182:185], 0
	v_mfma_f32_16x16x32_f16 v[104:107], v[214:217], v[174:177], 0
	v_mfma_f32_16x16x32_f16 v[100:103], v[214:217], v[182:185], 0
	v_mfma_f32_16x16x32_f16 v[128:131], v[194:197], v[178:181], v[128:131]
	v_mfma_f32_16x16x32_f16 v[124:127], v[194:197], v[186:189], v[124:127]
	v_mfma_f32_16x16x32_f16 v[120:123], v[202:205], v[178:181], v[120:123]
	v_mfma_f32_16x16x32_f16 v[116:119], v[202:205], v[186:189], v[116:119]
	v_mfma_f32_16x16x32_f16 v[112:115], v[210:213], v[178:181], v[112:115]
	v_mfma_f32_16x16x32_f16 v[108:111], v[210:213], v[186:189], v[108:111]
	v_mfma_f32_16x16x32_f16 v[104:107], v[218:221], v[178:181], v[104:107]
	v_mfma_f32_16x16x32_f16 v[100:103], v[218:221], v[186:189], v[100:103]
	s_setprio 0
	s_barrier
	v_lshl_add_u64 v[228:229], v[142:143], 0, s[14:15]
	v_readfirstlane_b32 s20, v151
	v_lshl_add_u64 v[236:237], v[228:229], 0, s[30:31]
	s_mov_b32 m0, s20
	ds_read_b128 v[230:233], v168
	ds_read_b128 v[238:241], v168 offset:1024
	ds_read_b128 v[242:245], v168 offset:2048
	ds_read_b128 v[246:249], v168 offset:3072
	global_load_lds_dwordx4 v[236:237], off
	v_lshl_add_u64 v[236:237], v[144:145], 0, s[14:15]
	v_readfirstlane_b32 s20, v158
	v_lshl_add_u64 v[250:251], v[236:237], 0, s[30:31]
	s_mov_b32 m0, s20
	s_nop 0
	global_load_lds_dwordx4 v[250:251], off
	s_barrier
; #define LDA8(dst, b, h) _Pragma("unroll") for (int m = 0; m < 4; ++m) _Pragma("unroll") for (int k = 0; k < 2; ++k) \
;     dst[m][k] = *(const bf16x8*)((const char*)SA8(b, h) + lds_byte8(wr * 64 + m * 16 + fr, k * 32 + fq * 8))
; #define LDB8(dst, b, h) _Pragma("unroll") for (int n = 0; n < 2; ++n) _Pragma("unroll") for (int k = 0; k < 2; ++k) \
;     dst[n][k] = *(const bf16x8*)((const char*)SB8(b, h) + lds_byte8(wc * 32 + n * 16 + fr, k * 32 + fq * 8))
; #define WAIT_V8(n) asm volatile("s_waitcnt vmcnt(" #n ")" ::: "memory")
; #define WAIT_L8(n) asm volatile("s_waitcnt lgkmcnt(" #n ")" ::: "memory")
; #define BAR8 __builtin_amdgcn_s_barrier()
; #define SCHED8 __builtin_amdgcn_sched_barrier(0)
;     ...
;     LDB8(B1, 0, 1); STAGE8(SB8(0, 0), Bt, K, bcol, tt + 2);
;     BAR8; WAIT_L8(0); MMA8(0, 1, At, B1); BAR8;
;     LDA8(At, 0, 1); STAGE8(SA8(0, 0), A, lda, brow, tt + 2);
;     BAR8; WAIT_L8(0); MMA8(1, 0, At, B0); BAR8; SCHED8;
;     STAGE8(SB8(0, 1), Bt, K, bcol + 128, tt + 2);
;     WAIT_V8(6); BAR8; MMA8(1, 1, At, B1); BAR8;
;     LDB8(B0, 1, 0); SCHED8; LDA8(At, 1, 0); STAGE8(SA8(0, 1), A, lda, brow + 128, tt + 2);
;     WAIT_L8(8); BAR8; WAIT_L8(0); MMA8(0, 0, At, B0); BAR8; SCHED8;
	s_waitcnt lgkmcnt(0)
	s_setprio 1
	s_waitcnt lgkmcnt(0)
	v_mfma_f32_16x16x32_f16 v[96:99], v[190:193], v[230:233], 0
	v_mfma_f32_16x16x32_f16 v[92:95], v[190:193], v[242:245], 0
	v_mfma_f32_16x16x32_f16 v[88:91], v[198:201], v[230:233], 0
	v_mfma_f32_16x16x32_f16 v[84:87], v[198:201], v[242:245], 0
	v_mfma_f32_16x16x32_f16 v[80:83], v[206:209], v[230:233], 0
	v_mfma_f32_16x16x32_f16 v[76:79], v[206:209], v[242:245], 0
	v_mfma_f32_16x16x32_f16 v[72:75], v[214:217], v[230:233], 0
	v_mfma_f32_16x16x32_f16 v[68:71], v[214:217], v[242:245], 0
	v_mfma_f32_16x16x32_f16 v[96:99], v[194:197], v[238:241], v[96:99]
	v_mfma_f32_16x16x32_f16 v[92:95], v[194:197], v[246:249], v[92:95]
	v_mfma_f32_16x16x32_f16 v[88:91], v[202:205], v[238:241], v[88:91]
	v_mfma_f32_16x16x32_f16 v[84:87], v[202:205], v[246:249], v[84:87]
	v_mfma_f32_16x16x32_f16 v[80:83], v[210:213], v[238:241], v[80:83]
	v_mfma_f32_16x16x32_f16 v[76:79], v[210:213], v[246:249], v[76:79]
	v_mfma_f32_16x16x32_f16 v[72:75], v[218:221], v[238:241], v[72:75]
	v_mfma_f32_16x16x32_f16 v[68:71], v[218:221], v[246:249], v[68:71]
	s_setprio 0
	v_readfirstlane_b32 s20, v150
	v_lshl_add_u64 v[250:251], v[222:223], 0, s[10:11]
	s_mov_b32 m0, s20
	v_readfirstlane_b32 s20, v155
	s_barrier
	ds_read_b128 v[190:193], v156 offset:16384
	ds_read_b128 v[194:197], v156 offset:17408
	ds_read_b128 v[198:201], v154 offset:16384
	ds_read_b128 v[202:205], v154 offset:17408
	ds_read_b128 v[206:209], v153 offset:16384
	ds_read_b128 v[210:213], v153 offset:17408
	ds_read_b128 v[214:217], v152 offset:16384
	ds_read_b128 v[218:221], v152 offset:17408
	global_load_lds_dwordx4 v[250:251], off
	v_lshl_add_u64 v[250:251], v[226:227], 0, s[10:11]
	s_mov_b32 m0, s20
	s_nop 0
	global_load_lds_dwordx4 v[250:251], off
	s_barrier
	s_waitcnt lgkmcnt(0)
	s_setprio 1
	s_waitcnt lgkmcnt(0)
	v_mfma_f32_16x16x32_f16 v[64:67], v[190:193], v[174:177], 0
	v_mfma_f32_16x16x32_f16 v[60:63], v[190:193], v[182:185], 0
	v_mfma_f32_16x16x32_f16 v[56:59], v[198:201], v[174:177], 0
	v_mfma_f32_16x16x32_f16 v[52:55], v[198:201], v[182:185], 0
	v_mfma_f32_16x16x32_f16 v[48:51], v[206:209], v[174:177], 0
	v_mfma_f32_16x16x32_f16 v[44:47], v[206:209], v[182:185], 0
	v_mfma_f32_16x16x32_f16 v[40:43], v[214:217], v[174:177], 0
	v_mfma_f32_16x16x32_f16 v[36:39], v[214:217], v[182:185], 0
	v_mfma_f32_16x16x32_f16 v[64:67], v[194:197], v[178:181], v[64:67]
	v_mfma_f32_16x16x32_f16 v[60:63], v[194:197], v[186:189], v[60:63]
	v_mfma_f32_16x16x32_f16 v[56:59], v[202:205], v[178:181], v[56:59]
	v_mfma_f32_16x16x32_f16 v[52:55], v[202:205], v[186:189], v[52:55]
	v_mfma_f32_16x16x32_f16 v[48:51], v[210:213], v[178:181], v[48:51]
	v_mfma_f32_16x16x32_f16 v[44:47], v[210:213], v[186:189], v[44:47]
	v_mfma_f32_16x16x32_f16 v[40:43], v[218:221], v[178:181], v[40:43]
	v_mfma_f32_16x16x32_f16 v[36:39], v[218:221], v[186:189], v[36:39]
	s_setprio 0
	s_barrier
	v_readfirstlane_b32 s20, v160
	v_lshl_add_u64 v[174:175], v[228:229], 0, s[56:57]
	s_mov_b32 m0, s20
	v_readfirstlane_b32 s20, v161
	global_load_lds_dwordx4 v[174:175], off
	v_lshl_add_u64 v[174:175], v[236:237], 0, s[56:57]
	s_mov_b32 m0, s20
	s_nop 0
	global_load_lds_dwordx4 v[174:175], off
	s_waitcnt vmcnt(6)
	s_barrier
	s_setprio 1
	v_mfma_f32_16x16x32_f16 v[32:35], v[190:193], v[230:233], 0
	v_mfma_f32_16x16x32_f16 v[28:31], v[190:193], v[242:245], 0
	v_mfma_f32_16x16x32_f16 v[24:27], v[198:201], v[230:233], 0
	v_mfma_f32_16x16x32_f16 v[20:23], v[198:201], v[242:245], 0
	v_mfma_f32_16x16x32_f16 v[16:19], v[206:209], v[230:233], 0
	v_mfma_f32_16x16x32_f16 v[12:15], v[206:209], v[242:245], 0
	v_mfma_f32_16x16x32_f16 v[8:11], v[214:217], v[230:233], 0
	v_mfma_f32_16x16x32_f16 v[4:7], v[214:217], v[242:245], 0
	v_mfma_f32_16x16x32_f16 v[32:35], v[194:197], v[238:241], v[32:35]
	v_mfma_f32_16x16x32_f16 v[28:31], v[194:197], v[246:249], v[28:31]
	v_mfma_f32_16x16x32_f16 v[24:27], v[202:205], v[238:241], v[24:27]
	v_mfma_f32_16x16x32_f16 v[20:23], v[202:205], v[246:249], v[20:23]
	v_mfma_f32_16x16x32_f16 v[16:19], v[210:213], v[238:241], v[16:19]
	v_mfma_f32_16x16x32_f16 v[12:15], v[210:213], v[246:249], v[12:15]
	v_mfma_f32_16x16x32_f16 v[8:11], v[218:221], v[238:241], v[8:11]
	v_mfma_f32_16x16x32_f16 v[4:7], v[218:221], v[246:249], v[4:7]
	s_setprio 0
	s_barrier
	ds_read_b128 v[174:177], v159
	ds_read_b128 v[178:181], v159 offset:1024
	ds_read_b128 v[182:185], v159 offset:2048
	ds_read_b128 v[186:189], v159 offset:3072
	v_readfirstlane_b32 s20, v162
	v_lshl_add_u64 v[230:231], v[222:223], 0, s[18:19]
	s_mov_b32 m0, s20
	v_readfirstlane_b32 s20, v163
	ds_read_b128 v[190:193], v156 offset:32768
	ds_read_b128 v[194:197], v156 offset:33792
	ds_read_b128 v[198:201], v154 offset:32768
	ds_read_b128 v[202:205], v154 offset:33792
	ds_read_b128 v[206:209], v153 offset:32768
	ds_read_b128 v[210:213], v153 offset:33792
	ds_read_b128 v[214:217], v152 offset:32768
	ds_read_b128 v[218:221], v152 offset:33792
	global_load_lds_dwordx4 v[230:231], off
	v_lshl_add_u64 v[230:231], v[226:227], 0, s[18:19]
	s_mov_b32 m0, s20
	s_nop 0
	global_load_lds_dwordx4 v[230:231], off
	s_waitcnt lgkmcnt(8)
	s_barrier
; #define LDA8(dst, b, h) _Pragma("unroll") for (int m = 0; m < 4; ++m) _Pragma("unroll") for (int k = 0; k < 2; ++k) \
;     dst[m][k] = *(const bf16x8*)((const char*)SA8(b, h) + lds_byte8(wr * 64 + m * 16 + fr, k * 32 + fq * 8))
; #define LDB8(dst, b, h) _Pragma("unroll") for (int n = 0; n < 2; ++n) _Pragma("unroll") for (int k = 0; k < 2; ++k) \
;     dst[n][k] = *(const bf16x8*)((const char*)SB8(b, h) + lds_byte8(wc * 32 + n * 16 + fr, k * 32 + fq * 8))
; #define WAIT_V8(n) asm volatile("s_waitcnt vmcnt(" #n ")" ::: "memory")
; #define WAIT_L8(n) asm volatile("s_waitcnt lgkmcnt(" #n ")" ::: "memory")
; #define BAR8 __builtin_amdgcn_s_barrier()
; #define SCHED8 __builtin_amdgcn_sched_barrier(0)
;     ...
;     WAIT_L8(8); BAR8; WAIT_L8(0); MMA8(0, 0, At, B0); BAR8; SCHED8;
;     LDB8(B1, 1, 1); STAGE8(SB8(1, 0), Bt, K, bcol, tt + 3);
;     BAR8; WAIT_L8(0); MMA8(0, 1, At, B1); BAR8;
;     LDA8(At, 1, 1); STAGE8(SA8(1, 0), A, lda, brow, tt + 3);
;     BAR8; WAIT_L8(0); MMA8(1, 0, At, B0); BAR8; SCHED8;
;     STAGE8(SB8(1, 1), Bt, K, bcol + 128, tt + 3);
;     WAIT_V8(6); BAR8; MMA8(1, 1, At, B1); BAR8;
;   }
	s_waitcnt lgkmcnt(0)
	s_setprio 1
	s_waitcnt lgkmcnt(0)
	v_mfma_f32_16x16x32_f16 v[128:131], v[190:193], v[174:177], v[128:131]
	v_mfma_f32_16x16x32_f16 v[124:127], v[190:193], v[182:185], v[124:127]
	v_mfma_f32_16x16x32_f16 v[120:123], v[198:201], v[174:177], v[120:123]
	v_mfma_f32_16x16x32_f16 v[116:119], v[198:201], v[182:185], v[116:119]
	v_mfma_f32_16x16x32_f16 v[112:115], v[206:209], v[174:177], v[112:115]
	v_mfma_f32_16x16x32_f16 v[108:111], v[206:209], v[182:185], v[108:111]
	v_mfma_f32_16x16x32_f16 v[104:107], v[214:217], v[174:177], v[104:107]
	v_mfma_f32_16x16x32_f16 v[100:103], v[214:217], v[182:185], v[100:103]
	v_mfma_f32_16x16x32_f16 v[128:131], v[194:197], v[178:181], v[128:131]
	v_mfma_f32_16x16x32_f16 v[124:127], v[194:197], v[186:189], v[124:127]
	v_mfma_f32_16x16x32_f16 v[120:123], v[202:205], v[178:181], v[120:123]
	v_mfma_f32_16x16x32_f16 v[116:119], v[202:205], v[186:189], v[116:119]
	v_mfma_f32_16x16x32_f16 v[112:115], v[210:213], v[178:181], v[112:115]
	v_mfma_f32_16x16x32_f16 v[108:111], v[210:213], v[186:189], v[108:111]
	v_mfma_f32_16x16x32_f16 v[104:107], v[218:221], v[178:181], v[104:107]
	v_mfma_f32_16x16x32_f16 v[100:103], v[218:221], v[186:189], v[100:103]
	s_setprio 0
	s_barrier
	v_readfirstlane_b32 s20, v164
	v_lshl_add_u64 v[250:251], v[228:229], 0, s[58:59]
	s_mov_b32 m0, s20
	v_readfirstlane_b32 s20, v165
	ds_read_b128 v[230:233], v157
	ds_read_b128 v[238:241], v157 offset:1024
	ds_read_b128 v[242:245], v157 offset:2048
	ds_read_b128 v[246:249], v157 offset:3072
	global_load_lds_dwordx4 v[250:251], off
	v_lshl_add_u64 v[250:251], v[236:237], 0, s[58:59]
	s_mov_b32 m0, s20
	s_nop 0
	global_load_lds_dwordx4 v[250:251], off
	s_barrier
	s_waitcnt lgkmcnt(0)
	s_setprio 1
	s_waitcnt lgkmcnt(0)
	v_mfma_f32_16x16x32_f16 v[96:99], v[190:193], v[230:233], v[96:99]
	v_mfma_f32_16x16x32_f16 v[92:95], v[190:193], v[242:245], v[92:95]
	v_mfma_f32_16x16x32_f16 v[88:91], v[198:201], v[230:233], v[88:91]
	v_mfma_f32_16x16x32_f16 v[84:87], v[198:201], v[242:245], v[84:87]
	v_mfma_f32_16x16x32_f16 v[80:83], v[206:209], v[230:233], v[80:83]
	v_mfma_f32_16x16x32_f16 v[76:79], v[206:209], v[242:245], v[76:79]
	v_mfma_f32_16x16x32_f16 v[72:75], v[214:217], v[230:233], v[72:75]
	v_mfma_f32_16x16x32_f16 v[68:71], v[214:217], v[242:245], v[68:71]
	v_mfma_f32_16x16x32_f16 v[96:99], v[194:197], v[238:241], v[96:99]
	v_mfma_f32_16x16x32_f16 v[92:95], v[194:197], v[246:249], v[92:95]
	v_mfma_f32_16x16x32_f16 v[88:91], v[202:205], v[238:241], v[88:91]
	v_mfma_f32_16x16x32_f16 v[84:87], v[202:205], v[246:249], v[84:87]
	v_mfma_f32_16x16x32_f16 v[80:83], v[210:213], v[238:241], v[80:83]
	v_mfma_f32_16x16x32_f16 v[76:79], v[210:213], v[246:249], v[76:79]
	v_mfma_f32_16x16x32_f16 v[72:75], v[218:221], v[238:241], v[72:75]
	v_mfma_f32_16x16x32_f16 v[68:71], v[218:221], v[246:249], v[68:71]
	s_setprio 0
	v_readfirstlane_b32 s20, v166
	v_lshl_add_u64 v[222:223], v[222:223], 0, s[22:23]
	s_mov_b32 m0, s20
	v_readfirstlane_b32 s20, v167
	s_barrier
	ds_read_b128 v[190:193], v156 offset:49152
	ds_read_b128 v[194:197], v156 offset:50176
	ds_read_b128 v[198:201], v154 offset:49152
	ds_read_b128 v[202:205], v154 offset:50176
	ds_read_b128 v[206:209], v153 offset:49152
	ds_read_b128 v[210:213], v153 offset:50176
	ds_read_b128 v[214:217], v152 offset:49152
	ds_read_b128 v[218:221], v152 offset:50176
	global_load_lds_dwordx4 v[222:223], off
	v_lshl_add_u64 v[222:223], v[226:227], 0, s[22:23]
	s_mov_b32 m0, s20
	s_nop 0
	global_load_lds_dwordx4 v[222:223], off
	s_barrier
	s_waitcnt lgkmcnt(0)
	s_setprio 1
	s_waitcnt lgkmcnt(0)
	v_mfma_f32_16x16x32_f16 v[64:67], v[190:193], v[174:177], v[64:67]
	v_mfma_f32_16x16x32_f16 v[60:63], v[190:193], v[182:185], v[60:63]
	v_mfma_f32_16x16x32_f16 v[56:59], v[198:201], v[174:177], v[56:59]
	v_mfma_f32_16x16x32_f16 v[52:55], v[198:201], v[182:185], v[52:55]
	v_mfma_f32_16x16x32_f16 v[48:51], v[206:209], v[174:177], v[48:51]
	v_mfma_f32_16x16x32_f16 v[44:47], v[206:209], v[182:185], v[44:47]
	v_mfma_f32_16x16x32_f16 v[40:43], v[214:217], v[174:177], v[40:43]
	v_mfma_f32_16x16x32_f16 v[36:39], v[214:217], v[182:185], v[36:39]
	v_mfma_f32_16x16x32_f16 v[64:67], v[194:197], v[178:181], v[64:67]
	v_mfma_f32_16x16x32_f16 v[60:63], v[194:197], v[186:189], v[60:63]
	v_mfma_f32_16x16x32_f16 v[56:59], v[202:205], v[178:181], v[56:59]
	v_mfma_f32_16x16x32_f16 v[52:55], v[202:205], v[186:189], v[52:55]
	v_mfma_f32_16x16x32_f16 v[48:51], v[210:213], v[178:181], v[48:51]
	v_mfma_f32_16x16x32_f16 v[44:47], v[210:213], v[186:189], v[44:47]
	v_mfma_f32_16x16x32_f16 v[40:43], v[218:221], v[178:181], v[40:43]
	v_mfma_f32_16x16x32_f16 v[36:39], v[218:221], v[186:189], v[36:39]
	s_setprio 0
	s_barrier
	v_readfirstlane_b32 s20, v169
	v_lshl_add_u64 v[174:175], v[228:229], 0, s[60:61]
	s_mov_b32 m0, s20
	v_readfirstlane_b32 s20, v170
	global_load_lds_dwordx4 v[174:175], off
	v_lshl_add_u64 v[174:175], v[236:237], 0, s[60:61]
	s_mov_b32 m0, s20
	s_nop 0
	global_load_lds_dwordx4 v[174:175], off
	s_waitcnt vmcnt(6)
	s_barrier
	s_setprio 1
	v_mfma_f32_16x16x32_f16 v[32:35], v[190:193], v[230:233], v[32:35]
	v_mfma_f32_16x16x32_f16 v[28:31], v[190:193], v[242:245], v[28:31]
	v_mfma_f32_16x16x32_f16 v[24:27], v[198:201], v[230:233], v[24:27]
	v_mfma_f32_16x16x32_f16 v[20:23], v[198:201], v[242:245], v[20:23]
	v_mfma_f32_16x16x32_f16 v[16:19], v[206:209], v[230:233], v[16:19]
	v_mfma_f32_16x16x32_f16 v[12:15], v[206:209], v[242:245], v[12:15]
	v_mfma_f32_16x16x32_f16 v[8:11], v[214:217], v[230:233], v[8:11]
	v_mfma_f32_16x16x32_f16 v[4:7], v[214:217], v[242:245], v[4:7]
	v_mfma_f32_16x16x32_f16 v[32:35], v[194:197], v[238:241], v[32:35]
	v_mfma_f32_16x16x32_f16 v[28:31], v[194:197], v[246:249], v[28:31]
	v_mfma_f32_16x16x32_f16 v[24:27], v[202:205], v[238:241], v[24:27]
	v_mfma_f32_16x16x32_f16 v[20:23], v[202:205], v[246:249], v[20:23]
	v_mfma_f32_16x16x32_f16 v[16:19], v[210:213], v[238:241], v[16:19]
	v_mfma_f32_16x16x32_f16 v[12:15], v[210:213], v[246:249], v[12:15]
	v_mfma_f32_16x16x32_f16 v[8:11], v[218:221], v[238:241], v[8:11]
	v_mfma_f32_16x16x32_f16 v[4:7], v[218:221], v[246:249], v[4:7]
	s_setprio 0
	s_add_i32 s1, s1, 2
	s_add_u32 s14, s14, 0x100
	s_addc_u32 s15, s15, 0
	s_cmp_lt_u32 s1, 12
	s_barrier
	s_cbranch_scc0 .Lpk_exit_1

; #define LDA8(dst, b, h) _Pragma("unroll") for (int m = 0; m < 4; ++m) _Pragma("unroll") for (int k = 0; k < 2; ++k) \
;     dst[m][k] = *(const bf16x8*)((const char*)SA8(b, h) + lds_byte8(wr * 64 + m * 16 + fr, k * 32 + fq * 8))
; #define LDB8(dst, b, h) _Pragma("unroll") for (int n = 0; n < 2; ++n) _Pragma("unroll") for (int k = 0; k < 2; ++k) \
;     dst[n][k] = *(const bf16x8*)((const char*)SB8(b, h) + lds_byte8(wc * 32 + n * 16 + fr, k * 32 + fq * 8))
; #define WAIT_V8(n) asm volatile("s_waitcnt vmcnt(" #n ")" ::: "memory")
; #define WAIT_L8(n) asm volatile("s_waitcnt lgkmcnt(" #n ")" ::: "memory")
; #define BAR8 __builtin_amdgcn_s_barrier()
;     ...
;   { LDB8(B0, 0, 0); LDA8(At, 0, 0); STAGE8(SA8(1, 1), A, lda, brow + 128, nt - 1);
;     BAR8; WAIT_L8(0); MMA8(0, 0, At, B0); BAR8;
;     LDB8(B1, 0, 1); BAR8; WAIT_L8(0); MMA8(0, 1, At, B1); BAR8;
;     LDA8(At, 0, 1); WAIT_V8(4); BAR8; WAIT_L8(0); MMA8(1, 0, At, B0); MMA8(1, 1, At, B1); BAR8; }
;   { LDB8(B0, 1, 0); LDA8(At, 1, 0); WAIT_V8(2); BAR8; WAIT_L8(0); MMA8(0, 0, At, B0); BAR8;
;     LDB8(B1, 1, 1); WAIT_V8(0); BAR8; WAIT_L8(0); MMA8(0, 1, At, B1); BAR8;
.Lpk_exit_1:
	s_add_u32 s12, s12, 0x40780
	s_addc_u32 s13, s13, 0
	v_lshl_add_u64 v[132:133], s[12:13], 0, v[132:133]
	v_readfirstlane_b32 s1, v172
	v_lshl_add_u64 v[0:1], v[0:1], 1, v[132:133]
	s_mov_b32 m0, s1
	ds_read_b128 v[138:141], v171
	ds_read_b128 v[142:145], v171 offset:1024
	ds_read_b128 v[160:163], v171 offset:2048
	ds_read_b128 v[164:167], v171 offset:3072
	ds_read_b128 v[174:177], v156
	ds_read_b128 v[178:181], v156 offset:1024
	ds_read_b128 v[182:185], v154
	ds_read_b128 v[186:189], v154 offset:1024
	ds_read_b128 v[190:193], v153
	ds_read_b128 v[194:197], v153 offset:1024
	ds_read_b128 v[198:201], v152
	ds_read_b128 v[202:205], v152 offset:1024
	global_load_lds_dwordx4 v[0:1], off
	v_lshl_add_u64 v[0:1], s[12:13], 0, v[136:137]
	v_readfirstlane_b32 s1, v173
	v_lshl_add_u64 v[0:1], v[134:135], 1, v[0:1]
	s_mov_b32 m0, s1
	s_nop 0
	global_load_lds_dwordx4 v[0:1], off
	s_barrier
	s_waitcnt lgkmcnt(0)
	s_setprio 1
	s_waitcnt lgkmcnt(0)
	v_mfma_f32_16x16x32_f16 v[128:131], v[174:177], v[138:141], v[128:131]
	v_mfma_f32_16x16x32_f16 v[124:127], v[174:177], v[160:163], v[124:127]
	v_mfma_f32_16x16x32_f16 v[120:123], v[182:185], v[138:141], v[120:123]
	v_mfma_f32_16x16x32_f16 v[112:115], v[190:193], v[138:141], v[112:115]
	v_mfma_f32_16x16x32_f16 v[128:131], v[178:181], v[142:145], v[128:131]
	v_mfma_f32_16x16x32_f16 v[124:127], v[178:181], v[164:167], v[124:127]
	v_mfma_f32_16x16x32_f16 v[120:123], v[186:189], v[142:145], v[120:123]
	v_mfma_f32_16x16x32_f16 v[116:119], v[182:185], v[160:163], v[116:119]
	v_mfma_f32_16x16x32_f16 v[112:115], v[194:197], v[142:145], v[112:115]
	v_mfma_f32_16x16x32_f16 v[108:111], v[190:193], v[160:163], v[108:111]
	v_mfma_f32_16x16x32_f16 v[104:107], v[198:201], v[138:141], v[104:107]
	v_mfma_f32_16x16x32_f16 v[100:103], v[198:201], v[160:163], v[100:103]
	v_mfma_f32_16x16x32_f16 v[132:135], v[186:189], v[164:167], v[116:119]
	v_mfma_f32_16x16x32_f16 v[170:173], v[194:197], v[164:167], v[108:111]
	v_mfma_f32_16x16x32_f16 v[206:209], v[202:205], v[142:145], v[104:107]
	v_mfma_f32_16x16x32_f16 v[210:213], v[202:205], v[164:167], v[100:103]
	s_setprio 0
	s_barrier
	s_nop 1
	ds_read_b128 v[100:103], v168
	ds_read_b128 v[104:107], v168 offset:1024
	ds_read_b128 v[108:111], v168 offset:2048
	ds_read_b128 v[116:119], v168 offset:3072
	s_barrier
	s_waitcnt lgkmcnt(0)
	s_setprio 1
	s_waitcnt lgkmcnt(0)
	v_mfma_f32_16x16x32_f16 v[80:83], v[190:193], v[100:103], v[80:83]
	v_mfma_f32_16x16x32_f16 v[76:79], v[190:193], v[108:111], v[76:79]
	v_mfma_f32_16x16x32_f16 v[72:75], v[198:201], v[100:103], v[72:75]
	v_mfma_f32_16x16x32_f16 v[68:71], v[198:201], v[108:111], v[68:71]
	v_mfma_f32_16x16x32_f16 v[96:99], v[174:177], v[100:103], v[96:99]
	v_mfma_f32_16x16x32_f16 v[92:95], v[174:177], v[108:111], v[92:95]
	v_mfma_f32_16x16x32_f16 v[88:91], v[182:185], v[100:103], v[88:91]
	v_mfma_f32_16x16x32_f16 v[84:87], v[182:185], v[108:111], v[84:87]
	v_mfma_f32_16x16x32_f16 v[80:83], v[194:197], v[104:107], v[80:83]
	v_mfma_f32_16x16x32_f16 v[76:79], v[194:197], v[116:119], v[76:79]
	v_mfma_f32_16x16x32_f16 v[72:75], v[202:205], v[104:107], v[72:75]
	v_mfma_f32_16x16x32_f16 v[68:71], v[202:205], v[116:119], v[68:71]
	v_mfma_f32_16x16x32_f16 v[214:217], v[178:181], v[104:107], v[96:99]
	v_mfma_f32_16x16x32_f16 v[174:177], v[178:181], v[116:119], v[92:95]
	v_mfma_f32_16x16x32_f16 v[178:181], v[186:189], v[104:107], v[88:91]
	v_mfma_f32_16x16x32_f16 v[182:185], v[186:189], v[116:119], v[84:87]
	s_setprio 0
	s_barrier
	s_nop 0
	ds_read_b128 v[84:87], v156 offset:16384
	ds_read_b128 v[88:91], v156 offset:17408
	ds_read_b128 v[92:95], v154 offset:16384
	ds_read_b128 v[96:99], v154 offset:17408
	ds_read_b128 v[186:189], v153 offset:16384
	ds_read_b128 v[190:193], v153 offset:17408
	ds_read_b128 v[194:197], v152 offset:16384
	ds_read_b128 v[198:201], v152 offset:17408
	s_waitcnt vmcnt(4)
	s_barrier
	s_waitcnt lgkmcnt(0)
	s_setprio 1
	s_waitcnt lgkmcnt(0)
	v_mfma_f32_16x16x32_f16 v[64:67], v[84:87], v[138:141], v[64:67]
	v_mfma_f32_16x16x32_f16 v[60:63], v[84:87], v[160:163], v[60:63]
	v_mfma_f32_16x16x32_f16 v[56:59], v[92:95], v[138:141], v[56:59]
	v_mfma_f32_16x16x32_f16 v[52:55], v[92:95], v[160:163], v[52:55]
	v_mfma_f32_16x16x32_f16 v[48:51], v[186:189], v[138:141], v[48:51]
	v_mfma_f32_16x16x32_f16 v[44:47], v[186:189], v[160:163], v[44:47]
	v_mfma_f32_16x16x32_f16 v[40:43], v[194:197], v[138:141], v[40:43]
	v_mfma_f32_16x16x32_f16 v[36:39], v[194:197], v[160:163], v[36:39]
	v_mfma_f32_16x16x32_f16 v[64:67], v[88:91], v[142:145], v[64:67]
	v_mfma_f32_16x16x32_f16 v[60:63], v[88:91], v[164:167], v[60:63]
	v_mfma_f32_16x16x32_f16 v[56:59], v[96:99], v[142:145], v[56:59]
	v_mfma_f32_16x16x32_f16 v[52:55], v[96:99], v[164:167], v[52:55]
	v_mfma_f32_16x16x32_f16 v[48:51], v[190:193], v[142:145], v[48:51]
	v_mfma_f32_16x16x32_f16 v[44:47], v[190:193], v[164:167], v[44:47]
	v_mfma_f32_16x16x32_f16 v[40:43], v[198:201], v[142:145], v[40:43]
	v_mfma_f32_16x16x32_f16 v[36:39], v[198:201], v[164:167], v[36:39]
	s_setprio 0
	s_setprio 1
	v_mfma_f32_16x16x32_f16 v[32:35], v[84:87], v[100:103], v[32:35]
	v_mfma_f32_16x16x32_f16 v[28:31], v[84:87], v[108:111], v[28:31]
	v_mfma_f32_16x16x32_f16 v[24:27], v[92:95], v[100:103], v[24:27]
	v_mfma_f32_16x16x32_f16 v[20:23], v[92:95], v[108:111], v[20:23]
	v_mfma_f32_16x16x32_f16 v[16:19], v[186:189], v[100:103], v[16:19]
	v_mfma_f32_16x16x32_f16 v[12:15], v[186:189], v[108:111], v[12:15]
	v_mfma_f32_16x16x32_f16 v[8:11], v[194:197], v[100:103], v[8:11]
	v_mfma_f32_16x16x32_f16 v[4:7], v[194:197], v[108:111], v[4:7]
	v_mfma_f32_16x16x32_f16 v[136:139], v[88:91], v[104:107], v[32:35]
	v_mfma_f32_16x16x32_f16 v[140:143], v[88:91], v[116:119], v[28:31]
	v_mfma_f32_16x16x32_f16 v[160:163], v[96:99], v[104:107], v[24:27]
	v_mfma_f32_16x16x32_f16 v[164:167], v[96:99], v[116:119], v[20:23]
	v_mfma_f32_16x16x32_f16 v[202:205], v[190:193], v[104:107], v[16:19]
	v_mfma_f32_16x16x32_f16 v[186:189], v[190:193], v[116:119], v[12:15]
	v_mfma_f32_16x16x32_f16 v[190:193], v[198:201], v[104:107], v[8:11]
	v_mfma_f32_16x16x32_f16 v[194:197], v[198:201], v[116:119], v[4:7]
	s_setprio 0
	s_barrier
; #define LDA8(dst, b, h) _Pragma("unroll") for (int m = 0; m < 4; ++m) _Pragma("unroll") for (int k = 0; k < 2; ++k) \
;     dst[m][k] = *(const bf16x8*)((const char*)SA8(b, h) + lds_byte8(wr * 64 + m * 16 + fr, k * 32 + fq * 8))
; #define LDB8(dst, b, h) _Pragma("unroll") for (int n = 0; n < 2; ++n) _Pragma("unroll") for (int k = 0; k < 2; ++k) \
;     dst[n][k] = *(const bf16x8*)((const char*)SB8(b, h) + lds_byte8(wc * 32 + n * 16 + fr, k * 32 + fq * 8))
; #define WAIT_V8(n) asm volatile("s_waitcnt vmcnt(" #n ")" ::: "memory")
; #define WAIT_L8(n) asm volatile("s_waitcnt lgkmcnt(" #n ")" ::: "memory")
; #define BAR8 __builtin_amdgcn_s_barrier()
;     ...
;   { LDB8(B0, 1, 0); LDA8(At, 1, 0); WAIT_V8(2); BAR8; WAIT_L8(0); MMA8(0, 0, At, B0); BAR8;
;     LDB8(B1, 1, 1); WAIT_V8(0); BAR8; WAIT_L8(0); MMA8(0, 1, At, B1); BAR8;
;     LDA8(At, 1, 1); BAR8; WAIT_L8(0); MMA8(1, 0, At, B0); MMA8(1, 1, At, B1); BAR8; }
;   if (wr == 0) BAR8;
;   __syncthreads();
;     ...
;   if (t < 256) {
	ds_read_b128 v[198:201], v159
	ds_read_b128 v[218:221], v159 offset:1024
	ds_read_b128 v[230:233], v159 offset:2048
	ds_read_b128 v[238:241], v159 offset:3072
	ds_read_b128 v[8:11], v156 offset:32768
	ds_read_b128 v[12:15], v156 offset:33792
	ds_read_b128 v[16:19], v154 offset:32768
	ds_read_b128 v[24:27], v154 offset:33792
	ds_read_b128 v[28:31], v153 offset:32768
	ds_read_b128 v[32:35], v153 offset:33792
	ds_read_b128 v[242:245], v152 offset:32768
	ds_read_b128 v[246:249], v152 offset:33792
	s_waitcnt vmcnt(2)
	s_barrier
	s_waitcnt lgkmcnt(0)
	s_setprio 1
	s_waitcnt lgkmcnt(0)
	v_mfma_f32_16x16x32_f16 v[4:7], v[8:11], v[198:201], v[128:131]
	v_mfma_f32_16x16x32_f16 v[104:107], v[12:15], v[218:221], v[4:7]
	v_mfma_f32_16x16x32_f16 v[4:7], v[8:11], v[230:233], v[124:127]
	v_mfma_f32_16x16x32_f16 v[116:119], v[12:15], v[238:241], v[4:7]
	v_mfma_f32_16x16x32_f16 v[4:7], v[16:19], v[198:201], v[120:123]
	v_mfma_f32_16x16x32_f16 v[100:103], v[24:27], v[218:221], v[4:7]
	v_mfma_f32_16x16x32_f16 v[4:7], v[16:19], v[230:233], v[132:135]
	v_mfma_f32_16x16x32_f16 v[108:111], v[24:27], v[238:241], v[4:7]
	v_mfma_f32_16x16x32_f16 v[4:7], v[28:31], v[198:201], v[112:115]
	v_mfma_f32_16x16x32_f16 v[92:95], v[32:35], v[218:221], v[4:7]
	v_mfma_f32_16x16x32_f16 v[4:7], v[28:31], v[230:233], v[170:173]
	v_mfma_f32_16x16x32_f16 v[96:99], v[32:35], v[238:241], v[4:7]
	v_mfma_f32_16x16x32_f16 v[4:7], v[242:245], v[198:201], v[206:209]
	v_mfma_f32_16x16x32_f16 v[84:87], v[246:249], v[218:221], v[4:7]
	v_mfma_f32_16x16x32_f16 v[4:7], v[242:245], v[230:233], v[210:213]
	v_mfma_f32_16x16x32_f16 v[88:91], v[246:249], v[238:241], v[4:7]
	s_setprio 0
	s_barrier
	ds_read_b128 v[132:135], v157
	ds_read_b128 v[168:171], v157 offset:1024
	ds_read_b128 v[206:209], v157 offset:2048
	ds_read_b128 v[210:213], v157 offset:3072
	s_waitcnt vmcnt(0)
	s_barrier
	s_waitcnt lgkmcnt(0)
	s_setprio 1
	s_waitcnt lgkmcnt(0)
	v_mfma_f32_16x16x32_f16 v[4:7], v[8:11], v[132:135], v[214:217]
	v_mfma_f32_16x16x32_f16 v[8:11], v[8:11], v[206:209], v[174:177]
	v_mfma_f32_16x16x32_f16 v[4:7], v[12:15], v[168:171], v[4:7]
	v_mfma_f32_16x16x32_f16 v[20:23], v[12:15], v[210:213], v[8:11]
	v_mfma_f32_16x16x32_f16 v[8:11], v[16:19], v[132:135], v[178:181]
	v_mfma_f32_16x16x32_f16 v[12:15], v[16:19], v[206:209], v[182:185]
	v_mfma_f32_16x16x32_f16 v[8:11], v[24:27], v[168:171], v[8:11]
	v_mfma_f32_16x16x32_f16 v[24:27], v[24:27], v[210:213], v[12:15]
	v_mfma_f32_16x16x32_f16 v[12:15], v[28:31], v[132:135], v[80:83]
	v_mfma_f32_16x16x32_f16 v[16:19], v[28:31], v[206:209], v[76:79]
	v_mfma_f32_16x16x32_f16 v[12:15], v[32:35], v[168:171], v[12:15]
	v_mfma_f32_16x16x32_f16 v[28:31], v[32:35], v[210:213], v[16:19]
	v_mfma_f32_16x16x32_f16 v[16:19], v[242:245], v[132:135], v[72:75]
	v_mfma_f32_16x16x32_f16 v[32:35], v[242:245], v[206:209], v[68:71]
	v_mfma_f32_16x16x32_f16 v[16:19], v[246:249], v[168:171], v[16:19]
	v_mfma_f32_16x16x32_f16 v[32:35], v[246:249], v[210:213], v[32:35]
	s_setprio 0
	s_barrier
	ds_read_b128 v[172:175], v156 offset:49152
	ds_read_b128 v[156:159], v156 offset:50176
	ds_read_b128 v[176:179], v154 offset:49152
	ds_read_b128 v[180:183], v154 offset:50176
	ds_read_b128 v[214:217], v153 offset:49152
	ds_read_b128 v[242:245], v153 offset:50176
	ds_read_b128 v[246:249], v152 offset:49152
	ds_read_b128 v[150:153], v152 offset:50176
	s_barrier
	s_waitcnt lgkmcnt(0)
	s_setprio 1
	s_waitcnt lgkmcnt(0)
	v_mfma_f32_16x16x32_f16 v[64:67], v[172:175], v[198:201], v[64:67]
	v_mfma_f32_16x16x32_f16 v[60:63], v[172:175], v[230:233], v[60:63]
	v_mfma_f32_16x16x32_f16 v[56:59], v[176:179], v[198:201], v[56:59]
	v_mfma_f32_16x16x32_f16 v[52:55], v[176:179], v[230:233], v[52:55]
	v_mfma_f32_16x16x32_f16 v[48:51], v[214:217], v[198:201], v[48:51]
	v_mfma_f32_16x16x32_f16 v[44:47], v[214:217], v[230:233], v[44:47]
	v_mfma_f32_16x16x32_f16 v[40:43], v[246:249], v[198:201], v[40:43]
	v_mfma_f32_16x16x32_f16 v[36:39], v[246:249], v[230:233], v[36:39]
	v_mfma_f32_16x16x32_f16 v[128:131], v[156:159], v[218:221], v[64:67]
	v_mfma_f32_16x16x32_f16 v[124:127], v[156:159], v[238:241], v[60:63]
	v_mfma_f32_16x16x32_f16 v[120:123], v[180:183], v[218:221], v[56:59]
	v_mfma_f32_16x16x32_f16 v[112:115], v[180:183], v[238:241], v[52:55]
	v_mfma_f32_16x16x32_f16 v[80:83], v[242:245], v[218:221], v[48:51]
	v_mfma_f32_16x16x32_f16 v[76:79], v[242:245], v[238:241], v[44:47]
	v_mfma_f32_16x16x32_f16 v[72:75], v[150:153], v[218:221], v[40:43]
	v_mfma_f32_16x16x32_f16 v[68:71], v[150:153], v[238:241], v[36:39]
	s_setprio 0
	s_setprio 1
	v_mfma_f32_16x16x32_f16 v[40:43], v[172:175], v[206:209], v[140:143]
	v_mfma_f32_16x16x32_f16 v[44:47], v[176:179], v[206:209], v[164:167]
	v_mfma_f32_16x16x32_f16 v[48:51], v[214:217], v[206:209], v[186:189]
	v_mfma_f32_16x16x32_f16 v[36:39], v[172:175], v[132:135], v[136:139]
	v_mfma_f32_16x16x32_f16 v[52:55], v[156:159], v[210:213], v[40:43]
	v_mfma_f32_16x16x32_f16 v[40:43], v[176:179], v[132:135], v[160:163]
	v_mfma_f32_16x16x32_f16 v[56:59], v[180:183], v[210:213], v[44:47]
	v_mfma_f32_16x16x32_f16 v[44:47], v[214:217], v[132:135], v[202:205]
	v_mfma_f32_16x16x32_f16 v[60:63], v[242:245], v[210:213], v[48:51]
	v_mfma_f32_16x16x32_f16 v[48:51], v[246:249], v[132:135], v[190:193]
	v_mfma_f32_16x16x32_f16 v[64:67], v[246:249], v[206:209], v[194:197]
	v_mfma_f32_16x16x32_f16 v[36:39], v[156:159], v[168:171], v[36:39]
	v_mfma_f32_16x16x32_f16 v[40:43], v[180:183], v[168:171], v[40:43]
	v_mfma_f32_16x16x32_f16 v[44:47], v[242:245], v[168:171], v[44:47]
	v_mfma_f32_16x16x32_f16 v[48:51], v[150:153], v[168:171], v[48:51]
	v_mfma_f32_16x16x32_f16 v[64:67], v[150:153], v[210:213], v[64:67]
	s_setprio 0
	s_movk_i32 s1, 0x100
	v_cmp_gt_u32_e32 vcc, s1, v3
	s_barrier
	s_and_saveexec_b64 s[12:13], vcc
	s_cbranch_execz .LBB0_245
	s_barrier

; #define LDA8(dst, b, h) _Pragma("unroll") for (int m = 0; m < 4; ++m) _Pragma("unroll") for (int k = 0; k < 2; ++k) \
;     dst[m][k] = *(const bf16x8*)((const char*)SA8(b, h) + lds_byte8(wr * 64 + m * 16 + fr, k * 32 + fq * 8))
; #define LDB8(dst, b, h) _Pragma("unroll") for (int n = 0; n < 2; ++n) _Pragma("unroll") for (int k = 0; k < 2; ++k) \
;     dst[n][k] = *(const bf16x8*)((const char*)SB8(b, h) + lds_byte8(wc * 32 + n * 16 + fr, k * 32 + fq * 8))
; #define WAIT_V8(n) asm volatile("s_waitcnt vmcnt(" #n ")" ::: "memory")
; #define WAIT_L8(n) asm volatile("s_waitcnt lgkmcnt(" #n ")" ::: "memory")
; #define BAR8 __builtin_amdgcn_s_barrier()
; #define SCHED8 __builtin_amdgcn_sched_barrier(0)
;     ...
;   f32x4 acc[2][2][4][2];
;   {
;     float zinit = 0.f;
;     asm volatile("" : "+v"(zinit));
; #pragma unroll
;     for (int a = 0; a < 2; ++a)
; #pragma unroll
;       for (int b = 0; b < 2; ++b)
; #pragma unroll
;         for (int m = 0; m < 4; ++m)
; #pragma unroll
;           for (int n = 0; n < 2; ++n)
; #pragma unroll
;             for (int j = 0; j < 4; ++j) acc[a][b][m][n][j] = zinit;
;   }
;   bf16x8 At[4][2], B0[2][2], B1[2][2];
;   const int nt = K / 64;
;   if (!pre) {
;     STAGE8(SB8(0, 0), Bt, K, bcol, 0); STAGE8(SA8(0, 0), A, lda, brow, 0);
;     STAGE8(SB8(0, 1), Bt, K, bcol + 128, 0); STAGE8(SA8(0, 1), A, lda, brow + 128, 0);
;   }
;   if (wr == 1) BAR8;
;   WAIT_V8(4); BAR8;
;   STAGE8(SB8(1, 0), Bt, K, bcol, 1); STAGE8(SA8(1, 0), A, lda, brow, 1); STAGE8(SB8(1, 1), Bt, K, bcol + 128, 1);
;   WAIT_V8(6); BAR8;
;   for (int tt = 0; tt < nt - 2; tt += 2) {
;     LDB8(B0, 0, 0); SCHED8; LDA8(At, 0, 0); STAGE8(SA8(1, 1), A, lda, brow + 128, tt + 1);
;     WAIT_L8(8); BAR8; WAIT_L8(0); MMA8(0, 0, At, B0); BAR8; SCHED8;
.LBB0_907:
	s_or_b64 exec, exec, s[12:13]
	s_lshl_b32 s29, s20, 11
	s_waitcnt vmcnt(0)
	v_add_u32_e32 v164, 0x18000, v150
	s_and_b32 s36, s29, 0x1f80000
	s_mov_b64 s[38:39], 0x80
	v_readfirstlane_b32 s29, v164
	v_add_u32_e32 v165, 0x1a000, v150
	v_lshl_add_u64 v[14:15], v[14:15], 0, s[38:39]
	s_mov_b32 m0, s29
	v_readfirstlane_b32 s29, v165
	v_add_u32_e32 v166, 0x8000, v150
	s_waitcnt vmcnt(4)
	s_barrier
	global_load_lds_dwordx4 v[14:15], off
	v_lshl_add_u64 v[14:15], v[18:19], 0, s[38:39]
	s_mov_b32 m0, s29
	v_readfirstlane_b32 s29, v166
	v_add_u32_e32 v168, 0xa000, v150
	global_load_lds_dwordx4 v[14:15], off
	v_lshl_add_u64 v[14:15], v[20:21], 0, s[38:39]
	s_mov_b32 m0, s29
	v_readfirstlane_b32 s29, v168
	v_add_u32_e32 v169, 0x1c000, v150
	global_load_lds_dwordx4 v[14:15], off
	v_lshl_add_u64 v[14:15], v[22:23], 0, s[38:39]
	s_mov_b32 m0, s29
	v_readfirstlane_b32 s29, v169
	v_add_u32_e32 v170, 0x1e000, v150
	global_load_lds_dwordx4 v[14:15], off
	v_lshl_add_u64 v[14:15], v[26:27], 0, s[38:39]
	s_mov_b32 m0, s29
	v_readfirstlane_b32 s29, v170
	global_load_lds_dwordx4 v[14:15], off
	v_lshl_add_u64 v[14:15], v[28:29], 0, s[38:39]
	s_mov_b32 m0, s29
	v_and_b32_e32 v147, 15, v3
	global_load_lds_dwordx4 v[14:15], off
	v_bfe_u32 v148, v3, 4, 2
	v_lshlrev_b32_e32 v14, 4, v148
	v_lshlrev_b32_e32 v15, 6, v147
	v_lshlrev_b32_e32 v18, 2, v3
	v_lshlrev_b64 v[136:137], 10, v[16:17]
	v_or_b32_e32 v17, v14, v15
	v_and_b32_e32 v18, 32, v18
	s_mov_b32 s29, 0x10000
	s_and_b32 s12, s21, 0xffffff00
	v_bitop3_b32 v20, v17, s29, v18 bitop3:0xde
	s_mov_b32 s29, 0x14000
	s_ashr_i32 s13, s12, 31
	v_readlane_b32 s40, v254, 35
	v_bitop3_b32 v19, v14, v18, v15 bitop3:0x36
	v_bitop3_b32 v21, v17, s29, v18 bitop3:0xde
	s_mov_b32 s29, 0x18000
	v_lshlrev_b32_e32 v15, 6, v3
	s_lshl_b64 s[12:13], s[12:13], 11
	s_mov_b32 s37, s40
	v_bitop3_b32 v22, v17, s29, v18 bitop3:0xde
	s_mov_b32 s29, 0x1c000
	v_and_b32_e32 v15, 0x3c0, v15
	v_bitop3_b32 v17, v17, s29, v18 bitop3:0xde
	v_bitop3_b32 v18, v15, v18, v14 bitop3:0x36
	v_lshl_add_u64 v[14:15], s[12:13], 0, v[6:7]
	v_lshl_add_u64 v[6:7], s[36:37], 0, v[6:7]
	v_lshl_add_u64 v[14:15], v[14:15], 0, v[8:9]
	v_lshl_add_u64 v[6:7], v[6:7], 0, v[8:9]
	v_bfe_u32 v146, v3, 6, 2
	s_waitcnt vmcnt(6)
	v_lshlrev_b32_e32 v149, 6, v5
	v_lshlrev_b32_e32 v5, 13, v5
	v_lshl_add_u64 v[138:139], s[4:5], 0, v[14:15]
	v_lshl_add_u64 v[14:15], s[12:13], 0, v[10:11]
	v_lshl_add_u64 v[142:143], s[2:3], 0, v[6:7]
	v_lshl_add_u64 v[6:7], s[36:37], 0, v[10:11]
	v_lshlrev_b64 v[134:135], 10, v[24:25]
	v_readlane_b32 s41, v254, 36
	v_readlane_b32 s42, v254, 37
	v_readlane_b32 s43, v254, 38
	v_lshlrev_b32_e32 v16, 12, v146
	v_or_b32_e32 v23, 0x800, v5
	v_or_b32_e32 v24, 0x1000, v5
	v_or_b32_e32 v25, 0x1800, v5
	v_lshl_add_u64 v[14:15], v[14:15], 0, v[12:13]
	v_lshl_add_u64 v[6:7], v[6:7], 0, v[12:13]
	v_lshl_add_u64 v[140:141], s[4:5], 0, v[14:15]
	v_lshl_add_u64 v[144:145], s[2:3], 0, v[6:7]
	s_mov_b32 s29, -2
	s_mov_b64 s[12:13], 0
	v_add_u32_e32 v171, v20, v16
	v_add_u32_e32 v156, v19, v5
	v_add_u32_e32 v155, v18, v23
	v_add_u32_e32 v154, v18, v24
	v_add_u32_e32 v153, v18, v25
	v_add_u32_e32 v167, v21, v16
	v_add_u32_e32 v160, v22, v16
	v_add_u32_e32 v158, v17, v16
	s_mov_b64 s[36:37], 0x6040080
	s_mov_b64 s[38:39], 0xc4a0100
	s_mov_b64 s[40:41], 0x6000100
	s_mov_b64 s[42:43], 0xc4e0100
	s_mov_b64 s[44:45], 0x6040100
	s_mov_b64 s[46:47], 0xc4a0180
	s_mov_b64 s[48:49], 0x6000180
	s_mov_b64 s[50:51], 0xc4e0180
	s_barrier
	ds_read_b128 v[174:177], v171
	ds_read_b128 v[178:181], v171 offset:1024
	ds_read_b128 v[182:185], v171 offset:2048
	ds_read_b128 v[186:189], v171 offset:3072
	v_add_u32_e32 v172, 0xc000, v150
	v_lshl_add_u64 v[222:223], v[142:143], 0, s[12:13]
	v_readfirstlane_b32 s31, v172
	v_lshl_add_u64 v[226:227], v[222:223], 0, s[36:37]
	s_mov_b32 m0, s31
	v_add_u32_e32 v173, 0xe000, v150
	ds_read_b128 v[190:193], v156
	ds_read_b128 v[194:197], v156 offset:1024
	ds_read_b128 v[198:201], v155
	ds_read_b128 v[202:205], v155 offset:1024
	ds_read_b128 v[206:209], v154
	ds_read_b128 v[210:213], v154 offset:1024
	ds_read_b128 v[214:217], v153
	ds_read_b128 v[218:221], v153 offset:1024
	global_load_lds_dwordx4 v[226:227], off
	v_lshl_add_u64 v[226:227], v[144:145], 0, s[12:13]
	v_readfirstlane_b32 s31, v173
	v_lshl_add_u64 v[228:229], v[226:227], 0, s[36:37]
	s_mov_b32 m0, s31
	s_nop 0
	global_load_lds_dwordx4 v[228:229], off
	s_waitcnt lgkmcnt(8)
	s_barrier
	s_waitcnt lgkmcnt(0)
	s_setprio 1
	s_waitcnt lgkmcnt(0)
	v_mfma_f32_16x16x32_bf16 v[128:131], v[190:193], v[174:177], 0
	v_mfma_f32_16x16x32_bf16 v[124:127], v[190:193], v[182:185], 0
	v_mfma_f32_16x16x32_bf16 v[120:123], v[198:201], v[174:177], 0
	v_mfma_f32_16x16x32_bf16 v[116:119], v[198:201], v[182:185], 0
	v_mfma_f32_16x16x32_bf16 v[112:115], v[206:209], v[174:177], 0
	v_mfma_f32_16x16x32_bf16 v[108:111], v[206:209], v[182:185], 0
	v_mfma_f32_16x16x32_bf16 v[104:107], v[214:217], v[174:177], 0
	v_mfma_f32_16x16x32_bf16 v[100:103], v[214:217], v[182:185], 0
	v_mfma_f32_16x16x32_bf16 v[128:131], v[194:197], v[178:181], v[128:131]
	v_mfma_f32_16x16x32_bf16 v[124:127], v[194:197], v[186:189], v[124:127]
	v_mfma_f32_16x16x32_bf16 v[120:123], v[202:205], v[178:181], v[120:123]
	v_mfma_f32_16x16x32_bf16 v[116:119], v[202:205], v[186:189], v[116:119]
	v_mfma_f32_16x16x32_bf16 v[112:115], v[210:213], v[178:181], v[112:115]
	v_mfma_f32_16x16x32_bf16 v[108:111], v[210:213], v[186:189], v[108:111]
	v_mfma_f32_16x16x32_bf16 v[104:107], v[218:221], v[178:181], v[104:107]
	v_mfma_f32_16x16x32_bf16 v[100:103], v[218:221], v[186:189], v[100:103]
	s_setprio 0
	s_barrier
; #define LDA8(dst, b, h) _Pragma("unroll") for (int m = 0; m < 4; ++m) _Pragma("unroll") for (int k = 0; k < 2; ++k) \
;     dst[m][k] = *(const bf16x8*)((const char*)SA8(b, h) + lds_byte8(wr * 64 + m * 16 + fr, k * 32 + fq * 8))
; #define LDB8(dst, b, h) _Pragma("unroll") for (int n = 0; n < 2; ++n) _Pragma("unroll") for (int k = 0; k < 2; ++k) \
;     dst[n][k] = *(const bf16x8*)((const char*)SB8(b, h) + lds_byte8(wc * 32 + n * 16 + fr, k * 32 + fq * 8))
; #define WAIT_V8(n) asm volatile("s_waitcnt vmcnt(" #n ")" ::: "memory")
; #define WAIT_L8(n) asm volatile("s_waitcnt lgkmcnt(" #n ")" ::: "memory")
; #define BAR8 __builtin_amdgcn_s_barrier()
; #define SCHED8 __builtin_amdgcn_sched_barrier(0)
;     ...
;     LDB8(B1, 0, 1); STAGE8(SB8(0, 0), Bt, K, bcol, tt + 2);
;     BAR8; WAIT_L8(0); MMA8(0, 1, At, B1); BAR8;
;     LDA8(At, 0, 1); STAGE8(SA8(0, 0), A, lda, brow, tt + 2);
;     BAR8; WAIT_L8(0); MMA8(1, 0, At, B0); BAR8; SCHED8;
;     STAGE8(SB8(0, 1), Bt, K, bcol + 128, tt + 2);
;     WAIT_V8(6); BAR8; MMA8(1, 1, At, B1); BAR8;
;     LDB8(B0, 1, 0); SCHED8; LDA8(At, 1, 0); STAGE8(SA8(0, 1), A, lda, brow + 128, tt + 2);
;     WAIT_L8(8); BAR8; WAIT_L8(0); MMA8(0, 0, At, B0); BAR8; SCHED8;
	v_lshl_add_u64 v[228:229], v[138:139], 0, s[12:13]
	v_readfirstlane_b32 s31, v151
	v_lshl_add_u64 v[236:237], v[228:229], 0, s[38:39]
	s_mov_b32 m0, s31
	ds_read_b128 v[230:233], v167
	ds_read_b128 v[238:241], v167 offset:1024
	ds_read_b128 v[242:245], v167 offset:2048
	ds_read_b128 v[246:249], v167 offset:3072
	global_load_lds_dwordx4 v[236:237], off
	v_lshl_add_u64 v[236:237], v[140:141], 0, s[12:13]
	v_readfirstlane_b32 s31, v157
	v_lshl_add_u64 v[250:251], v[236:237], 0, s[38:39]
	s_mov_b32 m0, s31
	s_nop 0
	global_load_lds_dwordx4 v[250:251], off
	s_barrier
	s_waitcnt lgkmcnt(0)
	s_setprio 1
	s_waitcnt lgkmcnt(0)
	v_mfma_f32_16x16x32_bf16 v[96:99], v[190:193], v[230:233], 0
	v_mfma_f32_16x16x32_bf16 v[92:95], v[190:193], v[242:245], 0
	v_mfma_f32_16x16x32_bf16 v[88:91], v[198:201], v[230:233], 0
	v_mfma_f32_16x16x32_bf16 v[84:87], v[198:201], v[242:245], 0
	v_mfma_f32_16x16x32_bf16 v[80:83], v[206:209], v[230:233], 0
	v_mfma_f32_16x16x32_bf16 v[76:79], v[206:209], v[242:245], 0
	v_mfma_f32_16x16x32_bf16 v[72:75], v[214:217], v[230:233], 0
	v_mfma_f32_16x16x32_bf16 v[68:71], v[214:217], v[242:245], 0
	v_mfma_f32_16x16x32_bf16 v[96:99], v[194:197], v[238:241], v[96:99]
	v_mfma_f32_16x16x32_bf16 v[92:95], v[194:197], v[246:249], v[92:95]
	v_mfma_f32_16x16x32_bf16 v[88:91], v[202:205], v[238:241], v[88:91]
	v_mfma_f32_16x16x32_bf16 v[84:87], v[202:205], v[246:249], v[84:87]
	v_mfma_f32_16x16x32_bf16 v[80:83], v[210:213], v[238:241], v[80:83]
	v_mfma_f32_16x16x32_bf16 v[76:79], v[210:213], v[246:249], v[76:79]
	v_mfma_f32_16x16x32_bf16 v[72:75], v[218:221], v[238:241], v[72:75]
	v_mfma_f32_16x16x32_bf16 v[68:71], v[218:221], v[246:249], v[68:71]
	s_setprio 0
	v_readfirstlane_b32 s31, v150
	v_lshl_add_u64 v[250:251], v[222:223], 0, s[40:41]
	s_mov_b32 m0, s31
	v_readfirstlane_b32 s31, v152
	s_barrier
	ds_read_b128 v[190:193], v156 offset:16384
	ds_read_b128 v[194:197], v156 offset:17408
	ds_read_b128 v[198:201], v155 offset:16384
	ds_read_b128 v[202:205], v155 offset:17408
	ds_read_b128 v[206:209], v154 offset:16384
	ds_read_b128 v[210:213], v154 offset:17408
	ds_read_b128 v[214:217], v153 offset:16384
	ds_read_b128 v[218:221], v153 offset:17408
	global_load_lds_dwordx4 v[250:251], off
	v_lshl_add_u64 v[250:251], v[226:227], 0, s[40:41]
	s_mov_b32 m0, s31
	s_nop 0
	global_load_lds_dwordx4 v[250:251], off
	s_barrier
	s_waitcnt lgkmcnt(0)
	s_setprio 1
	s_waitcnt lgkmcnt(0)
	v_mfma_f32_16x16x32_bf16 v[64:67], v[190:193], v[174:177], 0
	v_mfma_f32_16x16x32_bf16 v[60:63], v[190:193], v[182:185], 0
	v_mfma_f32_16x16x32_bf16 v[56:59], v[198:201], v[174:177], 0
	v_mfma_f32_16x16x32_bf16 v[52:55], v[198:201], v[182:185], 0
	v_mfma_f32_16x16x32_bf16 v[48:51], v[206:209], v[174:177], 0
	v_mfma_f32_16x16x32_bf16 v[44:47], v[206:209], v[182:185], 0
	v_mfma_f32_16x16x32_bf16 v[40:43], v[214:217], v[174:177], 0
	v_mfma_f32_16x16x32_bf16 v[36:39], v[214:217], v[182:185], 0
	v_mfma_f32_16x16x32_bf16 v[64:67], v[194:197], v[178:181], v[64:67]
	v_mfma_f32_16x16x32_bf16 v[60:63], v[194:197], v[186:189], v[60:63]
	v_mfma_f32_16x16x32_bf16 v[56:59], v[202:205], v[178:181], v[56:59]
	v_mfma_f32_16x16x32_bf16 v[52:55], v[202:205], v[186:189], v[52:55]
	v_mfma_f32_16x16x32_bf16 v[48:51], v[210:213], v[178:181], v[48:51]
	v_mfma_f32_16x16x32_bf16 v[44:47], v[210:213], v[186:189], v[44:47]
	v_mfma_f32_16x16x32_bf16 v[40:43], v[218:221], v[178:181], v[40:43]
	v_mfma_f32_16x16x32_bf16 v[36:39], v[218:221], v[186:189], v[36:39]
	s_setprio 0
	s_barrier
	v_readfirstlane_b32 s31, v159
	v_lshl_add_u64 v[174:175], v[228:229], 0, s[42:43]
	s_mov_b32 m0, s31
	v_readfirstlane_b32 s31, v161
	global_load_lds_dwordx4 v[174:175], off
	v_lshl_add_u64 v[174:175], v[236:237], 0, s[42:43]
	s_mov_b32 m0, s31
	s_nop 0
	global_load_lds_dwordx4 v[174:175], off
	s_waitcnt vmcnt(6)
	s_barrier
	s_setprio 1
	v_mfma_f32_16x16x32_bf16 v[32:35], v[190:193], v[230:233], 0
	v_mfma_f32_16x16x32_bf16 v[28:31], v[190:193], v[242:245], 0
	v_mfma_f32_16x16x32_bf16 v[24:27], v[198:201], v[230:233], 0
	v_mfma_f32_16x16x32_bf16 v[20:23], v[198:201], v[242:245], 0
	v_mfma_f32_16x16x32_bf16 v[16:19], v[206:209], v[230:233], 0
	v_mfma_f32_16x16x32_bf16 v[12:15], v[206:209], v[242:245], 0
	v_mfma_f32_16x16x32_bf16 v[8:11], v[214:217], v[230:233], 0
	v_mfma_f32_16x16x32_bf16 v[4:7], v[214:217], v[242:245], 0
	v_mfma_f32_16x16x32_bf16 v[32:35], v[194:197], v[238:241], v[32:35]
	v_mfma_f32_16x16x32_bf16 v[28:31], v[194:197], v[246:249], v[28:31]
	v_mfma_f32_16x16x32_bf16 v[24:27], v[202:205], v[238:241], v[24:27]
	v_mfma_f32_16x16x32_bf16 v[20:23], v[202:205], v[246:249], v[20:23]
	v_mfma_f32_16x16x32_bf16 v[16:19], v[210:213], v[238:241], v[16:19]
	v_mfma_f32_16x16x32_bf16 v[12:15], v[210:213], v[246:249], v[12:15]
	v_mfma_f32_16x16x32_bf16 v[8:11], v[218:221], v[238:241], v[8:11]
	v_mfma_f32_16x16x32_bf16 v[4:7], v[218:221], v[246:249], v[4:7]
	s_setprio 0
	s_barrier
	ds_read_b128 v[174:177], v160
	ds_read_b128 v[178:181], v160 offset:1024
	ds_read_b128 v[182:185], v160 offset:2048
	ds_read_b128 v[186:189], v160 offset:3072
	v_readfirstlane_b32 s31, v162
	v_lshl_add_u64 v[230:231], v[222:223], 0, s[44:45]
	s_mov_b32 m0, s31
	v_readfirstlane_b32 s31, v163
	ds_read_b128 v[190:193], v156 offset:32768
	ds_read_b128 v[194:197], v156 offset:33792
	ds_read_b128 v[198:201], v155 offset:32768
	ds_read_b128 v[202:205], v155 offset:33792
	ds_read_b128 v[206:209], v154 offset:32768
	ds_read_b128 v[210:213], v154 offset:33792
	ds_read_b128 v[214:217], v153 offset:32768
	ds_read_b128 v[218:221], v153 offset:33792
	global_load_lds_dwordx4 v[230:231], off
	v_lshl_add_u64 v[230:231], v[226:227], 0, s[44:45]
	s_mov_b32 m0, s31
	s_nop 0
	global_load_lds_dwordx4 v[230:231], off
	s_waitcnt lgkmcnt(8)
	s_barrier
; #define LDA8(dst, b, h) _Pragma("unroll") for (int m = 0; m < 4; ++m) _Pragma("unroll") for (int k = 0; k < 2; ++k) \
;     dst[m][k] = *(const bf16x8*)((const char*)SA8(b, h) + lds_byte8(wr * 64 + m * 16 + fr, k * 32 + fq * 8))
; #define LDB8(dst, b, h) _Pragma("unroll") for (int n = 0; n < 2; ++n) _Pragma("unroll") for (int k = 0; k < 2; ++k) \
;     dst[n][k] = *(const bf16x8*)((const char*)SB8(b, h) + lds_byte8(wc * 32 + n * 16 + fr, k * 32 + fq * 8))
; #define WAIT_V8(n) asm volatile("s_waitcnt vmcnt(" #n ")" ::: "memory")
; #define WAIT_L8(n) asm volatile("s_waitcnt lgkmcnt(" #n ")" ::: "memory")
; #define BAR8 __builtin_amdgcn_s_barrier()
; #define SCHED8 __builtin_amdgcn_sched_barrier(0)
;     ...
;     WAIT_L8(8); BAR8; WAIT_L8(0); MMA8(0, 0, At, B0); BAR8; SCHED8;
;     LDB8(B1, 1, 1); STAGE8(SB8(1, 0), Bt, K, bcol, tt + 3);
;     BAR8; WAIT_L8(0); MMA8(0, 1, At, B1); BAR8;
;     LDA8(At, 1, 1); STAGE8(SA8(1, 0), A, lda, brow, tt + 3);
;     BAR8; WAIT_L8(0); MMA8(1, 0, At, B0); BAR8; SCHED8;
;     STAGE8(SB8(1, 1), Bt, K, bcol + 128, tt + 3);
;     WAIT_V8(6); BAR8; MMA8(1, 1, At, B1); BAR8;
;   }
	s_waitcnt lgkmcnt(0)
	s_setprio 1
	s_waitcnt lgkmcnt(0)
	v_mfma_f32_16x16x32_bf16 v[128:131], v[190:193], v[174:177], v[128:131]
	v_mfma_f32_16x16x32_bf16 v[124:127], v[190:193], v[182:185], v[124:127]
	v_mfma_f32_16x16x32_bf16 v[120:123], v[198:201], v[174:177], v[120:123]
	v_mfma_f32_16x16x32_bf16 v[116:119], v[198:201], v[182:185], v[116:119]
	v_mfma_f32_16x16x32_bf16 v[112:115], v[206:209], v[174:177], v[112:115]
	v_mfma_f32_16x16x32_bf16 v[108:111], v[206:209], v[182:185], v[108:111]
	v_mfma_f32_16x16x32_bf16 v[104:107], v[214:217], v[174:177], v[104:107]
	v_mfma_f32_16x16x32_bf16 v[100:103], v[214:217], v[182:185], v[100:103]
	v_mfma_f32_16x16x32_bf16 v[128:131], v[194:197], v[178:181], v[128:131]
	v_mfma_f32_16x16x32_bf16 v[124:127], v[194:197], v[186:189], v[124:127]
	v_mfma_f32_16x16x32_bf16 v[120:123], v[202:205], v[178:181], v[120:123]
	v_mfma_f32_16x16x32_bf16 v[116:119], v[202:205], v[186:189], v[116:119]
	v_mfma_f32_16x16x32_bf16 v[112:115], v[210:213], v[178:181], v[112:115]
	v_mfma_f32_16x16x32_bf16 v[108:111], v[210:213], v[186:189], v[108:111]
	v_mfma_f32_16x16x32_bf16 v[104:107], v[218:221], v[178:181], v[104:107]
	v_mfma_f32_16x16x32_bf16 v[100:103], v[218:221], v[186:189], v[100:103]
	s_setprio 0
	s_barrier
	v_readfirstlane_b32 s31, v164
	v_lshl_add_u64 v[250:251], v[228:229], 0, s[46:47]
	s_mov_b32 m0, s31
	v_readfirstlane_b32 s31, v165
	ds_read_b128 v[230:233], v158
	ds_read_b128 v[238:241], v158 offset:1024
	ds_read_b128 v[242:245], v158 offset:2048
	ds_read_b128 v[246:249], v158 offset:3072
	global_load_lds_dwordx4 v[250:251], off
	v_lshl_add_u64 v[250:251], v[236:237], 0, s[46:47]
	s_mov_b32 m0, s31
	s_nop 0
	global_load_lds_dwordx4 v[250:251], off
	s_barrier
	s_waitcnt lgkmcnt(0)
	s_setprio 1
	s_waitcnt lgkmcnt(0)
	v_mfma_f32_16x16x32_bf16 v[96:99], v[190:193], v[230:233], v[96:99]
	v_mfma_f32_16x16x32_bf16 v[92:95], v[190:193], v[242:245], v[92:95]
	v_mfma_f32_16x16x32_bf16 v[88:91], v[198:201], v[230:233], v[88:91]
	v_mfma_f32_16x16x32_bf16 v[84:87], v[198:201], v[242:245], v[84:87]
	v_mfma_f32_16x16x32_bf16 v[80:83], v[206:209], v[230:233], v[80:83]
	v_mfma_f32_16x16x32_bf16 v[76:79], v[206:209], v[242:245], v[76:79]
	v_mfma_f32_16x16x32_bf16 v[72:75], v[214:217], v[230:233], v[72:75]
	v_mfma_f32_16x16x32_bf16 v[68:71], v[214:217], v[242:245], v[68:71]
	v_mfma_f32_16x16x32_bf16 v[96:99], v[194:197], v[238:241], v[96:99]
	v_mfma_f32_16x16x32_bf16 v[92:95], v[194:197], v[246:249], v[92:95]
	v_mfma_f32_16x16x32_bf16 v[88:91], v[202:205], v[238:241], v[88:91]
	v_mfma_f32_16x16x32_bf16 v[84:87], v[202:205], v[246:249], v[84:87]
	v_mfma_f32_16x16x32_bf16 v[80:83], v[210:213], v[238:241], v[80:83]
	v_mfma_f32_16x16x32_bf16 v[76:79], v[210:213], v[246:249], v[76:79]
	v_mfma_f32_16x16x32_bf16 v[72:75], v[218:221], v[238:241], v[72:75]
	v_mfma_f32_16x16x32_bf16 v[68:71], v[218:221], v[246:249], v[68:71]
	s_setprio 0
	v_readfirstlane_b32 s31, v166
	v_lshl_add_u64 v[222:223], v[222:223], 0, s[48:49]
	s_mov_b32 m0, s31
	v_readfirstlane_b32 s31, v168
	s_barrier
	ds_read_b128 v[190:193], v156 offset:49152
	ds_read_b128 v[194:197], v156 offset:50176
	ds_read_b128 v[198:201], v155 offset:49152
	ds_read_b128 v[202:205], v155 offset:50176
	ds_read_b128 v[206:209], v154 offset:49152
	ds_read_b128 v[210:213], v154 offset:50176
	ds_read_b128 v[214:217], v153 offset:49152
	ds_read_b128 v[218:221], v153 offset:50176
	global_load_lds_dwordx4 v[222:223], off
	v_lshl_add_u64 v[222:223], v[226:227], 0, s[48:49]
	s_mov_b32 m0, s31
	s_nop 0
	global_load_lds_dwordx4 v[222:223], off
	s_barrier
	s_waitcnt lgkmcnt(0)
	s_setprio 1
	s_waitcnt lgkmcnt(0)
	v_mfma_f32_16x16x32_bf16 v[64:67], v[190:193], v[174:177], v[64:67]
	v_mfma_f32_16x16x32_bf16 v[60:63], v[190:193], v[182:185], v[60:63]
	v_mfma_f32_16x16x32_bf16 v[56:59], v[198:201], v[174:177], v[56:59]
	v_mfma_f32_16x16x32_bf16 v[52:55], v[198:201], v[182:185], v[52:55]
	v_mfma_f32_16x16x32_bf16 v[48:51], v[206:209], v[174:177], v[48:51]
	v_mfma_f32_16x16x32_bf16 v[44:47], v[206:209], v[182:185], v[44:47]
	v_mfma_f32_16x16x32_bf16 v[40:43], v[214:217], v[174:177], v[40:43]
	v_mfma_f32_16x16x32_bf16 v[36:39], v[214:217], v[182:185], v[36:39]
	v_mfma_f32_16x16x32_bf16 v[64:67], v[194:197], v[178:181], v[64:67]
	v_mfma_f32_16x16x32_bf16 v[60:63], v[194:197], v[186:189], v[60:63]
	v_mfma_f32_16x16x32_bf16 v[56:59], v[202:205], v[178:181], v[56:59]
	v_mfma_f32_16x16x32_bf16 v[52:55], v[202:205], v[186:189], v[52:55]
	v_mfma_f32_16x16x32_bf16 v[48:51], v[210:213], v[178:181], v[48:51]
	v_mfma_f32_16x16x32_bf16 v[44:47], v[210:213], v[186:189], v[44:47]
	v_mfma_f32_16x16x32_bf16 v[40:43], v[218:221], v[178:181], v[40:43]
	v_mfma_f32_16x16x32_bf16 v[36:39], v[218:221], v[186:189], v[36:39]
	s_setprio 0
	s_barrier
	v_readfirstlane_b32 s31, v169
	v_lshl_add_u64 v[174:175], v[228:229], 0, s[50:51]
	s_mov_b32 m0, s31
	v_readfirstlane_b32 s31, v170
	global_load_lds_dwordx4 v[174:175], off
	v_lshl_add_u64 v[174:175], v[236:237], 0, s[50:51]
	s_mov_b32 m0, s31
	s_nop 0
	global_load_lds_dwordx4 v[174:175], off
	s_waitcnt vmcnt(6)
	s_barrier
	s_setprio 1
	v_mfma_f32_16x16x32_bf16 v[32:35], v[190:193], v[230:233], v[32:35]
	v_mfma_f32_16x16x32_bf16 v[28:31], v[190:193], v[242:245], v[28:31]
	v_mfma_f32_16x16x32_bf16 v[24:27], v[198:201], v[230:233], v[24:27]
	v_mfma_f32_16x16x32_bf16 v[20:23], v[198:201], v[242:245], v[20:23]
	v_mfma_f32_16x16x32_bf16 v[16:19], v[206:209], v[230:233], v[16:19]
	v_mfma_f32_16x16x32_bf16 v[12:15], v[206:209], v[242:245], v[12:15]
	v_mfma_f32_16x16x32_bf16 v[8:11], v[214:217], v[230:233], v[8:11]
	v_mfma_f32_16x16x32_bf16 v[4:7], v[214:217], v[242:245], v[4:7]
	v_mfma_f32_16x16x32_bf16 v[32:35], v[194:197], v[238:241], v[32:35]
	v_mfma_f32_16x16x32_bf16 v[28:31], v[194:197], v[246:249], v[28:31]
	v_mfma_f32_16x16x32_bf16 v[24:27], v[202:205], v[238:241], v[24:27]
	v_mfma_f32_16x16x32_bf16 v[20:23], v[202:205], v[246:249], v[20:23]
	v_mfma_f32_16x16x32_bf16 v[16:19], v[210:213], v[238:241], v[16:19]
	v_mfma_f32_16x16x32_bf16 v[12:15], v[210:213], v[246:249], v[12:15]
	v_mfma_f32_16x16x32_bf16 v[8:11], v[218:221], v[238:241], v[8:11]
	v_mfma_f32_16x16x32_bf16 v[4:7], v[218:221], v[246:249], v[4:7]
	s_setprio 0
	s_add_i32 s29, s29, 2
	s_add_u32 s12, s12, 0x100
	s_addc_u32 s13, s13, 0
	s_cmp_lt_u32 s29, 12
	s_barrier
	s_cbranch_scc0 .Lpk_exit_2

; #define LDA8(dst, b, h) _Pragma("unroll") for (int m = 0; m < 4; ++m) _Pragma("unroll") for (int k = 0; k < 2; ++k) \
;     dst[m][k] = *(const bf16x8*)((const char*)SA8(b, h) + lds_byte8(wr * 64 + m * 16 + fr, k * 32 + fq * 8))
; #define LDB8(dst, b, h) _Pragma("unroll") for (int n = 0; n < 2; ++n) _Pragma("unroll") for (int k = 0; k < 2; ++k) \
;     dst[n][k] = *(const bf16x8*)((const char*)SB8(b, h) + lds_byte8(wc * 32 + n * 16 + fr, k * 32 + fq * 8))
; #define WAIT_V8(n) asm volatile("s_waitcnt vmcnt(" #n ")" ::: "memory")
; #define WAIT_L8(n) asm volatile("s_waitcnt lgkmcnt(" #n ")" ::: "memory")
; #define BAR8 __builtin_amdgcn_s_barrier()
;     ...
;   { LDB8(B0, 0, 0); LDA8(At, 0, 0); STAGE8(SA8(1, 1), A, lda, brow + 128, nt - 1);
;     BAR8; WAIT_L8(0); MMA8(0, 0, At, B0); BAR8;
;     LDB8(B1, 0, 1); BAR8; WAIT_L8(0); MMA8(0, 1, At, B1); BAR8;
;     LDA8(At, 0, 1); WAIT_V8(4); BAR8; WAIT_L8(0); MMA8(1, 0, At, B0); MMA8(1, 1, At, B1); BAR8; }
.Lpk_exit_2:
	s_add_u32 s2, s2, s27
	s_addc_u32 s3, s3, 0
	s_add_u32 s2, s2, 0x6000780
	s_addc_u32 s3, s3, 0
	v_lshl_add_u64 v[136:137], v[136:137], 1, s[2:3]
	v_readfirstlane_b32 s12, v172
	v_lshl_add_u64 v[0:1], v[0:1], 1, v[136:137]
	s_mov_b32 m0, s12
	ds_read_b128 v[138:141], v171
	ds_read_b128 v[142:145], v171 offset:1024
	ds_read_b128 v[162:165], v171 offset:2048
	ds_read_b128 v[168:171], v171 offset:3072
	ds_read_b128 v[174:177], v156
	ds_read_b128 v[178:181], v156 offset:1024
	ds_read_b128 v[182:185], v155
	ds_read_b128 v[186:189], v155 offset:1024
	ds_read_b128 v[190:193], v154
	ds_read_b128 v[194:197], v154 offset:1024
	ds_read_b128 v[198:201], v153
	ds_read_b128 v[202:205], v153 offset:1024
	global_load_lds_dwordx4 v[0:1], off
	v_lshl_add_u64 v[0:1], v[134:135], 1, s[2:3]
	v_readfirstlane_b32 s2, v173
	v_lshl_add_u64 v[0:1], v[132:133], 1, v[0:1]
	s_mov_b32 m0, s2
	s_nop 0
	global_load_lds_dwordx4 v[0:1], off
	s_barrier
	s_waitcnt lgkmcnt(0)
	s_setprio 1
	s_waitcnt lgkmcnt(0)
	v_mfma_f32_16x16x32_bf16 v[128:131], v[174:177], v[138:141], v[128:131]
	v_mfma_f32_16x16x32_bf16 v[124:127], v[174:177], v[162:165], v[124:127]
	v_mfma_f32_16x16x32_bf16 v[120:123], v[182:185], v[138:141], v[120:123]
	v_mfma_f32_16x16x32_bf16 v[112:115], v[190:193], v[138:141], v[112:115]
	v_mfma_f32_16x16x32_bf16 v[128:131], v[178:181], v[142:145], v[128:131]
	v_mfma_f32_16x16x32_bf16 v[124:127], v[178:181], v[168:171], v[124:127]
	v_mfma_f32_16x16x32_bf16 v[120:123], v[186:189], v[142:145], v[120:123]
	v_mfma_f32_16x16x32_bf16 v[116:119], v[182:185], v[162:165], v[116:119]
	v_mfma_f32_16x16x32_bf16 v[112:115], v[194:197], v[142:145], v[112:115]
	v_mfma_f32_16x16x32_bf16 v[108:111], v[190:193], v[162:165], v[108:111]
	v_mfma_f32_16x16x32_bf16 v[104:107], v[198:201], v[138:141], v[104:107]
	v_mfma_f32_16x16x32_bf16 v[100:103], v[198:201], v[162:165], v[100:103]
	v_mfma_f32_16x16x32_bf16 v[132:135], v[186:189], v[168:171], v[116:119]
	v_mfma_f32_16x16x32_bf16 v[206:209], v[194:197], v[168:171], v[108:111]
	v_mfma_f32_16x16x32_bf16 v[210:213], v[202:205], v[142:145], v[104:107]
	v_mfma_f32_16x16x32_bf16 v[214:217], v[202:205], v[168:171], v[100:103]
	s_setprio 0
	s_barrier
	s_nop 1
	ds_read_b128 v[100:103], v167
	ds_read_b128 v[104:107], v167 offset:1024
	ds_read_b128 v[108:111], v167 offset:2048
	ds_read_b128 v[116:119], v167 offset:3072
	s_barrier
	s_waitcnt lgkmcnt(0)
	s_setprio 1
	s_waitcnt lgkmcnt(0)
	v_mfma_f32_16x16x32_bf16 v[80:83], v[190:193], v[100:103], v[80:83]
	v_mfma_f32_16x16x32_bf16 v[76:79], v[190:193], v[108:111], v[76:79]
	v_mfma_f32_16x16x32_bf16 v[72:75], v[198:201], v[100:103], v[72:75]
	v_mfma_f32_16x16x32_bf16 v[68:71], v[198:201], v[108:111], v[68:71]
	v_mfma_f32_16x16x32_bf16 v[96:99], v[174:177], v[100:103], v[96:99]
	v_mfma_f32_16x16x32_bf16 v[92:95], v[174:177], v[108:111], v[92:95]
	v_mfma_f32_16x16x32_bf16 v[88:91], v[182:185], v[100:103], v[88:91]
	v_mfma_f32_16x16x32_bf16 v[84:87], v[182:185], v[108:111], v[84:87]
	v_mfma_f32_16x16x32_bf16 v[80:83], v[194:197], v[104:107], v[80:83]
	v_mfma_f32_16x16x32_bf16 v[76:79], v[194:197], v[116:119], v[76:79]
	v_mfma_f32_16x16x32_bf16 v[72:75], v[202:205], v[104:107], v[72:75]
	v_mfma_f32_16x16x32_bf16 v[68:71], v[202:205], v[116:119], v[68:71]
	v_mfma_f32_16x16x32_bf16 v[218:221], v[178:181], v[104:107], v[96:99]
	v_mfma_f32_16x16x32_bf16 v[172:175], v[178:181], v[116:119], v[92:95]
	v_mfma_f32_16x16x32_bf16 v[176:179], v[186:189], v[104:107], v[88:91]
	v_mfma_f32_16x16x32_bf16 v[180:183], v[186:189], v[116:119], v[84:87]
	s_setprio 0
	s_barrier
	s_nop 0
	ds_read_b128 v[84:87], v156 offset:16384
	ds_read_b128 v[88:91], v156 offset:17408
	ds_read_b128 v[92:95], v155 offset:16384
	ds_read_b128 v[96:99], v155 offset:17408
	ds_read_b128 v[184:187], v154 offset:16384
	ds_read_b128 v[188:191], v154 offset:17408
	ds_read_b128 v[192:195], v153 offset:16384
	ds_read_b128 v[196:199], v153 offset:17408
	s_waitcnt vmcnt(4)
	s_barrier
	s_waitcnt lgkmcnt(0)
	s_setprio 1
	s_waitcnt lgkmcnt(0)
	v_mfma_f32_16x16x32_bf16 v[64:67], v[84:87], v[138:141], v[64:67]
	v_mfma_f32_16x16x32_bf16 v[60:63], v[84:87], v[162:165], v[60:63]
	v_mfma_f32_16x16x32_bf16 v[56:59], v[92:95], v[138:141], v[56:59]
	v_mfma_f32_16x16x32_bf16 v[52:55], v[92:95], v[162:165], v[52:55]
	v_mfma_f32_16x16x32_bf16 v[48:51], v[184:187], v[138:141], v[48:51]
	v_mfma_f32_16x16x32_bf16 v[44:47], v[184:187], v[162:165], v[44:47]
	v_mfma_f32_16x16x32_bf16 v[40:43], v[192:195], v[138:141], v[40:43]
	v_mfma_f32_16x16x32_bf16 v[36:39], v[192:195], v[162:165], v[36:39]
	v_mfma_f32_16x16x32_bf16 v[64:67], v[88:91], v[142:145], v[64:67]
	v_mfma_f32_16x16x32_bf16 v[60:63], v[88:91], v[168:171], v[60:63]
	v_mfma_f32_16x16x32_bf16 v[56:59], v[96:99], v[142:145], v[56:59]
	v_mfma_f32_16x16x32_bf16 v[52:55], v[96:99], v[168:171], v[52:55]
	v_mfma_f32_16x16x32_bf16 v[48:51], v[188:191], v[142:145], v[48:51]
	v_mfma_f32_16x16x32_bf16 v[44:47], v[188:191], v[168:171], v[44:47]
	v_mfma_f32_16x16x32_bf16 v[40:43], v[196:199], v[142:145], v[40:43]
	v_mfma_f32_16x16x32_bf16 v[36:39], v[196:199], v[168:171], v[36:39]
	s_setprio 0
	s_setprio 1
	v_mfma_f32_16x16x32_bf16 v[32:35], v[84:87], v[100:103], v[32:35]
	v_mfma_f32_16x16x32_bf16 v[28:31], v[84:87], v[108:111], v[28:31]
	v_mfma_f32_16x16x32_bf16 v[24:27], v[92:95], v[100:103], v[24:27]
	v_mfma_f32_16x16x32_bf16 v[20:23], v[92:95], v[108:111], v[20:23]
	v_mfma_f32_16x16x32_bf16 v[16:19], v[184:187], v[100:103], v[16:19]
	v_mfma_f32_16x16x32_bf16 v[12:15], v[184:187], v[108:111], v[12:15]
	v_mfma_f32_16x16x32_bf16 v[8:11], v[192:195], v[100:103], v[8:11]
	v_mfma_f32_16x16x32_bf16 v[4:7], v[192:195], v[108:111], v[4:7]
	v_mfma_f32_16x16x32_bf16 v[136:139], v[88:91], v[104:107], v[32:35]
	v_mfma_f32_16x16x32_bf16 v[140:143], v[88:91], v[116:119], v[28:31]
	v_mfma_f32_16x16x32_bf16 v[162:165], v[96:99], v[104:107], v[24:27]
	v_mfma_f32_16x16x32_bf16 v[166:169], v[96:99], v[116:119], v[20:23]
	v_mfma_f32_16x16x32_bf16 v[200:203], v[188:191], v[104:107], v[16:19]
	v_mfma_f32_16x16x32_bf16 v[184:187], v[188:191], v[116:119], v[12:15]
	v_mfma_f32_16x16x32_bf16 v[188:191], v[196:199], v[104:107], v[8:11]
	v_mfma_f32_16x16x32_bf16 v[192:195], v[196:199], v[116:119], v[4:7]
	s_setprio 0
	s_barrier
; #define LDA8(dst, b, h) _Pragma("unroll") for (int m = 0; m < 4; ++m) _Pragma("unroll") for (int k = 0; k < 2; ++k) \
;     dst[m][k] = *(const bf16x8*)((const char*)SA8(b, h) + lds_byte8(wr * 64 + m * 16 + fr, k * 32 + fq * 8))
; #define LDB8(dst, b, h) _Pragma("unroll") for (int n = 0; n < 2; ++n) _Pragma("unroll") for (int k = 0; k < 2; ++k) \
;     dst[n][k] = *(const bf16x8*)((const char*)SB8(b, h) + lds_byte8(wc * 32 + n * 16 + fr, k * 32 + fq * 8))
; #define WAIT_V8(n) asm volatile("s_waitcnt vmcnt(" #n ")" ::: "memory")
; #define WAIT_L8(n) asm volatile("s_waitcnt lgkmcnt(" #n ")" ::: "memory")
; #define BAR8 __builtin_amdgcn_s_barrier()
;     ...
;   { LDB8(B0, 1, 0); LDA8(At, 1, 0); WAIT_V8(2); BAR8; WAIT_L8(0); MMA8(0, 0, At, B0); BAR8;
;     LDB8(B1, 1, 1); WAIT_V8(0); BAR8; WAIT_L8(0); MMA8(0, 1, At, B1); BAR8;
;     LDA8(At, 1, 1); BAR8; WAIT_L8(0); MMA8(1, 0, At, B0); MMA8(1, 1, At, B1); BAR8; }
;   if (wr == 0) BAR8;
;   __syncthreads();
;     ...
;   if (t < 256) {
	ds_read_b128 v[196:199], v160
	ds_read_b128 v[230:233], v160 offset:1024
	ds_read_b128 v[238:241], v160 offset:2048
	ds_read_b128 v[242:245], v160 offset:3072
	ds_read_b128 v[8:11], v156 offset:32768
	ds_read_b128 v[12:15], v156 offset:33792
	ds_read_b128 v[16:19], v155 offset:32768
	ds_read_b128 v[24:27], v155 offset:33792
	ds_read_b128 v[28:31], v154 offset:32768
	ds_read_b128 v[32:35], v154 offset:33792
	ds_read_b128 v[246:249], v153 offset:32768
	ds_read_b128 v[226:229], v153 offset:33792
	s_waitcnt vmcnt(2)
	s_barrier
	s_waitcnt lgkmcnt(0)
	s_setprio 1
	s_waitcnt lgkmcnt(0)
	v_mfma_f32_16x16x32_bf16 v[4:7], v[8:11], v[196:199], v[128:131]
	v_mfma_f32_16x16x32_bf16 v[104:107], v[12:15], v[230:233], v[4:7]
	v_mfma_f32_16x16x32_bf16 v[4:7], v[8:11], v[238:241], v[124:127]
	v_mfma_f32_16x16x32_bf16 v[116:119], v[12:15], v[242:245], v[4:7]
	v_mfma_f32_16x16x32_bf16 v[4:7], v[16:19], v[196:199], v[120:123]
	v_mfma_f32_16x16x32_bf16 v[100:103], v[24:27], v[230:233], v[4:7]
	v_mfma_f32_16x16x32_bf16 v[4:7], v[16:19], v[238:241], v[132:135]
	v_mfma_f32_16x16x32_bf16 v[108:111], v[24:27], v[242:245], v[4:7]
	v_mfma_f32_16x16x32_bf16 v[4:7], v[28:31], v[196:199], v[112:115]
	v_mfma_f32_16x16x32_bf16 v[92:95], v[32:35], v[230:233], v[4:7]
	v_mfma_f32_16x16x32_bf16 v[4:7], v[28:31], v[238:241], v[206:209]
	v_mfma_f32_16x16x32_bf16 v[96:99], v[32:35], v[242:245], v[4:7]
	v_mfma_f32_16x16x32_bf16 v[4:7], v[246:249], v[196:199], v[210:213]
	v_mfma_f32_16x16x32_bf16 v[84:87], v[226:229], v[230:233], v[4:7]
	v_mfma_f32_16x16x32_bf16 v[4:7], v[246:249], v[238:241], v[214:217]
	v_mfma_f32_16x16x32_bf16 v[88:91], v[226:229], v[242:245], v[4:7]
	s_setprio 0
	s_barrier
	ds_read_b128 v[132:135], v158
	ds_read_b128 v[204:207], v158 offset:1024
	ds_read_b128 v[208:211], v158 offset:2048
	ds_read_b128 v[158:161], v158 offset:3072
	s_waitcnt vmcnt(0)
	s_barrier
	s_waitcnt lgkmcnt(0)
	s_setprio 1
	s_waitcnt lgkmcnt(0)
	v_mfma_f32_16x16x32_bf16 v[4:7], v[8:11], v[132:135], v[218:221]
	v_mfma_f32_16x16x32_bf16 v[8:11], v[8:11], v[208:211], v[172:175]
	v_mfma_f32_16x16x32_bf16 v[4:7], v[12:15], v[204:207], v[4:7]
	v_mfma_f32_16x16x32_bf16 v[20:23], v[12:15], v[158:161], v[8:11]
	v_mfma_f32_16x16x32_bf16 v[8:11], v[16:19], v[132:135], v[176:179]
	v_mfma_f32_16x16x32_bf16 v[12:15], v[16:19], v[208:211], v[180:183]
	v_mfma_f32_16x16x32_bf16 v[8:11], v[24:27], v[204:207], v[8:11]
	v_mfma_f32_16x16x32_bf16 v[24:27], v[24:27], v[158:161], v[12:15]
	v_mfma_f32_16x16x32_bf16 v[12:15], v[28:31], v[132:135], v[80:83]
	v_mfma_f32_16x16x32_bf16 v[16:19], v[28:31], v[208:211], v[76:79]
	v_mfma_f32_16x16x32_bf16 v[12:15], v[32:35], v[204:207], v[12:15]
	v_mfma_f32_16x16x32_bf16 v[28:31], v[32:35], v[158:161], v[16:19]
	v_mfma_f32_16x16x32_bf16 v[16:19], v[246:249], v[132:135], v[72:75]
	v_mfma_f32_16x16x32_bf16 v[32:35], v[246:249], v[208:211], v[68:71]
	v_mfma_f32_16x16x32_bf16 v[16:19], v[226:229], v[204:207], v[16:19]
	v_mfma_f32_16x16x32_bf16 v[32:35], v[226:229], v[158:161], v[32:35]
	s_setprio 0
	s_barrier
	ds_read_b128 v[170:173], v156 offset:49152
	ds_read_b128 v[174:177], v156 offset:50176
	ds_read_b128 v[178:181], v155 offset:49152
	ds_read_b128 v[212:215], v155 offset:50176
	ds_read_b128 v[216:219], v154 offset:49152
	ds_read_b128 v[154:157], v154 offset:50176
	ds_read_b128 v[220:223], v153 offset:49152
	ds_read_b128 v[150:153], v153 offset:50176
	s_barrier
	s_waitcnt lgkmcnt(0)
	s_setprio 1
	s_waitcnt lgkmcnt(0)
	v_mfma_f32_16x16x32_bf16 v[64:67], v[170:173], v[196:199], v[64:67]
	v_mfma_f32_16x16x32_bf16 v[60:63], v[170:173], v[238:241], v[60:63]
	v_mfma_f32_16x16x32_bf16 v[56:59], v[178:181], v[196:199], v[56:59]
	v_mfma_f32_16x16x32_bf16 v[52:55], v[178:181], v[238:241], v[52:55]
	v_mfma_f32_16x16x32_bf16 v[48:51], v[216:219], v[196:199], v[48:51]
	v_mfma_f32_16x16x32_bf16 v[44:47], v[216:219], v[238:241], v[44:47]
	v_mfma_f32_16x16x32_bf16 v[40:43], v[220:223], v[196:199], v[40:43]
	v_mfma_f32_16x16x32_bf16 v[36:39], v[220:223], v[238:241], v[36:39]
	v_mfma_f32_16x16x32_bf16 v[128:131], v[174:177], v[230:233], v[64:67]
	v_mfma_f32_16x16x32_bf16 v[124:127], v[174:177], v[242:245], v[60:63]
	v_mfma_f32_16x16x32_bf16 v[120:123], v[212:215], v[230:233], v[56:59]
	v_mfma_f32_16x16x32_bf16 v[112:115], v[212:215], v[242:245], v[52:55]
	v_mfma_f32_16x16x32_bf16 v[80:83], v[154:157], v[230:233], v[48:51]
	v_mfma_f32_16x16x32_bf16 v[76:79], v[154:157], v[242:245], v[44:47]
	v_mfma_f32_16x16x32_bf16 v[72:75], v[150:153], v[230:233], v[40:43]
	v_mfma_f32_16x16x32_bf16 v[68:71], v[150:153], v[242:245], v[36:39]
	s_setprio 0
	s_setprio 1
	v_mfma_f32_16x16x32_bf16 v[40:43], v[170:173], v[208:211], v[140:143]
	v_mfma_f32_16x16x32_bf16 v[44:47], v[178:181], v[208:211], v[166:169]
	v_mfma_f32_16x16x32_bf16 v[48:51], v[216:219], v[208:211], v[184:187]
	v_mfma_f32_16x16x32_bf16 v[36:39], v[170:173], v[132:135], v[136:139]
	v_mfma_f32_16x16x32_bf16 v[52:55], v[174:177], v[158:161], v[40:43]
	v_mfma_f32_16x16x32_bf16 v[40:43], v[178:181], v[132:135], v[162:165]
	v_mfma_f32_16x16x32_bf16 v[56:59], v[212:215], v[158:161], v[44:47]
	v_mfma_f32_16x16x32_bf16 v[44:47], v[216:219], v[132:135], v[200:203]
	v_mfma_f32_16x16x32_bf16 v[60:63], v[154:157], v[158:161], v[48:51]
	v_mfma_f32_16x16x32_bf16 v[48:51], v[220:223], v[132:135], v[188:191]
	v_mfma_f32_16x16x32_bf16 v[64:67], v[220:223], v[208:211], v[192:195]
	v_mfma_f32_16x16x32_bf16 v[36:39], v[174:177], v[204:207], v[36:39]
	v_mfma_f32_16x16x32_bf16 v[40:43], v[212:215], v[204:207], v[40:43]
	v_mfma_f32_16x16x32_bf16 v[44:47], v[154:157], v[204:207], v[44:47]
	v_mfma_f32_16x16x32_bf16 v[48:51], v[150:153], v[204:207], v[48:51]
	v_mfma_f32_16x16x32_bf16 v[64:67], v[150:153], v[158:161], v[64:67]
	s_setprio 0
	s_movk_i32 s2, 0x100
	v_cmp_gt_u32_e32 vcc, s2, v3
	s_barrier
	s_and_saveexec_b64 s[2:3], vcc
	s_cbranch_execz .LBB0_911
	s_barrier

; #define LDA8(dst, b, h) _Pragma("unroll") for (int m = 0; m < 4; ++m) _Pragma("unroll") for (int k = 0; k < 2; ++k) \
;     dst[m][k] = *(const bf16x8*)((const char*)SA8(b, h) + lds_byte8(wr * 64 + m * 16 + fr, k * 32 + fq * 8))
; #define LDB8(dst, b, h) _Pragma("unroll") for (int n = 0; n < 2; ++n) _Pragma("unroll") for (int k = 0; k < 2; ++k) \
;     dst[n][k] = *(const bf16x8*)((const char*)SB8(b, h) + lds_byte8(wc * 32 + n * 16 + fr, k * 32 + fq * 8))
; #define WAIT_V8(n) asm volatile("s_waitcnt vmcnt(" #n ")" ::: "memory")
; #define WAIT_L8(n) asm volatile("s_waitcnt lgkmcnt(" #n ")" ::: "memory")
; #define BAR8 __builtin_amdgcn_s_barrier()
; #define SCHED8 __builtin_amdgcn_sched_barrier(0)
;     ...
;     STAGE8(SB8(0, 0), Bt, K, bcol, 0); STAGE8(SA8(0, 0), A, lda, brow, 0);
;     STAGE8(SB8(0, 1), Bt, K, bcol + 128, 0); STAGE8(SA8(0, 1), A, lda, brow + 128, 0);
;   }
;   if (wr == 1) BAR8;
;   WAIT_V8(4); BAR8;
;   STAGE8(SB8(1, 0), Bt, K, bcol, 1); STAGE8(SA8(1, 0), A, lda, brow, 1); STAGE8(SB8(1, 1), Bt, K, bcol + 128, 1);
;   WAIT_V8(6); BAR8;
;   for (int tt = 0; tt < nt - 2; tt += 2) {
;     LDB8(B0, 0, 0); SCHED8; LDA8(At, 0, 0); STAGE8(SA8(1, 1), A, lda, brow + 128, tt + 1);
;     WAIT_L8(8); BAR8; WAIT_L8(0); MMA8(0, 0, At, B0); BAR8; SCHED8;
.LBB0_1004:
	s_or_b64 exec, exec, s[20:21]
	v_readlane_b32 s40, v254, 35
	s_lshl_b32 s20, s36, 10
	v_readlane_b32 s42, v254, 37
	v_readlane_b32 s43, v254, 38
	s_waitcnt vmcnt(0)
	v_add_u32_e32 v164, 0x18000, v150
	s_and_b32 s20, s20, 0xfffc0000
	s_mov_b32 s21, s40
	s_mov_b64 s[42:43], 0x80
	v_readfirstlane_b32 s40, v164
	v_add_u32_e32 v165, 0x1a000, v150
	s_and_b32 s1, s27, 7
	s_add_i32 s20, s20, 0xffc00000
	v_lshl_add_u64 v[10:11], v[10:11], 0, s[42:43]
	s_mov_b32 m0, s40
	v_readfirstlane_b32 s40, v165
	v_add_u32_e32 v166, 0x8000, v150
	s_lshl_b32 s1, s1, 19
	s_lshl_b64 s[20:21], s[20:21], 1
	s_waitcnt vmcnt(4)
	s_barrier
	global_load_lds_dwordx4 v[10:11], off
	v_lshl_add_u64 v[10:11], v[12:13], 0, s[42:43]
	s_mov_b32 m0, s40
	v_readfirstlane_b32 s40, v166
	v_add_u32_e32 v167, 0xa000, v150
	global_load_lds_dwordx4 v[10:11], off
	v_lshl_add_u64 v[10:11], v[16:17], 0, s[42:43]
	s_mov_b32 m0, s40
	v_readfirstlane_b32 s40, v167
	s_add_u32 s14, s14, 0x40080
	global_load_lds_dwordx4 v[10:11], off
	v_lshl_add_u64 v[10:11], v[14:15], 0, s[42:43]
	s_mov_b32 m0, s40
	s_addc_u32 s15, s15, 0
	v_add_u32_e32 v169, 0x1c000, v150
	global_load_lds_dwordx4 v[10:11], off
	v_lshl_add_u64 v[10:11], s[14:15], 0, v[132:133]
	v_readfirstlane_b32 s40, v169
	v_lshl_add_u64 v[10:11], v[10:11], 0, v[6:7]
	s_mov_b32 m0, s40
	v_add_u32_e32 v170, 0x1e000, v150
	global_load_lds_dwordx4 v[10:11], off
	v_lshl_add_u64 v[10:11], s[14:15], 0, v[136:137]
	v_readfirstlane_b32 s14, v170
	v_lshl_add_u64 v[10:11], v[10:11], 0, v[8:9]
	s_mov_b32 m0, s14
	v_and_b32_e32 v147, 15, v3
	global_load_lds_dwordx4 v[10:11], off
	v_bfe_u32 v148, v3, 4, 2
	v_lshlrev_b32_e32 v11, 4, v148
	v_lshlrev_b32_e32 v12, 6, v147
	v_lshlrev_b32_e32 v14, 2, v3
	v_or_b32_e32 v13, v11, v12
	v_and_b32_e32 v14, 32, v14
	s_mov_b32 s14, 0x10000
	v_bitop3_b32 v15, v13, s14, v14 bitop3:0xde
	s_mov_b32 s14, 0x14000
	s_add_u32 s12, s12, s1
	v_bitop3_b32 v16, v13, s14, v14 bitop3:0xde
	s_mov_b32 s14, 0x18000
	v_lshlrev_b32_e32 v18, 6, v3
	s_addc_u32 s13, s13, 0
	v_lshl_add_u64 v[8:9], v[136:137], 0, v[8:9]
	v_lshl_add_u64 v[6:7], v[132:133], 0, v[6:7]
	v_bfe_u32 v146, v3, 6, 2
	s_waitcnt vmcnt(6)
	v_lshlrev_b32_e32 v149, 6, v5
	v_bitop3_b32 v17, v13, s14, v14 bitop3:0xde
	s_mov_b32 s14, 0x1c000
	v_lshlrev_b32_e32 v5, 13, v5
	v_and_b32_e32 v18, 0x3c0, v18
	v_lshl_add_u64 v[138:139], s[12:13], 0, v[8:9]
	v_lshl_add_u64 v[140:141], s[12:13], 0, v[6:7]
	s_add_u32 s12, s4, s20
	v_readlane_b32 s41, v254, 36
	v_lshlrev_b32_e32 v10, 12, v146
	v_bitop3_b32 v12, v11, v14, v12 bitop3:0x36
	v_bitop3_b32 v13, v13, s14, v14 bitop3:0xde
	v_bitop3_b32 v11, v18, v14, v11 bitop3:0x36
	v_or_b32_e32 v14, 0x800, v5
	v_or_b32_e32 v18, 0x1000, v5
	v_or_b32_e32 v19, 0x1800, v5
	s_addc_u32 s13, s5, s21
	v_lshl_add_u64 v[142:143], s[12:13], 0, v[6:7]
	v_lshl_add_u64 v[144:145], s[12:13], 0, v[8:9]
	s_mov_b32 s1, -2
	s_mov_b64 s[12:13], 0
	v_add_u32_e32 v171, v15, v10
	v_add_u32_e32 v156, v12, v5
	v_add_u32_e32 v155, v11, v14
	v_add_u32_e32 v154, v11, v18
	v_add_u32_e32 v153, v11, v19
	v_add_u32_e32 v168, v16, v10
	v_add_u32_e32 v161, v17, v10
	v_add_u32_e32 v158, v13, v10
	s_mov_b64 s[20:21], 0xb840080
	s_mov_b64 s[40:41], 0xc7a0100
	s_mov_b64 s[42:43], 0xb800100
	s_mov_b64 s[44:45], 0xc7e0100
	s_mov_b64 s[46:47], 0xb840100
	s_mov_b64 s[48:49], 0xc7a0180
	s_mov_b64 s[50:51], 0xb800180
	s_mov_b64 s[52:53], 0xc7e0180
	s_barrier
	ds_read_b128 v[174:177], v171
	ds_read_b128 v[178:181], v171 offset:1024
	ds_read_b128 v[182:185], v171 offset:2048
	ds_read_b128 v[186:189], v171 offset:3072
	v_add_u32_e32 v172, 0xc000, v150
	v_lshl_add_u64 v[222:223], v[140:141], 0, s[12:13]
	v_readfirstlane_b32 s14, v172
	v_add_u32_e32 v173, 0xe000, v150
	v_lshl_add_u64 v[226:227], v[222:223], 0, s[20:21]
	s_mov_b32 m0, s14
	v_lshl_add_u64 v[236:237], v[138:139], 0, s[12:13]
	v_readfirstlane_b32 s14, v173
	ds_read_b128 v[190:193], v156
	ds_read_b128 v[194:197], v156 offset:1024
	ds_read_b128 v[198:201], v155
	ds_read_b128 v[202:205], v155 offset:1024
	ds_read_b128 v[206:209], v154
	ds_read_b128 v[210:213], v154 offset:1024
	ds_read_b128 v[214:217], v153
	ds_read_b128 v[218:221], v153 offset:1024
	global_load_lds_dwordx4 v[226:227], off
	v_lshl_add_u64 v[226:227], v[236:237], 0, s[20:21]
	s_mov_b32 m0, s14
	s_nop 0
	global_load_lds_dwordx4 v[226:227], off
	s_waitcnt lgkmcnt(8)
	s_barrier
	s_waitcnt lgkmcnt(0)
	s_setprio 1
	s_waitcnt lgkmcnt(0)
	v_mfma_f32_16x16x32_bf16 v[128:131], v[190:193], v[174:177], 0
	v_mfma_f32_16x16x32_bf16 v[124:127], v[190:193], v[182:185], 0
	v_mfma_f32_16x16x32_bf16 v[120:123], v[198:201], v[174:177], 0
	v_mfma_f32_16x16x32_bf16 v[116:119], v[198:201], v[182:185], 0
	v_mfma_f32_16x16x32_bf16 v[112:115], v[206:209], v[174:177], 0
	v_mfma_f32_16x16x32_bf16 v[108:111], v[206:209], v[182:185], 0
	v_mfma_f32_16x16x32_bf16 v[104:107], v[214:217], v[174:177], 0
	v_mfma_f32_16x16x32_bf16 v[100:103], v[214:217], v[182:185], 0
	v_mfma_f32_16x16x32_bf16 v[128:131], v[194:197], v[178:181], v[128:131]
	v_mfma_f32_16x16x32_bf16 v[124:127], v[194:197], v[186:189], v[124:127]
	v_mfma_f32_16x16x32_bf16 v[120:123], v[202:205], v[178:181], v[120:123]
	v_mfma_f32_16x16x32_bf16 v[116:119], v[202:205], v[186:189], v[116:119]
	v_mfma_f32_16x16x32_bf16 v[112:115], v[210:213], v[178:181], v[112:115]
	v_mfma_f32_16x16x32_bf16 v[108:111], v[210:213], v[186:189], v[108:111]
	v_mfma_f32_16x16x32_bf16 v[104:107], v[218:221], v[178:181], v[104:107]
	v_mfma_f32_16x16x32_bf16 v[100:103], v[218:221], v[186:189], v[100:103]
	s_setprio 0
	s_barrier
; #define LDA8(dst, b, h) _Pragma("unroll") for (int m = 0; m < 4; ++m) _Pragma("unroll") for (int k = 0; k < 2; ++k) \
;     dst[m][k] = *(const bf16x8*)((const char*)SA8(b, h) + lds_byte8(wr * 64 + m * 16 + fr, k * 32 + fq * 8))
; #define LDB8(dst, b, h) _Pragma("unroll") for (int n = 0; n < 2; ++n) _Pragma("unroll") for (int k = 0; k < 2; ++k) \
;     dst[n][k] = *(const bf16x8*)((const char*)SB8(b, h) + lds_byte8(wc * 32 + n * 16 + fr, k * 32 + fq * 8))
; #define WAIT_V8(n) asm volatile("s_waitcnt vmcnt(" #n ")" ::: "memory")
; #define WAIT_L8(n) asm volatile("s_waitcnt lgkmcnt(" #n ")" ::: "memory")
; #define BAR8 __builtin_amdgcn_s_barrier()
; #define SCHED8 __builtin_amdgcn_sched_barrier(0)
;     ...
;     LDB8(B1, 0, 1); STAGE8(SB8(0, 0), Bt, K, bcol, tt + 2);
;     BAR8; WAIT_L8(0); MMA8(0, 1, At, B1); BAR8;
;     LDA8(At, 0, 1); STAGE8(SA8(0, 0), A, lda, brow, tt + 2);
;     BAR8; WAIT_L8(0); MMA8(1, 0, At, B0); BAR8; SCHED8;
;     STAGE8(SB8(0, 1), Bt, K, bcol + 128, tt + 2);
;     WAIT_V8(6); BAR8; MMA8(1, 1, At, B1); BAR8;
;     LDB8(B0, 1, 0); SCHED8; LDA8(At, 1, 0); STAGE8(SA8(0, 1), A, lda, brow + 128, tt + 2);
;     WAIT_L8(8); BAR8; WAIT_L8(0); MMA8(0, 0, At, B0); BAR8; SCHED8;
	v_lshl_add_u64 v[246:247], v[142:143], 0, s[12:13]
	v_readfirstlane_b32 s14, v151
	v_lshl_add_u64 v[248:249], v[246:247], 0, s[40:41]
	s_mov_b32 m0, s14
	ds_read_b128 v[226:229], v168
	ds_read_b128 v[230:233], v168 offset:1024
	ds_read_b128 v[238:241], v168 offset:2048
	ds_read_b128 v[242:245], v168 offset:3072
	global_load_lds_dwordx4 v[248:249], off
	v_lshl_add_u64 v[248:249], v[144:145], 0, s[12:13]
	v_readfirstlane_b32 s14, v157
	v_lshl_add_u64 v[250:251], v[248:249], 0, s[40:41]
	s_mov_b32 m0, s14
	s_nop 0
	global_load_lds_dwordx4 v[250:251], off
	s_barrier
	s_waitcnt lgkmcnt(0)
	s_setprio 1
	s_waitcnt lgkmcnt(0)
	v_mfma_f32_16x16x32_bf16 v[96:99], v[190:193], v[226:229], 0
	v_mfma_f32_16x16x32_bf16 v[92:95], v[190:193], v[238:241], 0
	v_mfma_f32_16x16x32_bf16 v[88:91], v[198:201], v[226:229], 0
	v_mfma_f32_16x16x32_bf16 v[84:87], v[198:201], v[238:241], 0
	v_mfma_f32_16x16x32_bf16 v[80:83], v[206:209], v[226:229], 0
	v_mfma_f32_16x16x32_bf16 v[76:79], v[206:209], v[238:241], 0
	v_mfma_f32_16x16x32_bf16 v[72:75], v[214:217], v[226:229], 0
	v_mfma_f32_16x16x32_bf16 v[68:71], v[214:217], v[238:241], 0
	v_mfma_f32_16x16x32_bf16 v[96:99], v[194:197], v[230:233], v[96:99]
	v_mfma_f32_16x16x32_bf16 v[92:95], v[194:197], v[242:245], v[92:95]
	v_mfma_f32_16x16x32_bf16 v[88:91], v[202:205], v[230:233], v[88:91]
	v_mfma_f32_16x16x32_bf16 v[84:87], v[202:205], v[242:245], v[84:87]
	v_mfma_f32_16x16x32_bf16 v[80:83], v[210:213], v[230:233], v[80:83]
	v_mfma_f32_16x16x32_bf16 v[76:79], v[210:213], v[242:245], v[76:79]
	v_mfma_f32_16x16x32_bf16 v[72:75], v[218:221], v[230:233], v[72:75]
	v_mfma_f32_16x16x32_bf16 v[68:71], v[218:221], v[242:245], v[68:71]
	s_setprio 0
	v_readfirstlane_b32 s14, v150
	v_lshl_add_u64 v[250:251], v[222:223], 0, s[42:43]
	s_mov_b32 m0, s14
	v_readfirstlane_b32 s14, v152
	s_barrier
	ds_read_b128 v[190:193], v156 offset:16384
	ds_read_b128 v[194:197], v156 offset:17408
	ds_read_b128 v[198:201], v155 offset:16384
	ds_read_b128 v[202:205], v155 offset:17408
	ds_read_b128 v[206:209], v154 offset:16384
	ds_read_b128 v[210:213], v154 offset:17408
	ds_read_b128 v[214:217], v153 offset:16384
	ds_read_b128 v[218:221], v153 offset:17408
	global_load_lds_dwordx4 v[250:251], off
	v_lshl_add_u64 v[250:251], v[236:237], 0, s[42:43]
	s_mov_b32 m0, s14
	s_nop 0
	global_load_lds_dwordx4 v[250:251], off
	s_barrier
	s_waitcnt lgkmcnt(0)
	s_setprio 1
	s_waitcnt lgkmcnt(0)
	v_mfma_f32_16x16x32_bf16 v[64:67], v[190:193], v[174:177], 0
	v_mfma_f32_16x16x32_bf16 v[60:63], v[190:193], v[182:185], 0
	v_mfma_f32_16x16x32_bf16 v[56:59], v[198:201], v[174:177], 0
	v_mfma_f32_16x16x32_bf16 v[52:55], v[198:201], v[182:185], 0
	v_mfma_f32_16x16x32_bf16 v[48:51], v[206:209], v[174:177], 0
	v_mfma_f32_16x16x32_bf16 v[44:47], v[206:209], v[182:185], 0
	v_mfma_f32_16x16x32_bf16 v[40:43], v[214:217], v[174:177], 0
	v_mfma_f32_16x16x32_bf16 v[36:39], v[214:217], v[182:185], 0
	v_mfma_f32_16x16x32_bf16 v[64:67], v[194:197], v[178:181], v[64:67]
	v_mfma_f32_16x16x32_bf16 v[60:63], v[194:197], v[186:189], v[60:63]
	v_mfma_f32_16x16x32_bf16 v[56:59], v[202:205], v[178:181], v[56:59]
	v_mfma_f32_16x16x32_bf16 v[52:55], v[202:205], v[186:189], v[52:55]
	v_mfma_f32_16x16x32_bf16 v[48:51], v[210:213], v[178:181], v[48:51]
	v_mfma_f32_16x16x32_bf16 v[44:47], v[210:213], v[186:189], v[44:47]
	v_mfma_f32_16x16x32_bf16 v[40:43], v[218:221], v[178:181], v[40:43]
	v_mfma_f32_16x16x32_bf16 v[36:39], v[218:221], v[186:189], v[36:39]
	s_setprio 0
	s_barrier
	v_readfirstlane_b32 s14, v159
	v_lshl_add_u64 v[174:175], v[246:247], 0, s[44:45]
	s_mov_b32 m0, s14
	v_readfirstlane_b32 s14, v160
	global_load_lds_dwordx4 v[174:175], off
	v_lshl_add_u64 v[174:175], v[248:249], 0, s[44:45]
	s_mov_b32 m0, s14
	s_nop 0
	global_load_lds_dwordx4 v[174:175], off
	s_waitcnt vmcnt(6)
	s_barrier
	s_setprio 1
	v_mfma_f32_16x16x32_bf16 v[32:35], v[190:193], v[226:229], 0
	v_mfma_f32_16x16x32_bf16 v[28:31], v[190:193], v[238:241], 0
	v_mfma_f32_16x16x32_bf16 v[24:27], v[198:201], v[226:229], 0
	v_mfma_f32_16x16x32_bf16 v[20:23], v[198:201], v[238:241], 0
	v_mfma_f32_16x16x32_bf16 v[16:19], v[206:209], v[226:229], 0
	v_mfma_f32_16x16x32_bf16 v[12:15], v[206:209], v[238:241], 0
	v_mfma_f32_16x16x32_bf16 v[8:11], v[214:217], v[226:229], 0
	v_mfma_f32_16x16x32_bf16 v[4:7], v[214:217], v[238:241], 0
	v_mfma_f32_16x16x32_bf16 v[32:35], v[194:197], v[230:233], v[32:35]
	v_mfma_f32_16x16x32_bf16 v[28:31], v[194:197], v[242:245], v[28:31]
	v_mfma_f32_16x16x32_bf16 v[24:27], v[202:205], v[230:233], v[24:27]
	v_mfma_f32_16x16x32_bf16 v[20:23], v[202:205], v[242:245], v[20:23]
	v_mfma_f32_16x16x32_bf16 v[16:19], v[210:213], v[230:233], v[16:19]
	v_mfma_f32_16x16x32_bf16 v[12:15], v[210:213], v[242:245], v[12:15]
	v_mfma_f32_16x16x32_bf16 v[8:11], v[218:221], v[230:233], v[8:11]
	v_mfma_f32_16x16x32_bf16 v[4:7], v[218:221], v[242:245], v[4:7]
	s_setprio 0
	s_barrier
	ds_read_b128 v[174:177], v161
	ds_read_b128 v[178:181], v161 offset:1024
	ds_read_b128 v[182:185], v161 offset:2048
	ds_read_b128 v[186:189], v161 offset:3072
	v_readfirstlane_b32 s14, v162
	v_lshl_add_u64 v[226:227], v[222:223], 0, s[46:47]
	s_mov_b32 m0, s14
	v_readfirstlane_b32 s14, v163
	ds_read_b128 v[190:193], v156 offset:32768
	ds_read_b128 v[194:197], v156 offset:33792
	ds_read_b128 v[198:201], v155 offset:32768
	ds_read_b128 v[202:205], v155 offset:33792
	ds_read_b128 v[206:209], v154 offset:32768
	ds_read_b128 v[210:213], v154 offset:33792
	ds_read_b128 v[214:217], v153 offset:32768
	ds_read_b128 v[218:221], v153 offset:33792
	global_load_lds_dwordx4 v[226:227], off
	v_lshl_add_u64 v[226:227], v[236:237], 0, s[46:47]
	s_mov_b32 m0, s14
	s_nop 0
	global_load_lds_dwordx4 v[226:227], off
	s_waitcnt lgkmcnt(8)
	s_barrier
; #define LDA8(dst, b, h) _Pragma("unroll") for (int m = 0; m < 4; ++m) _Pragma("unroll") for (int k = 0; k < 2; ++k) \
;     dst[m][k] = *(const bf16x8*)((const char*)SA8(b, h) + lds_byte8(wr * 64 + m * 16 + fr, k * 32 + fq * 8))
; #define LDB8(dst, b, h) _Pragma("unroll") for (int n = 0; n < 2; ++n) _Pragma("unroll") for (int k = 0; k < 2; ++k) \
;     dst[n][k] = *(const bf16x8*)((const char*)SB8(b, h) + lds_byte8(wc * 32 + n * 16 + fr, k * 32 + fq * 8))
; #define WAIT_V8(n) asm volatile("s_waitcnt vmcnt(" #n ")" ::: "memory")
; #define WAIT_L8(n) asm volatile("s_waitcnt lgkmcnt(" #n ")" ::: "memory")
; #define BAR8 __builtin_amdgcn_s_barrier()
; #define SCHED8 __builtin_amdgcn_sched_barrier(0)
;     ...
;     WAIT_L8(8); BAR8; WAIT_L8(0); MMA8(0, 0, At, B0); BAR8; SCHED8;
;     LDB8(B1, 1, 1); STAGE8(SB8(1, 0), Bt, K, bcol, tt + 3);
;     BAR8; WAIT_L8(0); MMA8(0, 1, At, B1); BAR8;
;     LDA8(At, 1, 1); STAGE8(SA8(1, 0), A, lda, brow, tt + 3);
;     BAR8; WAIT_L8(0); MMA8(1, 0, At, B0); BAR8; SCHED8;
;     STAGE8(SB8(1, 1), Bt, K, bcol + 128, tt + 3);
;     WAIT_V8(6); BAR8; MMA8(1, 1, At, B1); BAR8;
;   }
	s_waitcnt lgkmcnt(0)
	s_setprio 1
	s_waitcnt lgkmcnt(0)
	v_mfma_f32_16x16x32_bf16 v[128:131], v[190:193], v[174:177], v[128:131]
	v_mfma_f32_16x16x32_bf16 v[124:127], v[190:193], v[182:185], v[124:127]
	v_mfma_f32_16x16x32_bf16 v[120:123], v[198:201], v[174:177], v[120:123]
	v_mfma_f32_16x16x32_bf16 v[116:119], v[198:201], v[182:185], v[116:119]
	v_mfma_f32_16x16x32_bf16 v[112:115], v[206:209], v[174:177], v[112:115]
	v_mfma_f32_16x16x32_bf16 v[108:111], v[206:209], v[182:185], v[108:111]
	v_mfma_f32_16x16x32_bf16 v[104:107], v[214:217], v[174:177], v[104:107]
	v_mfma_f32_16x16x32_bf16 v[100:103], v[214:217], v[182:185], v[100:103]
	v_mfma_f32_16x16x32_bf16 v[128:131], v[194:197], v[178:181], v[128:131]
	v_mfma_f32_16x16x32_bf16 v[124:127], v[194:197], v[186:189], v[124:127]
	v_mfma_f32_16x16x32_bf16 v[120:123], v[202:205], v[178:181], v[120:123]
	v_mfma_f32_16x16x32_bf16 v[116:119], v[202:205], v[186:189], v[116:119]
	v_mfma_f32_16x16x32_bf16 v[112:115], v[210:213], v[178:181], v[112:115]
	v_mfma_f32_16x16x32_bf16 v[108:111], v[210:213], v[186:189], v[108:111]
	v_mfma_f32_16x16x32_bf16 v[104:107], v[218:221], v[178:181], v[104:107]
	v_mfma_f32_16x16x32_bf16 v[100:103], v[218:221], v[186:189], v[100:103]
	s_setprio 0
	s_barrier
	v_readfirstlane_b32 s14, v164
	v_lshl_add_u64 v[250:251], v[246:247], 0, s[48:49]
	s_mov_b32 m0, s14
	v_readfirstlane_b32 s14, v165
	ds_read_b128 v[226:229], v158
	ds_read_b128 v[230:233], v158 offset:1024
	ds_read_b128 v[238:241], v158 offset:2048
	ds_read_b128 v[242:245], v158 offset:3072
	global_load_lds_dwordx4 v[250:251], off
	v_lshl_add_u64 v[250:251], v[248:249], 0, s[48:49]
	s_mov_b32 m0, s14
	s_nop 0
	global_load_lds_dwordx4 v[250:251], off
	s_barrier
	s_waitcnt lgkmcnt(0)
	s_setprio 1
	s_waitcnt lgkmcnt(0)
	v_mfma_f32_16x16x32_bf16 v[96:99], v[190:193], v[226:229], v[96:99]
	v_mfma_f32_16x16x32_bf16 v[92:95], v[190:193], v[238:241], v[92:95]
	v_mfma_f32_16x16x32_bf16 v[88:91], v[198:201], v[226:229], v[88:91]
	v_mfma_f32_16x16x32_bf16 v[84:87], v[198:201], v[238:241], v[84:87]
	v_mfma_f32_16x16x32_bf16 v[80:83], v[206:209], v[226:229], v[80:83]
	v_mfma_f32_16x16x32_bf16 v[76:79], v[206:209], v[238:241], v[76:79]
	v_mfma_f32_16x16x32_bf16 v[72:75], v[214:217], v[226:229], v[72:75]
	v_mfma_f32_16x16x32_bf16 v[68:71], v[214:217], v[238:241], v[68:71]
	v_mfma_f32_16x16x32_bf16 v[96:99], v[194:197], v[230:233], v[96:99]
	v_mfma_f32_16x16x32_bf16 v[92:95], v[194:197], v[242:245], v[92:95]
	v_mfma_f32_16x16x32_bf16 v[88:91], v[202:205], v[230:233], v[88:91]
	v_mfma_f32_16x16x32_bf16 v[84:87], v[202:205], v[242:245], v[84:87]
	v_mfma_f32_16x16x32_bf16 v[80:83], v[210:213], v[230:233], v[80:83]
	v_mfma_f32_16x16x32_bf16 v[76:79], v[210:213], v[242:245], v[76:79]
	v_mfma_f32_16x16x32_bf16 v[72:75], v[218:221], v[230:233], v[72:75]
	v_mfma_f32_16x16x32_bf16 v[68:71], v[218:221], v[242:245], v[68:71]
	s_setprio 0
	v_readfirstlane_b32 s14, v166
	v_lshl_add_u64 v[222:223], v[222:223], 0, s[50:51]
	s_mov_b32 m0, s14
	v_readfirstlane_b32 s14, v167
	s_barrier
	ds_read_b128 v[190:193], v156 offset:49152
	ds_read_b128 v[194:197], v156 offset:50176
	ds_read_b128 v[198:201], v155 offset:49152
	ds_read_b128 v[202:205], v155 offset:50176
	ds_read_b128 v[206:209], v154 offset:49152
	ds_read_b128 v[210:213], v154 offset:50176
	ds_read_b128 v[214:217], v153 offset:49152
	ds_read_b128 v[218:221], v153 offset:50176
	global_load_lds_dwordx4 v[222:223], off
	v_lshl_add_u64 v[222:223], v[236:237], 0, s[50:51]
	s_mov_b32 m0, s14
	s_nop 0
	global_load_lds_dwordx4 v[222:223], off
	s_barrier
	s_waitcnt lgkmcnt(0)
	s_setprio 1
	s_waitcnt lgkmcnt(0)
	v_mfma_f32_16x16x32_bf16 v[64:67], v[190:193], v[174:177], v[64:67]
	v_mfma_f32_16x16x32_bf16 v[60:63], v[190:193], v[182:185], v[60:63]
	v_mfma_f32_16x16x32_bf16 v[56:59], v[198:201], v[174:177], v[56:59]
	v_mfma_f32_16x16x32_bf16 v[52:55], v[198:201], v[182:185], v[52:55]
	v_mfma_f32_16x16x32_bf16 v[48:51], v[206:209], v[174:177], v[48:51]
	v_mfma_f32_16x16x32_bf16 v[44:47], v[206:209], v[182:185], v[44:47]
	v_mfma_f32_16x16x32_bf16 v[40:43], v[214:217], v[174:177], v[40:43]
	v_mfma_f32_16x16x32_bf16 v[36:39], v[214:217], v[182:185], v[36:39]
	v_mfma_f32_16x16x32_bf16 v[64:67], v[194:197], v[178:181], v[64:67]
	v_mfma_f32_16x16x32_bf16 v[60:63], v[194:197], v[186:189], v[60:63]
	v_mfma_f32_16x16x32_bf16 v[56:59], v[202:205], v[178:181], v[56:59]
	v_mfma_f32_16x16x32_bf16 v[52:55], v[202:205], v[186:189], v[52:55]
	v_mfma_f32_16x16x32_bf16 v[48:51], v[210:213], v[178:181], v[48:51]
	v_mfma_f32_16x16x32_bf16 v[44:47], v[210:213], v[186:189], v[44:47]
	v_mfma_f32_16x16x32_bf16 v[40:43], v[218:221], v[178:181], v[40:43]
	v_mfma_f32_16x16x32_bf16 v[36:39], v[218:221], v[186:189], v[36:39]
	s_setprio 0
	s_barrier
	v_readfirstlane_b32 s14, v169
	v_lshl_add_u64 v[174:175], v[246:247], 0, s[52:53]
	s_mov_b32 m0, s14
	v_readfirstlane_b32 s14, v170
	global_load_lds_dwordx4 v[174:175], off
	v_lshl_add_u64 v[174:175], v[248:249], 0, s[52:53]
	s_mov_b32 m0, s14
	s_nop 0
	global_load_lds_dwordx4 v[174:175], off
	s_waitcnt vmcnt(6)
	s_barrier
	s_setprio 1
	v_mfma_f32_16x16x32_bf16 v[32:35], v[190:193], v[226:229], v[32:35]
	v_mfma_f32_16x16x32_bf16 v[28:31], v[190:193], v[238:241], v[28:31]
	v_mfma_f32_16x16x32_bf16 v[24:27], v[198:201], v[226:229], v[24:27]
	v_mfma_f32_16x16x32_bf16 v[20:23], v[198:201], v[238:241], v[20:23]
	v_mfma_f32_16x16x32_bf16 v[16:19], v[206:209], v[226:229], v[16:19]
	v_mfma_f32_16x16x32_bf16 v[12:15], v[206:209], v[238:241], v[12:15]
	v_mfma_f32_16x16x32_bf16 v[8:11], v[214:217], v[226:229], v[8:11]
	v_mfma_f32_16x16x32_bf16 v[4:7], v[214:217], v[238:241], v[4:7]
	v_mfma_f32_16x16x32_bf16 v[32:35], v[194:197], v[230:233], v[32:35]
	v_mfma_f32_16x16x32_bf16 v[28:31], v[194:197], v[242:245], v[28:31]
	v_mfma_f32_16x16x32_bf16 v[24:27], v[202:205], v[230:233], v[24:27]
	v_mfma_f32_16x16x32_bf16 v[20:23], v[202:205], v[242:245], v[20:23]
	v_mfma_f32_16x16x32_bf16 v[16:19], v[210:213], v[230:233], v[16:19]
	v_mfma_f32_16x16x32_bf16 v[12:15], v[210:213], v[242:245], v[12:15]
	v_mfma_f32_16x16x32_bf16 v[8:11], v[218:221], v[230:233], v[8:11]
	v_mfma_f32_16x16x32_bf16 v[4:7], v[218:221], v[242:245], v[4:7]
	s_setprio 0
	s_add_i32 s1, s1, 2
	s_add_u32 s12, s12, 0x100
	s_addc_u32 s13, s13, 0
	s_cmp_lt_u32 s1, 12
	s_barrier
	s_cbranch_scc0 .Lpk_exit_3

; #define LDA8(dst, b, h) _Pragma("unroll") for (int m = 0; m < 4; ++m) _Pragma("unroll") for (int k = 0; k < 2; ++k) \
;     dst[m][k] = *(const bf16x8*)((const char*)SA8(b, h) + lds_byte8(wr * 64 + m * 16 + fr, k * 32 + fq * 8))
; #define LDB8(dst, b, h) _Pragma("unroll") for (int n = 0; n < 2; ++n) _Pragma("unroll") for (int k = 0; k < 2; ++k) \
;     dst[n][k] = *(const bf16x8*)((const char*)SB8(b, h) + lds_byte8(wc * 32 + n * 16 + fr, k * 32 + fq * 8))
; #define WAIT_V8(n) asm volatile("s_waitcnt vmcnt(" #n ")" ::: "memory")
; #define WAIT_L8(n) asm volatile("s_waitcnt lgkmcnt(" #n ")" ::: "memory")
; #define BAR8 __builtin_amdgcn_s_barrier()
;     ...
;   { LDB8(B0, 0, 0); LDA8(At, 0, 0); STAGE8(SA8(1, 1), A, lda, brow + 128, nt - 1);
;     BAR8; WAIT_L8(0); MMA8(0, 0, At, B0); BAR8;
;     LDB8(B1, 0, 1); BAR8; WAIT_L8(0); MMA8(0, 1, At, B1); BAR8;
;     LDA8(At, 0, 1); WAIT_V8(4); BAR8; WAIT_L8(0); MMA8(1, 0, At, B0); MMA8(1, 1, At, B1); BAR8; }
.Lpk_exit_3:
	s_add_u32 s8, s8, 0x40780
	s_addc_u32 s9, s9, 0
	v_lshl_add_u64 v[132:133], s[8:9], 0, v[132:133]
	v_readfirstlane_b32 s1, v172
	v_lshl_add_u64 v[0:1], v[0:1], 1, v[132:133]
	s_mov_b32 m0, s1
	ds_read_b128 v[138:141], v171
	ds_read_b128 v[142:145], v171 offset:1024
	ds_read_b128 v[162:165], v171 offset:2048
	ds_read_b128 v[174:177], v171 offset:3072
	ds_read_b128 v[178:181], v156
	ds_read_b128 v[182:185], v156 offset:1024
	ds_read_b128 v[186:189], v155
	ds_read_b128 v[190:193], v155 offset:1024
	ds_read_b128 v[194:197], v154
	ds_read_b128 v[198:201], v154 offset:1024
	ds_read_b128 v[202:205], v153
	ds_read_b128 v[206:209], v153 offset:1024
	global_load_lds_dwordx4 v[0:1], off
	v_lshl_add_u64 v[0:1], s[8:9], 0, v[136:137]
	v_readfirstlane_b32 s1, v173
	v_lshl_add_u64 v[0:1], v[134:135], 1, v[0:1]
	s_mov_b32 m0, s1
	s_nop 0
	global_load_lds_dwordx4 v[0:1], off
	s_barrier
	s_waitcnt lgkmcnt(0)
	s_setprio 1
	s_waitcnt lgkmcnt(0)
	v_mfma_f32_16x16x32_bf16 v[128:131], v[178:181], v[138:141], v[128:131]
	v_mfma_f32_16x16x32_bf16 v[124:127], v[178:181], v[162:165], v[124:127]
	v_mfma_f32_16x16x32_bf16 v[120:123], v[186:189], v[138:141], v[120:123]
	v_mfma_f32_16x16x32_bf16 v[112:115], v[194:197], v[138:141], v[112:115]
	v_mfma_f32_16x16x32_bf16 v[128:131], v[182:185], v[142:145], v[128:131]
	v_mfma_f32_16x16x32_bf16 v[124:127], v[182:185], v[174:177], v[124:127]
	v_mfma_f32_16x16x32_bf16 v[120:123], v[190:193], v[142:145], v[120:123]
	v_mfma_f32_16x16x32_bf16 v[116:119], v[186:189], v[162:165], v[116:119]
	v_mfma_f32_16x16x32_bf16 v[112:115], v[198:201], v[142:145], v[112:115]
	v_mfma_f32_16x16x32_bf16 v[108:111], v[194:197], v[162:165], v[108:111]
	v_mfma_f32_16x16x32_bf16 v[104:107], v[202:205], v[138:141], v[104:107]
	v_mfma_f32_16x16x32_bf16 v[100:103], v[202:205], v[162:165], v[100:103]
	v_mfma_f32_16x16x32_bf16 v[132:135], v[190:193], v[174:177], v[116:119]
	v_mfma_f32_16x16x32_bf16 v[170:173], v[198:201], v[174:177], v[108:111]
	v_mfma_f32_16x16x32_bf16 v[210:213], v[206:209], v[142:145], v[104:107]
	v_mfma_f32_16x16x32_bf16 v[214:217], v[206:209], v[174:177], v[100:103]
	s_setprio 0
	s_barrier
	s_nop 1
	ds_read_b128 v[100:103], v168
	ds_read_b128 v[104:107], v168 offset:1024
	ds_read_b128 v[108:111], v168 offset:2048
	ds_read_b128 v[116:119], v168 offset:3072
	s_barrier
	s_waitcnt lgkmcnt(0)
	s_setprio 1
	s_waitcnt lgkmcnt(0)
	v_mfma_f32_16x16x32_bf16 v[80:83], v[194:197], v[100:103], v[80:83]
	v_mfma_f32_16x16x32_bf16 v[76:79], v[194:197], v[108:111], v[76:79]
	v_mfma_f32_16x16x32_bf16 v[72:75], v[202:205], v[100:103], v[72:75]
	v_mfma_f32_16x16x32_bf16 v[68:71], v[202:205], v[108:111], v[68:71]
	v_mfma_f32_16x16x32_bf16 v[96:99], v[178:181], v[100:103], v[96:99]
	v_mfma_f32_16x16x32_bf16 v[92:95], v[178:181], v[108:111], v[92:95]
	v_mfma_f32_16x16x32_bf16 v[88:91], v[186:189], v[100:103], v[88:91]
	v_mfma_f32_16x16x32_bf16 v[84:87], v[186:189], v[108:111], v[84:87]
	v_mfma_f32_16x16x32_bf16 v[80:83], v[198:201], v[104:107], v[80:83]
	v_mfma_f32_16x16x32_bf16 v[76:79], v[198:201], v[116:119], v[76:79]
	v_mfma_f32_16x16x32_bf16 v[72:75], v[206:209], v[104:107], v[72:75]
	v_mfma_f32_16x16x32_bf16 v[68:71], v[206:209], v[116:119], v[68:71]
	v_mfma_f32_16x16x32_bf16 v[166:169], v[182:185], v[104:107], v[96:99]
	v_mfma_f32_16x16x32_bf16 v[178:181], v[182:185], v[116:119], v[92:95]
	v_mfma_f32_16x16x32_bf16 v[182:185], v[190:193], v[104:107], v[88:91]
	v_mfma_f32_16x16x32_bf16 v[186:189], v[190:193], v[116:119], v[84:87]
	s_setprio 0
	s_barrier
	s_nop 0
	ds_read_b128 v[84:87], v156 offset:16384
	ds_read_b128 v[88:91], v156 offset:17408
	ds_read_b128 v[92:95], v155 offset:16384
	ds_read_b128 v[96:99], v155 offset:17408
	ds_read_b128 v[190:193], v154 offset:16384
	ds_read_b128 v[194:197], v154 offset:17408
	ds_read_b128 v[198:201], v153 offset:16384
	ds_read_b128 v[202:205], v153 offset:17408
	s_waitcnt vmcnt(4)
	s_barrier
	s_waitcnt lgkmcnt(0)
	s_setprio 1
	s_waitcnt lgkmcnt(0)
	v_mfma_f32_16x16x32_bf16 v[64:67], v[84:87], v[138:141], v[64:67]
	v_mfma_f32_16x16x32_bf16 v[60:63], v[84:87], v[162:165], v[60:63]
	v_mfma_f32_16x16x32_bf16 v[56:59], v[92:95], v[138:141], v[56:59]
	v_mfma_f32_16x16x32_bf16 v[52:55], v[92:95], v[162:165], v[52:55]
	v_mfma_f32_16x16x32_bf16 v[48:51], v[190:193], v[138:141], v[48:51]
	v_mfma_f32_16x16x32_bf16 v[44:47], v[190:193], v[162:165], v[44:47]
	v_mfma_f32_16x16x32_bf16 v[40:43], v[198:201], v[138:141], v[40:43]
	v_mfma_f32_16x16x32_bf16 v[36:39], v[198:201], v[162:165], v[36:39]
	v_mfma_f32_16x16x32_bf16 v[64:67], v[88:91], v[142:145], v[64:67]
	v_mfma_f32_16x16x32_bf16 v[60:63], v[88:91], v[174:177], v[60:63]
	v_mfma_f32_16x16x32_bf16 v[56:59], v[96:99], v[142:145], v[56:59]
	v_mfma_f32_16x16x32_bf16 v[52:55], v[96:99], v[174:177], v[52:55]
	v_mfma_f32_16x16x32_bf16 v[48:51], v[194:197], v[142:145], v[48:51]
	v_mfma_f32_16x16x32_bf16 v[44:47], v[194:197], v[174:177], v[44:47]
	v_mfma_f32_16x16x32_bf16 v[40:43], v[202:205], v[142:145], v[40:43]
	v_mfma_f32_16x16x32_bf16 v[36:39], v[202:205], v[174:177], v[36:39]
	s_setprio 0
	s_setprio 1
	v_mfma_f32_16x16x32_bf16 v[32:35], v[84:87], v[100:103], v[32:35]
	v_mfma_f32_16x16x32_bf16 v[28:31], v[84:87], v[108:111], v[28:31]
	v_mfma_f32_16x16x32_bf16 v[24:27], v[92:95], v[100:103], v[24:27]
	v_mfma_f32_16x16x32_bf16 v[20:23], v[92:95], v[108:111], v[20:23]
	v_mfma_f32_16x16x32_bf16 v[16:19], v[190:193], v[100:103], v[16:19]
	v_mfma_f32_16x16x32_bf16 v[12:15], v[190:193], v[108:111], v[12:15]
	v_mfma_f32_16x16x32_bf16 v[8:11], v[198:201], v[100:103], v[8:11]
	v_mfma_f32_16x16x32_bf16 v[4:7], v[198:201], v[108:111], v[4:7]
	v_mfma_f32_16x16x32_bf16 v[136:139], v[88:91], v[104:107], v[32:35]
	v_mfma_f32_16x16x32_bf16 v[140:143], v[88:91], v[116:119], v[28:31]
	v_mfma_f32_16x16x32_bf16 v[162:165], v[96:99], v[104:107], v[24:27]
	v_mfma_f32_16x16x32_bf16 v[174:177], v[96:99], v[116:119], v[20:23]
	v_mfma_f32_16x16x32_bf16 v[206:209], v[194:197], v[104:107], v[16:19]
	v_mfma_f32_16x16x32_bf16 v[190:193], v[194:197], v[116:119], v[12:15]
	v_mfma_f32_16x16x32_bf16 v[194:197], v[202:205], v[104:107], v[8:11]
	v_mfma_f32_16x16x32_bf16 v[198:201], v[202:205], v[116:119], v[4:7]
	s_setprio 0
	s_barrier
; #define LDA8(dst, b, h) _Pragma("unroll") for (int m = 0; m < 4; ++m) _Pragma("unroll") for (int k = 0; k < 2; ++k) \
;     dst[m][k] = *(const bf16x8*)((const char*)SA8(b, h) + lds_byte8(wr * 64 + m * 16 + fr, k * 32 + fq * 8))
; #define LDB8(dst, b, h) _Pragma("unroll") for (int n = 0; n < 2; ++n) _Pragma("unroll") for (int k = 0; k < 2; ++k) \
;     dst[n][k] = *(const bf16x8*)((const char*)SB8(b, h) + lds_byte8(wc * 32 + n * 16 + fr, k * 32 + fq * 8))
; #define WAIT_V8(n) asm volatile("s_waitcnt vmcnt(" #n ")" ::: "memory")
; #define WAIT_L8(n) asm volatile("s_waitcnt lgkmcnt(" #n ")" ::: "memory")
; #define BAR8 __builtin_amdgcn_s_barrier()
;     ...
;   { LDB8(B0, 1, 0); LDA8(At, 1, 0); WAIT_V8(2); BAR8; WAIT_L8(0); MMA8(0, 0, At, B0); BAR8;
;     LDB8(B1, 1, 1); WAIT_V8(0); BAR8; WAIT_L8(0); MMA8(0, 1, At, B1); BAR8;
;     LDA8(At, 1, 1); BAR8; WAIT_L8(0); MMA8(1, 0, At, B0); MMA8(1, 1, At, B1); BAR8; }
;   if (wr == 0) BAR8;
;   __syncthreads();
;     ...
;   if (t < 256) {
	ds_read_b128 v[202:205], v161
	ds_read_b128 v[218:221], v161 offset:1024
	ds_read_b128 v[226:229], v161 offset:2048
	ds_read_b128 v[230:233], v161 offset:3072
	ds_read_b128 v[8:11], v156 offset:32768
	ds_read_b128 v[12:15], v156 offset:33792
	ds_read_b128 v[16:19], v155 offset:32768
	ds_read_b128 v[24:27], v155 offset:33792
	ds_read_b128 v[28:31], v154 offset:32768
	ds_read_b128 v[32:35], v154 offset:33792
	ds_read_b128 v[238:241], v153 offset:32768
	ds_read_b128 v[242:245], v153 offset:33792
	s_waitcnt vmcnt(2)
	s_barrier
	s_waitcnt lgkmcnt(0)
	s_setprio 1
	s_waitcnt lgkmcnt(0)
	v_mfma_f32_16x16x32_bf16 v[4:7], v[8:11], v[202:205], v[128:131]
	v_mfma_f32_16x16x32_bf16 v[104:107], v[12:15], v[218:221], v[4:7]
	v_mfma_f32_16x16x32_bf16 v[4:7], v[8:11], v[226:229], v[124:127]
	v_mfma_f32_16x16x32_bf16 v[116:119], v[12:15], v[230:233], v[4:7]
	v_mfma_f32_16x16x32_bf16 v[4:7], v[16:19], v[202:205], v[120:123]
	v_mfma_f32_16x16x32_bf16 v[100:103], v[24:27], v[218:221], v[4:7]
	v_mfma_f32_16x16x32_bf16 v[4:7], v[16:19], v[226:229], v[132:135]
	v_mfma_f32_16x16x32_bf16 v[108:111], v[24:27], v[230:233], v[4:7]
	v_mfma_f32_16x16x32_bf16 v[4:7], v[28:31], v[202:205], v[112:115]
	v_mfma_f32_16x16x32_bf16 v[92:95], v[32:35], v[218:221], v[4:7]
	v_mfma_f32_16x16x32_bf16 v[4:7], v[28:31], v[226:229], v[170:173]
	v_mfma_f32_16x16x32_bf16 v[96:99], v[32:35], v[230:233], v[4:7]
	v_mfma_f32_16x16x32_bf16 v[4:7], v[238:241], v[202:205], v[210:213]
	v_mfma_f32_16x16x32_bf16 v[84:87], v[242:245], v[218:221], v[4:7]
	v_mfma_f32_16x16x32_bf16 v[4:7], v[238:241], v[226:229], v[214:217]
	v_mfma_f32_16x16x32_bf16 v[88:91], v[242:245], v[230:233], v[4:7]
	s_setprio 0
	s_barrier
	ds_read_b128 v[132:135], v158
	ds_read_b128 v[170:173], v158 offset:1024
	ds_read_b128 v[210:213], v158 offset:2048
	ds_read_b128 v[158:161], v158 offset:3072
	s_waitcnt vmcnt(0)
	s_barrier
	s_waitcnt lgkmcnt(0)
	s_setprio 1
	s_waitcnt lgkmcnt(0)
	v_mfma_f32_16x16x32_bf16 v[4:7], v[8:11], v[132:135], v[166:169]
	v_mfma_f32_16x16x32_bf16 v[8:11], v[8:11], v[210:213], v[178:181]
	v_mfma_f32_16x16x32_bf16 v[4:7], v[12:15], v[170:173], v[4:7]
	v_mfma_f32_16x16x32_bf16 v[20:23], v[12:15], v[158:161], v[8:11]
	v_mfma_f32_16x16x32_bf16 v[8:11], v[16:19], v[132:135], v[182:185]
	v_mfma_f32_16x16x32_bf16 v[12:15], v[16:19], v[210:213], v[186:189]
	v_mfma_f32_16x16x32_bf16 v[8:11], v[24:27], v[170:173], v[8:11]
	v_mfma_f32_16x16x32_bf16 v[24:27], v[24:27], v[158:161], v[12:15]
	v_mfma_f32_16x16x32_bf16 v[12:15], v[28:31], v[132:135], v[80:83]
	v_mfma_f32_16x16x32_bf16 v[16:19], v[28:31], v[210:213], v[76:79]
	v_mfma_f32_16x16x32_bf16 v[12:15], v[32:35], v[170:173], v[12:15]
	v_mfma_f32_16x16x32_bf16 v[28:31], v[32:35], v[158:161], v[16:19]
	v_mfma_f32_16x16x32_bf16 v[16:19], v[238:241], v[132:135], v[72:75]
	v_mfma_f32_16x16x32_bf16 v[32:35], v[238:241], v[210:213], v[68:71]
	v_mfma_f32_16x16x32_bf16 v[16:19], v[242:245], v[170:173], v[16:19]
	v_mfma_f32_16x16x32_bf16 v[32:35], v[242:245], v[158:161], v[32:35]
	s_setprio 0
	s_barrier
	ds_read_b128 v[166:169], v156 offset:49152
	ds_read_b128 v[178:181], v156 offset:50176
	ds_read_b128 v[182:185], v155 offset:49152
	ds_read_b128 v[186:189], v155 offset:50176
	ds_read_b128 v[214:217], v154 offset:49152
	ds_read_b128 v[154:157], v154 offset:50176
	ds_read_b128 v[238:241], v153 offset:49152
	ds_read_b128 v[150:153], v153 offset:50176
	s_barrier
	s_waitcnt lgkmcnt(0)
	s_setprio 1
	s_waitcnt lgkmcnt(0)
	v_mfma_f32_16x16x32_bf16 v[64:67], v[166:169], v[202:205], v[64:67]
	v_mfma_f32_16x16x32_bf16 v[60:63], v[166:169], v[226:229], v[60:63]
	v_mfma_f32_16x16x32_bf16 v[56:59], v[182:185], v[202:205], v[56:59]
	v_mfma_f32_16x16x32_bf16 v[52:55], v[182:185], v[226:229], v[52:55]
	v_mfma_f32_16x16x32_bf16 v[48:51], v[214:217], v[202:205], v[48:51]
	v_mfma_f32_16x16x32_bf16 v[44:47], v[214:217], v[226:229], v[44:47]
	v_mfma_f32_16x16x32_bf16 v[40:43], v[238:241], v[202:205], v[40:43]
	v_mfma_f32_16x16x32_bf16 v[36:39], v[238:241], v[226:229], v[36:39]
	v_mfma_f32_16x16x32_bf16 v[128:131], v[178:181], v[218:221], v[64:67]
	v_mfma_f32_16x16x32_bf16 v[124:127], v[178:181], v[230:233], v[60:63]
	v_mfma_f32_16x16x32_bf16 v[120:123], v[186:189], v[218:221], v[56:59]
	v_mfma_f32_16x16x32_bf16 v[112:115], v[186:189], v[230:233], v[52:55]
	v_mfma_f32_16x16x32_bf16 v[80:83], v[154:157], v[218:221], v[48:51]
	v_mfma_f32_16x16x32_bf16 v[76:79], v[154:157], v[230:233], v[44:47]
	v_mfma_f32_16x16x32_bf16 v[72:75], v[150:153], v[218:221], v[40:43]
	v_mfma_f32_16x16x32_bf16 v[68:71], v[150:153], v[230:233], v[36:39]
	s_setprio 0
	s_setprio 1
	v_mfma_f32_16x16x32_bf16 v[36:39], v[166:169], v[132:135], v[136:139]
	v_mfma_f32_16x16x32_bf16 v[64:67], v[178:181], v[170:173], v[36:39]
	v_mfma_f32_16x16x32_bf16 v[36:39], v[166:169], v[210:213], v[140:143]
	v_mfma_f32_16x16x32_bf16 v[60:63], v[178:181], v[158:161], v[36:39]
	v_mfma_f32_16x16x32_bf16 v[36:39], v[182:185], v[132:135], v[162:165]
	v_mfma_f32_16x16x32_bf16 v[56:59], v[186:189], v[170:173], v[36:39]
	v_mfma_f32_16x16x32_bf16 v[36:39], v[182:185], v[210:213], v[174:177]
	v_mfma_f32_16x16x32_bf16 v[52:55], v[186:189], v[158:161], v[36:39]
	v_mfma_f32_16x16x32_bf16 v[36:39], v[214:217], v[132:135], v[206:209]
	v_mfma_f32_16x16x32_bf16 v[48:51], v[154:157], v[170:173], v[36:39]
	v_mfma_f32_16x16x32_bf16 v[36:39], v[214:217], v[210:213], v[190:193]
	v_mfma_f32_16x16x32_bf16 v[44:47], v[154:157], v[158:161], v[36:39]
	v_mfma_f32_16x16x32_bf16 v[36:39], v[238:241], v[132:135], v[194:197]
	v_mfma_f32_16x16x32_bf16 v[40:43], v[150:153], v[170:173], v[36:39]
	v_mfma_f32_16x16x32_bf16 v[36:39], v[238:241], v[210:213], v[198:201]
	v_mfma_f32_16x16x32_bf16 v[36:39], v[150:153], v[158:161], v[36:39]
	s_setprio 0
	s_movk_i32 s1, 0x100
	v_cmp_gt_u32_e32 vcc, s1, v3
	s_barrier
	s_and_saveexec_b64 s[8:9], vcc
	s_cbranch_execz .LBB0_1008
	s_barrier

; #define LDA8(dst, b, h) _Pragma("unroll") for (int m = 0; m < 4; ++m) _Pragma("unroll") for (int k = 0; k < 2; ++k) \
;     dst[m][k] = *(const bf16x8*)((const char*)SA8(b, h) + lds_byte8(wr * 64 + m * 16 + fr, k * 32 + fq * 8))
; #define LDB8(dst, b, h) _Pragma("unroll") for (int n = 0; n < 2; ++n) _Pragma("unroll") for (int k = 0; k < 2; ++k) \
;     dst[n][k] = *(const bf16x8*)((const char*)SB8(b, h) + lds_byte8(wc * 32 + n * 16 + fr, k * 32 + fq * 8))
; #define WAIT_V8(n) asm volatile("s_waitcnt vmcnt(" #n ")" ::: "memory")
; #define WAIT_L8(n) asm volatile("s_waitcnt lgkmcnt(" #n ")" ::: "memory")
; #define BAR8 __builtin_amdgcn_s_barrier()
; #define SCHED8 __builtin_amdgcn_sched_barrier(0)
;     ...
;     STAGE8(SB8(0, 0), Bt, K, bcol, 0); STAGE8(SA8(0, 0), A, lda, brow, 0);
;     STAGE8(SB8(0, 1), Bt, K, bcol + 128, 0); STAGE8(SA8(0, 1), A, lda, brow + 128, 0);
;   }
;   if (wr == 1) BAR8;
;   WAIT_V8(4); BAR8;
;   STAGE8(SB8(1, 0), Bt, K, bcol, 1); STAGE8(SA8(1, 0), A, lda, brow, 1); STAGE8(SB8(1, 1), Bt, K, bcol + 128, 1);
;   WAIT_V8(6); BAR8;
;   for (int tt = 0; tt < nt - 2; tt += 2) {
;     LDB8(B0, 0, 0); SCHED8; LDA8(At, 0, 0); STAGE8(SA8(1, 1), A, lda, brow + 128, tt + 1);
;     WAIT_L8(8); BAR8; WAIT_L8(0); MMA8(0, 0, At, B0); BAR8; SCHED8;
.LBB0_1014:
	s_or_b64 exec, exec, s[14:15]
	v_readlane_b32 s40, v254, 35
	v_readlane_b32 s42, v254, 37
	v_readlane_b32 s43, v254, 38
	s_waitcnt vmcnt(0)
	v_add_u32_e32 v164, 0x18000, v150
	s_mov_b64 s[42:43], 0x80
	v_readfirstlane_b32 s21, v164
	v_add_u32_e32 v165, 0x1a000, v150
	v_lshl_add_u64 v[10:11], v[10:11], 0, s[42:43]
	s_mov_b32 m0, s21
	v_readfirstlane_b32 s21, v165
	v_add_u32_e32 v166, 0x8000, v150
	s_waitcnt vmcnt(4)
	s_barrier
	global_load_lds_dwordx4 v[10:11], off
	v_lshl_add_u64 v[10:11], v[12:13], 0, s[42:43]
	s_mov_b32 m0, s21
	v_readfirstlane_b32 s21, v166
	v_add_u32_e32 v167, 0xa000, v150
	global_load_lds_dwordx4 v[10:11], off
	v_lshl_add_u64 v[10:11], v[14:15], 0, s[42:43]
	s_mov_b32 m0, s21
	v_readfirstlane_b32 s21, v167
	v_add_u32_e32 v169, 0x1c000, v150
	global_load_lds_dwordx4 v[10:11], off
	v_lshl_add_u64 v[10:11], v[16:17], 0, s[42:43]
	s_mov_b32 m0, s21
	v_readfirstlane_b32 s21, v169
	v_add_u32_e32 v170, 0x1e000, v150
	global_load_lds_dwordx4 v[10:11], off
	v_lshl_add_u64 v[10:11], v[18:19], 0, s[42:43]
	s_mov_b32 m0, s21
	v_readfirstlane_b32 s21, v170
	global_load_lds_dwordx4 v[10:11], off
	v_lshl_add_u64 v[10:11], v[20:21], 0, s[42:43]
	s_mov_b32 m0, s21
	v_and_b32_e32 v147, 15, v3
	global_load_lds_dwordx4 v[10:11], off
	v_bfe_u32 v148, v3, 4, 2
	v_lshlrev_b32_e32 v10, 4, v148
	v_lshlrev_b32_e32 v11, 6, v147
	v_lshlrev_b32_e32 v14, 2, v3
	v_or_b32_e32 v13, v10, v11
	v_and_b32_e32 v14, 32, v14
	s_mov_b32 s21, 0x10000
	v_bitop3_b32 v16, v13, s21, v14 bitop3:0xde
	s_mov_b32 s21, 0x14000
	s_and_b32 s14, s27, 63
	v_bitop3_b32 v15, v10, v14, v11 bitop3:0x36
	v_bitop3_b32 v17, v13, s21, v14 bitop3:0xde
	s_mov_b32 s21, 0x18000
	v_lshlrev_b32_e32 v11, 6, v3
	s_lshl_b32 s14, s14, 19
	s_mov_b32 s15, s40
	v_bitop3_b32 v18, v13, s21, v14 bitop3:0xde
	s_mov_b32 s21, 0x1c000
	v_and_b32_e32 v11, 0x3c0, v11
	v_bitop3_b32 v13, v13, s21, v14 bitop3:0xde
	v_bitop3_b32 v14, v11, v14, v10 bitop3:0x36
	v_lshl_add_u64 v[10:11], s[14:15], 0, v[136:137]
	v_readlane_b32 s41, v254, 36
	s_and_b32 s40, s33, 0xffffff00
	v_lshl_add_u64 v[10:11], v[10:11], 0, v[8:9]
	s_ashr_i32 s41, s40, 31
	v_lshl_add_u64 v[138:139], s[12:13], 0, v[10:11]
	v_lshl_add_u64 v[10:11], s[14:15], 0, v[132:133]
	s_lshl_b64 s[40:41], s[40:41], 11
	v_lshl_add_u64 v[10:11], v[10:11], 0, v[6:7]
	v_lshl_add_u64 v[140:141], s[12:13], 0, v[10:11]
	v_lshl_add_u64 v[10:11], s[40:41], 0, v[132:133]
	v_lshl_add_u64 v[6:7], v[10:11], 0, v[6:7]
	v_bfe_u32 v146, v3, 6, 2
	s_waitcnt vmcnt(6)
	v_lshlrev_b32_e32 v149, 6, v5
	v_lshlrev_b32_e32 v5, 13, v5
	v_lshl_add_u64 v[142:143], s[4:5], 0, v[6:7]
	v_lshl_add_u64 v[6:7], s[40:41], 0, v[136:137]
	v_lshlrev_b32_e32 v12, 12, v146
	v_or_b32_e32 v19, 0x800, v5
	v_or_b32_e32 v20, 0x1000, v5
	v_or_b32_e32 v21, 0x1800, v5
	v_lshl_add_u64 v[6:7], v[6:7], 0, v[8:9]
	v_lshl_add_u64 v[144:145], s[4:5], 0, v[6:7]
	s_mov_b32 s14, -2
	s_mov_b64 s[12:13], 0
	v_add_u32_e32 v171, v16, v12
	v_add_u32_e32 v156, v15, v5
	v_add_u32_e32 v155, v14, v19
	v_add_u32_e32 v154, v14, v20
	v_add_u32_e32 v153, v14, v21
	v_add_u32_e32 v168, v17, v12
	v_add_u32_e32 v161, v18, v12
	v_add_u32_e32 v158, v13, v12
	s_mov_b64 s[40:41], 0xc6a0100
	s_mov_b64 s[42:43], 0xc6e0100
	s_mov_b64 s[44:45], 0xc6a0180
	s_mov_b64 s[46:47], 0xc6e0180
	s_barrier
	ds_read_b128 v[174:177], v171
	ds_read_b128 v[178:181], v171 offset:1024
	ds_read_b128 v[182:185], v171 offset:2048
	ds_read_b128 v[186:189], v171 offset:3072
	v_add_u32_e32 v172, 0xc000, v150
	v_lshl_add_u64 v[222:223], v[140:141], 0, s[12:13]
	v_readfirstlane_b32 s15, v172
	v_add_u32_e32 v173, 0xe000, v150
	v_lshl_add_u64 v[226:227], v[222:223], 0, s[34:35]
	s_mov_b32 m0, s15
	v_lshl_add_u64 v[236:237], v[138:139], 0, s[12:13]
	v_readfirstlane_b32 s15, v173
	ds_read_b128 v[190:193], v156
	ds_read_b128 v[194:197], v156 offset:1024
	ds_read_b128 v[198:201], v155
	ds_read_b128 v[202:205], v155 offset:1024
	ds_read_b128 v[206:209], v154
	ds_read_b128 v[210:213], v154 offset:1024
	ds_read_b128 v[214:217], v153
	ds_read_b128 v[218:221], v153 offset:1024
	global_load_lds_dwordx4 v[226:227], off
	v_lshl_add_u64 v[226:227], v[236:237], 0, s[34:35]
	s_mov_b32 m0, s15
	s_nop 0
	global_load_lds_dwordx4 v[226:227], off
	s_waitcnt lgkmcnt(8)
	s_barrier
	s_waitcnt lgkmcnt(0)
	s_setprio 1
	s_waitcnt lgkmcnt(0)
	v_mfma_f32_16x16x32_f16 v[128:131], v[190:193], v[174:177], 0
	v_mfma_f32_16x16x32_f16 v[124:127], v[190:193], v[182:185], 0
	v_mfma_f32_16x16x32_f16 v[120:123], v[198:201], v[174:177], 0
	v_mfma_f32_16x16x32_f16 v[116:119], v[198:201], v[182:185], 0
	v_mfma_f32_16x16x32_f16 v[112:115], v[206:209], v[174:177], 0
	v_mfma_f32_16x16x32_f16 v[108:111], v[206:209], v[182:185], 0
	v_mfma_f32_16x16x32_f16 v[104:107], v[214:217], v[174:177], 0
	v_mfma_f32_16x16x32_f16 v[100:103], v[214:217], v[182:185], 0
	v_mfma_f32_16x16x32_f16 v[128:131], v[194:197], v[178:181], v[128:131]
	v_mfma_f32_16x16x32_f16 v[124:127], v[194:197], v[186:189], v[124:127]
	v_mfma_f32_16x16x32_f16 v[120:123], v[202:205], v[178:181], v[120:123]
	v_mfma_f32_16x16x32_f16 v[116:119], v[202:205], v[186:189], v[116:119]
	v_mfma_f32_16x16x32_f16 v[112:115], v[210:213], v[178:181], v[112:115]
	v_mfma_f32_16x16x32_f16 v[108:111], v[210:213], v[186:189], v[108:111]
	v_mfma_f32_16x16x32_f16 v[104:107], v[218:221], v[178:181], v[104:107]
	v_mfma_f32_16x16x32_f16 v[100:103], v[218:221], v[186:189], v[100:103]
	s_setprio 0
	s_barrier
; #define LDA8(dst, b, h) _Pragma("unroll") for (int m = 0; m < 4; ++m) _Pragma("unroll") for (int k = 0; k < 2; ++k) \
;     dst[m][k] = *(const bf16x8*)((const char*)SA8(b, h) + lds_byte8(wr * 64 + m * 16 + fr, k * 32 + fq * 8))
; #define LDB8(dst, b, h) _Pragma("unroll") for (int n = 0; n < 2; ++n) _Pragma("unroll") for (int k = 0; k < 2; ++k) \
;     dst[n][k] = *(const bf16x8*)((const char*)SB8(b, h) + lds_byte8(wc * 32 + n * 16 + fr, k * 32 + fq * 8))
; #define WAIT_V8(n) asm volatile("s_waitcnt vmcnt(" #n ")" ::: "memory")
; #define WAIT_L8(n) asm volatile("s_waitcnt lgkmcnt(" #n ")" ::: "memory")
; #define BAR8 __builtin_amdgcn_s_barrier()
; #define SCHED8 __builtin_amdgcn_sched_barrier(0)
;     ...
;     LDB8(B1, 0, 1); STAGE8(SB8(0, 0), Bt, K, bcol, tt + 2);
;     BAR8; WAIT_L8(0); MMA8(0, 1, At, B1); BAR8;
;     LDA8(At, 0, 1); STAGE8(SA8(0, 0), A, lda, brow, tt + 2);
;     BAR8; WAIT_L8(0); MMA8(1, 0, At, B0); BAR8; SCHED8;
;     STAGE8(SB8(0, 1), Bt, K, bcol + 128, tt + 2);
;     WAIT_V8(6); BAR8; MMA8(1, 1, At, B1); BAR8;
;     LDB8(B0, 1, 0); SCHED8; LDA8(At, 1, 0); STAGE8(SA8(0, 1), A, lda, brow + 128, tt + 2);
;     WAIT_L8(8); BAR8; WAIT_L8(0); MMA8(0, 0, At, B0); BAR8; SCHED8;
	v_lshl_add_u64 v[246:247], v[142:143], 0, s[12:13]
	v_readfirstlane_b32 s15, v151
	v_lshl_add_u64 v[248:249], v[246:247], 0, s[40:41]
	s_mov_b32 m0, s15
	ds_read_b128 v[226:229], v168
	ds_read_b128 v[230:233], v168 offset:1024
	ds_read_b128 v[238:241], v168 offset:2048
	ds_read_b128 v[242:245], v168 offset:3072
	global_load_lds_dwordx4 v[248:249], off
	v_lshl_add_u64 v[248:249], v[144:145], 0, s[12:13]
	v_readfirstlane_b32 s15, v157
	v_lshl_add_u64 v[250:251], v[248:249], 0, s[40:41]
	s_mov_b32 m0, s15
	s_nop 0
	global_load_lds_dwordx4 v[250:251], off
	s_barrier
	s_waitcnt lgkmcnt(0)
	s_setprio 1
	s_waitcnt lgkmcnt(0)
	v_mfma_f32_16x16x32_f16 v[96:99], v[190:193], v[226:229], 0
	v_mfma_f32_16x16x32_f16 v[92:95], v[190:193], v[238:241], 0
	v_mfma_f32_16x16x32_f16 v[88:91], v[198:201], v[226:229], 0
	v_mfma_f32_16x16x32_f16 v[84:87], v[198:201], v[238:241], 0
	v_mfma_f32_16x16x32_f16 v[80:83], v[206:209], v[226:229], 0
	v_mfma_f32_16x16x32_f16 v[76:79], v[206:209], v[238:241], 0
	v_mfma_f32_16x16x32_f16 v[72:75], v[214:217], v[226:229], 0
	v_mfma_f32_16x16x32_f16 v[68:71], v[214:217], v[238:241], 0
	v_mfma_f32_16x16x32_f16 v[96:99], v[194:197], v[230:233], v[96:99]
	v_mfma_f32_16x16x32_f16 v[92:95], v[194:197], v[242:245], v[92:95]
	v_mfma_f32_16x16x32_f16 v[88:91], v[202:205], v[230:233], v[88:91]
	v_mfma_f32_16x16x32_f16 v[84:87], v[202:205], v[242:245], v[84:87]
	v_mfma_f32_16x16x32_f16 v[80:83], v[210:213], v[230:233], v[80:83]
	v_mfma_f32_16x16x32_f16 v[76:79], v[210:213], v[242:245], v[76:79]
	v_mfma_f32_16x16x32_f16 v[72:75], v[218:221], v[230:233], v[72:75]
	v_mfma_f32_16x16x32_f16 v[68:71], v[218:221], v[242:245], v[68:71]
	s_setprio 0
	v_readfirstlane_b32 s15, v150
	v_lshl_add_u64 v[250:251], v[222:223], 0, s[10:11]
	s_mov_b32 m0, s15
	v_readfirstlane_b32 s15, v152
	s_barrier
	ds_read_b128 v[190:193], v156 offset:16384
	ds_read_b128 v[194:197], v156 offset:17408
	ds_read_b128 v[198:201], v155 offset:16384
	ds_read_b128 v[202:205], v155 offset:17408
	ds_read_b128 v[206:209], v154 offset:16384
	ds_read_b128 v[210:213], v154 offset:17408
	ds_read_b128 v[214:217], v153 offset:16384
	ds_read_b128 v[218:221], v153 offset:17408
	global_load_lds_dwordx4 v[250:251], off
	v_lshl_add_u64 v[250:251], v[236:237], 0, s[10:11]
	s_mov_b32 m0, s15
	s_nop 0
	global_load_lds_dwordx4 v[250:251], off
	s_barrier
	s_waitcnt lgkmcnt(0)
	s_setprio 1
	s_waitcnt lgkmcnt(0)
	v_mfma_f32_16x16x32_f16 v[64:67], v[190:193], v[174:177], 0
	v_mfma_f32_16x16x32_f16 v[60:63], v[190:193], v[182:185], 0
	v_mfma_f32_16x16x32_f16 v[56:59], v[198:201], v[174:177], 0
	v_mfma_f32_16x16x32_f16 v[52:55], v[198:201], v[182:185], 0
	v_mfma_f32_16x16x32_f16 v[48:51], v[206:209], v[174:177], 0
	v_mfma_f32_16x16x32_f16 v[44:47], v[206:209], v[182:185], 0
	v_mfma_f32_16x16x32_f16 v[40:43], v[214:217], v[174:177], 0
	v_mfma_f32_16x16x32_f16 v[36:39], v[214:217], v[182:185], 0
	v_mfma_f32_16x16x32_f16 v[64:67], v[194:197], v[178:181], v[64:67]
	v_mfma_f32_16x16x32_f16 v[60:63], v[194:197], v[186:189], v[60:63]
	v_mfma_f32_16x16x32_f16 v[56:59], v[202:205], v[178:181], v[56:59]
	v_mfma_f32_16x16x32_f16 v[52:55], v[202:205], v[186:189], v[52:55]
	v_mfma_f32_16x16x32_f16 v[48:51], v[210:213], v[178:181], v[48:51]
	v_mfma_f32_16x16x32_f16 v[44:47], v[210:213], v[186:189], v[44:47]
	v_mfma_f32_16x16x32_f16 v[40:43], v[218:221], v[178:181], v[40:43]
	v_mfma_f32_16x16x32_f16 v[36:39], v[218:221], v[186:189], v[36:39]
	s_setprio 0
	s_barrier
	v_readfirstlane_b32 s15, v159
	v_lshl_add_u64 v[174:175], v[246:247], 0, s[42:43]
	s_mov_b32 m0, s15
	v_readfirstlane_b32 s15, v160
	global_load_lds_dwordx4 v[174:175], off
	v_lshl_add_u64 v[174:175], v[248:249], 0, s[42:43]
	s_mov_b32 m0, s15
	s_nop 0
	global_load_lds_dwordx4 v[174:175], off
	s_waitcnt vmcnt(6)
	s_barrier
	s_setprio 1
	v_mfma_f32_16x16x32_f16 v[32:35], v[190:193], v[226:229], 0
	v_mfma_f32_16x16x32_f16 v[28:31], v[190:193], v[238:241], 0
	v_mfma_f32_16x16x32_f16 v[24:27], v[198:201], v[226:229], 0
	v_mfma_f32_16x16x32_f16 v[20:23], v[198:201], v[238:241], 0
	v_mfma_f32_16x16x32_f16 v[16:19], v[206:209], v[226:229], 0
	v_mfma_f32_16x16x32_f16 v[12:15], v[206:209], v[238:241], 0
	v_mfma_f32_16x16x32_f16 v[8:11], v[214:217], v[226:229], 0
	v_mfma_f32_16x16x32_f16 v[4:7], v[214:217], v[238:241], 0
	v_mfma_f32_16x16x32_f16 v[32:35], v[194:197], v[230:233], v[32:35]
	v_mfma_f32_16x16x32_f16 v[28:31], v[194:197], v[242:245], v[28:31]
	v_mfma_f32_16x16x32_f16 v[24:27], v[202:205], v[230:233], v[24:27]
	v_mfma_f32_16x16x32_f16 v[20:23], v[202:205], v[242:245], v[20:23]
	v_mfma_f32_16x16x32_f16 v[16:19], v[210:213], v[230:233], v[16:19]
	v_mfma_f32_16x16x32_f16 v[12:15], v[210:213], v[242:245], v[12:15]
	v_mfma_f32_16x16x32_f16 v[8:11], v[218:221], v[230:233], v[8:11]
	v_mfma_f32_16x16x32_f16 v[4:7], v[218:221], v[242:245], v[4:7]
	s_setprio 0
	s_barrier
	ds_read_b128 v[174:177], v161
	ds_read_b128 v[178:181], v161 offset:1024
	ds_read_b128 v[182:185], v161 offset:2048
	ds_read_b128 v[186:189], v161 offset:3072
	v_readfirstlane_b32 s15, v162
	v_lshl_add_u64 v[226:227], v[222:223], 0, s[18:19]
	s_mov_b32 m0, s15
	v_readfirstlane_b32 s15, v163
	ds_read_b128 v[190:193], v156 offset:32768
	ds_read_b128 v[194:197], v156 offset:33792
	ds_read_b128 v[198:201], v155 offset:32768
	ds_read_b128 v[202:205], v155 offset:33792
	ds_read_b128 v[206:209], v154 offset:32768
	ds_read_b128 v[210:213], v154 offset:33792
	ds_read_b128 v[214:217], v153 offset:32768
	ds_read_b128 v[218:221], v153 offset:33792
	global_load_lds_dwordx4 v[226:227], off
	v_lshl_add_u64 v[226:227], v[236:237], 0, s[18:19]
	s_mov_b32 m0, s15
	s_nop 0
	global_load_lds_dwordx4 v[226:227], off
	s_waitcnt lgkmcnt(8)
	s_barrier
; #define LDA8(dst, b, h) _Pragma("unroll") for (int m = 0; m < 4; ++m) _Pragma("unroll") for (int k = 0; k < 2; ++k) \
;     dst[m][k] = *(const bf16x8*)((const char*)SA8(b, h) + lds_byte8(wr * 64 + m * 16 + fr, k * 32 + fq * 8))
; #define LDB8(dst, b, h) _Pragma("unroll") for (int n = 0; n < 2; ++n) _Pragma("unroll") for (int k = 0; k < 2; ++k) \
;     dst[n][k] = *(const bf16x8*)((const char*)SB8(b, h) + lds_byte8(wc * 32 + n * 16 + fr, k * 32 + fq * 8))
; #define WAIT_V8(n) asm volatile("s_waitcnt vmcnt(" #n ")" ::: "memory")
; #define WAIT_L8(n) asm volatile("s_waitcnt lgkmcnt(" #n ")" ::: "memory")
; #define BAR8 __builtin_amdgcn_s_barrier()
; #define SCHED8 __builtin_amdgcn_sched_barrier(0)
;     ...
;     WAIT_L8(8); BAR8; WAIT_L8(0); MMA8(0, 0, At, B0); BAR8; SCHED8;
;     LDB8(B1, 1, 1); STAGE8(SB8(1, 0), Bt, K, bcol, tt + 3);
;     BAR8; WAIT_L8(0); MMA8(0, 1, At, B1); BAR8;
;     LDA8(At, 1, 1); STAGE8(SA8(1, 0), A, lda, brow, tt + 3);
;     BAR8; WAIT_L8(0); MMA8(1, 0, At, B0); BAR8; SCHED8;
;     STAGE8(SB8(1, 1), Bt, K, bcol + 128, tt + 3);
;     WAIT_V8(6); BAR8; MMA8(1, 1, At, B1); BAR8;
;   }
	s_waitcnt lgkmcnt(0)
	s_setprio 1
	s_waitcnt lgkmcnt(0)
	v_mfma_f32_16x16x32_f16 v[128:131], v[190:193], v[174:177], v[128:131]
	v_mfma_f32_16x16x32_f16 v[124:127], v[190:193], v[182:185], v[124:127]
	v_mfma_f32_16x16x32_f16 v[120:123], v[198:201], v[174:177], v[120:123]
	v_mfma_f32_16x16x32_f16 v[116:119], v[198:201], v[182:185], v[116:119]
	v_mfma_f32_16x16x32_f16 v[112:115], v[206:209], v[174:177], v[112:115]
	v_mfma_f32_16x16x32_f16 v[108:111], v[206:209], v[182:185], v[108:111]
	v_mfma_f32_16x16x32_f16 v[104:107], v[214:217], v[174:177], v[104:107]
	v_mfma_f32_16x16x32_f16 v[100:103], v[214:217], v[182:185], v[100:103]
	v_mfma_f32_16x16x32_f16 v[128:131], v[194:197], v[178:181], v[128:131]
	v_mfma_f32_16x16x32_f16 v[124:127], v[194:197], v[186:189], v[124:127]
	v_mfma_f32_16x16x32_f16 v[120:123], v[202:205], v[178:181], v[120:123]
	v_mfma_f32_16x16x32_f16 v[116:119], v[202:205], v[186:189], v[116:119]
	v_mfma_f32_16x16x32_f16 v[112:115], v[210:213], v[178:181], v[112:115]
	v_mfma_f32_16x16x32_f16 v[108:111], v[210:213], v[186:189], v[108:111]
	v_mfma_f32_16x16x32_f16 v[104:107], v[218:221], v[178:181], v[104:107]
	v_mfma_f32_16x16x32_f16 v[100:103], v[218:221], v[186:189], v[100:103]
	s_setprio 0
	s_barrier
	v_readfirstlane_b32 s15, v164
	v_lshl_add_u64 v[250:251], v[246:247], 0, s[44:45]
	s_mov_b32 m0, s15
	v_readfirstlane_b32 s15, v165
	ds_read_b128 v[226:229], v158
	ds_read_b128 v[230:233], v158 offset:1024
	ds_read_b128 v[238:241], v158 offset:2048
	ds_read_b128 v[242:245], v158 offset:3072
	global_load_lds_dwordx4 v[250:251], off
	v_lshl_add_u64 v[250:251], v[248:249], 0, s[44:45]
	s_mov_b32 m0, s15
	s_nop 0
	global_load_lds_dwordx4 v[250:251], off
	s_barrier
	s_waitcnt lgkmcnt(0)
	s_setprio 1
	s_waitcnt lgkmcnt(0)
	v_mfma_f32_16x16x32_f16 v[96:99], v[190:193], v[226:229], v[96:99]
	v_mfma_f32_16x16x32_f16 v[92:95], v[190:193], v[238:241], v[92:95]
	v_mfma_f32_16x16x32_f16 v[88:91], v[198:201], v[226:229], v[88:91]
	v_mfma_f32_16x16x32_f16 v[84:87], v[198:201], v[238:241], v[84:87]
	v_mfma_f32_16x16x32_f16 v[80:83], v[206:209], v[226:229], v[80:83]
	v_mfma_f32_16x16x32_f16 v[76:79], v[206:209], v[238:241], v[76:79]
	v_mfma_f32_16x16x32_f16 v[72:75], v[214:217], v[226:229], v[72:75]
	v_mfma_f32_16x16x32_f16 v[68:71], v[214:217], v[238:241], v[68:71]
	v_mfma_f32_16x16x32_f16 v[96:99], v[194:197], v[230:233], v[96:99]
	v_mfma_f32_16x16x32_f16 v[92:95], v[194:197], v[242:245], v[92:95]
	v_mfma_f32_16x16x32_f16 v[88:91], v[202:205], v[230:233], v[88:91]
	v_mfma_f32_16x16x32_f16 v[84:87], v[202:205], v[242:245], v[84:87]
	v_mfma_f32_16x16x32_f16 v[80:83], v[210:213], v[230:233], v[80:83]
	v_mfma_f32_16x16x32_f16 v[76:79], v[210:213], v[242:245], v[76:79]
	v_mfma_f32_16x16x32_f16 v[72:75], v[218:221], v[230:233], v[72:75]
	v_mfma_f32_16x16x32_f16 v[68:71], v[218:221], v[242:245], v[68:71]
	s_setprio 0
	v_readfirstlane_b32 s15, v166
	v_lshl_add_u64 v[222:223], v[222:223], 0, s[22:23]
	s_mov_b32 m0, s15
	v_readfirstlane_b32 s15, v167
	s_barrier
	ds_read_b128 v[190:193], v156 offset:49152
	ds_read_b128 v[194:197], v156 offset:50176
	ds_read_b128 v[198:201], v155 offset:49152
	ds_read_b128 v[202:205], v155 offset:50176
	ds_read_b128 v[206:209], v154 offset:49152
	ds_read_b128 v[210:213], v154 offset:50176
	ds_read_b128 v[214:217], v153 offset:49152
	ds_read_b128 v[218:221], v153 offset:50176
	global_load_lds_dwordx4 v[222:223], off
	v_lshl_add_u64 v[222:223], v[236:237], 0, s[22:23]
	s_mov_b32 m0, s15
	s_nop 0
	global_load_lds_dwordx4 v[222:223], off
	s_barrier
	s_waitcnt lgkmcnt(0)
	s_setprio 1
	s_waitcnt lgkmcnt(0)
	v_mfma_f32_16x16x32_f16 v[64:67], v[190:193], v[174:177], v[64:67]
	v_mfma_f32_16x16x32_f16 v[60:63], v[190:193], v[182:185], v[60:63]
	v_mfma_f32_16x16x32_f16 v[56:59], v[198:201], v[174:177], v[56:59]
	v_mfma_f32_16x16x32_f16 v[52:55], v[198:201], v[182:185], v[52:55]
	v_mfma_f32_16x16x32_f16 v[48:51], v[206:209], v[174:177], v[48:51]
	v_mfma_f32_16x16x32_f16 v[44:47], v[206:209], v[182:185], v[44:47]
	v_mfma_f32_16x16x32_f16 v[40:43], v[214:217], v[174:177], v[40:43]
	v_mfma_f32_16x16x32_f16 v[36:39], v[214:217], v[182:185], v[36:39]
	v_mfma_f32_16x16x32_f16 v[64:67], v[194:197], v[178:181], v[64:67]
	v_mfma_f32_16x16x32_f16 v[60:63], v[194:197], v[186:189], v[60:63]
	v_mfma_f32_16x16x32_f16 v[56:59], v[202:205], v[178:181], v[56:59]
	v_mfma_f32_16x16x32_f16 v[52:55], v[202:205], v[186:189], v[52:55]
	v_mfma_f32_16x16x32_f16 v[48:51], v[210:213], v[178:181], v[48:51]
	v_mfma_f32_16x16x32_f16 v[44:47], v[210:213], v[186:189], v[44:47]
	v_mfma_f32_16x16x32_f16 v[40:43], v[218:221], v[178:181], v[40:43]
	v_mfma_f32_16x16x32_f16 v[36:39], v[218:221], v[186:189], v[36:39]
	s_setprio 0
	s_barrier
	v_readfirstlane_b32 s15, v169
	v_lshl_add_u64 v[174:175], v[246:247], 0, s[46:47]
	s_mov_b32 m0, s15
	v_readfirstlane_b32 s15, v170
	global_load_lds_dwordx4 v[174:175], off
	v_lshl_add_u64 v[174:175], v[248:249], 0, s[46:47]
	s_mov_b32 m0, s15
	s_nop 0
	global_load_lds_dwordx4 v[174:175], off
	s_waitcnt vmcnt(6)
	s_barrier
	s_setprio 1
	v_mfma_f32_16x16x32_f16 v[32:35], v[190:193], v[226:229], v[32:35]
	v_mfma_f32_16x16x32_f16 v[28:31], v[190:193], v[238:241], v[28:31]
	v_mfma_f32_16x16x32_f16 v[24:27], v[198:201], v[226:229], v[24:27]
	v_mfma_f32_16x16x32_f16 v[20:23], v[198:201], v[238:241], v[20:23]
	v_mfma_f32_16x16x32_f16 v[16:19], v[206:209], v[226:229], v[16:19]
	v_mfma_f32_16x16x32_f16 v[12:15], v[206:209], v[238:241], v[12:15]
	v_mfma_f32_16x16x32_f16 v[8:11], v[214:217], v[226:229], v[8:11]
	v_mfma_f32_16x16x32_f16 v[4:7], v[214:217], v[238:241], v[4:7]
	v_mfma_f32_16x16x32_f16 v[32:35], v[194:197], v[230:233], v[32:35]
	v_mfma_f32_16x16x32_f16 v[28:31], v[194:197], v[242:245], v[28:31]
	v_mfma_f32_16x16x32_f16 v[24:27], v[202:205], v[230:233], v[24:27]
	v_mfma_f32_16x16x32_f16 v[20:23], v[202:205], v[242:245], v[20:23]
	v_mfma_f32_16x16x32_f16 v[16:19], v[210:213], v[230:233], v[16:19]
	v_mfma_f32_16x16x32_f16 v[12:15], v[210:213], v[242:245], v[12:15]
	v_mfma_f32_16x16x32_f16 v[8:11], v[218:221], v[230:233], v[8:11]
	v_mfma_f32_16x16x32_f16 v[4:7], v[218:221], v[242:245], v[4:7]
	s_setprio 0
	s_add_i32 s14, s14, 2
	s_add_u32 s12, s12, 0x100
	s_addc_u32 s13, s13, 0
	s_cmp_lt_u32 s14, 12
	s_barrier
	s_cbranch_scc0 .Lpk_exit_4

; #define LDA8(dst, b, h) _Pragma("unroll") for (int m = 0; m < 4; ++m) _Pragma("unroll") for (int k = 0; k < 2; ++k) \
;     dst[m][k] = *(const bf16x8*)((const char*)SA8(b, h) + lds_byte8(wr * 64 + m * 16 + fr, k * 32 + fq * 8))
; #define LDB8(dst, b, h) _Pragma("unroll") for (int n = 0; n < 2; ++n) _Pragma("unroll") for (int k = 0; k < 2; ++k) \
;     dst[n][k] = *(const bf16x8*)((const char*)SB8(b, h) + lds_byte8(wc * 32 + n * 16 + fr, k * 32 + fq * 8))
; #define WAIT_V8(n) asm volatile("s_waitcnt vmcnt(" #n ")" ::: "memory")
; #define WAIT_L8(n) asm volatile("s_waitcnt lgkmcnt(" #n ")" ::: "memory")
; #define BAR8 __builtin_amdgcn_s_barrier()
;     ...
;   { LDB8(B0, 0, 0); LDA8(At, 0, 0); STAGE8(SA8(1, 1), A, lda, brow + 128, nt - 1);
;     BAR8; WAIT_L8(0); MMA8(0, 0, At, B0); BAR8;
;     LDB8(B1, 0, 1); BAR8; WAIT_L8(0); MMA8(0, 1, At, B1); BAR8;
;     LDA8(At, 0, 1); WAIT_V8(4); BAR8; WAIT_L8(0); MMA8(1, 0, At, B0); MMA8(1, 1, At, B1); BAR8; }
.Lpk_exit_4:
	s_add_u32 s8, s8, 0x40780
	s_addc_u32 s9, s9, 0
	v_lshl_add_u64 v[132:133], s[8:9], 0, v[132:133]
	v_readfirstlane_b32 s12, v172
	v_lshl_add_u64 v[0:1], v[0:1], 1, v[132:133]
	s_mov_b32 m0, s12
	ds_read_b128 v[138:141], v171
	ds_read_b128 v[142:145], v171 offset:1024
	ds_read_b128 v[162:165], v171 offset:2048
	ds_read_b128 v[174:177], v171 offset:3072
	ds_read_b128 v[178:181], v156
	ds_read_b128 v[182:185], v156 offset:1024
	ds_read_b128 v[186:189], v155
	ds_read_b128 v[190:193], v155 offset:1024
	ds_read_b128 v[194:197], v154
	ds_read_b128 v[198:201], v154 offset:1024
	ds_read_b128 v[202:205], v153
	ds_read_b128 v[206:209], v153 offset:1024
	global_load_lds_dwordx4 v[0:1], off
	v_lshl_add_u64 v[0:1], s[8:9], 0, v[136:137]
	v_readfirstlane_b32 s8, v173
	v_lshl_add_u64 v[0:1], v[134:135], 1, v[0:1]
	s_mov_b32 m0, s8
	s_nop 0
	global_load_lds_dwordx4 v[0:1], off
	s_barrier
	s_waitcnt lgkmcnt(0)
	s_setprio 1
	s_waitcnt lgkmcnt(0)
	v_mfma_f32_16x16x32_f16 v[128:131], v[178:181], v[138:141], v[128:131]
	v_mfma_f32_16x16x32_f16 v[124:127], v[178:181], v[162:165], v[124:127]
	v_mfma_f32_16x16x32_f16 v[120:123], v[186:189], v[138:141], v[120:123]
	v_mfma_f32_16x16x32_f16 v[112:115], v[194:197], v[138:141], v[112:115]
	v_mfma_f32_16x16x32_f16 v[128:131], v[182:185], v[142:145], v[128:131]
	v_mfma_f32_16x16x32_f16 v[124:127], v[182:185], v[174:177], v[124:127]
	v_mfma_f32_16x16x32_f16 v[120:123], v[190:193], v[142:145], v[120:123]
	v_mfma_f32_16x16x32_f16 v[116:119], v[186:189], v[162:165], v[116:119]
	v_mfma_f32_16x16x32_f16 v[112:115], v[198:201], v[142:145], v[112:115]
	v_mfma_f32_16x16x32_f16 v[108:111], v[194:197], v[162:165], v[108:111]
	v_mfma_f32_16x16x32_f16 v[104:107], v[202:205], v[138:141], v[104:107]
	v_mfma_f32_16x16x32_f16 v[100:103], v[202:205], v[162:165], v[100:103]
	v_mfma_f32_16x16x32_f16 v[132:135], v[190:193], v[174:177], v[116:119]
	v_mfma_f32_16x16x32_f16 v[170:173], v[198:201], v[174:177], v[108:111]
	v_mfma_f32_16x16x32_f16 v[210:213], v[206:209], v[142:145], v[104:107]
	v_mfma_f32_16x16x32_f16 v[214:217], v[206:209], v[174:177], v[100:103]
	s_setprio 0
	s_barrier
	s_nop 1
	ds_read_b128 v[100:103], v168
	ds_read_b128 v[104:107], v168 offset:1024
	ds_read_b128 v[108:111], v168 offset:2048
	ds_read_b128 v[116:119], v168 offset:3072
	s_barrier
	s_waitcnt lgkmcnt(0)
	s_setprio 1
	s_waitcnt lgkmcnt(0)
	v_mfma_f32_16x16x32_f16 v[80:83], v[194:197], v[100:103], v[80:83]
	v_mfma_f32_16x16x32_f16 v[76:79], v[194:197], v[108:111], v[76:79]
	v_mfma_f32_16x16x32_f16 v[72:75], v[202:205], v[100:103], v[72:75]
	v_mfma_f32_16x16x32_f16 v[68:71], v[202:205], v[108:111], v[68:71]
	v_mfma_f32_16x16x32_f16 v[96:99], v[178:181], v[100:103], v[96:99]
	v_mfma_f32_16x16x32_f16 v[92:95], v[178:181], v[108:111], v[92:95]
	v_mfma_f32_16x16x32_f16 v[88:91], v[186:189], v[100:103], v[88:91]
	v_mfma_f32_16x16x32_f16 v[84:87], v[186:189], v[108:111], v[84:87]
	v_mfma_f32_16x16x32_f16 v[80:83], v[198:201], v[104:107], v[80:83]
	v_mfma_f32_16x16x32_f16 v[76:79], v[198:201], v[116:119], v[76:79]
	v_mfma_f32_16x16x32_f16 v[72:75], v[206:209], v[104:107], v[72:75]
	v_mfma_f32_16x16x32_f16 v[68:71], v[206:209], v[116:119], v[68:71]
	v_mfma_f32_16x16x32_f16 v[166:169], v[182:185], v[104:107], v[96:99]
	v_mfma_f32_16x16x32_f16 v[178:181], v[182:185], v[116:119], v[92:95]
	v_mfma_f32_16x16x32_f16 v[182:185], v[190:193], v[104:107], v[88:91]
	v_mfma_f32_16x16x32_f16 v[186:189], v[190:193], v[116:119], v[84:87]
	s_setprio 0
	s_barrier
	s_nop 0
	ds_read_b128 v[84:87], v156 offset:16384
	ds_read_b128 v[88:91], v156 offset:17408
	ds_read_b128 v[92:95], v155 offset:16384
	ds_read_b128 v[96:99], v155 offset:17408
	ds_read_b128 v[190:193], v154 offset:16384
	ds_read_b128 v[194:197], v154 offset:17408
	ds_read_b128 v[198:201], v153 offset:16384
	ds_read_b128 v[202:205], v153 offset:17408
	s_waitcnt vmcnt(4)
	s_barrier
	s_waitcnt lgkmcnt(0)
	s_setprio 1
	s_waitcnt lgkmcnt(0)
	v_mfma_f32_16x16x32_f16 v[64:67], v[84:87], v[138:141], v[64:67]
	v_mfma_f32_16x16x32_f16 v[60:63], v[84:87], v[162:165], v[60:63]
	v_mfma_f32_16x16x32_f16 v[56:59], v[92:95], v[138:141], v[56:59]
	v_mfma_f32_16x16x32_f16 v[52:55], v[92:95], v[162:165], v[52:55]
	v_mfma_f32_16x16x32_f16 v[48:51], v[190:193], v[138:141], v[48:51]
	v_mfma_f32_16x16x32_f16 v[44:47], v[190:193], v[162:165], v[44:47]
	v_mfma_f32_16x16x32_f16 v[40:43], v[198:201], v[138:141], v[40:43]
	v_mfma_f32_16x16x32_f16 v[36:39], v[198:201], v[162:165], v[36:39]
	v_mfma_f32_16x16x32_f16 v[64:67], v[88:91], v[142:145], v[64:67]
	v_mfma_f32_16x16x32_f16 v[60:63], v[88:91], v[174:177], v[60:63]
	v_mfma_f32_16x16x32_f16 v[56:59], v[96:99], v[142:145], v[56:59]
	v_mfma_f32_16x16x32_f16 v[52:55], v[96:99], v[174:177], v[52:55]
	v_mfma_f32_16x16x32_f16 v[48:51], v[194:197], v[142:145], v[48:51]
	v_mfma_f32_16x16x32_f16 v[44:47], v[194:197], v[174:177], v[44:47]
	v_mfma_f32_16x16x32_f16 v[40:43], v[202:205], v[142:145], v[40:43]
	v_mfma_f32_16x16x32_f16 v[36:39], v[202:205], v[174:177], v[36:39]
	s_setprio 0
	s_setprio 1
	v_mfma_f32_16x16x32_f16 v[32:35], v[84:87], v[100:103], v[32:35]
	v_mfma_f32_16x16x32_f16 v[28:31], v[84:87], v[108:111], v[28:31]
	v_mfma_f32_16x16x32_f16 v[24:27], v[92:95], v[100:103], v[24:27]
	v_mfma_f32_16x16x32_f16 v[20:23], v[92:95], v[108:111], v[20:23]
	v_mfma_f32_16x16x32_f16 v[16:19], v[190:193], v[100:103], v[16:19]
	v_mfma_f32_16x16x32_f16 v[12:15], v[190:193], v[108:111], v[12:15]
	v_mfma_f32_16x16x32_f16 v[8:11], v[198:201], v[100:103], v[8:11]
	v_mfma_f32_16x16x32_f16 v[4:7], v[198:201], v[108:111], v[4:7]
	v_mfma_f32_16x16x32_f16 v[136:139], v[88:91], v[104:107], v[32:35]
	v_mfma_f32_16x16x32_f16 v[140:143], v[88:91], v[116:119], v[28:31]
	v_mfma_f32_16x16x32_f16 v[162:165], v[96:99], v[104:107], v[24:27]
	v_mfma_f32_16x16x32_f16 v[174:177], v[96:99], v[116:119], v[20:23]
	v_mfma_f32_16x16x32_f16 v[206:209], v[194:197], v[104:107], v[16:19]
	v_mfma_f32_16x16x32_f16 v[190:193], v[194:197], v[116:119], v[12:15]
	v_mfma_f32_16x16x32_f16 v[194:197], v[202:205], v[104:107], v[8:11]
	v_mfma_f32_16x16x32_f16 v[198:201], v[202:205], v[116:119], v[4:7]
	s_setprio 0
	s_barrier
; #define LDA8(dst, b, h) _Pragma("unroll") for (int m = 0; m < 4; ++m) _Pragma("unroll") for (int k = 0; k < 2; ++k) \
;     dst[m][k] = *(const bf16x8*)((const char*)SA8(b, h) + lds_byte8(wr * 64 + m * 16 + fr, k * 32 + fq * 8))
; #define LDB8(dst, b, h) _Pragma("unroll") for (int n = 0; n < 2; ++n) _Pragma("unroll") for (int k = 0; k < 2; ++k) \
;     dst[n][k] = *(const bf16x8*)((const char*)SB8(b, h) + lds_byte8(wc * 32 + n * 16 + fr, k * 32 + fq * 8))
; #define WAIT_V8(n) asm volatile("s_waitcnt vmcnt(" #n ")" ::: "memory")
; #define WAIT_L8(n) asm volatile("s_waitcnt lgkmcnt(" #n ")" ::: "memory")
; #define BAR8 __builtin_amdgcn_s_barrier()
;     ...
;   { LDB8(B0, 1, 0); LDA8(At, 1, 0); WAIT_V8(2); BAR8; WAIT_L8(0); MMA8(0, 0, At, B0); BAR8;
;     LDB8(B1, 1, 1); WAIT_V8(0); BAR8; WAIT_L8(0); MMA8(0, 1, At, B1); BAR8;
;     LDA8(At, 1, 1); BAR8; WAIT_L8(0); MMA8(1, 0, At, B0); MMA8(1, 1, At, B1); BAR8; }
;   if (wr == 0) BAR8;
;   __syncthreads();
;     ...
;   if (t < 256) {
	ds_read_b128 v[202:205], v161
	ds_read_b128 v[218:221], v161 offset:1024
	ds_read_b128 v[226:229], v161 offset:2048
	ds_read_b128 v[230:233], v161 offset:3072
	ds_read_b128 v[8:11], v156 offset:32768
	ds_read_b128 v[12:15], v156 offset:33792
	ds_read_b128 v[16:19], v155 offset:32768
	ds_read_b128 v[24:27], v155 offset:33792
	ds_read_b128 v[28:31], v154 offset:32768
	ds_read_b128 v[32:35], v154 offset:33792
	ds_read_b128 v[238:241], v153 offset:32768
	ds_read_b128 v[242:245], v153 offset:33792
	s_waitcnt vmcnt(2)
	s_barrier
	s_waitcnt lgkmcnt(0)
	s_setprio 1
	s_waitcnt lgkmcnt(0)
	v_mfma_f32_16x16x32_f16 v[4:7], v[8:11], v[202:205], v[128:131]
	v_mfma_f32_16x16x32_f16 v[104:107], v[12:15], v[218:221], v[4:7]
	v_mfma_f32_16x16x32_f16 v[4:7], v[8:11], v[226:229], v[124:127]
	v_mfma_f32_16x16x32_f16 v[116:119], v[12:15], v[230:233], v[4:7]
	v_mfma_f32_16x16x32_f16 v[4:7], v[16:19], v[202:205], v[120:123]
	v_mfma_f32_16x16x32_f16 v[100:103], v[24:27], v[218:221], v[4:7]
	v_mfma_f32_16x16x32_f16 v[4:7], v[16:19], v[226:229], v[132:135]
	v_mfma_f32_16x16x32_f16 v[108:111], v[24:27], v[230:233], v[4:7]
	v_mfma_f32_16x16x32_f16 v[4:7], v[28:31], v[202:205], v[112:115]
	v_mfma_f32_16x16x32_f16 v[92:95], v[32:35], v[218:221], v[4:7]
	v_mfma_f32_16x16x32_f16 v[4:7], v[28:31], v[226:229], v[170:173]
	v_mfma_f32_16x16x32_f16 v[96:99], v[32:35], v[230:233], v[4:7]
	v_mfma_f32_16x16x32_f16 v[4:7], v[238:241], v[202:205], v[210:213]
	v_mfma_f32_16x16x32_f16 v[84:87], v[242:245], v[218:221], v[4:7]
	v_mfma_f32_16x16x32_f16 v[4:7], v[238:241], v[226:229], v[214:217]
	v_mfma_f32_16x16x32_f16 v[88:91], v[242:245], v[230:233], v[4:7]
	s_setprio 0
	s_barrier
	ds_read_b128 v[132:135], v158
	ds_read_b128 v[170:173], v158 offset:1024
	ds_read_b128 v[210:213], v158 offset:2048
	ds_read_b128 v[158:161], v158 offset:3072
	s_waitcnt vmcnt(0)
	s_barrier
	s_waitcnt lgkmcnt(0)
	s_setprio 1
	s_waitcnt lgkmcnt(0)
	v_mfma_f32_16x16x32_f16 v[4:7], v[8:11], v[132:135], v[166:169]
	v_mfma_f32_16x16x32_f16 v[8:11], v[8:11], v[210:213], v[178:181]
	v_mfma_f32_16x16x32_f16 v[4:7], v[12:15], v[170:173], v[4:7]
	v_mfma_f32_16x16x32_f16 v[20:23], v[12:15], v[158:161], v[8:11]
	v_mfma_f32_16x16x32_f16 v[8:11], v[16:19], v[132:135], v[182:185]
	v_mfma_f32_16x16x32_f16 v[12:15], v[16:19], v[210:213], v[186:189]
	v_mfma_f32_16x16x32_f16 v[8:11], v[24:27], v[170:173], v[8:11]
	v_mfma_f32_16x16x32_f16 v[24:27], v[24:27], v[158:161], v[12:15]
	v_mfma_f32_16x16x32_f16 v[12:15], v[28:31], v[132:135], v[80:83]
	v_mfma_f32_16x16x32_f16 v[16:19], v[28:31], v[210:213], v[76:79]
	v_mfma_f32_16x16x32_f16 v[12:15], v[32:35], v[170:173], v[12:15]
	v_mfma_f32_16x16x32_f16 v[28:31], v[32:35], v[158:161], v[16:19]
	v_mfma_f32_16x16x32_f16 v[16:19], v[238:241], v[132:135], v[72:75]
	v_mfma_f32_16x16x32_f16 v[32:35], v[238:241], v[210:213], v[68:71]
	v_mfma_f32_16x16x32_f16 v[16:19], v[242:245], v[170:173], v[16:19]
	v_mfma_f32_16x16x32_f16 v[32:35], v[242:245], v[158:161], v[32:35]
	s_setprio 0
	s_barrier
	ds_read_b128 v[166:169], v156 offset:49152
	ds_read_b128 v[178:181], v156 offset:50176
	ds_read_b128 v[182:185], v155 offset:49152
	ds_read_b128 v[186:189], v155 offset:50176
	ds_read_b128 v[214:217], v154 offset:49152
	ds_read_b128 v[154:157], v154 offset:50176
	ds_read_b128 v[238:241], v153 offset:49152
	ds_read_b128 v[150:153], v153 offset:50176
	s_barrier
	s_waitcnt lgkmcnt(0)
	s_setprio 1
	s_waitcnt lgkmcnt(0)
	v_mfma_f32_16x16x32_f16 v[64:67], v[166:169], v[202:205], v[64:67]
	v_mfma_f32_16x16x32_f16 v[60:63], v[166:169], v[226:229], v[60:63]
	v_mfma_f32_16x16x32_f16 v[56:59], v[182:185], v[202:205], v[56:59]
	v_mfma_f32_16x16x32_f16 v[52:55], v[182:185], v[226:229], v[52:55]
	v_mfma_f32_16x16x32_f16 v[48:51], v[214:217], v[202:205], v[48:51]
	v_mfma_f32_16x16x32_f16 v[44:47], v[214:217], v[226:229], v[44:47]
	v_mfma_f32_16x16x32_f16 v[40:43], v[238:241], v[202:205], v[40:43]
	v_mfma_f32_16x16x32_f16 v[36:39], v[238:241], v[226:229], v[36:39]
	v_mfma_f32_16x16x32_f16 v[128:131], v[178:181], v[218:221], v[64:67]
	v_mfma_f32_16x16x32_f16 v[124:127], v[178:181], v[230:233], v[60:63]
	v_mfma_f32_16x16x32_f16 v[120:123], v[186:189], v[218:221], v[56:59]
	v_mfma_f32_16x16x32_f16 v[112:115], v[186:189], v[230:233], v[52:55]
	v_mfma_f32_16x16x32_f16 v[80:83], v[154:157], v[218:221], v[48:51]
	v_mfma_f32_16x16x32_f16 v[76:79], v[154:157], v[230:233], v[44:47]
	v_mfma_f32_16x16x32_f16 v[72:75], v[150:153], v[218:221], v[40:43]
	v_mfma_f32_16x16x32_f16 v[68:71], v[150:153], v[230:233], v[36:39]
	s_setprio 0
	s_setprio 1
	v_mfma_f32_16x16x32_f16 v[36:39], v[166:169], v[132:135], v[136:139]
	v_mfma_f32_16x16x32_f16 v[64:67], v[178:181], v[170:173], v[36:39]
	v_mfma_f32_16x16x32_f16 v[36:39], v[166:169], v[210:213], v[140:143]
	v_mfma_f32_16x16x32_f16 v[60:63], v[178:181], v[158:161], v[36:39]
	v_mfma_f32_16x16x32_f16 v[36:39], v[182:185], v[132:135], v[162:165]
	v_mfma_f32_16x16x32_f16 v[56:59], v[186:189], v[170:173], v[36:39]
	v_mfma_f32_16x16x32_f16 v[36:39], v[182:185], v[210:213], v[174:177]
	v_mfma_f32_16x16x32_f16 v[52:55], v[186:189], v[158:161], v[36:39]
	v_mfma_f32_16x16x32_f16 v[36:39], v[214:217], v[132:135], v[206:209]
	v_mfma_f32_16x16x32_f16 v[48:51], v[154:157], v[170:173], v[36:39]
	v_mfma_f32_16x16x32_f16 v[36:39], v[214:217], v[210:213], v[190:193]
	v_mfma_f32_16x16x32_f16 v[44:47], v[154:157], v[158:161], v[36:39]
	v_mfma_f32_16x16x32_f16 v[36:39], v[238:241], v[132:135], v[194:197]
	v_mfma_f32_16x16x32_f16 v[40:43], v[150:153], v[170:173], v[36:39]
	v_mfma_f32_16x16x32_f16 v[36:39], v[238:241], v[210:213], v[198:201]
	v_mfma_f32_16x16x32_f16 v[36:39], v[150:153], v[158:161], v[36:39]
	s_setprio 0
	s_movk_i32 s8, 0x100
	v_cmp_gt_u32_e32 vcc, s8, v3
	s_barrier
	s_and_saveexec_b64 s[8:9], vcc
	s_cbranch_execz .LBB0_1018
	s_barrier

; #define LDA8(dst, b, h) _Pragma("unroll") for (int m = 0; m < 4; ++m) _Pragma("unroll") for (int k = 0; k < 2; ++k) \
;     dst[m][k] = *(const bf16x8*)((const char*)SA8(b, h) + lds_byte8(wr * 64 + m * 16 + fr, k * 32 + fq * 8))
; #define LDB8(dst, b, h) _Pragma("unroll") for (int n = 0; n < 2; ++n) _Pragma("unroll") for (int k = 0; k < 2; ++k) \
;     dst[n][k] = *(const bf16x8*)((const char*)SB8(b, h) + lds_byte8(wc * 32 + n * 16 + fr, k * 32 + fq * 8))
; #define WAIT_V8(n) asm volatile("s_waitcnt vmcnt(" #n ")" ::: "memory")
; #define WAIT_L8(n) asm volatile("s_waitcnt lgkmcnt(" #n ")" ::: "memory")
; #define BAR8 __builtin_amdgcn_s_barrier()
; #define SCHED8 __builtin_amdgcn_sched_barrier(0)
;     ...
;     STAGE8(SB8(0, 0), Bt, K, bcol, 0); STAGE8(SA8(0, 0), A, lda, brow, 0);
;     STAGE8(SB8(0, 1), Bt, K, bcol + 128, 0); STAGE8(SA8(0, 1), A, lda, brow + 128, 0);
;   }
;   if (wr == 1) BAR8;
;   WAIT_V8(4); BAR8;
;   STAGE8(SB8(1, 0), Bt, K, bcol, 1); STAGE8(SA8(1, 0), A, lda, brow, 1); STAGE8(SB8(1, 1), Bt, K, bcol + 128, 1);
;   WAIT_V8(6); BAR8;
;   for (int tt = 0; tt < nt - 2; tt += 2) {
;     LDB8(B0, 0, 0); SCHED8; LDA8(At, 0, 0); STAGE8(SA8(1, 1), A, lda, brow + 128, tt + 1);
;     WAIT_L8(8); BAR8; WAIT_L8(0); MMA8(0, 0, At, B0); BAR8; SCHED8;
.LBB0_1151:
	s_or_b64 exec, exec, s[12:13]
	s_lshl_b32 s29, s20, 10
	v_add_u32_e32 v164, 0x18000, v150
	s_and_b32 s36, s29, 0xfc0000
	s_mov_b64 s[38:39], 0x80
	v_readfirstlane_b32 s29, v164
	v_add_u32_e32 v165, 0x1a000, v150
	v_lshl_add_u64 v[14:15], v[14:15], 0, s[38:39]
	s_mov_b32 m0, s29
	v_readfirstlane_b32 s29, v165
	v_add_u32_e32 v166, 0x8000, v150
	s_waitcnt vmcnt(4)
	s_barrier
	global_load_lds_dwordx4 v[14:15], off
	v_lshl_add_u64 v[14:15], v[18:19], 0, s[38:39]
	s_mov_b32 m0, s29
	v_readfirstlane_b32 s29, v166
	v_add_u32_e32 v168, 0xa000, v150
	global_load_lds_dwordx4 v[14:15], off
	v_lshl_add_u64 v[14:15], v[20:21], 0, s[38:39]
	s_mov_b32 m0, s29
	v_readfirstlane_b32 s29, v168
	v_add_u32_e32 v169, 0x1c000, v150
	global_load_lds_dwordx4 v[14:15], off
	v_lshl_add_u64 v[14:15], v[22:23], 0, s[38:39]
	s_mov_b32 m0, s29
	v_readfirstlane_b32 s29, v169
	v_add_u32_e32 v170, 0x1e000, v150
	global_load_lds_dwordx4 v[14:15], off
	v_lshl_add_u64 v[14:15], v[26:27], 0, s[38:39]
	s_mov_b32 m0, s29
	v_readfirstlane_b32 s29, v170
	global_load_lds_dwordx4 v[14:15], off
	v_lshl_add_u64 v[14:15], v[28:29], 0, s[38:39]
	s_mov_b32 m0, s29
	v_and_b32_e32 v147, 15, v3
	global_load_lds_dwordx4 v[14:15], off
	v_bfe_u32 v148, v3, 4, 2
	v_lshlrev_b32_e32 v14, 4, v148
	v_lshlrev_b32_e32 v15, 6, v147
	v_lshlrev_b32_e32 v18, 2, v3
	v_lshlrev_b64 v[136:137], 9, v[16:17]
	v_or_b32_e32 v17, v14, v15
	v_and_b32_e32 v18, 32, v18
	s_mov_b32 s29, 0x10000
	s_and_b32 s12, s21, 0xffffff00
	v_bitop3_b32 v20, v17, s29, v18 bitop3:0xde
	s_mov_b32 s29, 0x14000
	s_ashr_i32 s13, s12, 31
	v_readlane_b32 s40, v254, 35
	v_bitop3_b32 v19, v14, v18, v15 bitop3:0x36
	v_bitop3_b32 v21, v17, s29, v18 bitop3:0xde
	s_mov_b32 s29, 0x18000
	v_lshlrev_b32_e32 v15, 6, v3
	s_lshl_b64 s[12:13], s[12:13], 10
	s_mov_b32 s37, s40
	v_bitop3_b32 v22, v17, s29, v18 bitop3:0xde
	s_mov_b32 s29, 0x1c000
	v_and_b32_e32 v15, 0x3c0, v15
	v_bitop3_b32 v17, v17, s29, v18 bitop3:0xde
	v_bitop3_b32 v18, v15, v18, v14 bitop3:0x36
	v_lshl_add_u64 v[14:15], s[12:13], 0, v[6:7]
	v_lshl_add_u64 v[6:7], s[36:37], 0, v[6:7]
	v_lshl_add_u64 v[14:15], v[14:15], 0, v[8:9]
	v_lshl_add_u64 v[6:7], v[6:7], 0, v[8:9]
	v_bfe_u32 v146, v3, 6, 2
	s_waitcnt vmcnt(6)
	v_lshlrev_b32_e32 v149, 6, v5
	v_lshlrev_b32_e32 v5, 13, v5
	v_lshl_add_u64 v[138:139], s[4:5], 0, v[14:15]
	v_lshl_add_u64 v[14:15], s[12:13], 0, v[10:11]
	v_lshl_add_u64 v[142:143], s[2:3], 0, v[6:7]
	v_lshl_add_u64 v[6:7], s[36:37], 0, v[10:11]
	v_lshlrev_b64 v[134:135], 9, v[24:25]
	v_readlane_b32 s41, v254, 36
	v_readlane_b32 s42, v254, 37
	v_readlane_b32 s43, v254, 38
	v_lshlrev_b32_e32 v16, 12, v146
	v_or_b32_e32 v23, 0x800, v5
	v_or_b32_e32 v24, 0x1000, v5
	v_or_b32_e32 v25, 0x1800, v5
	v_lshl_add_u64 v[14:15], v[14:15], 0, v[12:13]
	v_lshl_add_u64 v[6:7], v[6:7], 0, v[12:13]
	v_lshl_add_u64 v[140:141], s[4:5], 0, v[14:15]
	v_lshl_add_u64 v[144:145], s[2:3], 0, v[6:7]
	s_mov_b32 s29, -2
	s_mov_b64 s[12:13], 0
	v_add_u32_e32 v171, v20, v16
	v_add_u32_e32 v156, v19, v5
	v_add_u32_e32 v155, v18, v23
	v_add_u32_e32 v154, v18, v24
	v_add_u32_e32 v153, v18, v25
	v_add_u32_e32 v167, v21, v16
	v_add_u32_e32 v160, v22, v16
	v_add_u32_e32 v158, v17, v16
	s_mov_b64 s[36:37], 0x3020080
	s_mov_b64 s[38:39], 0xc9a0100
	s_mov_b64 s[40:41], 0x3000100
	s_mov_b64 s[42:43], 0xc9c0100
	s_mov_b64 s[44:45], 0x3020100
	s_mov_b64 s[46:47], 0xc9a0180
	s_mov_b64 s[48:49], 0x3000180
	s_mov_b64 s[50:51], 0xc9c0180
	s_barrier
	ds_read_b128 v[174:177], v171
	ds_read_b128 v[178:181], v171 offset:1024
	ds_read_b128 v[182:185], v171 offset:2048
	ds_read_b128 v[186:189], v171 offset:3072
	v_add_u32_e32 v172, 0xc000, v150
	v_lshl_add_u64 v[222:223], v[142:143], 0, s[12:13]
	v_readfirstlane_b32 s31, v172
	v_add_u32_e32 v173, 0xe000, v150
	v_lshl_add_u64 v[226:227], v[222:223], 0, s[36:37]
	s_mov_b32 m0, s31
	v_lshl_add_u64 v[236:237], v[144:145], 0, s[12:13]
	v_readfirstlane_b32 s31, v173
	ds_read_b128 v[190:193], v156
	ds_read_b128 v[194:197], v156 offset:1024
	ds_read_b128 v[198:201], v155
	ds_read_b128 v[202:205], v155 offset:1024
	ds_read_b128 v[206:209], v154
	ds_read_b128 v[210:213], v154 offset:1024
	ds_read_b128 v[214:217], v153
	ds_read_b128 v[218:221], v153 offset:1024
	global_load_lds_dwordx4 v[226:227], off
	v_lshl_add_u64 v[226:227], v[236:237], 0, s[36:37]
	s_mov_b32 m0, s31
	s_nop 0
	global_load_lds_dwordx4 v[226:227], off
	s_waitcnt lgkmcnt(8)
	s_barrier
	s_waitcnt lgkmcnt(0)
	s_setprio 1
	s_waitcnt lgkmcnt(0)
	v_mfma_f32_16x16x32_bf16 v[128:131], v[190:193], v[174:177], 0
	v_mfma_f32_16x16x32_bf16 v[124:127], v[190:193], v[182:185], 0
	v_mfma_f32_16x16x32_bf16 v[120:123], v[198:201], v[174:177], 0
	v_mfma_f32_16x16x32_bf16 v[116:119], v[198:201], v[182:185], 0
	v_mfma_f32_16x16x32_bf16 v[112:115], v[206:209], v[174:177], 0
	v_mfma_f32_16x16x32_bf16 v[108:111], v[206:209], v[182:185], 0
	v_mfma_f32_16x16x32_bf16 v[104:107], v[214:217], v[174:177], 0
	v_mfma_f32_16x16x32_bf16 v[100:103], v[214:217], v[182:185], 0
	v_mfma_f32_16x16x32_bf16 v[128:131], v[194:197], v[178:181], v[128:131]
	v_mfma_f32_16x16x32_bf16 v[124:127], v[194:197], v[186:189], v[124:127]
	v_mfma_f32_16x16x32_bf16 v[120:123], v[202:205], v[178:181], v[120:123]
	v_mfma_f32_16x16x32_bf16 v[116:119], v[202:205], v[186:189], v[116:119]
	v_mfma_f32_16x16x32_bf16 v[112:115], v[210:213], v[178:181], v[112:115]
	v_mfma_f32_16x16x32_bf16 v[108:111], v[210:213], v[186:189], v[108:111]
	v_mfma_f32_16x16x32_bf16 v[104:107], v[218:221], v[178:181], v[104:107]
	v_mfma_f32_16x16x32_bf16 v[100:103], v[218:221], v[186:189], v[100:103]
	s_setprio 0
	s_barrier
; #define LDA8(dst, b, h) _Pragma("unroll") for (int m = 0; m < 4; ++m) _Pragma("unroll") for (int k = 0; k < 2; ++k) \
;     dst[m][k] = *(const bf16x8*)((const char*)SA8(b, h) + lds_byte8(wr * 64 + m * 16 + fr, k * 32 + fq * 8))
; #define LDB8(dst, b, h) _Pragma("unroll") for (int n = 0; n < 2; ++n) _Pragma("unroll") for (int k = 0; k < 2; ++k) \
;     dst[n][k] = *(const bf16x8*)((const char*)SB8(b, h) + lds_byte8(wc * 32 + n * 16 + fr, k * 32 + fq * 8))
; #define WAIT_V8(n) asm volatile("s_waitcnt vmcnt(" #n ")" ::: "memory")
; #define WAIT_L8(n) asm volatile("s_waitcnt lgkmcnt(" #n ")" ::: "memory")
; #define BAR8 __builtin_amdgcn_s_barrier()
; #define SCHED8 __builtin_amdgcn_sched_barrier(0)
;     ...
;     LDB8(B1, 0, 1); STAGE8(SB8(0, 0), Bt, K, bcol, tt + 2);
;     BAR8; WAIT_L8(0); MMA8(0, 1, At, B1); BAR8;
;     LDA8(At, 0, 1); STAGE8(SA8(0, 0), A, lda, brow, tt + 2);
;     BAR8; WAIT_L8(0); MMA8(1, 0, At, B0); BAR8; SCHED8;
;     STAGE8(SB8(0, 1), Bt, K, bcol + 128, tt + 2);
;     WAIT_V8(6); BAR8; MMA8(1, 1, At, B1); BAR8;
;     LDB8(B0, 1, 0); SCHED8; LDA8(At, 1, 0); STAGE8(SA8(0, 1), A, lda, brow + 128, tt + 2);
;     WAIT_L8(8); BAR8; WAIT_L8(0); MMA8(0, 0, At, B0); BAR8; SCHED8;
	v_lshl_add_u64 v[246:247], v[138:139], 0, s[12:13]
	v_readfirstlane_b32 s31, v151
	v_lshl_add_u64 v[248:249], v[246:247], 0, s[38:39]
	s_mov_b32 m0, s31
	ds_read_b128 v[226:229], v167
	ds_read_b128 v[230:233], v167 offset:1024
	ds_read_b128 v[238:241], v167 offset:2048
	ds_read_b128 v[242:245], v167 offset:3072
	global_load_lds_dwordx4 v[248:249], off
	v_lshl_add_u64 v[248:249], v[140:141], 0, s[12:13]
	v_readfirstlane_b32 s31, v157
	v_lshl_add_u64 v[250:251], v[248:249], 0, s[38:39]
	s_mov_b32 m0, s31
	s_nop 0
	global_load_lds_dwordx4 v[250:251], off
	s_barrier
	s_waitcnt lgkmcnt(0)
	s_setprio 1
	s_waitcnt lgkmcnt(0)
	v_mfma_f32_16x16x32_bf16 v[96:99], v[190:193], v[226:229], 0
	v_mfma_f32_16x16x32_bf16 v[92:95], v[190:193], v[238:241], 0
	v_mfma_f32_16x16x32_bf16 v[88:91], v[198:201], v[226:229], 0
	v_mfma_f32_16x16x32_bf16 v[84:87], v[198:201], v[238:241], 0
	v_mfma_f32_16x16x32_bf16 v[80:83], v[206:209], v[226:229], 0
	v_mfma_f32_16x16x32_bf16 v[76:79], v[206:209], v[238:241], 0
	v_mfma_f32_16x16x32_bf16 v[72:75], v[214:217], v[226:229], 0
	v_mfma_f32_16x16x32_bf16 v[68:71], v[214:217], v[238:241], 0
	v_mfma_f32_16x16x32_bf16 v[96:99], v[194:197], v[230:233], v[96:99]
	v_mfma_f32_16x16x32_bf16 v[92:95], v[194:197], v[242:245], v[92:95]
	v_mfma_f32_16x16x32_bf16 v[88:91], v[202:205], v[230:233], v[88:91]
	v_mfma_f32_16x16x32_bf16 v[84:87], v[202:205], v[242:245], v[84:87]
	v_mfma_f32_16x16x32_bf16 v[80:83], v[210:213], v[230:233], v[80:83]
	v_mfma_f32_16x16x32_bf16 v[76:79], v[210:213], v[242:245], v[76:79]
	v_mfma_f32_16x16x32_bf16 v[72:75], v[218:221], v[230:233], v[72:75]
	v_mfma_f32_16x16x32_bf16 v[68:71], v[218:221], v[242:245], v[68:71]
	s_setprio 0
	v_readfirstlane_b32 s31, v150
	v_lshl_add_u64 v[250:251], v[222:223], 0, s[40:41]
	s_mov_b32 m0, s31
	v_readfirstlane_b32 s31, v152
	s_barrier
	ds_read_b128 v[190:193], v156 offset:16384
	ds_read_b128 v[194:197], v156 offset:17408
	ds_read_b128 v[198:201], v155 offset:16384
	ds_read_b128 v[202:205], v155 offset:17408
	ds_read_b128 v[206:209], v154 offset:16384
	ds_read_b128 v[210:213], v154 offset:17408
	ds_read_b128 v[214:217], v153 offset:16384
	ds_read_b128 v[218:221], v153 offset:17408
	global_load_lds_dwordx4 v[250:251], off
	v_lshl_add_u64 v[250:251], v[236:237], 0, s[40:41]
	s_mov_b32 m0, s31
	s_nop 0
	global_load_lds_dwordx4 v[250:251], off
	s_barrier
	s_waitcnt lgkmcnt(0)
	s_setprio 1
	s_waitcnt lgkmcnt(0)
	v_mfma_f32_16x16x32_bf16 v[64:67], v[190:193], v[174:177], 0
	v_mfma_f32_16x16x32_bf16 v[60:63], v[190:193], v[182:185], 0
	v_mfma_f32_16x16x32_bf16 v[56:59], v[198:201], v[174:177], 0
	v_mfma_f32_16x16x32_bf16 v[52:55], v[198:201], v[182:185], 0
	v_mfma_f32_16x16x32_bf16 v[48:51], v[206:209], v[174:177], 0
	v_mfma_f32_16x16x32_bf16 v[44:47], v[206:209], v[182:185], 0
	v_mfma_f32_16x16x32_bf16 v[40:43], v[214:217], v[174:177], 0
	v_mfma_f32_16x16x32_bf16 v[36:39], v[214:217], v[182:185], 0
	v_mfma_f32_16x16x32_bf16 v[64:67], v[194:197], v[178:181], v[64:67]
	v_mfma_f32_16x16x32_bf16 v[60:63], v[194:197], v[186:189], v[60:63]
	v_mfma_f32_16x16x32_bf16 v[56:59], v[202:205], v[178:181], v[56:59]
	v_mfma_f32_16x16x32_bf16 v[52:55], v[202:205], v[186:189], v[52:55]
	v_mfma_f32_16x16x32_bf16 v[48:51], v[210:213], v[178:181], v[48:51]
	v_mfma_f32_16x16x32_bf16 v[44:47], v[210:213], v[186:189], v[44:47]
	v_mfma_f32_16x16x32_bf16 v[40:43], v[218:221], v[178:181], v[40:43]
	v_mfma_f32_16x16x32_bf16 v[36:39], v[218:221], v[186:189], v[36:39]
	s_setprio 0
	s_barrier
	v_readfirstlane_b32 s31, v159
	v_lshl_add_u64 v[174:175], v[246:247], 0, s[42:43]
	s_mov_b32 m0, s31
	v_readfirstlane_b32 s31, v161
	global_load_lds_dwordx4 v[174:175], off
	v_lshl_add_u64 v[174:175], v[248:249], 0, s[42:43]
	s_mov_b32 m0, s31
	s_nop 0
	global_load_lds_dwordx4 v[174:175], off
	s_waitcnt vmcnt(6)
	s_barrier
	s_setprio 1
	v_mfma_f32_16x16x32_bf16 v[32:35], v[190:193], v[226:229], 0
	v_mfma_f32_16x16x32_bf16 v[28:31], v[190:193], v[238:241], 0
	v_mfma_f32_16x16x32_bf16 v[24:27], v[198:201], v[226:229], 0
	v_mfma_f32_16x16x32_bf16 v[20:23], v[198:201], v[238:241], 0
	v_mfma_f32_16x16x32_bf16 v[16:19], v[206:209], v[226:229], 0
	v_mfma_f32_16x16x32_bf16 v[12:15], v[206:209], v[238:241], 0
	v_mfma_f32_16x16x32_bf16 v[8:11], v[214:217], v[226:229], 0
	v_mfma_f32_16x16x32_bf16 v[4:7], v[214:217], v[238:241], 0
	v_mfma_f32_16x16x32_bf16 v[32:35], v[194:197], v[230:233], v[32:35]
	v_mfma_f32_16x16x32_bf16 v[28:31], v[194:197], v[242:245], v[28:31]
	v_mfma_f32_16x16x32_bf16 v[24:27], v[202:205], v[230:233], v[24:27]
	v_mfma_f32_16x16x32_bf16 v[20:23], v[202:205], v[242:245], v[20:23]
	v_mfma_f32_16x16x32_bf16 v[16:19], v[210:213], v[230:233], v[16:19]
	v_mfma_f32_16x16x32_bf16 v[12:15], v[210:213], v[242:245], v[12:15]
	v_mfma_f32_16x16x32_bf16 v[8:11], v[218:221], v[230:233], v[8:11]
	v_mfma_f32_16x16x32_bf16 v[4:7], v[218:221], v[242:245], v[4:7]
	s_setprio 0
	s_barrier
	ds_read_b128 v[174:177], v160
	ds_read_b128 v[178:181], v160 offset:1024
	ds_read_b128 v[182:185], v160 offset:2048
	ds_read_b128 v[186:189], v160 offset:3072
	v_readfirstlane_b32 s31, v162
	v_lshl_add_u64 v[226:227], v[222:223], 0, s[44:45]
	s_mov_b32 m0, s31
	v_readfirstlane_b32 s31, v163
	ds_read_b128 v[190:193], v156 offset:32768
	ds_read_b128 v[194:197], v156 offset:33792
	ds_read_b128 v[198:201], v155 offset:32768
	ds_read_b128 v[202:205], v155 offset:33792
	ds_read_b128 v[206:209], v154 offset:32768
	ds_read_b128 v[210:213], v154 offset:33792
	ds_read_b128 v[214:217], v153 offset:32768
	ds_read_b128 v[218:221], v153 offset:33792
	global_load_lds_dwordx4 v[226:227], off
	v_lshl_add_u64 v[226:227], v[236:237], 0, s[44:45]
	s_mov_b32 m0, s31
	s_nop 0
	global_load_lds_dwordx4 v[226:227], off
	s_waitcnt lgkmcnt(8)
	s_barrier
; #define LDA8(dst, b, h) _Pragma("unroll") for (int m = 0; m < 4; ++m) _Pragma("unroll") for (int k = 0; k < 2; ++k) \
;     dst[m][k] = *(const bf16x8*)((const char*)SA8(b, h) + lds_byte8(wr * 64 + m * 16 + fr, k * 32 + fq * 8))
; #define LDB8(dst, b, h) _Pragma("unroll") for (int n = 0; n < 2; ++n) _Pragma("unroll") for (int k = 0; k < 2; ++k) \
;     dst[n][k] = *(const bf16x8*)((const char*)SB8(b, h) + lds_byte8(wc * 32 + n * 16 + fr, k * 32 + fq * 8))
; #define WAIT_V8(n) asm volatile("s_waitcnt vmcnt(" #n ")" ::: "memory")
; #define WAIT_L8(n) asm volatile("s_waitcnt lgkmcnt(" #n ")" ::: "memory")
; #define BAR8 __builtin_amdgcn_s_barrier()
; #define SCHED8 __builtin_amdgcn_sched_barrier(0)
;     ...
;     WAIT_L8(8); BAR8; WAIT_L8(0); MMA8(0, 0, At, B0); BAR8; SCHED8;
;     LDB8(B1, 1, 1); STAGE8(SB8(1, 0), Bt, K, bcol, tt + 3);
;     BAR8; WAIT_L8(0); MMA8(0, 1, At, B1); BAR8;
;     LDA8(At, 1, 1); STAGE8(SA8(1, 0), A, lda, brow, tt + 3);
;     BAR8; WAIT_L8(0); MMA8(1, 0, At, B0); BAR8; SCHED8;
;     STAGE8(SB8(1, 1), Bt, K, bcol + 128, tt + 3);
;     WAIT_V8(6); BAR8; MMA8(1, 1, At, B1); BAR8;
;   }
	s_waitcnt lgkmcnt(0)
	s_setprio 1
	s_waitcnt lgkmcnt(0)
	v_mfma_f32_16x16x32_bf16 v[128:131], v[190:193], v[174:177], v[128:131]
	v_mfma_f32_16x16x32_bf16 v[124:127], v[190:193], v[182:185], v[124:127]
	v_mfma_f32_16x16x32_bf16 v[120:123], v[198:201], v[174:177], v[120:123]
	v_mfma_f32_16x16x32_bf16 v[116:119], v[198:201], v[182:185], v[116:119]
	v_mfma_f32_16x16x32_bf16 v[112:115], v[206:209], v[174:177], v[112:115]
	v_mfma_f32_16x16x32_bf16 v[108:111], v[206:209], v[182:185], v[108:111]
	v_mfma_f32_16x16x32_bf16 v[104:107], v[214:217], v[174:177], v[104:107]
	v_mfma_f32_16x16x32_bf16 v[100:103], v[214:217], v[182:185], v[100:103]
	v_mfma_f32_16x16x32_bf16 v[128:131], v[194:197], v[178:181], v[128:131]
	v_mfma_f32_16x16x32_bf16 v[124:127], v[194:197], v[186:189], v[124:127]
	v_mfma_f32_16x16x32_bf16 v[120:123], v[202:205], v[178:181], v[120:123]
	v_mfma_f32_16x16x32_bf16 v[116:119], v[202:205], v[186:189], v[116:119]
	v_mfma_f32_16x16x32_bf16 v[112:115], v[210:213], v[178:181], v[112:115]
	v_mfma_f32_16x16x32_bf16 v[108:111], v[210:213], v[186:189], v[108:111]
	v_mfma_f32_16x16x32_bf16 v[104:107], v[218:221], v[178:181], v[104:107]
	v_mfma_f32_16x16x32_bf16 v[100:103], v[218:221], v[186:189], v[100:103]
	s_setprio 0
	s_barrier
	v_readfirstlane_b32 s31, v164
	v_lshl_add_u64 v[250:251], v[246:247], 0, s[46:47]
	s_mov_b32 m0, s31
	v_readfirstlane_b32 s31, v165
	ds_read_b128 v[226:229], v158
	ds_read_b128 v[230:233], v158 offset:1024
	ds_read_b128 v[238:241], v158 offset:2048
	ds_read_b128 v[242:245], v158 offset:3072
	global_load_lds_dwordx4 v[250:251], off
	v_lshl_add_u64 v[250:251], v[248:249], 0, s[46:47]
	s_mov_b32 m0, s31
	s_nop 0
	global_load_lds_dwordx4 v[250:251], off
	s_barrier
	s_waitcnt lgkmcnt(0)
	s_setprio 1
	s_waitcnt lgkmcnt(0)
	v_mfma_f32_16x16x32_bf16 v[96:99], v[190:193], v[226:229], v[96:99]
	v_mfma_f32_16x16x32_bf16 v[92:95], v[190:193], v[238:241], v[92:95]
	v_mfma_f32_16x16x32_bf16 v[88:91], v[198:201], v[226:229], v[88:91]
	v_mfma_f32_16x16x32_bf16 v[84:87], v[198:201], v[238:241], v[84:87]
	v_mfma_f32_16x16x32_bf16 v[80:83], v[206:209], v[226:229], v[80:83]
	v_mfma_f32_16x16x32_bf16 v[76:79], v[206:209], v[238:241], v[76:79]
	v_mfma_f32_16x16x32_bf16 v[72:75], v[214:217], v[226:229], v[72:75]
	v_mfma_f32_16x16x32_bf16 v[68:71], v[214:217], v[238:241], v[68:71]
	v_mfma_f32_16x16x32_bf16 v[96:99], v[194:197], v[230:233], v[96:99]
	v_mfma_f32_16x16x32_bf16 v[92:95], v[194:197], v[242:245], v[92:95]
	v_mfma_f32_16x16x32_bf16 v[88:91], v[202:205], v[230:233], v[88:91]
	v_mfma_f32_16x16x32_bf16 v[84:87], v[202:205], v[242:245], v[84:87]
	v_mfma_f32_16x16x32_bf16 v[80:83], v[210:213], v[230:233], v[80:83]
	v_mfma_f32_16x16x32_bf16 v[76:79], v[210:213], v[242:245], v[76:79]
	v_mfma_f32_16x16x32_bf16 v[72:75], v[218:221], v[230:233], v[72:75]
	v_mfma_f32_16x16x32_bf16 v[68:71], v[218:221], v[242:245], v[68:71]
	s_setprio 0
	v_readfirstlane_b32 s31, v166
	v_lshl_add_u64 v[222:223], v[222:223], 0, s[48:49]
	s_mov_b32 m0, s31
	v_readfirstlane_b32 s31, v168
	s_barrier
	ds_read_b128 v[190:193], v156 offset:49152
	ds_read_b128 v[194:197], v156 offset:50176
	ds_read_b128 v[198:201], v155 offset:49152
	ds_read_b128 v[202:205], v155 offset:50176
	ds_read_b128 v[206:209], v154 offset:49152
	ds_read_b128 v[210:213], v154 offset:50176
	ds_read_b128 v[214:217], v153 offset:49152
	ds_read_b128 v[218:221], v153 offset:50176
	global_load_lds_dwordx4 v[222:223], off
	v_lshl_add_u64 v[222:223], v[236:237], 0, s[48:49]
	s_mov_b32 m0, s31
	s_nop 0
	global_load_lds_dwordx4 v[222:223], off
	s_barrier
	s_waitcnt lgkmcnt(0)
	s_setprio 1
	s_waitcnt lgkmcnt(0)
	v_mfma_f32_16x16x32_bf16 v[64:67], v[190:193], v[174:177], v[64:67]
	v_mfma_f32_16x16x32_bf16 v[60:63], v[190:193], v[182:185], v[60:63]
	v_mfma_f32_16x16x32_bf16 v[56:59], v[198:201], v[174:177], v[56:59]
	v_mfma_f32_16x16x32_bf16 v[52:55], v[198:201], v[182:185], v[52:55]
	v_mfma_f32_16x16x32_bf16 v[48:51], v[206:209], v[174:177], v[48:51]
	v_mfma_f32_16x16x32_bf16 v[44:47], v[206:209], v[182:185], v[44:47]
	v_mfma_f32_16x16x32_bf16 v[40:43], v[214:217], v[174:177], v[40:43]
	v_mfma_f32_16x16x32_bf16 v[36:39], v[214:217], v[182:185], v[36:39]
	v_mfma_f32_16x16x32_bf16 v[64:67], v[194:197], v[178:181], v[64:67]
	v_mfma_f32_16x16x32_bf16 v[60:63], v[194:197], v[186:189], v[60:63]
	v_mfma_f32_16x16x32_bf16 v[56:59], v[202:205], v[178:181], v[56:59]
	v_mfma_f32_16x16x32_bf16 v[52:55], v[202:205], v[186:189], v[52:55]
	v_mfma_f32_16x16x32_bf16 v[48:51], v[210:213], v[178:181], v[48:51]
	v_mfma_f32_16x16x32_bf16 v[44:47], v[210:213], v[186:189], v[44:47]
	v_mfma_f32_16x16x32_bf16 v[40:43], v[218:221], v[178:181], v[40:43]
	v_mfma_f32_16x16x32_bf16 v[36:39], v[218:221], v[186:189], v[36:39]
	s_setprio 0
	s_barrier
	v_readfirstlane_b32 s31, v169
	v_lshl_add_u64 v[174:175], v[246:247], 0, s[50:51]
	s_mov_b32 m0, s31
	v_readfirstlane_b32 s31, v170
	global_load_lds_dwordx4 v[174:175], off
	v_lshl_add_u64 v[174:175], v[248:249], 0, s[50:51]
	s_mov_b32 m0, s31
	s_nop 0
	global_load_lds_dwordx4 v[174:175], off
	s_waitcnt vmcnt(6)
	s_barrier
	s_setprio 1
	v_mfma_f32_16x16x32_bf16 v[32:35], v[190:193], v[226:229], v[32:35]
	v_mfma_f32_16x16x32_bf16 v[28:31], v[190:193], v[238:241], v[28:31]
	v_mfma_f32_16x16x32_bf16 v[24:27], v[198:201], v[226:229], v[24:27]
	v_mfma_f32_16x16x32_bf16 v[20:23], v[198:201], v[238:241], v[20:23]
	v_mfma_f32_16x16x32_bf16 v[16:19], v[206:209], v[226:229], v[16:19]
	v_mfma_f32_16x16x32_bf16 v[12:15], v[206:209], v[238:241], v[12:15]
	v_mfma_f32_16x16x32_bf16 v[8:11], v[214:217], v[226:229], v[8:11]
	v_mfma_f32_16x16x32_bf16 v[4:7], v[214:217], v[238:241], v[4:7]
	v_mfma_f32_16x16x32_bf16 v[32:35], v[194:197], v[230:233], v[32:35]
	v_mfma_f32_16x16x32_bf16 v[28:31], v[194:197], v[242:245], v[28:31]
	v_mfma_f32_16x16x32_bf16 v[24:27], v[202:205], v[230:233], v[24:27]
	v_mfma_f32_16x16x32_bf16 v[20:23], v[202:205], v[242:245], v[20:23]
	v_mfma_f32_16x16x32_bf16 v[16:19], v[210:213], v[230:233], v[16:19]
	v_mfma_f32_16x16x32_bf16 v[12:15], v[210:213], v[242:245], v[12:15]
	v_mfma_f32_16x16x32_bf16 v[8:11], v[218:221], v[230:233], v[8:11]
	v_mfma_f32_16x16x32_bf16 v[4:7], v[218:221], v[242:245], v[4:7]
	s_setprio 0
	s_add_i32 s29, s29, 2
	s_add_u32 s12, s12, 0x100
	s_addc_u32 s13, s13, 0
	s_cmp_lt_u32 s29, 4
	s_barrier
	s_cbranch_scc0 .Lpk_exit_5

; #define LDA8(dst, b, h) _Pragma("unroll") for (int m = 0; m < 4; ++m) _Pragma("unroll") for (int k = 0; k < 2; ++k) \
;     dst[m][k] = *(const bf16x8*)((const char*)SA8(b, h) + lds_byte8(wr * 64 + m * 16 + fr, k * 32 + fq * 8))
; #define LDB8(dst, b, h) _Pragma("unroll") for (int n = 0; n < 2; ++n) _Pragma("unroll") for (int k = 0; k < 2; ++k) \
;     dst[n][k] = *(const bf16x8*)((const char*)SB8(b, h) + lds_byte8(wc * 32 + n * 16 + fr, k * 32 + fq * 8))
; #define WAIT_V8(n) asm volatile("s_waitcnt vmcnt(" #n ")" ::: "memory")
; #define WAIT_L8(n) asm volatile("s_waitcnt lgkmcnt(" #n ")" ::: "memory")
; #define BAR8 __builtin_amdgcn_s_barrier()
;     ...
;   { LDB8(B0, 0, 0); LDA8(At, 0, 0); STAGE8(SA8(1, 1), A, lda, brow + 128, nt - 1);
;     BAR8; WAIT_L8(0); MMA8(0, 0, At, B0); BAR8;
;     LDB8(B1, 0, 1); BAR8; WAIT_L8(0); MMA8(0, 1, At, B1); BAR8;
;     LDA8(At, 0, 1); WAIT_V8(4); BAR8; WAIT_L8(0); MMA8(1, 0, At, B0); MMA8(1, 1, At, B1); BAR8; }
.Lpk_exit_5:
	s_add_u32 s2, s2, s27
	s_addc_u32 s3, s3, 0
	s_add_u32 s2, s2, 0x3000380
	s_addc_u32 s3, s3, 0
	v_lshl_add_u64 v[136:137], v[136:137], 1, s[2:3]
	v_readfirstlane_b32 s12, v172
	v_lshl_add_u64 v[0:1], v[0:1], 1, v[136:137]
	s_mov_b32 m0, s12
	ds_read_b128 v[138:141], v171
	ds_read_b128 v[142:145], v171 offset:1024
	ds_read_b128 v[162:165], v171 offset:2048
	ds_read_b128 v[168:171], v171 offset:3072
	ds_read_b128 v[174:177], v156
	ds_read_b128 v[178:181], v156 offset:1024
	ds_read_b128 v[182:185], v155
	ds_read_b128 v[186:189], v155 offset:1024
	ds_read_b128 v[190:193], v154
	ds_read_b128 v[194:197], v154 offset:1024
	ds_read_b128 v[198:201], v153
	ds_read_b128 v[202:205], v153 offset:1024
	global_load_lds_dwordx4 v[0:1], off
	v_lshl_add_u64 v[0:1], v[134:135], 1, s[2:3]
	v_readfirstlane_b32 s2, v173
	v_lshl_add_u64 v[0:1], v[132:133], 1, v[0:1]
	s_mov_b32 m0, s2
	s_nop 0
	global_load_lds_dwordx4 v[0:1], off
	s_barrier
	s_waitcnt lgkmcnt(0)
	s_setprio 1
	s_waitcnt lgkmcnt(0)
	v_mfma_f32_16x16x32_bf16 v[128:131], v[174:177], v[138:141], v[128:131]
	v_mfma_f32_16x16x32_bf16 v[124:127], v[174:177], v[162:165], v[124:127]
	v_mfma_f32_16x16x32_bf16 v[120:123], v[182:185], v[138:141], v[120:123]
	v_mfma_f32_16x16x32_bf16 v[112:115], v[190:193], v[138:141], v[112:115]
	v_mfma_f32_16x16x32_bf16 v[128:131], v[178:181], v[142:145], v[128:131]
	v_mfma_f32_16x16x32_bf16 v[124:127], v[178:181], v[168:171], v[124:127]
	v_mfma_f32_16x16x32_bf16 v[120:123], v[186:189], v[142:145], v[120:123]
	v_mfma_f32_16x16x32_bf16 v[116:119], v[182:185], v[162:165], v[116:119]
	v_mfma_f32_16x16x32_bf16 v[112:115], v[194:197], v[142:145], v[112:115]
	v_mfma_f32_16x16x32_bf16 v[108:111], v[190:193], v[162:165], v[108:111]
	v_mfma_f32_16x16x32_bf16 v[104:107], v[198:201], v[138:141], v[104:107]
	v_mfma_f32_16x16x32_bf16 v[100:103], v[198:201], v[162:165], v[100:103]
	v_mfma_f32_16x16x32_bf16 v[132:135], v[186:189], v[168:171], v[116:119]
	v_mfma_f32_16x16x32_bf16 v[206:209], v[194:197], v[168:171], v[108:111]
	v_mfma_f32_16x16x32_bf16 v[210:213], v[202:205], v[142:145], v[104:107]
	v_mfma_f32_16x16x32_bf16 v[214:217], v[202:205], v[168:171], v[100:103]
	s_setprio 0
	s_barrier
	s_nop 1
	ds_read_b128 v[100:103], v167
	ds_read_b128 v[104:107], v167 offset:1024
	ds_read_b128 v[108:111], v167 offset:2048
	ds_read_b128 v[116:119], v167 offset:3072
	s_barrier
	s_waitcnt lgkmcnt(0)
	s_setprio 1
	s_waitcnt lgkmcnt(0)
	v_mfma_f32_16x16x32_bf16 v[80:83], v[190:193], v[100:103], v[80:83]
	v_mfma_f32_16x16x32_bf16 v[76:79], v[190:193], v[108:111], v[76:79]
	v_mfma_f32_16x16x32_bf16 v[72:75], v[198:201], v[100:103], v[72:75]
	v_mfma_f32_16x16x32_bf16 v[68:71], v[198:201], v[108:111], v[68:71]
	v_mfma_f32_16x16x32_bf16 v[96:99], v[174:177], v[100:103], v[96:99]
	v_mfma_f32_16x16x32_bf16 v[92:95], v[174:177], v[108:111], v[92:95]
	v_mfma_f32_16x16x32_bf16 v[88:91], v[182:185], v[100:103], v[88:91]
	v_mfma_f32_16x16x32_bf16 v[84:87], v[182:185], v[108:111], v[84:87]
	v_mfma_f32_16x16x32_bf16 v[80:83], v[194:197], v[104:107], v[80:83]
	v_mfma_f32_16x16x32_bf16 v[76:79], v[194:197], v[116:119], v[76:79]
	v_mfma_f32_16x16x32_bf16 v[72:75], v[202:205], v[104:107], v[72:75]
	v_mfma_f32_16x16x32_bf16 v[68:71], v[202:205], v[116:119], v[68:71]
	v_mfma_f32_16x16x32_bf16 v[218:221], v[178:181], v[104:107], v[96:99]
	v_mfma_f32_16x16x32_bf16 v[172:175], v[178:181], v[116:119], v[92:95]
	v_mfma_f32_16x16x32_bf16 v[176:179], v[186:189], v[104:107], v[88:91]
	v_mfma_f32_16x16x32_bf16 v[180:183], v[186:189], v[116:119], v[84:87]
	s_setprio 0
	s_barrier
	s_nop 0
	ds_read_b128 v[84:87], v156 offset:16384
	ds_read_b128 v[88:91], v156 offset:17408
	ds_read_b128 v[92:95], v155 offset:16384
	ds_read_b128 v[96:99], v155 offset:17408
	ds_read_b128 v[184:187], v154 offset:16384
	ds_read_b128 v[188:191], v154 offset:17408
	ds_read_b128 v[192:195], v153 offset:16384
	ds_read_b128 v[196:199], v153 offset:17408
	s_waitcnt vmcnt(4)
	s_barrier
	s_waitcnt lgkmcnt(0)
	s_setprio 1
	s_waitcnt lgkmcnt(0)
	v_mfma_f32_16x16x32_bf16 v[64:67], v[84:87], v[138:141], v[64:67]
	v_mfma_f32_16x16x32_bf16 v[60:63], v[84:87], v[162:165], v[60:63]
	v_mfma_f32_16x16x32_bf16 v[56:59], v[92:95], v[138:141], v[56:59]
	v_mfma_f32_16x16x32_bf16 v[52:55], v[92:95], v[162:165], v[52:55]
	v_mfma_f32_16x16x32_bf16 v[48:51], v[184:187], v[138:141], v[48:51]
	v_mfma_f32_16x16x32_bf16 v[44:47], v[184:187], v[162:165], v[44:47]
	v_mfma_f32_16x16x32_bf16 v[40:43], v[192:195], v[138:141], v[40:43]
	v_mfma_f32_16x16x32_bf16 v[36:39], v[192:195], v[162:165], v[36:39]
	v_mfma_f32_16x16x32_bf16 v[64:67], v[88:91], v[142:145], v[64:67]
	v_mfma_f32_16x16x32_bf16 v[60:63], v[88:91], v[168:171], v[60:63]
	v_mfma_f32_16x16x32_bf16 v[56:59], v[96:99], v[142:145], v[56:59]
	v_mfma_f32_16x16x32_bf16 v[52:55], v[96:99], v[168:171], v[52:55]
	v_mfma_f32_16x16x32_bf16 v[48:51], v[188:191], v[142:145], v[48:51]
	v_mfma_f32_16x16x32_bf16 v[44:47], v[188:191], v[168:171], v[44:47]
	v_mfma_f32_16x16x32_bf16 v[40:43], v[196:199], v[142:145], v[40:43]
	v_mfma_f32_16x16x32_bf16 v[36:39], v[196:199], v[168:171], v[36:39]
	s_setprio 0
	s_setprio 1
	v_mfma_f32_16x16x32_bf16 v[32:35], v[84:87], v[100:103], v[32:35]
	v_mfma_f32_16x16x32_bf16 v[28:31], v[84:87], v[108:111], v[28:31]
	v_mfma_f32_16x16x32_bf16 v[24:27], v[92:95], v[100:103], v[24:27]
	v_mfma_f32_16x16x32_bf16 v[20:23], v[92:95], v[108:111], v[20:23]
	v_mfma_f32_16x16x32_bf16 v[16:19], v[184:187], v[100:103], v[16:19]
	v_mfma_f32_16x16x32_bf16 v[12:15], v[184:187], v[108:111], v[12:15]
	v_mfma_f32_16x16x32_bf16 v[8:11], v[192:195], v[100:103], v[8:11]
	v_mfma_f32_16x16x32_bf16 v[4:7], v[192:195], v[108:111], v[4:7]
	v_mfma_f32_16x16x32_bf16 v[136:139], v[88:91], v[104:107], v[32:35]
	v_mfma_f32_16x16x32_bf16 v[140:143], v[88:91], v[116:119], v[28:31]
	v_mfma_f32_16x16x32_bf16 v[162:165], v[96:99], v[104:107], v[24:27]
	v_mfma_f32_16x16x32_bf16 v[166:169], v[96:99], v[116:119], v[20:23]
	v_mfma_f32_16x16x32_bf16 v[200:203], v[188:191], v[104:107], v[16:19]
	v_mfma_f32_16x16x32_bf16 v[184:187], v[188:191], v[116:119], v[12:15]
	v_mfma_f32_16x16x32_bf16 v[188:191], v[196:199], v[104:107], v[8:11]
	v_mfma_f32_16x16x32_bf16 v[192:195], v[196:199], v[116:119], v[4:7]
	s_setprio 0
	s_barrier
; #define LDA8(dst, b, h) _Pragma("unroll") for (int m = 0; m < 4; ++m) _Pragma("unroll") for (int k = 0; k < 2; ++k) \
;     dst[m][k] = *(const bf16x8*)((const char*)SA8(b, h) + lds_byte8(wr * 64 + m * 16 + fr, k * 32 + fq * 8))
; #define LDB8(dst, b, h) _Pragma("unroll") for (int n = 0; n < 2; ++n) _Pragma("unroll") for (int k = 0; k < 2; ++k) \
;     dst[n][k] = *(const bf16x8*)((const char*)SB8(b, h) + lds_byte8(wc * 32 + n * 16 + fr, k * 32 + fq * 8))
; #define WAIT_V8(n) asm volatile("s_waitcnt vmcnt(" #n ")" ::: "memory")
; #define WAIT_L8(n) asm volatile("s_waitcnt lgkmcnt(" #n ")" ::: "memory")
; #define BAR8 __builtin_amdgcn_s_barrier()
;     ...
;   { LDB8(B0, 1, 0); LDA8(At, 1, 0); WAIT_V8(2); BAR8; WAIT_L8(0); MMA8(0, 0, At, B0); BAR8;
;     LDB8(B1, 1, 1); WAIT_V8(0); BAR8; WAIT_L8(0); MMA8(0, 1, At, B1); BAR8;
;     LDA8(At, 1, 1); BAR8; WAIT_L8(0); MMA8(1, 0, At, B0); MMA8(1, 1, At, B1); BAR8; }
;   if (wr == 0) BAR8;
;   __syncthreads();
;     ...
;   if (t < 256) {
	ds_read_b128 v[196:199], v160
	ds_read_b128 v[226:229], v160 offset:1024
	ds_read_b128 v[230:233], v160 offset:2048
	ds_read_b128 v[238:241], v160 offset:3072
	ds_read_b128 v[8:11], v156 offset:32768
	ds_read_b128 v[12:15], v156 offset:33792
	ds_read_b128 v[16:19], v155 offset:32768
	ds_read_b128 v[24:27], v155 offset:33792
	ds_read_b128 v[28:31], v154 offset:32768
	ds_read_b128 v[32:35], v154 offset:33792
	ds_read_b128 v[242:245], v153 offset:32768
	ds_read_b128 v[246:249], v153 offset:33792
	s_waitcnt vmcnt(2)
	s_barrier
	s_waitcnt lgkmcnt(0)
	s_setprio 1
	s_waitcnt lgkmcnt(0)
	v_mfma_f32_16x16x32_bf16 v[4:7], v[8:11], v[196:199], v[128:131]
	v_mfma_f32_16x16x32_bf16 v[104:107], v[12:15], v[226:229], v[4:7]
	v_mfma_f32_16x16x32_bf16 v[4:7], v[8:11], v[230:233], v[124:127]
	v_mfma_f32_16x16x32_bf16 v[116:119], v[12:15], v[238:241], v[4:7]
	v_mfma_f32_16x16x32_bf16 v[4:7], v[16:19], v[196:199], v[120:123]
	v_mfma_f32_16x16x32_bf16 v[100:103], v[24:27], v[226:229], v[4:7]
	v_mfma_f32_16x16x32_bf16 v[4:7], v[16:19], v[230:233], v[132:135]
	v_mfma_f32_16x16x32_bf16 v[108:111], v[24:27], v[238:241], v[4:7]
	v_mfma_f32_16x16x32_bf16 v[4:7], v[28:31], v[196:199], v[112:115]
	v_mfma_f32_16x16x32_bf16 v[92:95], v[32:35], v[226:229], v[4:7]
	v_mfma_f32_16x16x32_bf16 v[4:7], v[28:31], v[230:233], v[206:209]
	v_mfma_f32_16x16x32_bf16 v[96:99], v[32:35], v[238:241], v[4:7]
	v_mfma_f32_16x16x32_bf16 v[4:7], v[242:245], v[196:199], v[210:213]
	v_mfma_f32_16x16x32_bf16 v[84:87], v[246:249], v[226:229], v[4:7]
	v_mfma_f32_16x16x32_bf16 v[4:7], v[242:245], v[230:233], v[214:217]
	v_mfma_f32_16x16x32_bf16 v[88:91], v[246:249], v[238:241], v[4:7]
	s_setprio 0
	s_barrier
	ds_read_b128 v[132:135], v158
	ds_read_b128 v[204:207], v158 offset:1024
	ds_read_b128 v[208:211], v158 offset:2048
	ds_read_b128 v[158:161], v158 offset:3072
	s_waitcnt vmcnt(0)
	s_barrier
	s_waitcnt lgkmcnt(0)
	s_setprio 1
	s_waitcnt lgkmcnt(0)
	v_mfma_f32_16x16x32_bf16 v[4:7], v[8:11], v[132:135], v[218:221]
	v_mfma_f32_16x16x32_bf16 v[8:11], v[8:11], v[208:211], v[172:175]
	v_mfma_f32_16x16x32_bf16 v[4:7], v[12:15], v[204:207], v[4:7]
	v_mfma_f32_16x16x32_bf16 v[20:23], v[12:15], v[158:161], v[8:11]
	v_mfma_f32_16x16x32_bf16 v[8:11], v[16:19], v[132:135], v[176:179]
	v_mfma_f32_16x16x32_bf16 v[12:15], v[16:19], v[208:211], v[180:183]
	v_mfma_f32_16x16x32_bf16 v[8:11], v[24:27], v[204:207], v[8:11]
	v_mfma_f32_16x16x32_bf16 v[24:27], v[24:27], v[158:161], v[12:15]
	v_mfma_f32_16x16x32_bf16 v[12:15], v[28:31], v[132:135], v[80:83]
	v_mfma_f32_16x16x32_bf16 v[16:19], v[28:31], v[208:211], v[76:79]
	v_mfma_f32_16x16x32_bf16 v[12:15], v[32:35], v[204:207], v[12:15]
	v_mfma_f32_16x16x32_bf16 v[28:31], v[32:35], v[158:161], v[16:19]
	v_mfma_f32_16x16x32_bf16 v[16:19], v[242:245], v[132:135], v[72:75]
	v_mfma_f32_16x16x32_bf16 v[32:35], v[242:245], v[208:211], v[68:71]
	v_mfma_f32_16x16x32_bf16 v[16:19], v[246:249], v[204:207], v[16:19]
	v_mfma_f32_16x16x32_bf16 v[32:35], v[246:249], v[158:161], v[32:35]
	s_setprio 0
	s_barrier
	ds_read_b128 v[170:173], v156 offset:49152
	ds_read_b128 v[174:177], v156 offset:50176
	ds_read_b128 v[178:181], v155 offset:49152
	ds_read_b128 v[212:215], v155 offset:50176
	ds_read_b128 v[216:219], v154 offset:49152
	ds_read_b128 v[154:157], v154 offset:50176
	ds_read_b128 v[220:223], v153 offset:49152
	ds_read_b128 v[150:153], v153 offset:50176
	s_barrier
	s_waitcnt lgkmcnt(0)
	s_setprio 1
	s_waitcnt lgkmcnt(0)
	v_mfma_f32_16x16x32_bf16 v[64:67], v[170:173], v[196:199], v[64:67]
	v_mfma_f32_16x16x32_bf16 v[60:63], v[170:173], v[230:233], v[60:63]
	v_mfma_f32_16x16x32_bf16 v[56:59], v[178:181], v[196:199], v[56:59]
	v_mfma_f32_16x16x32_bf16 v[52:55], v[178:181], v[230:233], v[52:55]
	v_mfma_f32_16x16x32_bf16 v[48:51], v[216:219], v[196:199], v[48:51]
	v_mfma_f32_16x16x32_bf16 v[44:47], v[216:219], v[230:233], v[44:47]
	v_mfma_f32_16x16x32_bf16 v[40:43], v[220:223], v[196:199], v[40:43]
	v_mfma_f32_16x16x32_bf16 v[36:39], v[220:223], v[230:233], v[36:39]
	v_mfma_f32_16x16x32_bf16 v[128:131], v[174:177], v[226:229], v[64:67]
	v_mfma_f32_16x16x32_bf16 v[124:127], v[174:177], v[238:241], v[60:63]
	v_mfma_f32_16x16x32_bf16 v[120:123], v[212:215], v[226:229], v[56:59]
	v_mfma_f32_16x16x32_bf16 v[112:115], v[212:215], v[238:241], v[52:55]
	v_mfma_f32_16x16x32_bf16 v[80:83], v[154:157], v[226:229], v[48:51]
	v_mfma_f32_16x16x32_bf16 v[76:79], v[154:157], v[238:241], v[44:47]
	v_mfma_f32_16x16x32_bf16 v[72:75], v[150:153], v[226:229], v[40:43]
	v_mfma_f32_16x16x32_bf16 v[68:71], v[150:153], v[238:241], v[36:39]
	s_setprio 0
	s_setprio 1
	v_mfma_f32_16x16x32_bf16 v[40:43], v[170:173], v[208:211], v[140:143]
	v_mfma_f32_16x16x32_bf16 v[44:47], v[178:181], v[208:211], v[166:169]
	v_mfma_f32_16x16x32_bf16 v[48:51], v[216:219], v[208:211], v[184:187]
	v_mfma_f32_16x16x32_bf16 v[36:39], v[170:173], v[132:135], v[136:139]
	v_mfma_f32_16x16x32_bf16 v[52:55], v[174:177], v[158:161], v[40:43]
	v_mfma_f32_16x16x32_bf16 v[40:43], v[178:181], v[132:135], v[162:165]
	v_mfma_f32_16x16x32_bf16 v[56:59], v[212:215], v[158:161], v[44:47]
	v_mfma_f32_16x16x32_bf16 v[44:47], v[216:219], v[132:135], v[200:203]
	v_mfma_f32_16x16x32_bf16 v[60:63], v[154:157], v[158:161], v[48:51]
	v_mfma_f32_16x16x32_bf16 v[48:51], v[220:223], v[132:135], v[188:191]
	v_mfma_f32_16x16x32_bf16 v[64:67], v[220:223], v[208:211], v[192:195]
	v_mfma_f32_16x16x32_bf16 v[36:39], v[174:177], v[204:207], v[36:39]
	v_mfma_f32_16x16x32_bf16 v[40:43], v[212:215], v[204:207], v[40:43]
	v_mfma_f32_16x16x32_bf16 v[44:47], v[154:157], v[204:207], v[44:47]
	v_mfma_f32_16x16x32_bf16 v[48:51], v[150:153], v[204:207], v[48:51]
	v_mfma_f32_16x16x32_bf16 v[64:67], v[150:153], v[158:161], v[64:67]
	s_setprio 0
	s_movk_i32 s2, 0x100
	v_cmp_gt_u32_e32 vcc, s2, v3
	s_barrier
	s_and_saveexec_b64 s[2:3], vcc
	s_cbranch_execz .LBB0_1155
	s_barrier

; #define WAIT_V8(n) asm volatile("s_waitcnt vmcnt(" #n ")" ::: "memory")
; #define BAR8 __builtin_amdgcn_s_barrier()
;     ...
;     STAGE8(SB8(0, 0), Bt, K, bcol, 0); STAGE8(SA8(0, 0), A, lda, brow, 0);
;     STAGE8(SB8(0, 1), Bt, K, bcol + 128, 0); STAGE8(SA8(0, 1), A, lda, brow + 128, 0);
;   }
;   if (wr == 1) BAR8;
;   WAIT_V8(4); BAR8;
;   STAGE8(SB8(1, 0), Bt, K, bcol, 1); STAGE8(SA8(1, 0), A, lda, brow, 1); STAGE8(SB8(1, 1), Bt, K, bcol + 128, 1);
;   WAIT_V8(6); BAR8;
.LBB0_1258:
	s_or_b64 exec, exec, s[8:9]
	v_add_u32_e32 v0, v150, v0
	v_and_b32_e32 v0, 0xfffffc00, v0
	v_sub_u32_e32 v0, v150, v0
	v_lshrrev_b32_e32 v6, 4, v0
	v_add_u32_e32 v1, v3, v1
	v_bitop3_b32 v7, v6, v0, 32 bitop3:0x6c
	v_ashrrev_i32_e32 v0, 31, v0
	v_ashrrev_i32_e32 v1, 6, v1
	v_lshrrev_b32_e32 v0, 26, v0
	v_lshlrev_b32_e32 v6, 3, v1
	v_add_u32_e32 v0, v7, v0
	v_and_b32_e32 v6, -16, v6
	v_ashrrev_i32_e32 v0, 6, v0
	s_and_b32 s1, s12, 63
	s_and_b32 s8, s20, 0xffffff00
	v_add_u32_e32 v6, v0, v6
	v_mul_i32_i24_e32 v0, 64, v0
	s_lshl_b32 s12, s1, 19
	s_ashr_i32 s9, s8, 31
	s_ashr_i32 s1, s0, 31
	v_lshlrev_b32_e32 v1, 5, v1
	v_sub_u32_e32 v0, v7, v0
	v_mov_b32_e32 v13, 1
	s_lshl_b64 s[14:15], s[8:9], 11
	s_lshl_b64 s[8:9], s[0:1], 11
	v_and_b32_e32 v1, 32, v1
	v_ashrrev_i16_sdwa v0, v13, sext(v0) dst_sel:DWORD dst_unused:UNUSED_PAD src0_sel:DWORD src1_sel:BYTE_0
	s_add_u32 s8, s4, s8
	v_add_u32_sdwa v0, v1, sext(v0) dst_sel:DWORD dst_unused:UNUSED_PAD src0_sel:DWORD src1_sel:WORD_0
	v_ashrrev_i32_e32 v7, 31, v6
	v_readlane_b32 s40, v254, 35
	s_addc_u32 s9, s5, s9
	v_lshlrev_b64 v[132:133], 11, v[6:7]
	v_ashrrev_i32_e32 v1, 31, v0
	v_readlane_b32 s41, v254, 36
	v_lshl_add_u64 v[6:7], s[8:9], 0, v[132:133]
	v_lshlrev_b64 v[8:9], 1, v[0:1]
	v_add_u32_e32 v164, 0x18000, v150
	s_mov_b32 s13, s40
	v_lshl_add_u64 v[6:7], v[6:7], 0, v[8:9]
	s_mov_b64 s[40:41], 0x80
	v_readfirstlane_b32 s1, v164
	v_lshl_add_u64 v[6:7], v[6:7], 0, s[40:41]
	s_mov_b32 m0, s1
	s_waitcnt vmcnt(4)
	s_barrier
	global_load_lds_dwordx4 v[6:7], off
	v_ashrrev_i32_e32 v6, 31, v152
	v_lshrrev_b32_e32 v6, 22, v6
	v_add_u32_e32 v6, v152, v6
	v_ashrrev_i32_e32 v7, 10, v6
	v_mul_i32_i24_e32 v6, 0x400, v7
	v_sub_u32_e32 v6, v152, v6
	v_lshrrev_b32_e32 v10, 4, v6
	v_bitop3_b32 v10, v10, v6, 32 bitop3:0x6c
	v_ashrrev_i32_e32 v11, 31, v10
	v_lshrrev_b32_e32 v11, 26, v11
	v_add_u32_e32 v11, v10, v11
	v_lshlrev_b32_e32 v6, 3, v7
	v_ashrrev_i32_e32 v12, 6, v11
	v_and_b32_e32 v11, 0xc0, v11
	v_and_b32_e32 v6, -16, v6
	v_lshlrev_b32_e32 v7, 5, v7
	v_sub_u32_e32 v10, v10, v11
	v_add_u32_e32 v6, v12, v6
	v_and_b32_e32 v7, 32, v7
	v_ashrrev_i16_sdwa v10, v13, sext(v10) dst_sel:DWORD dst_unused:UNUSED_PAD src0_sel:DWORD src1_sel:BYTE_0
	v_add_u32_sdwa v134, v7, sext(v10) dst_sel:DWORD dst_unused:UNUSED_PAD src0_sel:DWORD src1_sel:WORD_0
	v_ashrrev_i32_e32 v7, 31, v6
	v_add_u32_e32 v165, 0x1a000, v150
	v_lshlrev_b64 v[136:137], 11, v[6:7]
	v_ashrrev_i32_e32 v135, 31, v134
	v_readfirstlane_b32 s1, v165
	v_lshl_add_u64 v[6:7], s[8:9], 0, v[136:137]
	v_lshlrev_b64 v[10:11], 1, v[134:135]
	s_mov_b32 m0, s1
	s_lshl_b32 s1, s27, 11
	v_lshl_add_u64 v[6:7], v[6:7], 0, v[10:11]
	s_waitcnt lgkmcnt(0)
	s_add_u32 s8, s2, s1
	v_lshl_add_u64 v[6:7], v[6:7], 0, s[40:41]
	s_addc_u32 s9, s3, 0
	global_load_lds_dwordx4 v[6:7], off
	v_lshl_add_u64 v[6:7], s[8:9], 0, v[132:133]
	v_add_u32_e32 v166, 0x8000, v150
	v_lshl_add_u64 v[6:7], v[6:7], 0, v[8:9]
	v_readfirstlane_b32 s1, v166
	s_or_b32 s36, s0, 0x80
	v_lshl_add_u64 v[6:7], v[6:7], 0, s[40:41]
	s_mov_b32 m0, s1
	s_ashr_i32 s37, s36, 31
	global_load_lds_dwordx4 v[6:7], off
	v_lshl_add_u64 v[6:7], s[8:9], 0, v[136:137]
	v_add_u32_e32 v167, 0xa000, v150
	s_lshl_b64 s[36:37], s[36:37], 11
	v_lshl_add_u64 v[6:7], v[6:7], 0, v[10:11]
	v_readfirstlane_b32 s1, v167
	s_add_u32 s36, s4, s36
	v_lshl_add_u64 v[6:7], v[6:7], 0, s[40:41]
	s_mov_b32 m0, s1
	s_addc_u32 s37, s5, s37
	global_load_lds_dwordx4 v[6:7], off
	v_lshl_add_u64 v[6:7], s[36:37], 0, v[132:133]
	v_add_u32_e32 v168, 0x1c000, v150
	v_lshl_add_u64 v[6:7], v[6:7], 0, v[8:9]
	v_readfirstlane_b32 s1, v168
	v_lshl_add_u64 v[6:7], v[6:7], 0, s[40:41]
	s_mov_b32 m0, s1
	v_add_u32_e32 v170, 0x1e000, v150
	global_load_lds_dwordx4 v[6:7], off
	v_lshl_add_u64 v[6:7], s[36:37], 0, v[136:137]
	v_lshl_add_u64 v[6:7], v[6:7], 0, v[10:11]
	v_readfirstlane_b32 s1, v170
	v_lshl_add_u64 v[6:7], v[6:7], 0, s[40:41]
	s_mov_b32 m0, s1
	v_and_b32_e32 v147, 15, v3
	global_load_lds_dwordx4 v[6:7], off
	v_bfe_u32 v148, v3, 4, 2
	v_lshlrev_b32_e32 v6, 4, v148
	v_lshlrev_b32_e32 v7, 6, v147
	v_lshlrev_b32_e32 v14, 2, v3
	v_or_b32_e32 v13, v6, v7
	v_and_b32_e32 v14, 32, v14
	s_mov_b32 s1, 0x10000
	v_bitop3_b32 v16, v13, s1, v14 bitop3:0xde
	s_mov_b32 s1, 0x14000
	v_bitop3_b32 v15, v6, v14, v7 bitop3:0x36
	v_bitop3_b32 v17, v13, s1, v14 bitop3:0xde
	s_mov_b32 s1, 0x18000
	v_lshlrev_b32_e32 v7, 6, v3
	v_bitop3_b32 v18, v13, s1, v14 bitop3:0xde
	s_mov_b32 s1, 0x1c000
	v_and_b32_e32 v7, 0x3c0, v7
	v_bitop3_b32 v13, v13, s1, v14 bitop3:0xde
	v_bitop3_b32 v14, v7, v14, v6 bitop3:0x36
	v_lshl_add_u64 v[6:7], s[12:13], 0, v[132:133]
	v_lshl_add_u64 v[6:7], v[6:7], 0, v[8:9]
	v_lshl_add_u64 v[138:139], s[2:3], 0, v[6:7]
	v_lshl_add_u64 v[6:7], s[12:13], 0, v[136:137]
	v_lshl_add_u64 v[6:7], v[6:7], 0, v[10:11]
	v_lshl_add_u64 v[140:141], s[2:3], 0, v[6:7]
	v_lshl_add_u64 v[6:7], s[14:15], 0, v[132:133]
	v_lshl_add_u64 v[6:7], v[6:7], 0, v[8:9]
	v_bfe_u32 v146, v3, 6, 2
	s_waitcnt vmcnt(6)
	v_lshlrev_b32_e32 v149, 6, v5
	v_lshlrev_b32_e32 v5, 13, v5
	v_lshl_add_u64 v[142:143], s[6:7], 0, v[6:7]
	v_lshl_add_u64 v[6:7], s[14:15], 0, v[136:137]
	v_readlane_b32 s42, v254, 37
	v_readlane_b32 s43, v254, 38
	v_lshlrev_b32_e32 v12, 12, v146
	v_or_b32_e32 v19, 0x800, v5
	v_or_b32_e32 v20, 0x1000, v5
	v_or_b32_e32 v21, 0x1800, v5
	v_lshl_add_u64 v[6:7], v[6:7], 0, v[10:11]
	v_lshl_add_u64 v[144:145], s[6:7], 0, v[6:7]
	s_mov_b32 s1, -2
	s_mov_b64 s[12:13], 0
	v_add_u32_e32 v171, v16, v12
	v_add_u32_e32 v161, v15, v5
	v_add_u32_e32 v160, v14, v19
	v_add_u32_e32 v159, v14, v20
	v_add_u32_e32 v158, v14, v21
	v_add_u32_e32 v169, v17, v12
	v_add_u32_e32 v163, v18, v12
	v_add_u32_e32 v162, v13, v12
	s_mov_b64 s[36:37], 0xcaa0100
	s_mov_b64 s[40:41], 0xcae0100
	s_mov_b64 s[42:43], 0xcaa0180
	s_mov_b64 s[44:45], 0xcae0180
	s_barrier
; #define LDA8(dst, b, h) _Pragma("unroll") for (int m = 0; m < 4; ++m) _Pragma("unroll") for (int k = 0; k < 2; ++k) \
;     dst[m][k] = *(const bf16x8*)((const char*)SA8(b, h) + lds_byte8(wr * 64 + m * 16 + fr, k * 32 + fq * 8))
; #define LDB8(dst, b, h) _Pragma("unroll") for (int n = 0; n < 2; ++n) _Pragma("unroll") for (int k = 0; k < 2; ++k) \
;     dst[n][k] = *(const bf16x8*)((const char*)SB8(b, h) + lds_byte8(wc * 32 + n * 16 + fr, k * 32 + fq * 8))
; #define WAIT_L8(n) asm volatile("s_waitcnt lgkmcnt(" #n ")" ::: "memory")
; #define BAR8 __builtin_amdgcn_s_barrier()
; #define SCHED8 __builtin_amdgcn_sched_barrier(0)
;     ...
;     LDB8(B0, 0, 0); SCHED8; LDA8(At, 0, 0); STAGE8(SA8(1, 1), A, lda, brow + 128, tt + 1);
;     WAIT_L8(8); BAR8; WAIT_L8(0); MMA8(0, 0, At, B0); BAR8; SCHED8;
;     LDB8(B1, 0, 1); STAGE8(SB8(0, 0), Bt, K, bcol, tt + 2);
;     BAR8; WAIT_L8(0); MMA8(0, 1, At, B1); BAR8;
;     LDA8(At, 0, 1); STAGE8(SA8(0, 0), A, lda, brow, tt + 2);
;     BAR8; WAIT_L8(0); MMA8(1, 0, At, B0); BAR8; SCHED8;
	ds_read_b128 v[174:177], v171
	ds_read_b128 v[178:181], v171 offset:1024
	ds_read_b128 v[182:185], v171 offset:2048
	ds_read_b128 v[186:189], v171 offset:3072
	v_add_u32_e32 v172, 0xc000, v150
	v_lshl_add_u64 v[222:223], v[138:139], 0, s[12:13]
	v_readfirstlane_b32 s14, v172
	v_add_u32_e32 v173, 0xe000, v150
	v_lshl_add_u64 v[226:227], v[222:223], 0, s[34:35]
	s_mov_b32 m0, s14
	v_lshl_add_u64 v[236:237], v[140:141], 0, s[12:13]
	v_readfirstlane_b32 s14, v173
	ds_read_b128 v[190:193], v161
	ds_read_b128 v[194:197], v161 offset:1024
	ds_read_b128 v[198:201], v160
	ds_read_b128 v[202:205], v160 offset:1024
	ds_read_b128 v[206:209], v159
	ds_read_b128 v[210:213], v159 offset:1024
	ds_read_b128 v[214:217], v158
	ds_read_b128 v[218:221], v158 offset:1024
	global_load_lds_dwordx4 v[226:227], off
	v_lshl_add_u64 v[226:227], v[236:237], 0, s[34:35]
	s_mov_b32 m0, s14
	s_nop 0
	global_load_lds_dwordx4 v[226:227], off
	s_waitcnt lgkmcnt(8)
	s_barrier
	s_waitcnt lgkmcnt(0)
	s_setprio 1
	s_waitcnt lgkmcnt(0)
	v_mfma_f32_16x16x32_f16 v[128:131], v[190:193], v[174:177], 0
	v_mfma_f32_16x16x32_f16 v[124:127], v[190:193], v[182:185], 0
	v_mfma_f32_16x16x32_f16 v[120:123], v[198:201], v[174:177], 0
	v_mfma_f32_16x16x32_f16 v[116:119], v[198:201], v[182:185], 0
	v_mfma_f32_16x16x32_f16 v[112:115], v[206:209], v[174:177], 0
	v_mfma_f32_16x16x32_f16 v[108:111], v[206:209], v[182:185], 0
	v_mfma_f32_16x16x32_f16 v[104:107], v[214:217], v[174:177], 0
	v_mfma_f32_16x16x32_f16 v[100:103], v[214:217], v[182:185], 0
	v_mfma_f32_16x16x32_f16 v[128:131], v[194:197], v[178:181], v[128:131]
	v_mfma_f32_16x16x32_f16 v[124:127], v[194:197], v[186:189], v[124:127]
	v_mfma_f32_16x16x32_f16 v[120:123], v[202:205], v[178:181], v[120:123]
	v_mfma_f32_16x16x32_f16 v[116:119], v[202:205], v[186:189], v[116:119]
	v_mfma_f32_16x16x32_f16 v[112:115], v[210:213], v[178:181], v[112:115]
	v_mfma_f32_16x16x32_f16 v[108:111], v[210:213], v[186:189], v[108:111]
	v_mfma_f32_16x16x32_f16 v[104:107], v[218:221], v[178:181], v[104:107]
	v_mfma_f32_16x16x32_f16 v[100:103], v[218:221], v[186:189], v[100:103]
	s_setprio 0
	s_barrier
	v_lshl_add_u64 v[246:247], v[142:143], 0, s[12:13]
	v_readfirstlane_b32 s14, v151
	v_lshl_add_u64 v[248:249], v[246:247], 0, s[36:37]
	s_mov_b32 m0, s14
	ds_read_b128 v[226:229], v169
	ds_read_b128 v[230:233], v169 offset:1024
	ds_read_b128 v[238:241], v169 offset:2048
	ds_read_b128 v[242:245], v169 offset:3072
	global_load_lds_dwordx4 v[248:249], off
	v_lshl_add_u64 v[248:249], v[144:145], 0, s[12:13]
	v_readfirstlane_b32 s14, v153
	v_lshl_add_u64 v[250:251], v[248:249], 0, s[36:37]
	s_mov_b32 m0, s14
	s_nop 0
	global_load_lds_dwordx4 v[250:251], off
	s_barrier
	s_waitcnt lgkmcnt(0)
	s_setprio 1
	s_waitcnt lgkmcnt(0)
	v_mfma_f32_16x16x32_f16 v[96:99], v[190:193], v[226:229], 0
	v_mfma_f32_16x16x32_f16 v[92:95], v[190:193], v[238:241], 0
	v_mfma_f32_16x16x32_f16 v[88:91], v[198:201], v[226:229], 0
	v_mfma_f32_16x16x32_f16 v[84:87], v[198:201], v[238:241], 0
	v_mfma_f32_16x16x32_f16 v[80:83], v[206:209], v[226:229], 0
	v_mfma_f32_16x16x32_f16 v[76:79], v[206:209], v[238:241], 0
	v_mfma_f32_16x16x32_f16 v[72:75], v[214:217], v[226:229], 0
	v_mfma_f32_16x16x32_f16 v[68:71], v[214:217], v[238:241], 0
	v_mfma_f32_16x16x32_f16 v[96:99], v[194:197], v[230:233], v[96:99]
	v_mfma_f32_16x16x32_f16 v[92:95], v[194:197], v[242:245], v[92:95]
	v_mfma_f32_16x16x32_f16 v[88:91], v[202:205], v[230:233], v[88:91]
	v_mfma_f32_16x16x32_f16 v[84:87], v[202:205], v[242:245], v[84:87]
	v_mfma_f32_16x16x32_f16 v[80:83], v[210:213], v[230:233], v[80:83]
	v_mfma_f32_16x16x32_f16 v[76:79], v[210:213], v[242:245], v[76:79]
	v_mfma_f32_16x16x32_f16 v[72:75], v[218:221], v[230:233], v[72:75]
	v_mfma_f32_16x16x32_f16 v[68:71], v[218:221], v[242:245], v[68:71]
	s_setprio 0
	v_readfirstlane_b32 s14, v150
	v_lshl_add_u64 v[250:251], v[222:223], 0, s[10:11]
	s_mov_b32 m0, s14
	v_readfirstlane_b32 s14, v152
	s_barrier
	ds_read_b128 v[190:193], v161 offset:16384
	ds_read_b128 v[194:197], v161 offset:17408
	ds_read_b128 v[198:201], v160 offset:16384
	ds_read_b128 v[202:205], v160 offset:17408
	ds_read_b128 v[206:209], v159 offset:16384
	ds_read_b128 v[210:213], v159 offset:17408
	ds_read_b128 v[214:217], v158 offset:16384
	ds_read_b128 v[218:221], v158 offset:17408
	global_load_lds_dwordx4 v[250:251], off
	v_lshl_add_u64 v[250:251], v[236:237], 0, s[10:11]
	s_mov_b32 m0, s14
	s_nop 0
	global_load_lds_dwordx4 v[250:251], off
	s_barrier
	s_waitcnt lgkmcnt(0)
	s_setprio 1
	s_waitcnt lgkmcnt(0)
	v_mfma_f32_16x16x32_f16 v[64:67], v[190:193], v[174:177], 0
	v_mfma_f32_16x16x32_f16 v[60:63], v[190:193], v[182:185], 0
	v_mfma_f32_16x16x32_f16 v[56:59], v[198:201], v[174:177], 0
	v_mfma_f32_16x16x32_f16 v[52:55], v[198:201], v[182:185], 0
	v_mfma_f32_16x16x32_f16 v[48:51], v[206:209], v[174:177], 0
	v_mfma_f32_16x16x32_f16 v[44:47], v[206:209], v[182:185], 0
	v_mfma_f32_16x16x32_f16 v[40:43], v[214:217], v[174:177], 0
	v_mfma_f32_16x16x32_f16 v[36:39], v[214:217], v[182:185], 0
	v_mfma_f32_16x16x32_f16 v[64:67], v[194:197], v[178:181], v[64:67]
	v_mfma_f32_16x16x32_f16 v[60:63], v[194:197], v[186:189], v[60:63]
	v_mfma_f32_16x16x32_f16 v[56:59], v[202:205], v[178:181], v[56:59]
	v_mfma_f32_16x16x32_f16 v[52:55], v[202:205], v[186:189], v[52:55]
	v_mfma_f32_16x16x32_f16 v[48:51], v[210:213], v[178:181], v[48:51]
	v_mfma_f32_16x16x32_f16 v[44:47], v[210:213], v[186:189], v[44:47]
	v_mfma_f32_16x16x32_f16 v[40:43], v[218:221], v[178:181], v[40:43]
	v_mfma_f32_16x16x32_f16 v[36:39], v[218:221], v[186:189], v[36:39]
	s_setprio 0
	s_barrier
; #define LDA8(dst, b, h) _Pragma("unroll") for (int m = 0; m < 4; ++m) _Pragma("unroll") for (int k = 0; k < 2; ++k) \
;     dst[m][k] = *(const bf16x8*)((const char*)SA8(b, h) + lds_byte8(wr * 64 + m * 16 + fr, k * 32 + fq * 8))
; #define LDB8(dst, b, h) _Pragma("unroll") for (int n = 0; n < 2; ++n) _Pragma("unroll") for (int k = 0; k < 2; ++k) \
;     dst[n][k] = *(const bf16x8*)((const char*)SB8(b, h) + lds_byte8(wc * 32 + n * 16 + fr, k * 32 + fq * 8))
; #define WAIT_V8(n) asm volatile("s_waitcnt vmcnt(" #n ")" ::: "memory")
; #define WAIT_L8(n) asm volatile("s_waitcnt lgkmcnt(" #n ")" ::: "memory")
; #define BAR8 __builtin_amdgcn_s_barrier()
; #define SCHED8 __builtin_amdgcn_sched_barrier(0)
;     ...
;     STAGE8(SB8(0, 1), Bt, K, bcol + 128, tt + 2);
;     WAIT_V8(6); BAR8; MMA8(1, 1, At, B1); BAR8;
;     LDB8(B0, 1, 0); SCHED8; LDA8(At, 1, 0); STAGE8(SA8(0, 1), A, lda, brow + 128, tt + 2);
;     WAIT_L8(8); BAR8; WAIT_L8(0); MMA8(0, 0, At, B0); BAR8; SCHED8;
;     LDB8(B1, 1, 1); STAGE8(SB8(1, 0), Bt, K, bcol, tt + 3);
	v_readfirstlane_b32 s14, v154
	v_lshl_add_u64 v[174:175], v[246:247], 0, s[40:41]
	s_mov_b32 m0, s14
	v_readfirstlane_b32 s14, v155
	global_load_lds_dwordx4 v[174:175], off
	v_lshl_add_u64 v[174:175], v[248:249], 0, s[40:41]
	s_mov_b32 m0, s14
	s_nop 0
	global_load_lds_dwordx4 v[174:175], off
	s_waitcnt vmcnt(6)
	s_barrier
	s_setprio 1
	v_mfma_f32_16x16x32_f16 v[32:35], v[190:193], v[226:229], 0
	v_mfma_f32_16x16x32_f16 v[28:31], v[190:193], v[238:241], 0
	v_mfma_f32_16x16x32_f16 v[24:27], v[198:201], v[226:229], 0
	v_mfma_f32_16x16x32_f16 v[20:23], v[198:201], v[238:241], 0
	v_mfma_f32_16x16x32_f16 v[16:19], v[206:209], v[226:229], 0
	v_mfma_f32_16x16x32_f16 v[12:15], v[206:209], v[238:241], 0
	v_mfma_f32_16x16x32_f16 v[8:11], v[214:217], v[226:229], 0
	v_mfma_f32_16x16x32_f16 v[4:7], v[214:217], v[238:241], 0
	v_mfma_f32_16x16x32_f16 v[32:35], v[194:197], v[230:233], v[32:35]
	v_mfma_f32_16x16x32_f16 v[28:31], v[194:197], v[242:245], v[28:31]
	v_mfma_f32_16x16x32_f16 v[24:27], v[202:205], v[230:233], v[24:27]
	v_mfma_f32_16x16x32_f16 v[20:23], v[202:205], v[242:245], v[20:23]
	v_mfma_f32_16x16x32_f16 v[16:19], v[210:213], v[230:233], v[16:19]
	v_mfma_f32_16x16x32_f16 v[12:15], v[210:213], v[242:245], v[12:15]
	v_mfma_f32_16x16x32_f16 v[8:11], v[218:221], v[230:233], v[8:11]
	v_mfma_f32_16x16x32_f16 v[4:7], v[218:221], v[242:245], v[4:7]
	s_setprio 0
	s_barrier
	ds_read_b128 v[174:177], v163
	ds_read_b128 v[178:181], v163 offset:1024
	ds_read_b128 v[182:185], v163 offset:2048
	ds_read_b128 v[186:189], v163 offset:3072
	v_readfirstlane_b32 s14, v156
	v_lshl_add_u64 v[226:227], v[222:223], 0, s[18:19]
	s_mov_b32 m0, s14
	v_readfirstlane_b32 s14, v157
	ds_read_b128 v[190:193], v161 offset:32768
	ds_read_b128 v[194:197], v161 offset:33792
	ds_read_b128 v[198:201], v160 offset:32768
	ds_read_b128 v[202:205], v160 offset:33792
	ds_read_b128 v[206:209], v159 offset:32768
	ds_read_b128 v[210:213], v159 offset:33792
	ds_read_b128 v[214:217], v158 offset:32768
	ds_read_b128 v[218:221], v158 offset:33792
	global_load_lds_dwordx4 v[226:227], off
	v_lshl_add_u64 v[226:227], v[236:237], 0, s[18:19]
	s_mov_b32 m0, s14
	s_nop 0
	global_load_lds_dwordx4 v[226:227], off
	s_waitcnt lgkmcnt(8)
	s_barrier
	s_waitcnt lgkmcnt(0)
	s_setprio 1
	s_waitcnt lgkmcnt(0)
	v_mfma_f32_16x16x32_f16 v[128:131], v[190:193], v[174:177], v[128:131]
	v_mfma_f32_16x16x32_f16 v[124:127], v[190:193], v[182:185], v[124:127]
	v_mfma_f32_16x16x32_f16 v[120:123], v[198:201], v[174:177], v[120:123]
	v_mfma_f32_16x16x32_f16 v[116:119], v[198:201], v[182:185], v[116:119]
	v_mfma_f32_16x16x32_f16 v[112:115], v[206:209], v[174:177], v[112:115]
	v_mfma_f32_16x16x32_f16 v[108:111], v[206:209], v[182:185], v[108:111]
	v_mfma_f32_16x16x32_f16 v[104:107], v[214:217], v[174:177], v[104:107]
	v_mfma_f32_16x16x32_f16 v[100:103], v[214:217], v[182:185], v[100:103]
	v_mfma_f32_16x16x32_f16 v[128:131], v[194:197], v[178:181], v[128:131]
	v_mfma_f32_16x16x32_f16 v[124:127], v[194:197], v[186:189], v[124:127]
	v_mfma_f32_16x16x32_f16 v[120:123], v[202:205], v[178:181], v[120:123]
	v_mfma_f32_16x16x32_f16 v[116:119], v[202:205], v[186:189], v[116:119]
	v_mfma_f32_16x16x32_f16 v[112:115], v[210:213], v[178:181], v[112:115]
	v_mfma_f32_16x16x32_f16 v[108:111], v[210:213], v[186:189], v[108:111]
	v_mfma_f32_16x16x32_f16 v[104:107], v[218:221], v[178:181], v[104:107]
	v_mfma_f32_16x16x32_f16 v[100:103], v[218:221], v[186:189], v[100:103]
	s_setprio 0
	s_barrier
	v_readfirstlane_b32 s14, v164
	v_lshl_add_u64 v[250:251], v[246:247], 0, s[42:43]
	s_mov_b32 m0, s14
	v_readfirstlane_b32 s14, v165
	ds_read_b128 v[226:229], v162
	ds_read_b128 v[230:233], v162 offset:1024
	ds_read_b128 v[238:241], v162 offset:2048
	ds_read_b128 v[242:245], v162 offset:3072
	global_load_lds_dwordx4 v[250:251], off
	v_lshl_add_u64 v[250:251], v[248:249], 0, s[42:43]
	s_mov_b32 m0, s14
	s_nop 0
	global_load_lds_dwordx4 v[250:251], off
	s_barrier
; #define LDA8(dst, b, h) _Pragma("unroll") for (int m = 0; m < 4; ++m) _Pragma("unroll") for (int k = 0; k < 2; ++k) \
;     dst[m][k] = *(const bf16x8*)((const char*)SA8(b, h) + lds_byte8(wr * 64 + m * 16 + fr, k * 32 + fq * 8))
; #define LDB8(dst, b, h) _Pragma("unroll") for (int n = 0; n < 2; ++n) _Pragma("unroll") for (int k = 0; k < 2; ++k) \
;     dst[n][k] = *(const bf16x8*)((const char*)SB8(b, h) + lds_byte8(wc * 32 + n * 16 + fr, k * 32 + fq * 8))
; #define WAIT_V8(n) asm volatile("s_waitcnt vmcnt(" #n ")" ::: "memory")
; #define WAIT_L8(n) asm volatile("s_waitcnt lgkmcnt(" #n ")" ::: "memory")
; #define BAR8 __builtin_amdgcn_s_barrier()
; #define SCHED8 __builtin_amdgcn_sched_barrier(0)
;     ...
;     LDB8(B1, 1, 1); STAGE8(SB8(1, 0), Bt, K, bcol, tt + 3);
;     BAR8; WAIT_L8(0); MMA8(0, 1, At, B1); BAR8;
;     LDA8(At, 1, 1); STAGE8(SA8(1, 0), A, lda, brow, tt + 3);
;     BAR8; WAIT_L8(0); MMA8(1, 0, At, B0); BAR8; SCHED8;
;     STAGE8(SB8(1, 1), Bt, K, bcol + 128, tt + 3);
;     WAIT_V8(6); BAR8; MMA8(1, 1, At, B1); BAR8;
	s_waitcnt lgkmcnt(0)
	s_setprio 1
	s_waitcnt lgkmcnt(0)
	v_mfma_f32_16x16x32_f16 v[96:99], v[190:193], v[226:229], v[96:99]
	v_mfma_f32_16x16x32_f16 v[92:95], v[190:193], v[238:241], v[92:95]
	v_mfma_f32_16x16x32_f16 v[88:91], v[198:201], v[226:229], v[88:91]
	v_mfma_f32_16x16x32_f16 v[84:87], v[198:201], v[238:241], v[84:87]
	v_mfma_f32_16x16x32_f16 v[80:83], v[206:209], v[226:229], v[80:83]
	v_mfma_f32_16x16x32_f16 v[76:79], v[206:209], v[238:241], v[76:79]
	v_mfma_f32_16x16x32_f16 v[72:75], v[214:217], v[226:229], v[72:75]
	v_mfma_f32_16x16x32_f16 v[68:71], v[214:217], v[238:241], v[68:71]
	v_mfma_f32_16x16x32_f16 v[96:99], v[194:197], v[230:233], v[96:99]
	v_mfma_f32_16x16x32_f16 v[92:95], v[194:197], v[242:245], v[92:95]
	v_mfma_f32_16x16x32_f16 v[88:91], v[202:205], v[230:233], v[88:91]
	v_mfma_f32_16x16x32_f16 v[84:87], v[202:205], v[242:245], v[84:87]
	v_mfma_f32_16x16x32_f16 v[80:83], v[210:213], v[230:233], v[80:83]
	v_mfma_f32_16x16x32_f16 v[76:79], v[210:213], v[242:245], v[76:79]
	v_mfma_f32_16x16x32_f16 v[72:75], v[218:221], v[230:233], v[72:75]
	v_mfma_f32_16x16x32_f16 v[68:71], v[218:221], v[242:245], v[68:71]
	s_setprio 0
	v_readfirstlane_b32 s14, v166
	v_lshl_add_u64 v[222:223], v[222:223], 0, s[22:23]
	s_mov_b32 m0, s14
	v_readfirstlane_b32 s14, v167
	s_barrier
	ds_read_b128 v[190:193], v161 offset:49152
	ds_read_b128 v[194:197], v161 offset:50176
	ds_read_b128 v[198:201], v160 offset:49152
	ds_read_b128 v[202:205], v160 offset:50176
	ds_read_b128 v[206:209], v159 offset:49152
	ds_read_b128 v[210:213], v159 offset:50176
	ds_read_b128 v[214:217], v158 offset:49152
	ds_read_b128 v[218:221], v158 offset:50176
	global_load_lds_dwordx4 v[222:223], off
	v_lshl_add_u64 v[222:223], v[236:237], 0, s[22:23]
	s_mov_b32 m0, s14
	s_nop 0
	global_load_lds_dwordx4 v[222:223], off
	s_barrier
	s_waitcnt lgkmcnt(0)
	s_setprio 1
	s_waitcnt lgkmcnt(0)
	v_mfma_f32_16x16x32_f16 v[64:67], v[190:193], v[174:177], v[64:67]
	v_mfma_f32_16x16x32_f16 v[60:63], v[190:193], v[182:185], v[60:63]
	v_mfma_f32_16x16x32_f16 v[56:59], v[198:201], v[174:177], v[56:59]
	v_mfma_f32_16x16x32_f16 v[52:55], v[198:201], v[182:185], v[52:55]
	v_mfma_f32_16x16x32_f16 v[48:51], v[206:209], v[174:177], v[48:51]
	v_mfma_f32_16x16x32_f16 v[44:47], v[206:209], v[182:185], v[44:47]
	v_mfma_f32_16x16x32_f16 v[40:43], v[214:217], v[174:177], v[40:43]
	v_mfma_f32_16x16x32_f16 v[36:39], v[214:217], v[182:185], v[36:39]
	v_mfma_f32_16x16x32_f16 v[64:67], v[194:197], v[178:181], v[64:67]
	v_mfma_f32_16x16x32_f16 v[60:63], v[194:197], v[186:189], v[60:63]
	v_mfma_f32_16x16x32_f16 v[56:59], v[202:205], v[178:181], v[56:59]
	v_mfma_f32_16x16x32_f16 v[52:55], v[202:205], v[186:189], v[52:55]
	v_mfma_f32_16x16x32_f16 v[48:51], v[210:213], v[178:181], v[48:51]
	v_mfma_f32_16x16x32_f16 v[44:47], v[210:213], v[186:189], v[44:47]
	v_mfma_f32_16x16x32_f16 v[40:43], v[218:221], v[178:181], v[40:43]
	v_mfma_f32_16x16x32_f16 v[36:39], v[218:221], v[186:189], v[36:39]
	s_setprio 0
	s_barrier
	v_readfirstlane_b32 s14, v168
	v_lshl_add_u64 v[174:175], v[246:247], 0, s[44:45]
	s_mov_b32 m0, s14
	v_readfirstlane_b32 s14, v170
	global_load_lds_dwordx4 v[174:175], off
	v_lshl_add_u64 v[174:175], v[248:249], 0, s[44:45]
	s_mov_b32 m0, s14
	s_nop 0
	global_load_lds_dwordx4 v[174:175], off
	s_waitcnt vmcnt(6)
	s_barrier
	s_setprio 1
	v_mfma_f32_16x16x32_f16 v[32:35], v[190:193], v[226:229], v[32:35]
	v_mfma_f32_16x16x32_f16 v[28:31], v[190:193], v[238:241], v[28:31]
	v_mfma_f32_16x16x32_f16 v[24:27], v[198:201], v[226:229], v[24:27]
	v_mfma_f32_16x16x32_f16 v[20:23], v[198:201], v[238:241], v[20:23]
	v_mfma_f32_16x16x32_f16 v[16:19], v[206:209], v[226:229], v[16:19]
	v_mfma_f32_16x16x32_f16 v[12:15], v[206:209], v[238:241], v[12:15]
	v_mfma_f32_16x16x32_f16 v[8:11], v[214:217], v[226:229], v[8:11]
	v_mfma_f32_16x16x32_f16 v[4:7], v[214:217], v[238:241], v[4:7]
	v_mfma_f32_16x16x32_f16 v[32:35], v[194:197], v[230:233], v[32:35]
	v_mfma_f32_16x16x32_f16 v[28:31], v[194:197], v[242:245], v[28:31]
	v_mfma_f32_16x16x32_f16 v[24:27], v[202:205], v[230:233], v[24:27]
	v_mfma_f32_16x16x32_f16 v[20:23], v[202:205], v[242:245], v[20:23]
	v_mfma_f32_16x16x32_f16 v[16:19], v[210:213], v[230:233], v[16:19]
	v_mfma_f32_16x16x32_f16 v[12:15], v[210:213], v[242:245], v[12:15]
	v_mfma_f32_16x16x32_f16 v[8:11], v[218:221], v[230:233], v[8:11]
	v_mfma_f32_16x16x32_f16 v[4:7], v[218:221], v[242:245], v[4:7]
	s_setprio 0
	s_add_i32 s1, s1, 2
	s_add_u32 s12, s12, 0x100
	s_addc_u32 s13, s13, 0
	s_cmp_lt_u32 s1, 12
	s_barrier
	s_cbranch_scc0 .Lpk_exit_6

; #define LDA8(dst, b, h) _Pragma("unroll") for (int m = 0; m < 4; ++m) _Pragma("unroll") for (int k = 0; k < 2; ++k) \
;     dst[m][k] = *(const bf16x8*)((const char*)SA8(b, h) + lds_byte8(wr * 64 + m * 16 + fr, k * 32 + fq * 8))
; #define LDB8(dst, b, h) _Pragma("unroll") for (int n = 0; n < 2; ++n) _Pragma("unroll") for (int k = 0; k < 2; ++k) \
;     dst[n][k] = *(const bf16x8*)((const char*)SB8(b, h) + lds_byte8(wc * 32 + n * 16 + fr, k * 32 + fq * 8))
; #define WAIT_V8(n) asm volatile("s_waitcnt vmcnt(" #n ")" ::: "memory")
; #define WAIT_L8(n) asm volatile("s_waitcnt lgkmcnt(" #n ")" ::: "memory")
; #define BAR8 __builtin_amdgcn_s_barrier()
;     ...
;   { LDB8(B0, 0, 0); LDA8(At, 0, 0); STAGE8(SA8(1, 1), A, lda, brow + 128, nt - 1);
;     BAR8; WAIT_L8(0); MMA8(0, 0, At, B0); BAR8;
;     LDB8(B1, 0, 1); BAR8; WAIT_L8(0); MMA8(0, 1, At, B1); BAR8;
;     LDA8(At, 0, 1); WAIT_V8(4); BAR8; WAIT_L8(0); MMA8(1, 0, At, B0); MMA8(1, 1, At, B1); BAR8; }
.Lpk_exit_6:
	s_add_u32 s8, s8, 0x40780
	s_addc_u32 s9, s9, 0
	v_lshl_add_u64 v[132:133], s[8:9], 0, v[132:133]
	v_readfirstlane_b32 s1, v172
	v_lshl_add_u64 v[0:1], v[0:1], 1, v[132:133]
	s_mov_b32 m0, s1
	ds_read_b128 v[138:141], v171
	ds_read_b128 v[142:145], v171 offset:1024
	ds_read_b128 v[150:153], v171 offset:2048
	ds_read_b128 v[154:157], v171 offset:3072
	ds_read_b128 v[164:167], v161
	ds_read_b128 v[174:177], v161 offset:1024
	ds_read_b128 v[178:181], v160
	ds_read_b128 v[182:185], v160 offset:1024
	ds_read_b128 v[186:189], v159
	ds_read_b128 v[190:193], v159 offset:1024
	ds_read_b128 v[194:197], v158
	ds_read_b128 v[198:201], v158 offset:1024
	global_load_lds_dwordx4 v[0:1], off
	v_lshl_add_u64 v[0:1], s[8:9], 0, v[136:137]
	v_readfirstlane_b32 s1, v173
	v_lshl_add_u64 v[0:1], v[134:135], 1, v[0:1]
	s_mov_b32 m0, s1
	s_nop 0
	global_load_lds_dwordx4 v[0:1], off
	s_barrier
	s_waitcnt lgkmcnt(0)
	s_setprio 1
	s_waitcnt lgkmcnt(0)
	v_mfma_f32_16x16x32_f16 v[128:131], v[164:167], v[138:141], v[128:131]
	v_mfma_f32_16x16x32_f16 v[124:127], v[164:167], v[150:153], v[124:127]
	v_mfma_f32_16x16x32_f16 v[120:123], v[178:181], v[138:141], v[120:123]
	v_mfma_f32_16x16x32_f16 v[116:119], v[178:181], v[150:153], v[116:119]
	v_mfma_f32_16x16x32_f16 v[104:107], v[194:197], v[138:141], v[104:107]
	v_mfma_f32_16x16x32_f16 v[100:103], v[194:197], v[150:153], v[100:103]
	v_mfma_f32_16x16x32_f16 v[128:131], v[174:177], v[142:145], v[128:131]
	v_mfma_f32_16x16x32_f16 v[124:127], v[174:177], v[154:157], v[124:127]
	v_mfma_f32_16x16x32_f16 v[120:123], v[182:185], v[142:145], v[120:123]
	v_mfma_f32_16x16x32_f16 v[116:119], v[182:185], v[154:157], v[116:119]
	v_mfma_f32_16x16x32_f16 v[112:115], v[186:189], v[138:141], v[112:115]
	v_mfma_f32_16x16x32_f16 v[108:111], v[186:189], v[150:153], v[108:111]
	v_mfma_f32_16x16x32_f16 v[104:107], v[198:201], v[142:145], v[104:107]
	v_mfma_f32_16x16x32_f16 v[100:103], v[198:201], v[154:157], v[100:103]
	v_mfma_f32_16x16x32_f16 v[132:135], v[190:193], v[142:145], v[112:115]
	v_mfma_f32_16x16x32_f16 v[170:173], v[190:193], v[154:157], v[108:111]
	s_setprio 0
	s_barrier
	s_nop 1
	ds_read_b128 v[108:111], v169
	ds_read_b128 v[112:115], v169 offset:1024
	ds_read_b128 v[202:205], v169 offset:2048
	ds_read_b128 v[206:209], v169 offset:3072
	s_barrier
	s_waitcnt lgkmcnt(0)
	s_setprio 1
	s_waitcnt lgkmcnt(0)
	v_mfma_f32_16x16x32_f16 v[88:91], v[178:181], v[108:111], v[88:91]
	v_mfma_f32_16x16x32_f16 v[84:87], v[178:181], v[202:205], v[84:87]
	v_mfma_f32_16x16x32_f16 v[72:75], v[194:197], v[108:111], v[72:75]
	v_mfma_f32_16x16x32_f16 v[68:71], v[194:197], v[202:205], v[68:71]
	v_mfma_f32_16x16x32_f16 v[96:99], v[164:167], v[108:111], v[96:99]
	v_mfma_f32_16x16x32_f16 v[92:95], v[164:167], v[202:205], v[92:95]
	v_mfma_f32_16x16x32_f16 v[88:91], v[182:185], v[112:115], v[88:91]
	v_mfma_f32_16x16x32_f16 v[84:87], v[182:185], v[206:209], v[84:87]
	v_mfma_f32_16x16x32_f16 v[80:83], v[186:189], v[108:111], v[80:83]
	v_mfma_f32_16x16x32_f16 v[76:79], v[186:189], v[202:205], v[76:79]
	v_mfma_f32_16x16x32_f16 v[72:75], v[198:201], v[112:115], v[72:75]
	v_mfma_f32_16x16x32_f16 v[68:71], v[198:201], v[206:209], v[68:71]
	v_mfma_f32_16x16x32_f16 v[210:213], v[174:177], v[112:115], v[96:99]
	v_mfma_f32_16x16x32_f16 v[164:167], v[174:177], v[206:209], v[92:95]
	v_mfma_f32_16x16x32_f16 v[174:177], v[190:193], v[112:115], v[80:83]
	v_mfma_f32_16x16x32_f16 v[178:181], v[190:193], v[206:209], v[76:79]
	s_setprio 0
	s_barrier
	s_nop 0
	ds_read_b128 v[76:79], v161 offset:16384
	ds_read_b128 v[80:83], v161 offset:17408
	ds_read_b128 v[92:95], v160 offset:16384
	ds_read_b128 v[96:99], v160 offset:17408
	ds_read_b128 v[182:185], v159 offset:16384
	ds_read_b128 v[186:189], v159 offset:17408
	ds_read_b128 v[190:193], v158 offset:16384
	ds_read_b128 v[194:197], v158 offset:17408
	s_waitcnt vmcnt(4)
	s_barrier
	s_waitcnt lgkmcnt(0)
	s_setprio 1
	s_waitcnt lgkmcnt(0)
	v_mfma_f32_16x16x32_f16 v[64:67], v[76:79], v[138:141], v[64:67]
	v_mfma_f32_16x16x32_f16 v[60:63], v[76:79], v[150:153], v[60:63]
	v_mfma_f32_16x16x32_f16 v[56:59], v[92:95], v[138:141], v[56:59]
	v_mfma_f32_16x16x32_f16 v[52:55], v[92:95], v[150:153], v[52:55]
	v_mfma_f32_16x16x32_f16 v[40:43], v[190:193], v[138:141], v[40:43]
	v_mfma_f32_16x16x32_f16 v[36:39], v[190:193], v[150:153], v[36:39]
	v_mfma_f32_16x16x32_f16 v[64:67], v[80:83], v[142:145], v[64:67]
	v_mfma_f32_16x16x32_f16 v[60:63], v[80:83], v[154:157], v[60:63]
	v_mfma_f32_16x16x32_f16 v[56:59], v[96:99], v[142:145], v[56:59]
	v_mfma_f32_16x16x32_f16 v[52:55], v[96:99], v[154:157], v[52:55]
	v_mfma_f32_16x16x32_f16 v[48:51], v[182:185], v[138:141], v[48:51]
	v_mfma_f32_16x16x32_f16 v[44:47], v[182:185], v[150:153], v[44:47]
	v_mfma_f32_16x16x32_f16 v[40:43], v[194:197], v[142:145], v[40:43]
	v_mfma_f32_16x16x32_f16 v[36:39], v[194:197], v[154:157], v[36:39]
	v_mfma_f32_16x16x32_f16 v[198:201], v[186:189], v[142:145], v[48:51]
	v_mfma_f32_16x16x32_f16 v[214:217], v[186:189], v[154:157], v[44:47]
	s_setprio 0
	s_setprio 1
	v_mfma_f32_16x16x32_f16 v[24:27], v[92:95], v[108:111], v[24:27]
	v_mfma_f32_16x16x32_f16 v[20:23], v[92:95], v[202:205], v[20:23]
	v_mfma_f32_16x16x32_f16 v[8:11], v[190:193], v[108:111], v[8:11]
	v_mfma_f32_16x16x32_f16 v[4:7], v[190:193], v[202:205], v[4:7]
	v_mfma_f32_16x16x32_f16 v[32:35], v[76:79], v[108:111], v[32:35]
	v_mfma_f32_16x16x32_f16 v[28:31], v[76:79], v[202:205], v[28:31]
	v_mfma_f32_16x16x32_f16 v[24:27], v[96:99], v[112:115], v[24:27]
	v_mfma_f32_16x16x32_f16 v[20:23], v[96:99], v[206:209], v[20:23]
	v_mfma_f32_16x16x32_f16 v[16:19], v[182:185], v[108:111], v[16:19]
	v_mfma_f32_16x16x32_f16 v[12:15], v[182:185], v[202:205], v[12:15]
	v_mfma_f32_16x16x32_f16 v[8:11], v[194:197], v[112:115], v[8:11]
	v_mfma_f32_16x16x32_f16 v[4:7], v[194:197], v[206:209], v[4:7]
	v_mfma_f32_16x16x32_f16 v[136:139], v[80:83], v[112:115], v[32:35]
	v_mfma_f32_16x16x32_f16 v[140:143], v[80:83], v[206:209], v[28:31]
	v_mfma_f32_16x16x32_f16 v[150:153], v[186:189], v[112:115], v[16:19]
	v_mfma_f32_16x16x32_f16 v[154:157], v[186:189], v[206:209], v[12:15]
	s_setprio 0
	s_barrier
; #define LDA8(dst, b, h) _Pragma("unroll") for (int m = 0; m < 4; ++m) _Pragma("unroll") for (int k = 0; k < 2; ++k) \
;     dst[m][k] = *(const bf16x8*)((const char*)SA8(b, h) + lds_byte8(wr * 64 + m * 16 + fr, k * 32 + fq * 8))
; #define LDB8(dst, b, h) _Pragma("unroll") for (int n = 0; n < 2; ++n) _Pragma("unroll") for (int k = 0; k < 2; ++k) \
;     dst[n][k] = *(const bf16x8*)((const char*)SB8(b, h) + lds_byte8(wc * 32 + n * 16 + fr, k * 32 + fq * 8))
; #define WAIT_V8(n) asm volatile("s_waitcnt vmcnt(" #n ")" ::: "memory")
; #define WAIT_L8(n) asm volatile("s_waitcnt lgkmcnt(" #n ")" ::: "memory")
; #define BAR8 __builtin_amdgcn_s_barrier()
;     ...
;   { LDB8(B0, 1, 0); LDA8(At, 1, 0); WAIT_V8(2); BAR8; WAIT_L8(0); MMA8(0, 0, At, B0); BAR8;
;     LDB8(B1, 1, 1); WAIT_V8(0); BAR8; WAIT_L8(0); MMA8(0, 1, At, B1); BAR8;
;     LDA8(At, 1, 1); BAR8; WAIT_L8(0); MMA8(1, 0, At, B0); MMA8(1, 1, At, B1); BAR8; }
;   if (wr == 0) BAR8;
	s_nop 0
	ds_read_b128 v[12:15], v163
	ds_read_b128 v[16:19], v163 offset:1024
	ds_read_b128 v[182:185], v163 offset:2048
	ds_read_b128 v[186:189], v163 offset:3072
	ds_read_b128 v[28:31], v161 offset:32768
	ds_read_b128 v[32:35], v161 offset:33792
	ds_read_b128 v[44:47], v160 offset:32768
	ds_read_b128 v[48:51], v160 offset:33792
	ds_read_b128 v[190:193], v159 offset:32768
	ds_read_b128 v[194:197], v159 offset:33792
	ds_read_b128 v[202:205], v158 offset:32768
	ds_read_b128 v[206:209], v158 offset:33792
	s_waitcnt vmcnt(2)
	s_barrier
	s_waitcnt lgkmcnt(0)
	s_setprio 1
	s_waitcnt lgkmcnt(0)
	v_mfma_f32_16x16x32_f16 v[76:79], v[28:31], v[12:15], v[128:131]
	v_mfma_f32_16x16x32_f16 v[128:131], v[32:35], v[16:19], v[76:79]
	v_mfma_f32_16x16x32_f16 v[76:79], v[28:31], v[182:185], v[124:127]
	v_mfma_f32_16x16x32_f16 v[124:127], v[32:35], v[186:189], v[76:79]
	v_mfma_f32_16x16x32_f16 v[76:79], v[44:47], v[12:15], v[120:123]
	v_mfma_f32_16x16x32_f16 v[112:115], v[48:51], v[16:19], v[76:79]
	v_mfma_f32_16x16x32_f16 v[76:79], v[44:47], v[182:185], v[116:119]
	v_mfma_f32_16x16x32_f16 v[108:111], v[48:51], v[186:189], v[76:79]
	v_mfma_f32_16x16x32_f16 v[76:79], v[190:193], v[12:15], v[132:135]
	v_mfma_f32_16x16x32_f16 v[96:99], v[194:197], v[16:19], v[76:79]
	v_mfma_f32_16x16x32_f16 v[76:79], v[190:193], v[182:185], v[170:173]
	v_mfma_f32_16x16x32_f16 v[92:95], v[194:197], v[186:189], v[76:79]
	v_mfma_f32_16x16x32_f16 v[76:79], v[202:205], v[12:15], v[104:107]
	v_mfma_f32_16x16x32_f16 v[80:83], v[206:209], v[16:19], v[76:79]
	v_mfma_f32_16x16x32_f16 v[76:79], v[202:205], v[182:185], v[100:103]
	v_mfma_f32_16x16x32_f16 v[76:79], v[206:209], v[186:189], v[76:79]
	s_setprio 0
	s_barrier
	ds_read_b128 v[132:135], v162
	ds_read_b128 v[168:171], v162 offset:1024
	ds_read_b128 v[218:221], v162 offset:2048
	ds_read_b128 v[226:229], v162 offset:3072
	s_waitcnt vmcnt(0)
	s_barrier
	s_waitcnt lgkmcnt(0)
	s_setprio 1
	s_waitcnt lgkmcnt(0)
	v_mfma_f32_16x16x32_f16 v[100:103], v[28:31], v[132:135], v[210:213]
	v_mfma_f32_16x16x32_f16 v[28:31], v[28:31], v[218:221], v[164:167]
	v_mfma_f32_16x16x32_f16 v[116:119], v[32:35], v[226:229], v[28:31]
	v_mfma_f32_16x16x32_f16 v[28:31], v[44:47], v[132:135], v[88:91]
	v_mfma_f32_16x16x32_f16 v[104:107], v[48:51], v[168:171], v[28:31]
	v_mfma_f32_16x16x32_f16 v[28:31], v[44:47], v[218:221], v[84:87]
	v_mfma_f32_16x16x32_f16 v[120:123], v[32:35], v[168:171], v[100:103]
	v_mfma_f32_16x16x32_f16 v[100:103], v[48:51], v[226:229], v[28:31]
	v_mfma_f32_16x16x32_f16 v[28:31], v[190:193], v[132:135], v[174:177]
	v_mfma_f32_16x16x32_f16 v[88:91], v[194:197], v[168:171], v[28:31]
	v_mfma_f32_16x16x32_f16 v[28:31], v[190:193], v[218:221], v[178:181]
	v_mfma_f32_16x16x32_f16 v[84:87], v[194:197], v[226:229], v[28:31]
	v_mfma_f32_16x16x32_f16 v[28:31], v[202:205], v[132:135], v[72:75]
	v_mfma_f32_16x16x32_f16 v[72:75], v[206:209], v[168:171], v[28:31]
	v_mfma_f32_16x16x32_f16 v[28:31], v[202:205], v[218:221], v[68:71]
	v_mfma_f32_16x16x32_f16 v[68:71], v[206:209], v[226:229], v[28:31]
	s_setprio 0
	s_barrier
	ds_read_b128 v[162:165], v161 offset:49152
	ds_read_b128 v[172:175], v161 offset:50176
	ds_read_b128 v[176:179], v160 offset:49152
	ds_read_b128 v[190:193], v160 offset:50176
	ds_read_b128 v[194:197], v159 offset:49152
	ds_read_b128 v[202:205], v159 offset:50176
	ds_read_b128 v[206:209], v158 offset:49152
	ds_read_b128 v[158:161], v158 offset:50176
	s_barrier
	s_waitcnt lgkmcnt(0)
	s_setprio 1
	s_waitcnt lgkmcnt(0)
	v_mfma_f32_16x16x32_f16 v[28:31], v[162:165], v[12:15], v[64:67]
	v_mfma_f32_16x16x32_f16 v[64:67], v[172:175], v[16:19], v[28:31]
	v_mfma_f32_16x16x32_f16 v[28:31], v[162:165], v[182:185], v[60:63]
	v_mfma_f32_16x16x32_f16 v[60:63], v[172:175], v[186:189], v[28:31]
	v_mfma_f32_16x16x32_f16 v[28:31], v[176:179], v[12:15], v[56:59]
	v_mfma_f32_16x16x32_f16 v[48:51], v[190:193], v[16:19], v[28:31]
	v_mfma_f32_16x16x32_f16 v[28:31], v[176:179], v[182:185], v[52:55]
	v_mfma_f32_16x16x32_f16 v[44:47], v[190:193], v[186:189], v[28:31]
	v_mfma_f32_16x16x32_f16 v[28:31], v[194:197], v[12:15], v[198:201]
	v_mfma_f32_16x16x32_f16 v[12:15], v[206:209], v[12:15], v[40:43]
	v_mfma_f32_16x16x32_f16 v[32:35], v[202:205], v[16:19], v[28:31]
	v_mfma_f32_16x16x32_f16 v[28:31], v[194:197], v[182:185], v[214:217]
	v_mfma_f32_16x16x32_f16 v[16:19], v[158:161], v[16:19], v[12:15]
	v_mfma_f32_16x16x32_f16 v[12:15], v[206:209], v[182:185], v[36:39]
	v_mfma_f32_16x16x32_f16 v[28:31], v[202:205], v[186:189], v[28:31]
	v_mfma_f32_16x16x32_f16 v[12:15], v[158:161], v[186:189], v[12:15]
	s_setprio 0
	s_setprio 1
	v_mfma_f32_16x16x32_f16 v[36:39], v[162:165], v[132:135], v[136:139]
	v_mfma_f32_16x16x32_f16 v[56:59], v[172:175], v[168:171], v[36:39]
	v_mfma_f32_16x16x32_f16 v[36:39], v[162:165], v[218:221], v[140:143]
	v_mfma_f32_16x16x32_f16 v[20:23], v[176:179], v[218:221], v[20:23]
	v_mfma_f32_16x16x32_f16 v[52:55], v[172:175], v[226:229], v[36:39]
	v_mfma_f32_16x16x32_f16 v[24:27], v[176:179], v[132:135], v[24:27]
	v_mfma_f32_16x16x32_f16 v[36:39], v[190:193], v[226:229], v[20:23]
	v_mfma_f32_16x16x32_f16 v[20:23], v[194:197], v[132:135], v[150:153]
	v_mfma_f32_16x16x32_f16 v[40:43], v[190:193], v[168:171], v[24:27]
	v_mfma_f32_16x16x32_f16 v[24:27], v[202:205], v[168:171], v[20:23]
	v_mfma_f32_16x16x32_f16 v[20:23], v[194:197], v[218:221], v[154:157]
	v_mfma_f32_16x16x32_f16 v[8:11], v[206:209], v[132:135], v[8:11]
	v_mfma_f32_16x16x32_f16 v[4:7], v[206:209], v[218:221], v[4:7]
	v_mfma_f32_16x16x32_f16 v[20:23], v[202:205], v[226:229], v[20:23]
	v_mfma_f32_16x16x32_f16 v[8:11], v[158:161], v[168:171], v[8:11]
	v_mfma_f32_16x16x32_f16 v[4:7], v[158:161], v[226:229], v[4:7]
	s_setprio 0
	s_movk_i32 s1, 0x100
	v_cmp_gt_u32_e32 vcc, s1, v3
	s_barrier
	s_and_saveexec_b64 s[8:9], vcc
	s_cbranch_execz .LBB0_1262
	s_barrier

; #define LDA8(dst, b, h) _Pragma("unroll") for (int m = 0; m < 4; ++m) _Pragma("unroll") for (int k = 0; k < 2; ++k) \
;     dst[m][k] = *(const bf16x8*)((const char*)SA8(b, h) + lds_byte8(wr * 64 + m * 16 + fr, k * 32 + fq * 8))
; #define LDB8(dst, b, h) _Pragma("unroll") for (int n = 0; n < 2; ++n) _Pragma("unroll") for (int k = 0; k < 2; ++k) \
;     dst[n][k] = *(const bf16x8*)((const char*)SB8(b, h) + lds_byte8(wc * 32 + n * 16 + fr, k * 32 + fq * 8))
; #define WAIT_V8(n) asm volatile("s_waitcnt vmcnt(" #n ")" ::: "memory")
; #define WAIT_L8(n) asm volatile("s_waitcnt lgkmcnt(" #n ")" ::: "memory")
; #define BAR8 __builtin_amdgcn_s_barrier()
; #define SCHED8 __builtin_amdgcn_sched_barrier(0)
;     ...
;   const int brow = m0, bcol = n0;
;   const int wid = t >> 6, lane = t & 63, wr = wid >> 2, wc = wid & 3, fr = lane & 15, fq = lane >> 4;
;   f32x4 acc[2][2][4][2];
;   {
;     float zinit = 0.f;
;     asm volatile("" : "+v"(zinit));
; #pragma unroll
;     for (int a = 0; a < 2; ++a)
; #pragma unroll
;       for (int b = 0; b < 2; ++b)
; #pragma unroll
;         for (int m = 0; m < 4; ++m)
; #pragma unroll
;           for (int n = 0; n < 2; ++n)
; #pragma unroll
;             for (int j = 0; j < 4; ++j) acc[a][b][m][n][j] = zinit;
;   }
;   bf16x8 At[4][2], B0[2][2], B1[2][2];
;   const int nt = K / 64;
;   if (!pre) {
;     STAGE8(SB8(0, 0), Bt, K, bcol, 0); STAGE8(SA8(0, 0), A, lda, brow, 0);
;     STAGE8(SB8(0, 1), Bt, K, bcol + 128, 0); STAGE8(SA8(0, 1), A, lda, brow + 128, 0);
;   }
;   if (wr == 1) BAR8;
;   WAIT_V8(4); BAR8;
;   STAGE8(SB8(1, 0), Bt, K, bcol, 1); STAGE8(SA8(1, 0), A, lda, brow, 1); STAGE8(SB8(1, 1), Bt, K, bcol + 128, 1);
;   WAIT_V8(6); BAR8;
;   for (int tt = 0; tt < nt - 2; tt += 2) {
;     LDB8(B0, 0, 0); SCHED8; LDA8(At, 0, 0); STAGE8(SA8(1, 1), A, lda, brow + 128, tt + 1);
;     WAIT_L8(8); BAR8; WAIT_L8(0); MMA8(0, 0, At, B0); BAR8; SCHED8;
.LBB0_1324:
	s_or_b64 exec, exec, s[12:13]
	v_add_u32_e32 v164, 0x18000, v150
	s_mov_b64 s[36:37], 0x80
	v_readfirstlane_b32 s12, v164
	v_add_u32_e32 v165, 0x1a000, v150
	v_lshl_add_u64 v[10:11], v[10:11], 0, s[36:37]
	s_mov_b32 m0, s12
	v_readfirstlane_b32 s12, v165
	v_add_u32_e32 v166, 0x8000, v150
	s_waitcnt vmcnt(4)
	s_barrier
	global_load_lds_dwordx4 v[10:11], off
	v_lshl_add_u64 v[10:11], v[12:13], 0, s[36:37]
	s_mov_b32 m0, s12
	v_readfirstlane_b32 s12, v166
	v_add_u32_e32 v167, 0xa000, v150
	global_load_lds_dwordx4 v[10:11], off
	v_lshl_add_u64 v[10:11], v[14:15], 0, s[36:37]
	s_mov_b32 m0, s12
	v_readfirstlane_b32 s12, v167
	v_add_u32_e32 v168, 0x1c000, v150
	global_load_lds_dwordx4 v[10:11], off
	v_lshl_add_u64 v[10:11], v[16:17], 0, s[36:37]
	s_mov_b32 m0, s12
	v_readfirstlane_b32 s12, v168
	v_add_u32_e32 v170, 0x1e000, v150
	global_load_lds_dwordx4 v[10:11], off
	v_lshl_add_u64 v[10:11], v[18:19], 0, s[36:37]
	s_mov_b32 m0, s12
	v_readfirstlane_b32 s12, v170
	global_load_lds_dwordx4 v[10:11], off
	v_lshl_add_u64 v[10:11], v[20:21], 0, s[36:37]
	s_mov_b32 m0, s12
	v_and_b32_e32 v147, 15, v3
	global_load_lds_dwordx4 v[10:11], off
	v_bfe_u32 v148, v3, 4, 2
	v_lshlrev_b32_e32 v10, 4, v148
	v_lshlrev_b32_e32 v11, 6, v147
	v_lshlrev_b32_e32 v13, 2, v3
	v_or_b32_e32 v12, v10, v11
	v_and_b32_e32 v13, 32, v13
	s_mov_b32 s12, 0x10000
	v_bitop3_b32 v18, v12, s12, v13 bitop3:0xde
	s_mov_b32 s12, 0x14000
	v_bitop3_b32 v17, v10, v13, v11 bitop3:0x36
	v_bitop3_b32 v19, v12, s12, v13 bitop3:0xde
	s_mov_b32 s12, 0x18000
	v_lshlrev_b32_e32 v11, 6, v3
	v_bitop3_b32 v20, v12, s12, v13 bitop3:0xde
	s_mov_b32 s12, 0x1c000
	v_and_b32_e32 v11, 0x3c0, v11
	s_movk_i32 s31, 0x1600
	s_and_b32 s29, s21, 0xffffff00
	v_bitop3_b32 v21, v12, s12, v13 bitop3:0xde
	v_bitop3_b32 v24, v11, v13, v10 bitop3:0x36
	v_mad_i64_i32 v[10:11], s[12:13], v5, s31, 0
	v_mov_b32_e32 v5, 0x1600
	v_mad_i64_i32 v[12:13], s[12:13], s29, v5, v[10:11]
	v_lshl_add_u64 v[12:13], v[12:13], 0, v[6:7]
	v_lshl_add_u64 v[138:139], s[4:5], 0, v[12:13]
	v_mad_i64_i32 v[12:13], s[12:13], v22, s31, 0
	v_mad_i64_i32 v[14:15], s[12:13], s29, v5, v[12:13]
	s_bfe_u32 s29, s20, 0x60008
	v_mov_b32_e32 v5, 0x160000
	v_mad_u64_u32 v[10:11], s[12:13], s29, v5, v[10:11]
	v_lshl_add_u64 v[6:7], v[10:11], 0, v[6:7]
	v_bfe_u32 v146, v3, 6, 2
	s_waitcnt vmcnt(6)
	v_lshlrev_b32_e32 v149, 6, v23
	v_lshlrev_b32_e32 v23, 13, v23
	v_lshl_add_u64 v[142:143], s[2:3], 0, v[6:7]
	v_mad_u64_u32 v[6:7], s[12:13], s29, v5, v[12:13]
	v_lshlrev_b32_e32 v16, 12, v146
	v_or_b32_e32 v25, 0x800, v23
	v_or_b32_e32 v26, 0x1000, v23
	v_or_b32_e32 v27, 0x1800, v23
	v_lshl_add_u64 v[14:15], v[14:15], 0, v[8:9]
	v_lshl_add_u64 v[6:7], v[6:7], 0, v[8:9]
	s_ashr_i32 s9, s8, 31
	v_lshl_add_u64 v[140:141], s[4:5], 0, v[14:15]
	v_lshl_add_u64 v[144:145], s[2:3], 0, v[6:7]
	s_mov_b32 s29, -2
	s_mov_b64 s[12:13], 0
	v_add_u32_e32 v171, v18, v16
	v_add_u32_e32 v156, v17, v23
	v_add_u32_e32 v155, v24, v25
	v_add_u32_e32 v154, v24, v26
	v_add_u32_e32 v153, v24, v27
	v_add_u32_e32 v169, v19, v16
	v_add_u32_e32 v159, v20, v16
	v_add_u32_e32 v158, v21, v16
	s_mov_b64 s[36:37], 0x20b0080
	s_mov_b64 s[38:39], 0xd5a0100
	s_mov_b64 s[40:41], 0x2000100
	s_mov_b64 s[42:43], 0xd650100
	s_mov_b64 s[44:45], 0x20b0100
	s_mov_b64 s[46:47], 0xd5a0180
	s_mov_b64 s[48:49], 0x2000180
	s_mov_b64 s[50:51], 0xd650180
	s_barrier
	ds_read_b128 v[174:177], v171
	ds_read_b128 v[178:181], v171 offset:1024
	ds_read_b128 v[182:185], v171 offset:2048
	ds_read_b128 v[186:189], v171 offset:3072
	v_add_u32_e32 v172, 0xc000, v150
	v_lshl_add_u64 v[222:223], v[142:143], 0, s[12:13]
	v_readfirstlane_b32 s31, v172
	v_add_u32_e32 v173, 0xe000, v150
	v_lshl_add_u64 v[226:227], v[222:223], 0, s[36:37]
	s_mov_b32 m0, s31
	v_lshl_add_u64 v[236:237], v[144:145], 0, s[12:13]
	v_readfirstlane_b32 s31, v173
	ds_read_b128 v[190:193], v156
	ds_read_b128 v[194:197], v156 offset:1024
	ds_read_b128 v[198:201], v155
	ds_read_b128 v[202:205], v155 offset:1024
	ds_read_b128 v[206:209], v154
	ds_read_b128 v[210:213], v154 offset:1024
	ds_read_b128 v[214:217], v153
	ds_read_b128 v[218:221], v153 offset:1024
	global_load_lds_dwordx4 v[226:227], off
	v_lshl_add_u64 v[226:227], v[236:237], 0, s[36:37]
	s_mov_b32 m0, s31
	s_nop 0
	global_load_lds_dwordx4 v[226:227], off
	s_waitcnt lgkmcnt(8)
	s_barrier
	s_waitcnt lgkmcnt(0)
	s_setprio 1
	s_waitcnt lgkmcnt(0)
	v_mfma_f32_16x16x32_bf16 v[128:131], v[190:193], v[174:177], 0
	v_mfma_f32_16x16x32_bf16 v[124:127], v[190:193], v[182:185], 0
	v_mfma_f32_16x16x32_bf16 v[120:123], v[198:201], v[174:177], 0
	v_mfma_f32_16x16x32_bf16 v[116:119], v[198:201], v[182:185], 0
	v_mfma_f32_16x16x32_bf16 v[112:115], v[206:209], v[174:177], 0
	v_mfma_f32_16x16x32_bf16 v[108:111], v[206:209], v[182:185], 0
	v_mfma_f32_16x16x32_bf16 v[104:107], v[214:217], v[174:177], 0
	v_mfma_f32_16x16x32_bf16 v[100:103], v[214:217], v[182:185], 0
	v_mfma_f32_16x16x32_bf16 v[128:131], v[194:197], v[178:181], v[128:131]
	v_mfma_f32_16x16x32_bf16 v[124:127], v[194:197], v[186:189], v[124:127]
	v_mfma_f32_16x16x32_bf16 v[120:123], v[202:205], v[178:181], v[120:123]
	v_mfma_f32_16x16x32_bf16 v[116:119], v[202:205], v[186:189], v[116:119]
	v_mfma_f32_16x16x32_bf16 v[112:115], v[210:213], v[178:181], v[112:115]
	v_mfma_f32_16x16x32_bf16 v[108:111], v[210:213], v[186:189], v[108:111]
	v_mfma_f32_16x16x32_bf16 v[104:107], v[218:221], v[178:181], v[104:107]
	v_mfma_f32_16x16x32_bf16 v[100:103], v[218:221], v[186:189], v[100:103]
	s_setprio 0
	s_barrier
; #define LDA8(dst, b, h) _Pragma("unroll") for (int m = 0; m < 4; ++m) _Pragma("unroll") for (int k = 0; k < 2; ++k) \
;     dst[m][k] = *(const bf16x8*)((const char*)SA8(b, h) + lds_byte8(wr * 64 + m * 16 + fr, k * 32 + fq * 8))
; #define LDB8(dst, b, h) _Pragma("unroll") for (int n = 0; n < 2; ++n) _Pragma("unroll") for (int k = 0; k < 2; ++k) \
;     dst[n][k] = *(const bf16x8*)((const char*)SB8(b, h) + lds_byte8(wc * 32 + n * 16 + fr, k * 32 + fq * 8))
; #define WAIT_V8(n) asm volatile("s_waitcnt vmcnt(" #n ")" ::: "memory")
; #define WAIT_L8(n) asm volatile("s_waitcnt lgkmcnt(" #n ")" ::: "memory")
; #define BAR8 __builtin_amdgcn_s_barrier()
; #define SCHED8 __builtin_amdgcn_sched_barrier(0)
;     ...
;     LDB8(B1, 0, 1); STAGE8(SB8(0, 0), Bt, K, bcol, tt + 2);
;     BAR8; WAIT_L8(0); MMA8(0, 1, At, B1); BAR8;
;     LDA8(At, 0, 1); STAGE8(SA8(0, 0), A, lda, brow, tt + 2);
;     BAR8; WAIT_L8(0); MMA8(1, 0, At, B0); BAR8; SCHED8;
;     STAGE8(SB8(0, 1), Bt, K, bcol + 128, tt + 2);
;     WAIT_V8(6); BAR8; MMA8(1, 1, At, B1); BAR8;
;     LDB8(B0, 1, 0); SCHED8; LDA8(At, 1, 0); STAGE8(SA8(0, 1), A, lda, brow + 128, tt + 2);
;     WAIT_L8(8); BAR8; WAIT_L8(0); MMA8(0, 0, At, B0); BAR8; SCHED8;
	v_lshl_add_u64 v[246:247], v[138:139], 0, s[12:13]
	v_readfirstlane_b32 s31, v151
	v_lshl_add_u64 v[248:249], v[246:247], 0, s[38:39]
	s_mov_b32 m0, s31
	ds_read_b128 v[226:229], v169
	ds_read_b128 v[230:233], v169 offset:1024
	ds_read_b128 v[238:241], v169 offset:2048
	ds_read_b128 v[242:245], v169 offset:3072
	global_load_lds_dwordx4 v[248:249], off
	v_lshl_add_u64 v[248:249], v[140:141], 0, s[12:13]
	v_readfirstlane_b32 s31, v157
	v_lshl_add_u64 v[250:251], v[248:249], 0, s[38:39]
	s_mov_b32 m0, s31
	s_nop 0
	global_load_lds_dwordx4 v[250:251], off
	s_barrier
	s_waitcnt lgkmcnt(0)
	s_setprio 1
	s_waitcnt lgkmcnt(0)
	v_mfma_f32_16x16x32_bf16 v[96:99], v[190:193], v[226:229], 0
	v_mfma_f32_16x16x32_bf16 v[92:95], v[190:193], v[238:241], 0
	v_mfma_f32_16x16x32_bf16 v[88:91], v[198:201], v[226:229], 0
	v_mfma_f32_16x16x32_bf16 v[84:87], v[198:201], v[238:241], 0
	v_mfma_f32_16x16x32_bf16 v[80:83], v[206:209], v[226:229], 0
	v_mfma_f32_16x16x32_bf16 v[76:79], v[206:209], v[238:241], 0
	v_mfma_f32_16x16x32_bf16 v[72:75], v[214:217], v[226:229], 0
	v_mfma_f32_16x16x32_bf16 v[68:71], v[214:217], v[238:241], 0
	v_mfma_f32_16x16x32_bf16 v[96:99], v[194:197], v[230:233], v[96:99]
	v_mfma_f32_16x16x32_bf16 v[92:95], v[194:197], v[242:245], v[92:95]
	v_mfma_f32_16x16x32_bf16 v[88:91], v[202:205], v[230:233], v[88:91]
	v_mfma_f32_16x16x32_bf16 v[84:87], v[202:205], v[242:245], v[84:87]
	v_mfma_f32_16x16x32_bf16 v[80:83], v[210:213], v[230:233], v[80:83]
	v_mfma_f32_16x16x32_bf16 v[76:79], v[210:213], v[242:245], v[76:79]
	v_mfma_f32_16x16x32_bf16 v[72:75], v[218:221], v[230:233], v[72:75]
	v_mfma_f32_16x16x32_bf16 v[68:71], v[218:221], v[242:245], v[68:71]
	s_setprio 0
	v_readfirstlane_b32 s31, v150
	v_lshl_add_u64 v[250:251], v[222:223], 0, s[40:41]
	s_mov_b32 m0, s31
	v_readfirstlane_b32 s31, v152
	s_barrier
	ds_read_b128 v[190:193], v156 offset:16384
	ds_read_b128 v[194:197], v156 offset:17408
	ds_read_b128 v[198:201], v155 offset:16384
	ds_read_b128 v[202:205], v155 offset:17408
	ds_read_b128 v[206:209], v154 offset:16384
	ds_read_b128 v[210:213], v154 offset:17408
	ds_read_b128 v[214:217], v153 offset:16384
	ds_read_b128 v[218:221], v153 offset:17408
	global_load_lds_dwordx4 v[250:251], off
	v_lshl_add_u64 v[250:251], v[236:237], 0, s[40:41]
	s_mov_b32 m0, s31
	s_nop 0
	global_load_lds_dwordx4 v[250:251], off
	s_barrier
	s_waitcnt lgkmcnt(0)
	s_setprio 1
	s_waitcnt lgkmcnt(0)
	v_mfma_f32_16x16x32_bf16 v[64:67], v[190:193], v[174:177], 0
	v_mfma_f32_16x16x32_bf16 v[60:63], v[190:193], v[182:185], 0
	v_mfma_f32_16x16x32_bf16 v[56:59], v[198:201], v[174:177], 0
	v_mfma_f32_16x16x32_bf16 v[52:55], v[198:201], v[182:185], 0
	v_mfma_f32_16x16x32_bf16 v[48:51], v[206:209], v[174:177], 0
	v_mfma_f32_16x16x32_bf16 v[44:47], v[206:209], v[182:185], 0
	v_mfma_f32_16x16x32_bf16 v[40:43], v[214:217], v[174:177], 0
	v_mfma_f32_16x16x32_bf16 v[36:39], v[214:217], v[182:185], 0
	v_mfma_f32_16x16x32_bf16 v[64:67], v[194:197], v[178:181], v[64:67]
	v_mfma_f32_16x16x32_bf16 v[60:63], v[194:197], v[186:189], v[60:63]
	v_mfma_f32_16x16x32_bf16 v[56:59], v[202:205], v[178:181], v[56:59]
	v_mfma_f32_16x16x32_bf16 v[52:55], v[202:205], v[186:189], v[52:55]
	v_mfma_f32_16x16x32_bf16 v[48:51], v[210:213], v[178:181], v[48:51]
	v_mfma_f32_16x16x32_bf16 v[44:47], v[210:213], v[186:189], v[44:47]
	v_mfma_f32_16x16x32_bf16 v[40:43], v[218:221], v[178:181], v[40:43]
	v_mfma_f32_16x16x32_bf16 v[36:39], v[218:221], v[186:189], v[36:39]
	s_setprio 0
	s_barrier
	v_readfirstlane_b32 s31, v160
	v_lshl_add_u64 v[174:175], v[246:247], 0, s[42:43]
	s_mov_b32 m0, s31
	v_readfirstlane_b32 s31, v161
	global_load_lds_dwordx4 v[174:175], off
	v_lshl_add_u64 v[174:175], v[248:249], 0, s[42:43]
	s_mov_b32 m0, s31
	s_nop 0
	global_load_lds_dwordx4 v[174:175], off
	s_waitcnt vmcnt(6)
	s_barrier
	s_setprio 1
	v_mfma_f32_16x16x32_bf16 v[32:35], v[190:193], v[226:229], 0
	v_mfma_f32_16x16x32_bf16 v[28:31], v[190:193], v[238:241], 0
	v_mfma_f32_16x16x32_bf16 v[24:27], v[198:201], v[226:229], 0
	v_mfma_f32_16x16x32_bf16 v[20:23], v[198:201], v[238:241], 0
	v_mfma_f32_16x16x32_bf16 v[16:19], v[206:209], v[226:229], 0
	v_mfma_f32_16x16x32_bf16 v[12:15], v[206:209], v[238:241], 0
	v_mfma_f32_16x16x32_bf16 v[8:11], v[214:217], v[226:229], 0
	v_mfma_f32_16x16x32_bf16 v[4:7], v[214:217], v[238:241], 0
	v_mfma_f32_16x16x32_bf16 v[32:35], v[194:197], v[230:233], v[32:35]
	v_mfma_f32_16x16x32_bf16 v[28:31], v[194:197], v[242:245], v[28:31]
	v_mfma_f32_16x16x32_bf16 v[24:27], v[202:205], v[230:233], v[24:27]
	v_mfma_f32_16x16x32_bf16 v[20:23], v[202:205], v[242:245], v[20:23]
	v_mfma_f32_16x16x32_bf16 v[16:19], v[210:213], v[230:233], v[16:19]
	v_mfma_f32_16x16x32_bf16 v[12:15], v[210:213], v[242:245], v[12:15]
	v_mfma_f32_16x16x32_bf16 v[8:11], v[218:221], v[230:233], v[8:11]
	v_mfma_f32_16x16x32_bf16 v[4:7], v[218:221], v[242:245], v[4:7]
	s_setprio 0
	s_barrier
	ds_read_b128 v[174:177], v159
	ds_read_b128 v[178:181], v159 offset:1024
	ds_read_b128 v[182:185], v159 offset:2048
	ds_read_b128 v[186:189], v159 offset:3072
	v_readfirstlane_b32 s31, v162
	v_lshl_add_u64 v[226:227], v[222:223], 0, s[44:45]
	s_mov_b32 m0, s31
	v_readfirstlane_b32 s31, v163
	ds_read_b128 v[190:193], v156 offset:32768
	ds_read_b128 v[194:197], v156 offset:33792
	ds_read_b128 v[198:201], v155 offset:32768
	ds_read_b128 v[202:205], v155 offset:33792
	ds_read_b128 v[206:209], v154 offset:32768
	ds_read_b128 v[210:213], v154 offset:33792
	ds_read_b128 v[214:217], v153 offset:32768
	ds_read_b128 v[218:221], v153 offset:33792
	global_load_lds_dwordx4 v[226:227], off
	v_lshl_add_u64 v[226:227], v[236:237], 0, s[44:45]
	s_mov_b32 m0, s31
	s_nop 0
	global_load_lds_dwordx4 v[226:227], off
	s_waitcnt lgkmcnt(8)
	s_barrier
; #define LDA8(dst, b, h) _Pragma("unroll") for (int m = 0; m < 4; ++m) _Pragma("unroll") for (int k = 0; k < 2; ++k) \
;     dst[m][k] = *(const bf16x8*)((const char*)SA8(b, h) + lds_byte8(wr * 64 + m * 16 + fr, k * 32 + fq * 8))
; #define LDB8(dst, b, h) _Pragma("unroll") for (int n = 0; n < 2; ++n) _Pragma("unroll") for (int k = 0; k < 2; ++k) \
;     dst[n][k] = *(const bf16x8*)((const char*)SB8(b, h) + lds_byte8(wc * 32 + n * 16 + fr, k * 32 + fq * 8))
; #define WAIT_V8(n) asm volatile("s_waitcnt vmcnt(" #n ")" ::: "memory")
; #define WAIT_L8(n) asm volatile("s_waitcnt lgkmcnt(" #n ")" ::: "memory")
; #define BAR8 __builtin_amdgcn_s_barrier()
; #define SCHED8 __builtin_amdgcn_sched_barrier(0)
;     ...
;     WAIT_L8(8); BAR8; WAIT_L8(0); MMA8(0, 0, At, B0); BAR8; SCHED8;
;     LDB8(B1, 1, 1); STAGE8(SB8(1, 0), Bt, K, bcol, tt + 3);
;     BAR8; WAIT_L8(0); MMA8(0, 1, At, B1); BAR8;
;     LDA8(At, 1, 1); STAGE8(SA8(1, 0), A, lda, brow, tt + 3);
;     BAR8; WAIT_L8(0); MMA8(1, 0, At, B0); BAR8; SCHED8;
;     STAGE8(SB8(1, 1), Bt, K, bcol + 128, tt + 3);
;     WAIT_V8(6); BAR8; MMA8(1, 1, At, B1); BAR8;
;   }
	s_waitcnt lgkmcnt(0)
	s_setprio 1
	s_waitcnt lgkmcnt(0)
	v_mfma_f32_16x16x32_bf16 v[128:131], v[190:193], v[174:177], v[128:131]
	v_mfma_f32_16x16x32_bf16 v[124:127], v[190:193], v[182:185], v[124:127]
	v_mfma_f32_16x16x32_bf16 v[120:123], v[198:201], v[174:177], v[120:123]
	v_mfma_f32_16x16x32_bf16 v[116:119], v[198:201], v[182:185], v[116:119]
	v_mfma_f32_16x16x32_bf16 v[112:115], v[206:209], v[174:177], v[112:115]
	v_mfma_f32_16x16x32_bf16 v[108:111], v[206:209], v[182:185], v[108:111]
	v_mfma_f32_16x16x32_bf16 v[104:107], v[214:217], v[174:177], v[104:107]
	v_mfma_f32_16x16x32_bf16 v[100:103], v[214:217], v[182:185], v[100:103]
	v_mfma_f32_16x16x32_bf16 v[128:131], v[194:197], v[178:181], v[128:131]
	v_mfma_f32_16x16x32_bf16 v[124:127], v[194:197], v[186:189], v[124:127]
	v_mfma_f32_16x16x32_bf16 v[120:123], v[202:205], v[178:181], v[120:123]
	v_mfma_f32_16x16x32_bf16 v[116:119], v[202:205], v[186:189], v[116:119]
	v_mfma_f32_16x16x32_bf16 v[112:115], v[210:213], v[178:181], v[112:115]
	v_mfma_f32_16x16x32_bf16 v[108:111], v[210:213], v[186:189], v[108:111]
	v_mfma_f32_16x16x32_bf16 v[104:107], v[218:221], v[178:181], v[104:107]
	v_mfma_f32_16x16x32_bf16 v[100:103], v[218:221], v[186:189], v[100:103]
	s_setprio 0
	s_barrier
	v_readfirstlane_b32 s31, v164
	v_lshl_add_u64 v[250:251], v[246:247], 0, s[46:47]
	s_mov_b32 m0, s31
	v_readfirstlane_b32 s31, v165
	ds_read_b128 v[226:229], v158
	ds_read_b128 v[230:233], v158 offset:1024
	ds_read_b128 v[238:241], v158 offset:2048
	ds_read_b128 v[242:245], v158 offset:3072
	global_load_lds_dwordx4 v[250:251], off
	v_lshl_add_u64 v[250:251], v[248:249], 0, s[46:47]
	s_mov_b32 m0, s31
	s_nop 0
	global_load_lds_dwordx4 v[250:251], off
	s_barrier
	s_waitcnt lgkmcnt(0)
	s_setprio 1
	s_waitcnt lgkmcnt(0)
	v_mfma_f32_16x16x32_bf16 v[96:99], v[190:193], v[226:229], v[96:99]
	v_mfma_f32_16x16x32_bf16 v[92:95], v[190:193], v[238:241], v[92:95]
	v_mfma_f32_16x16x32_bf16 v[88:91], v[198:201], v[226:229], v[88:91]
	v_mfma_f32_16x16x32_bf16 v[84:87], v[198:201], v[238:241], v[84:87]
	v_mfma_f32_16x16x32_bf16 v[80:83], v[206:209], v[226:229], v[80:83]
	v_mfma_f32_16x16x32_bf16 v[76:79], v[206:209], v[238:241], v[76:79]
	v_mfma_f32_16x16x32_bf16 v[72:75], v[214:217], v[226:229], v[72:75]
	v_mfma_f32_16x16x32_bf16 v[68:71], v[214:217], v[238:241], v[68:71]
	v_mfma_f32_16x16x32_bf16 v[96:99], v[194:197], v[230:233], v[96:99]
	v_mfma_f32_16x16x32_bf16 v[92:95], v[194:197], v[242:245], v[92:95]
	v_mfma_f32_16x16x32_bf16 v[88:91], v[202:205], v[230:233], v[88:91]
	v_mfma_f32_16x16x32_bf16 v[84:87], v[202:205], v[242:245], v[84:87]
	v_mfma_f32_16x16x32_bf16 v[80:83], v[210:213], v[230:233], v[80:83]
	v_mfma_f32_16x16x32_bf16 v[76:79], v[210:213], v[242:245], v[76:79]
	v_mfma_f32_16x16x32_bf16 v[72:75], v[218:221], v[230:233], v[72:75]
	v_mfma_f32_16x16x32_bf16 v[68:71], v[218:221], v[242:245], v[68:71]
	s_setprio 0
	v_readfirstlane_b32 s31, v166
	v_lshl_add_u64 v[222:223], v[222:223], 0, s[48:49]
	s_mov_b32 m0, s31
	v_readfirstlane_b32 s31, v167
	s_barrier
	ds_read_b128 v[190:193], v156 offset:49152
	ds_read_b128 v[194:197], v156 offset:50176
	ds_read_b128 v[198:201], v155 offset:49152
	ds_read_b128 v[202:205], v155 offset:50176
	ds_read_b128 v[206:209], v154 offset:49152
	ds_read_b128 v[210:213], v154 offset:50176
	ds_read_b128 v[214:217], v153 offset:49152
	ds_read_b128 v[218:221], v153 offset:50176
	global_load_lds_dwordx4 v[222:223], off
	v_lshl_add_u64 v[222:223], v[236:237], 0, s[48:49]
	s_mov_b32 m0, s31
	s_nop 0
	global_load_lds_dwordx4 v[222:223], off
	s_barrier
	s_waitcnt lgkmcnt(0)
	s_setprio 1
	s_waitcnt lgkmcnt(0)
	v_mfma_f32_16x16x32_bf16 v[64:67], v[190:193], v[174:177], v[64:67]
	v_mfma_f32_16x16x32_bf16 v[60:63], v[190:193], v[182:185], v[60:63]
	v_mfma_f32_16x16x32_bf16 v[56:59], v[198:201], v[174:177], v[56:59]
	v_mfma_f32_16x16x32_bf16 v[52:55], v[198:201], v[182:185], v[52:55]
	v_mfma_f32_16x16x32_bf16 v[48:51], v[206:209], v[174:177], v[48:51]
	v_mfma_f32_16x16x32_bf16 v[44:47], v[206:209], v[182:185], v[44:47]
	v_mfma_f32_16x16x32_bf16 v[40:43], v[214:217], v[174:177], v[40:43]
	v_mfma_f32_16x16x32_bf16 v[36:39], v[214:217], v[182:185], v[36:39]
	v_mfma_f32_16x16x32_bf16 v[64:67], v[194:197], v[178:181], v[64:67]
	v_mfma_f32_16x16x32_bf16 v[60:63], v[194:197], v[186:189], v[60:63]
	v_mfma_f32_16x16x32_bf16 v[56:59], v[202:205], v[178:181], v[56:59]
	v_mfma_f32_16x16x32_bf16 v[52:55], v[202:205], v[186:189], v[52:55]
	v_mfma_f32_16x16x32_bf16 v[48:51], v[210:213], v[178:181], v[48:51]
	v_mfma_f32_16x16x32_bf16 v[44:47], v[210:213], v[186:189], v[44:47]
	v_mfma_f32_16x16x32_bf16 v[40:43], v[218:221], v[178:181], v[40:43]
	v_mfma_f32_16x16x32_bf16 v[36:39], v[218:221], v[186:189], v[36:39]
	s_setprio 0
	s_barrier
	v_readfirstlane_b32 s31, v168
	v_lshl_add_u64 v[174:175], v[246:247], 0, s[50:51]
	s_mov_b32 m0, s31
	v_readfirstlane_b32 s31, v170
	global_load_lds_dwordx4 v[174:175], off
	v_lshl_add_u64 v[174:175], v[248:249], 0, s[50:51]
	s_mov_b32 m0, s31
	s_nop 0
	global_load_lds_dwordx4 v[174:175], off
	s_waitcnt vmcnt(6)
	s_barrier
	s_setprio 1
	v_mfma_f32_16x16x32_bf16 v[32:35], v[190:193], v[226:229], v[32:35]
	v_mfma_f32_16x16x32_bf16 v[28:31], v[190:193], v[238:241], v[28:31]
	v_mfma_f32_16x16x32_bf16 v[24:27], v[198:201], v[226:229], v[24:27]
	v_mfma_f32_16x16x32_bf16 v[20:23], v[198:201], v[238:241], v[20:23]
	v_mfma_f32_16x16x32_bf16 v[16:19], v[206:209], v[226:229], v[16:19]
	v_mfma_f32_16x16x32_bf16 v[12:15], v[206:209], v[238:241], v[12:15]
	v_mfma_f32_16x16x32_bf16 v[8:11], v[214:217], v[226:229], v[8:11]
	v_mfma_f32_16x16x32_bf16 v[4:7], v[214:217], v[238:241], v[4:7]
	v_mfma_f32_16x16x32_bf16 v[32:35], v[194:197], v[230:233], v[32:35]
	v_mfma_f32_16x16x32_bf16 v[28:31], v[194:197], v[242:245], v[28:31]
	v_mfma_f32_16x16x32_bf16 v[24:27], v[202:205], v[230:233], v[24:27]
	v_mfma_f32_16x16x32_bf16 v[20:23], v[202:205], v[242:245], v[20:23]
	v_mfma_f32_16x16x32_bf16 v[16:19], v[210:213], v[230:233], v[16:19]
	v_mfma_f32_16x16x32_bf16 v[12:15], v[210:213], v[242:245], v[12:15]
	v_mfma_f32_16x16x32_bf16 v[8:11], v[218:221], v[230:233], v[8:11]
	v_mfma_f32_16x16x32_bf16 v[4:7], v[218:221], v[242:245], v[4:7]
	s_setprio 0
	s_add_i32 s29, s29, 2
	s_add_u32 s12, s12, 0x100
	s_addc_u32 s13, s13, 0
	s_cmp_lt_u32 s29, 40
	s_barrier
	s_cbranch_scc0 .Lpk_exit_7

; #define LDA8(dst, b, h) _Pragma("unroll") for (int m = 0; m < 4; ++m) _Pragma("unroll") for (int k = 0; k < 2; ++k) \
;     dst[m][k] = *(const bf16x8*)((const char*)SA8(b, h) + lds_byte8(wr * 64 + m * 16 + fr, k * 32 + fq * 8))
; #define LDB8(dst, b, h) _Pragma("unroll") for (int n = 0; n < 2; ++n) _Pragma("unroll") for (int k = 0; k < 2; ++k) \
;     dst[n][k] = *(const bf16x8*)((const char*)SB8(b, h) + lds_byte8(wc * 32 + n * 16 + fr, k * 32 + fq * 8))
; #define WAIT_V8(n) asm volatile("s_waitcnt vmcnt(" #n ")" ::: "memory")
; #define WAIT_L8(n) asm volatile("s_waitcnt lgkmcnt(" #n ")" ::: "memory")
; #define BAR8 __builtin_amdgcn_s_barrier()
;     ...
;   { LDB8(B0, 0, 0); LDA8(At, 0, 0); STAGE8(SA8(1, 1), A, lda, brow + 128, nt - 1);
;     BAR8; WAIT_L8(0); MMA8(0, 0, At, B0); BAR8;
;     LDB8(B1, 0, 1); BAR8; WAIT_L8(0); MMA8(0, 1, At, B1); BAR8;
;     LDA8(At, 0, 1); WAIT_V8(4); BAR8; WAIT_L8(0); MMA8(1, 0, At, B0); MMA8(1, 1, At, B1); BAR8; }
.Lpk_exit_7:
	s_add_i32 s27, s27, 0xb0000
	s_add_u32 s2, s2, s27
	s_addc_u32 s3, s3, 0
	s_add_u32 s2, s2, 0x2001580
	s_addc_u32 s3, s3, 0
	v_lshl_add_u64 v[132:133], v[132:133], 1, s[2:3]
	v_readfirstlane_b32 s12, v172
	v_lshl_add_u64 v[0:1], v[0:1], 1, v[132:133]
	s_mov_b32 m0, s12
	ds_read_b128 v[138:141], v171
	ds_read_b128 v[142:145], v171 offset:1024
	ds_read_b128 v[160:163], v171 offset:2048
	ds_read_b128 v[164:167], v171 offset:3072
	ds_read_b128 v[174:177], v156
	ds_read_b128 v[178:181], v156 offset:1024
	ds_read_b128 v[182:185], v155
	ds_read_b128 v[186:189], v155 offset:1024
	ds_read_b128 v[190:193], v154
	ds_read_b128 v[194:197], v154 offset:1024
	ds_read_b128 v[198:201], v153
	ds_read_b128 v[202:205], v153 offset:1024
	global_load_lds_dwordx4 v[0:1], off
	v_lshl_add_u64 v[0:1], v[136:137], 1, s[2:3]
	v_readfirstlane_b32 s2, v173
	v_lshl_add_u64 v[0:1], v[134:135], 1, v[0:1]
	s_mov_b32 m0, s2
	s_nop 0
	global_load_lds_dwordx4 v[0:1], off
	s_barrier
	s_waitcnt lgkmcnt(0)
	s_setprio 1
	s_waitcnt lgkmcnt(0)
	v_mfma_f32_16x16x32_bf16 v[128:131], v[174:177], v[138:141], v[128:131]
	v_mfma_f32_16x16x32_bf16 v[124:127], v[174:177], v[160:163], v[124:127]
	v_mfma_f32_16x16x32_bf16 v[120:123], v[182:185], v[138:141], v[120:123]
	v_mfma_f32_16x16x32_bf16 v[112:115], v[190:193], v[138:141], v[112:115]
	v_mfma_f32_16x16x32_bf16 v[128:131], v[178:181], v[142:145], v[128:131]
	v_mfma_f32_16x16x32_bf16 v[124:127], v[178:181], v[164:167], v[124:127]
	v_mfma_f32_16x16x32_bf16 v[120:123], v[186:189], v[142:145], v[120:123]
	v_mfma_f32_16x16x32_bf16 v[116:119], v[182:185], v[160:163], v[116:119]
	v_mfma_f32_16x16x32_bf16 v[112:115], v[194:197], v[142:145], v[112:115]
	v_mfma_f32_16x16x32_bf16 v[108:111], v[190:193], v[160:163], v[108:111]
	v_mfma_f32_16x16x32_bf16 v[104:107], v[198:201], v[138:141], v[104:107]
	v_mfma_f32_16x16x32_bf16 v[100:103], v[198:201], v[160:163], v[100:103]
	v_mfma_f32_16x16x32_bf16 v[132:135], v[186:189], v[164:167], v[116:119]
	v_mfma_f32_16x16x32_bf16 v[170:173], v[194:197], v[164:167], v[108:111]
	v_mfma_f32_16x16x32_bf16 v[206:209], v[202:205], v[142:145], v[104:107]
	v_mfma_f32_16x16x32_bf16 v[210:213], v[202:205], v[164:167], v[100:103]
	s_setprio 0
	s_barrier
	s_nop 1
	ds_read_b128 v[100:103], v169
	ds_read_b128 v[104:107], v169 offset:1024
	ds_read_b128 v[108:111], v169 offset:2048
	ds_read_b128 v[116:119], v169 offset:3072
	s_barrier
	s_waitcnt lgkmcnt(0)
	s_setprio 1
	s_waitcnt lgkmcnt(0)
	v_mfma_f32_16x16x32_bf16 v[80:83], v[190:193], v[100:103], v[80:83]
	v_mfma_f32_16x16x32_bf16 v[76:79], v[190:193], v[108:111], v[76:79]
	v_mfma_f32_16x16x32_bf16 v[72:75], v[198:201], v[100:103], v[72:75]
	v_mfma_f32_16x16x32_bf16 v[68:71], v[198:201], v[108:111], v[68:71]
	v_mfma_f32_16x16x32_bf16 v[96:99], v[174:177], v[100:103], v[96:99]
	v_mfma_f32_16x16x32_bf16 v[92:95], v[174:177], v[108:111], v[92:95]
	v_mfma_f32_16x16x32_bf16 v[88:91], v[182:185], v[100:103], v[88:91]
	v_mfma_f32_16x16x32_bf16 v[84:87], v[182:185], v[108:111], v[84:87]
	v_mfma_f32_16x16x32_bf16 v[80:83], v[194:197], v[104:107], v[80:83]
	v_mfma_f32_16x16x32_bf16 v[76:79], v[194:197], v[116:119], v[76:79]
	v_mfma_f32_16x16x32_bf16 v[72:75], v[202:205], v[104:107], v[72:75]
	v_mfma_f32_16x16x32_bf16 v[68:71], v[202:205], v[116:119], v[68:71]
	v_mfma_f32_16x16x32_bf16 v[214:217], v[178:181], v[104:107], v[96:99]
	v_mfma_f32_16x16x32_bf16 v[174:177], v[178:181], v[116:119], v[92:95]
	v_mfma_f32_16x16x32_bf16 v[178:181], v[186:189], v[104:107], v[88:91]
	v_mfma_f32_16x16x32_bf16 v[182:185], v[186:189], v[116:119], v[84:87]
	s_setprio 0
	s_barrier
	s_nop 0
	ds_read_b128 v[84:87], v156 offset:16384
	ds_read_b128 v[88:91], v156 offset:17408
	ds_read_b128 v[92:95], v155 offset:16384
	ds_read_b128 v[96:99], v155 offset:17408
	ds_read_b128 v[186:189], v154 offset:16384
	ds_read_b128 v[190:193], v154 offset:17408
	ds_read_b128 v[194:197], v153 offset:16384
	ds_read_b128 v[198:201], v153 offset:17408
	s_waitcnt vmcnt(4)
	s_barrier
	s_waitcnt lgkmcnt(0)
	s_setprio 1
	s_waitcnt lgkmcnt(0)
	v_mfma_f32_16x16x32_bf16 v[64:67], v[84:87], v[138:141], v[64:67]
	v_mfma_f32_16x16x32_bf16 v[60:63], v[84:87], v[160:163], v[60:63]
	v_mfma_f32_16x16x32_bf16 v[56:59], v[92:95], v[138:141], v[56:59]
	v_mfma_f32_16x16x32_bf16 v[52:55], v[92:95], v[160:163], v[52:55]
	v_mfma_f32_16x16x32_bf16 v[48:51], v[186:189], v[138:141], v[48:51]
	v_mfma_f32_16x16x32_bf16 v[44:47], v[186:189], v[160:163], v[44:47]
	v_mfma_f32_16x16x32_bf16 v[40:43], v[194:197], v[138:141], v[40:43]
	v_mfma_f32_16x16x32_bf16 v[36:39], v[194:197], v[160:163], v[36:39]
	v_mfma_f32_16x16x32_bf16 v[64:67], v[88:91], v[142:145], v[64:67]
	v_mfma_f32_16x16x32_bf16 v[60:63], v[88:91], v[164:167], v[60:63]
	v_mfma_f32_16x16x32_bf16 v[56:59], v[96:99], v[142:145], v[56:59]
	v_mfma_f32_16x16x32_bf16 v[52:55], v[96:99], v[164:167], v[52:55]
	v_mfma_f32_16x16x32_bf16 v[48:51], v[190:193], v[142:145], v[48:51]
	v_mfma_f32_16x16x32_bf16 v[44:47], v[190:193], v[164:167], v[44:47]
	v_mfma_f32_16x16x32_bf16 v[40:43], v[198:201], v[142:145], v[40:43]
	v_mfma_f32_16x16x32_bf16 v[36:39], v[198:201], v[164:167], v[36:39]
	s_setprio 0
	s_setprio 1
	v_mfma_f32_16x16x32_bf16 v[32:35], v[84:87], v[100:103], v[32:35]
	v_mfma_f32_16x16x32_bf16 v[28:31], v[84:87], v[108:111], v[28:31]
	v_mfma_f32_16x16x32_bf16 v[24:27], v[92:95], v[100:103], v[24:27]
	v_mfma_f32_16x16x32_bf16 v[20:23], v[92:95], v[108:111], v[20:23]
	v_mfma_f32_16x16x32_bf16 v[16:19], v[186:189], v[100:103], v[16:19]
	v_mfma_f32_16x16x32_bf16 v[12:15], v[186:189], v[108:111], v[12:15]
	v_mfma_f32_16x16x32_bf16 v[8:11], v[194:197], v[100:103], v[8:11]
	v_mfma_f32_16x16x32_bf16 v[4:7], v[194:197], v[108:111], v[4:7]
	v_mfma_f32_16x16x32_bf16 v[136:139], v[88:91], v[104:107], v[32:35]
	v_mfma_f32_16x16x32_bf16 v[140:143], v[88:91], v[116:119], v[28:31]
	v_mfma_f32_16x16x32_bf16 v[160:163], v[96:99], v[104:107], v[24:27]
	v_mfma_f32_16x16x32_bf16 v[164:167], v[96:99], v[116:119], v[20:23]
	v_mfma_f32_16x16x32_bf16 v[202:205], v[190:193], v[104:107], v[16:19]
	v_mfma_f32_16x16x32_bf16 v[186:189], v[190:193], v[116:119], v[12:15]
	v_mfma_f32_16x16x32_bf16 v[190:193], v[198:201], v[104:107], v[8:11]
	v_mfma_f32_16x16x32_bf16 v[194:197], v[198:201], v[116:119], v[4:7]
	s_setprio 0
	s_barrier
; #define LDA8(dst, b, h) _Pragma("unroll") for (int m = 0; m < 4; ++m) _Pragma("unroll") for (int k = 0; k < 2; ++k) \
;     dst[m][k] = *(const bf16x8*)((const char*)SA8(b, h) + lds_byte8(wr * 64 + m * 16 + fr, k * 32 + fq * 8))
; #define LDB8(dst, b, h) _Pragma("unroll") for (int n = 0; n < 2; ++n) _Pragma("unroll") for (int k = 0; k < 2; ++k) \
;     dst[n][k] = *(const bf16x8*)((const char*)SB8(b, h) + lds_byte8(wc * 32 + n * 16 + fr, k * 32 + fq * 8))
; #define WAIT_V8(n) asm volatile("s_waitcnt vmcnt(" #n ")" ::: "memory")
; #define WAIT_L8(n) asm volatile("s_waitcnt lgkmcnt(" #n ")" ::: "memory")
; #define BAR8 __builtin_amdgcn_s_barrier()
;     ...
;   { LDB8(B0, 1, 0); LDA8(At, 1, 0); WAIT_V8(2); BAR8; WAIT_L8(0); MMA8(0, 0, At, B0); BAR8;
;     LDB8(B1, 1, 1); WAIT_V8(0); BAR8; WAIT_L8(0); MMA8(0, 1, At, B1); BAR8;
;     LDA8(At, 1, 1); BAR8; WAIT_L8(0); MMA8(1, 0, At, B0); MMA8(1, 1, At, B1); BAR8; }
;   if (wr == 0) BAR8;
	ds_read_b128 v[198:201], v159
	ds_read_b128 v[218:221], v159 offset:1024
	ds_read_b128 v[226:229], v159 offset:2048
	ds_read_b128 v[230:233], v159 offset:3072
	ds_read_b128 v[8:11], v156 offset:32768
	ds_read_b128 v[12:15], v156 offset:33792
	ds_read_b128 v[16:19], v155 offset:32768
	ds_read_b128 v[24:27], v155 offset:33792
	ds_read_b128 v[28:31], v154 offset:32768
	ds_read_b128 v[32:35], v154 offset:33792
	ds_read_b128 v[238:241], v153 offset:32768
	ds_read_b128 v[242:245], v153 offset:33792
	s_waitcnt vmcnt(2)
	s_barrier
	s_waitcnt lgkmcnt(0)
	s_setprio 1
	s_waitcnt lgkmcnt(0)
	v_mfma_f32_16x16x32_bf16 v[4:7], v[8:11], v[198:201], v[128:131]
	v_mfma_f32_16x16x32_bf16 v[104:107], v[12:15], v[218:221], v[4:7]
	v_mfma_f32_16x16x32_bf16 v[4:7], v[8:11], v[226:229], v[124:127]
	v_mfma_f32_16x16x32_bf16 v[116:119], v[12:15], v[230:233], v[4:7]
	v_mfma_f32_16x16x32_bf16 v[4:7], v[16:19], v[198:201], v[120:123]
	v_mfma_f32_16x16x32_bf16 v[100:103], v[24:27], v[218:221], v[4:7]
	v_mfma_f32_16x16x32_bf16 v[4:7], v[16:19], v[226:229], v[132:135]
	v_mfma_f32_16x16x32_bf16 v[108:111], v[24:27], v[230:233], v[4:7]
	v_mfma_f32_16x16x32_bf16 v[4:7], v[28:31], v[198:201], v[112:115]
	v_mfma_f32_16x16x32_bf16 v[92:95], v[32:35], v[218:221], v[4:7]
	v_mfma_f32_16x16x32_bf16 v[4:7], v[28:31], v[226:229], v[170:173]
	v_mfma_f32_16x16x32_bf16 v[96:99], v[32:35], v[230:233], v[4:7]
	v_mfma_f32_16x16x32_bf16 v[4:7], v[238:241], v[198:201], v[206:209]
	v_mfma_f32_16x16x32_bf16 v[84:87], v[242:245], v[218:221], v[4:7]
	v_mfma_f32_16x16x32_bf16 v[4:7], v[238:241], v[226:229], v[210:213]
	v_mfma_f32_16x16x32_bf16 v[88:91], v[242:245], v[230:233], v[4:7]
	s_setprio 0
	s_barrier
	ds_read_b128 v[132:135], v158
	ds_read_b128 v[168:171], v158 offset:1024
	ds_read_b128 v[206:209], v158 offset:2048
	ds_read_b128 v[210:213], v158 offset:3072
	s_waitcnt vmcnt(0)
	s_barrier
	s_waitcnt lgkmcnt(0)
	s_setprio 1
	s_waitcnt lgkmcnt(0)
	v_mfma_f32_16x16x32_bf16 v[4:7], v[8:11], v[132:135], v[214:217]
	v_mfma_f32_16x16x32_bf16 v[8:11], v[8:11], v[206:209], v[174:177]
	v_mfma_f32_16x16x32_bf16 v[4:7], v[12:15], v[168:171], v[4:7]
	v_mfma_f32_16x16x32_bf16 v[20:23], v[12:15], v[210:213], v[8:11]
	v_mfma_f32_16x16x32_bf16 v[8:11], v[16:19], v[132:135], v[178:181]
	v_mfma_f32_16x16x32_bf16 v[12:15], v[16:19], v[206:209], v[182:185]
	v_mfma_f32_16x16x32_bf16 v[8:11], v[24:27], v[168:171], v[8:11]
	v_mfma_f32_16x16x32_bf16 v[24:27], v[24:27], v[210:213], v[12:15]
	v_mfma_f32_16x16x32_bf16 v[12:15], v[28:31], v[132:135], v[80:83]
	v_mfma_f32_16x16x32_bf16 v[16:19], v[28:31], v[206:209], v[76:79]
	v_mfma_f32_16x16x32_bf16 v[12:15], v[32:35], v[168:171], v[12:15]
	v_mfma_f32_16x16x32_bf16 v[28:31], v[32:35], v[210:213], v[16:19]
	v_mfma_f32_16x16x32_bf16 v[16:19], v[238:241], v[132:135], v[72:75]
	v_mfma_f32_16x16x32_bf16 v[32:35], v[238:241], v[206:209], v[68:71]
	v_mfma_f32_16x16x32_bf16 v[16:19], v[242:245], v[168:171], v[16:19]
	v_mfma_f32_16x16x32_bf16 v[32:35], v[242:245], v[210:213], v[32:35]
	s_setprio 0
	s_barrier
	ds_read_b128 v[172:175], v156 offset:49152
	ds_read_b128 v[156:159], v156 offset:50176
	ds_read_b128 v[176:179], v155 offset:49152
	ds_read_b128 v[180:183], v155 offset:50176
	ds_read_b128 v[214:217], v154 offset:49152
	ds_read_b128 v[238:241], v154 offset:50176
	ds_read_b128 v[242:245], v153 offset:49152
	ds_read_b128 v[150:153], v153 offset:50176
	s_barrier
	s_waitcnt lgkmcnt(0)
	s_setprio 1
	s_waitcnt lgkmcnt(0)
	v_mfma_f32_16x16x32_bf16 v[64:67], v[172:175], v[198:201], v[64:67]
	v_mfma_f32_16x16x32_bf16 v[60:63], v[172:175], v[226:229], v[60:63]
	v_mfma_f32_16x16x32_bf16 v[56:59], v[176:179], v[198:201], v[56:59]
	v_mfma_f32_16x16x32_bf16 v[52:55], v[176:179], v[226:229], v[52:55]
	v_mfma_f32_16x16x32_bf16 v[48:51], v[214:217], v[198:201], v[48:51]
	v_mfma_f32_16x16x32_bf16 v[44:47], v[214:217], v[226:229], v[44:47]
	v_mfma_f32_16x16x32_bf16 v[40:43], v[242:245], v[198:201], v[40:43]
	v_mfma_f32_16x16x32_bf16 v[36:39], v[242:245], v[226:229], v[36:39]
	v_mfma_f32_16x16x32_bf16 v[128:131], v[156:159], v[218:221], v[64:67]
	v_mfma_f32_16x16x32_bf16 v[124:127], v[156:159], v[230:233], v[60:63]
	v_mfma_f32_16x16x32_bf16 v[120:123], v[180:183], v[218:221], v[56:59]
	v_mfma_f32_16x16x32_bf16 v[112:115], v[180:183], v[230:233], v[52:55]
	v_mfma_f32_16x16x32_bf16 v[80:83], v[238:241], v[218:221], v[48:51]
	v_mfma_f32_16x16x32_bf16 v[76:79], v[238:241], v[230:233], v[44:47]
	v_mfma_f32_16x16x32_bf16 v[72:75], v[150:153], v[218:221], v[40:43]
	v_mfma_f32_16x16x32_bf16 v[68:71], v[150:153], v[230:233], v[36:39]
	s_setprio 0
	s_setprio 1
	v_mfma_f32_16x16x32_bf16 v[40:43], v[172:175], v[206:209], v[140:143]
	v_mfma_f32_16x16x32_bf16 v[44:47], v[176:179], v[206:209], v[164:167]
	v_mfma_f32_16x16x32_bf16 v[48:51], v[214:217], v[206:209], v[186:189]
	v_mfma_f32_16x16x32_bf16 v[36:39], v[172:175], v[132:135], v[136:139]
	v_mfma_f32_16x16x32_bf16 v[52:55], v[156:159], v[210:213], v[40:43]
	v_mfma_f32_16x16x32_bf16 v[40:43], v[176:179], v[132:135], v[160:163]
	v_mfma_f32_16x16x32_bf16 v[56:59], v[180:183], v[210:213], v[44:47]
	v_mfma_f32_16x16x32_bf16 v[44:47], v[214:217], v[132:135], v[202:205]
	v_mfma_f32_16x16x32_bf16 v[60:63], v[238:241], v[210:213], v[48:51]
	v_mfma_f32_16x16x32_bf16 v[48:51], v[242:245], v[132:135], v[190:193]
	v_mfma_f32_16x16x32_bf16 v[64:67], v[242:245], v[206:209], v[194:197]
	v_mfma_f32_16x16x32_bf16 v[36:39], v[156:159], v[168:171], v[36:39]
	v_mfma_f32_16x16x32_bf16 v[40:43], v[180:183], v[168:171], v[40:43]
	v_mfma_f32_16x16x32_bf16 v[44:47], v[238:241], v[168:171], v[44:47]
	v_mfma_f32_16x16x32_bf16 v[48:51], v[150:153], v[168:171], v[48:51]
	v_mfma_f32_16x16x32_bf16 v[64:67], v[150:153], v[210:213], v[64:67]
	s_setprio 0
	s_movk_i32 s2, 0x100
	v_cmp_gt_u32_e32 vcc, s2, v3
	s_barrier
	s_and_saveexec_b64 s[2:3], vcc
	s_cbranch_execz .LBB0_1328
	s_barrier
